# GEMM epilogues: tiles followed by another K-loop use plain write-back stores, only the last tiles before the grid barrier write through (sc1); dead old P1 epilogue code removed
# speedup vs baseline: 1.0124x; 1.0124x over previous
.LBB0_135:
	s_ashr_i32 s73, s46, 1
	s_and_b32 s71, s46, 1
	s_cmp_lt_u32 s8, 4
	s_cbranch_scc0 .Lp1_late
	s_cmp_lt_u32 s46, 4
	s_cbranch_scc1 .Lepi_plain_e
	s_cmp_eq_u32 s73, 4
	s_cbranch_scc1 .Lepi_plain_e
	s_cmp_eq_u32 s73, 6
	s_cbranch_scc1 .Lepi_gelu_e
	s_cmp_eq_u32 s73, 7
	s_cbranch_scc1 .Lepi_gelu_e
	s_cmp_lg_u32 s73, 2
	s_cbranch_scc1 .Lepi_silu_e
.Lp1_late:
	s_cmp_lt_u32 s46, 4
	s_cbranch_scc1 .Lepi_plain
	s_cmp_eq_u32 s73, 4
	s_cbranch_scc1 .Lepi_plain
	s_cmp_eq_u32 s73, 6
	s_cbranch_scc1 .Lepi_gelu
	s_cmp_eq_u32 s73, 7
	s_cbranch_scc1 .Lepi_gelu
	s_cmp_lg_u32 s73, 2
	s_cbranch_scc1 .Lepi_silu
	s_lshl_b32 s30, s48, 8
	s_cmp_eq_u32 s57, 2
	s_cselect_b32 s47, 0x80, 0
	s_add_i32 s57, s30, s60
	s_add_i32 s57, s57, s47
	s_cmp_lg_u32 s73, 2
	s_mov_b64 s[48:49], -1
	s_cbranch_scc0 .LBB0_324

.Lepi_gelu6:
	v_and_b32_e32 v132, 0x7fffffff, v128
	v_and_b32_e32 v133, 0x7fffffff, v129
	v_and_b32_e32 v134, 0x7fffffff, v130
	v_and_b32_e32 v135, 0x7fffffff, v131
	v_pk_mul_f32 v[144:145], v[128:129], v[128:129]
	v_pk_mul_f32 v[146:147], v[130:131], v[130:131]
	v_pk_fma_f32 v[136:137], v[132:133], s[84:85], 1.0 op_sel_hi:[1,0,0]
	v_pk_fma_f32 v[138:139], v[134:135], s[84:85], 1.0 op_sel_hi:[1,0,0]
	v_pk_mul_f32 v[144:145], v[144:145], s[80:81] op_sel_hi:[1,0]
	v_pk_mul_f32 v[146:147], v[146:147], s[80:81] op_sel_hi:[1,0]
	v_rcp_f32_e32 v136, v136
	v_rcp_f32_e32 v137, v137
	v_rcp_f32_e32 v138, v138
	v_rcp_f32_e32 v139, v139
	v_exp_f32_e32 v144, v144
	v_exp_f32_e32 v145, v145
	v_exp_f32_e32 v146, v146
	v_exp_f32_e32 v147, v147
	v_pk_fma_f32 v[140:141], v[136:137], s[86:87], v[0:1] op_sel_hi:[1,0,0]
	v_pk_fma_f32 v[142:143], v[138:139], s[86:87], v[0:1] op_sel_hi:[1,0,0]
	v_pk_fma_f32 v[140:141], v[136:137], v[140:141], s[88:89] op_sel_hi:[1,1,0]
	v_pk_fma_f32 v[142:143], v[138:139], v[142:143], s[88:89] op_sel_hi:[1,1,0]
	v_pk_fma_f32 v[140:141], v[136:137], v[140:141], s[82:83] op_sel_hi:[1,1,0]
	v_pk_fma_f32 v[142:143], v[138:139], v[142:143], s[82:83] op_sel_hi:[1,1,0]
	v_pk_fma_f32 v[140:141], v[136:137], v[140:141], s[48:49] op_sel_hi:[1,1,0]
	v_pk_fma_f32 v[142:143], v[138:139], v[142:143], s[48:49] op_sel_hi:[1,1,0]
	v_pk_mul_f32 v[140:141], v[136:137], v[140:141]
	v_pk_mul_f32 v[142:143], v[138:139], v[142:143]
	v_pk_mul_f32 v[140:141], v[140:141], v[144:145]
	v_pk_mul_f32 v[142:143], v[142:143], v[146:147]
	v_max_f32_e32 v128, 0, v128
	v_max_f32_e32 v129, 0, v129
	v_max_f32_e32 v130, 0, v130
	v_max_f32_e32 v131, 0, v131
	v_pk_fma_f32 v[128:129], v[132:133], v[140:141], v[128:129] neg_lo:[1,0,0] neg_hi:[1,0,0]
	v_pk_fma_f32 v[130:131], v[134:135], v[142:143], v[130:131] neg_lo:[1,0,0] neg_hi:[1,0,0]
	v_and_b32_e32 v132, 0x7fffffff, v120
	v_and_b32_e32 v133, 0x7fffffff, v121
	v_and_b32_e32 v134, 0x7fffffff, v122
	v_and_b32_e32 v135, 0x7fffffff, v123
	v_pk_mul_f32 v[144:145], v[120:121], v[120:121]
	v_pk_mul_f32 v[146:147], v[122:123], v[122:123]
	v_pk_fma_f32 v[136:137], v[132:133], s[84:85], 1.0 op_sel_hi:[1,0,0]
	v_pk_fma_f32 v[138:139], v[134:135], s[84:85], 1.0 op_sel_hi:[1,0,0]
	v_pk_mul_f32 v[144:145], v[144:145], s[80:81] op_sel_hi:[1,0]
	v_pk_mul_f32 v[146:147], v[146:147], s[80:81] op_sel_hi:[1,0]
	v_rcp_f32_e32 v136, v136
	v_rcp_f32_e32 v137, v137
	v_rcp_f32_e32 v138, v138
	v_rcp_f32_e32 v139, v139
	v_exp_f32_e32 v144, v144
	v_exp_f32_e32 v145, v145
	v_exp_f32_e32 v146, v146
	v_exp_f32_e32 v147, v147
	v_pk_fma_f32 v[140:141], v[136:137], s[86:87], v[0:1] op_sel_hi:[1,0,0]
	v_pk_fma_f32 v[142:143], v[138:139], s[86:87], v[0:1] op_sel_hi:[1,0,0]
	v_pk_fma_f32 v[140:141], v[136:137], v[140:141], s[88:89] op_sel_hi:[1,1,0]
	v_pk_fma_f32 v[142:143], v[138:139], v[142:143], s[88:89] op_sel_hi:[1,1,0]
	v_pk_fma_f32 v[140:141], v[136:137], v[140:141], s[82:83] op_sel_hi:[1,1,0]
	v_pk_fma_f32 v[142:143], v[138:139], v[142:143], s[82:83] op_sel_hi:[1,1,0]
	v_pk_fma_f32 v[140:141], v[136:137], v[140:141], s[48:49] op_sel_hi:[1,1,0]
	v_pk_fma_f32 v[142:143], v[138:139], v[142:143], s[48:49] op_sel_hi:[1,1,0]
	v_pk_mul_f32 v[140:141], v[136:137], v[140:141]
	v_pk_mul_f32 v[142:143], v[138:139], v[142:143]
	v_pk_mul_f32 v[140:141], v[140:141], v[144:145]
	v_pk_mul_f32 v[142:143], v[142:143], v[146:147]
	v_max_f32_e32 v120, 0, v120
	v_max_f32_e32 v121, 0, v121
	v_max_f32_e32 v122, 0, v122
	v_max_f32_e32 v123, 0, v123
	v_pk_fma_f32 v[120:121], v[132:133], v[140:141], v[120:121] neg_lo:[1,0,0] neg_hi:[1,0,0]
	v_pk_fma_f32 v[122:123], v[134:135], v[142:143], v[122:123] neg_lo:[1,0,0] neg_hi:[1,0,0]
	v_cvt_pk_bf16_f32 v128, v128, v129
	v_cvt_pk_bf16_f32 v129, v130, v131
	v_cvt_pk_bf16_f32 v130, v120, v121
	v_cvt_pk_bf16_f32 v131, v122, v123
	global_store_dwordx4 v148, v[128:131], s[50:51] sc1
	v_and_b32_e32 v132, 0x7fffffff, v112
	v_and_b32_e32 v133, 0x7fffffff, v113
	v_and_b32_e32 v134, 0x7fffffff, v114
	v_and_b32_e32 v135, 0x7fffffff, v115
	v_pk_mul_f32 v[144:145], v[112:113], v[112:113]
	v_pk_mul_f32 v[146:147], v[114:115], v[114:115]
	v_pk_fma_f32 v[136:137], v[132:133], s[84:85], 1.0 op_sel_hi:[1,0,0]
	v_pk_fma_f32 v[138:139], v[134:135], s[84:85], 1.0 op_sel_hi:[1,0,0]
	v_pk_mul_f32 v[144:145], v[144:145], s[80:81] op_sel_hi:[1,0]
	v_pk_mul_f32 v[146:147], v[146:147], s[80:81] op_sel_hi:[1,0]
	v_rcp_f32_e32 v136, v136
	v_rcp_f32_e32 v137, v137
	v_rcp_f32_e32 v138, v138
	v_rcp_f32_e32 v139, v139
	v_exp_f32_e32 v144, v144
	v_exp_f32_e32 v145, v145
	v_exp_f32_e32 v146, v146
	v_exp_f32_e32 v147, v147
	v_pk_fma_f32 v[140:141], v[136:137], s[86:87], v[0:1] op_sel_hi:[1,0,0]
	v_pk_fma_f32 v[142:143], v[138:139], s[86:87], v[0:1] op_sel_hi:[1,0,0]
	v_pk_fma_f32 v[140:141], v[136:137], v[140:141], s[88:89] op_sel_hi:[1,1,0]
	v_pk_fma_f32 v[142:143], v[138:139], v[142:143], s[88:89] op_sel_hi:[1,1,0]
	v_pk_fma_f32 v[140:141], v[136:137], v[140:141], s[82:83] op_sel_hi:[1,1,0]
	v_pk_fma_f32 v[142:143], v[138:139], v[142:143], s[82:83] op_sel_hi:[1,1,0]
	v_pk_fma_f32 v[140:141], v[136:137], v[140:141], s[48:49] op_sel_hi:[1,1,0]
	v_pk_fma_f32 v[142:143], v[138:139], v[142:143], s[48:49] op_sel_hi:[1,1,0]
	v_pk_mul_f32 v[140:141], v[136:137], v[140:141]
	v_pk_mul_f32 v[142:143], v[138:139], v[142:143]
	v_pk_mul_f32 v[140:141], v[140:141], v[144:145]
	v_pk_mul_f32 v[142:143], v[142:143], v[146:147]
	v_max_f32_e32 v112, 0, v112
	v_max_f32_e32 v113, 0, v113
	v_max_f32_e32 v114, 0, v114
	v_max_f32_e32 v115, 0, v115
	v_pk_fma_f32 v[112:113], v[132:133], v[140:141], v[112:113] neg_lo:[1,0,0] neg_hi:[1,0,0]
	v_pk_fma_f32 v[114:115], v[134:135], v[142:143], v[114:115] neg_lo:[1,0,0] neg_hi:[1,0,0]
	v_and_b32_e32 v132, 0x7fffffff, v104
	v_and_b32_e32 v133, 0x7fffffff, v105
	v_and_b32_e32 v134, 0x7fffffff, v106
	v_and_b32_e32 v135, 0x7fffffff, v107
	v_pk_mul_f32 v[144:145], v[104:105], v[104:105]
	v_pk_mul_f32 v[146:147], v[106:107], v[106:107]
	v_pk_fma_f32 v[136:137], v[132:133], s[84:85], 1.0 op_sel_hi:[1,0,0]
	v_pk_fma_f32 v[138:139], v[134:135], s[84:85], 1.0 op_sel_hi:[1,0,0]
	v_pk_mul_f32 v[144:145], v[144:145], s[80:81] op_sel_hi:[1,0]
	v_pk_mul_f32 v[146:147], v[146:147], s[80:81] op_sel_hi:[1,0]
	v_rcp_f32_e32 v136, v136
	v_rcp_f32_e32 v137, v137
	v_rcp_f32_e32 v138, v138
	v_rcp_f32_e32 v139, v139
	v_exp_f32_e32 v144, v144
	v_exp_f32_e32 v145, v145
	v_exp_f32_e32 v146, v146
	v_exp_f32_e32 v147, v147
	v_pk_fma_f32 v[140:141], v[136:137], s[86:87], v[0:1] op_sel_hi:[1,0,0]
	v_pk_fma_f32 v[142:143], v[138:139], s[86:87], v[0:1] op_sel_hi:[1,0,0]
	v_pk_fma_f32 v[140:141], v[136:137], v[140:141], s[88:89] op_sel_hi:[1,1,0]
	v_pk_fma_f32 v[142:143], v[138:139], v[142:143], s[88:89] op_sel_hi:[1,1,0]
	v_pk_fma_f32 v[140:141], v[136:137], v[140:141], s[82:83] op_sel_hi:[1,1,0]
	v_pk_fma_f32 v[142:143], v[138:139], v[142:143], s[82:83] op_sel_hi:[1,1,0]
	v_pk_fma_f32 v[140:141], v[136:137], v[140:141], s[48:49] op_sel_hi:[1,1,0]
	v_pk_fma_f32 v[142:143], v[138:139], v[142:143], s[48:49] op_sel_hi:[1,1,0]
	v_pk_mul_f32 v[140:141], v[136:137], v[140:141]
	v_pk_mul_f32 v[142:143], v[138:139], v[142:143]
	v_pk_mul_f32 v[140:141], v[140:141], v[144:145]
	v_pk_mul_f32 v[142:143], v[142:143], v[146:147]
	v_max_f32_e32 v104, 0, v104
	v_max_f32_e32 v105, 0, v105
	v_max_f32_e32 v106, 0, v106
	v_max_f32_e32 v107, 0, v107
	v_pk_fma_f32 v[104:105], v[132:133], v[140:141], v[104:105] neg_lo:[1,0,0] neg_hi:[1,0,0]
	v_pk_fma_f32 v[106:107], v[134:135], v[142:143], v[106:107] neg_lo:[1,0,0] neg_hi:[1,0,0]
	v_cvt_pk_bf16_f32 v112, v112, v113
	v_cvt_pk_bf16_f32 v113, v114, v115
	v_cvt_pk_bf16_f32 v114, v104, v105
	v_cvt_pk_bf16_f32 v115, v106, v107
	global_store_dwordx4 v148, v[112:115], s[50:51] offset:256 sc1
	v_add_u32_e32 v148, s81, v148
	v_and_b32_e32 v132, 0x7fffffff, v124
	v_and_b32_e32 v133, 0x7fffffff, v125
	v_and_b32_e32 v134, 0x7fffffff, v126
	v_and_b32_e32 v135, 0x7fffffff, v127
	v_pk_mul_f32 v[144:145], v[124:125], v[124:125]
	v_pk_mul_f32 v[146:147], v[126:127], v[126:127]
	v_pk_fma_f32 v[136:137], v[132:133], s[84:85], 1.0 op_sel_hi:[1,0,0]
	v_pk_fma_f32 v[138:139], v[134:135], s[84:85], 1.0 op_sel_hi:[1,0,0]
	v_pk_mul_f32 v[144:145], v[144:145], s[80:81] op_sel_hi:[1,0]
	v_pk_mul_f32 v[146:147], v[146:147], s[80:81] op_sel_hi:[1,0]
	v_rcp_f32_e32 v136, v136
	v_rcp_f32_e32 v137, v137
	v_rcp_f32_e32 v138, v138
	v_rcp_f32_e32 v139, v139
	v_exp_f32_e32 v144, v144
	v_exp_f32_e32 v145, v145
	v_exp_f32_e32 v146, v146
	v_exp_f32_e32 v147, v147
	v_pk_fma_f32 v[140:141], v[136:137], s[86:87], v[0:1] op_sel_hi:[1,0,0]
	v_pk_fma_f32 v[142:143], v[138:139], s[86:87], v[0:1] op_sel_hi:[1,0,0]
	v_pk_fma_f32 v[140:141], v[136:137], v[140:141], s[88:89] op_sel_hi:[1,1,0]
	v_pk_fma_f32 v[142:143], v[138:139], v[142:143], s[88:89] op_sel_hi:[1,1,0]
	v_pk_fma_f32 v[140:141], v[136:137], v[140:141], s[82:83] op_sel_hi:[1,1,0]
	v_pk_fma_f32 v[142:143], v[138:139], v[142:143], s[82:83] op_sel_hi:[1,1,0]
	v_pk_fma_f32 v[140:141], v[136:137], v[140:141], s[48:49] op_sel_hi:[1,1,0]
	v_pk_fma_f32 v[142:143], v[138:139], v[142:143], s[48:49] op_sel_hi:[1,1,0]
	v_pk_mul_f32 v[140:141], v[136:137], v[140:141]
	v_pk_mul_f32 v[142:143], v[138:139], v[142:143]
	v_pk_mul_f32 v[140:141], v[140:141], v[144:145]
	v_pk_mul_f32 v[142:143], v[142:143], v[146:147]
	v_max_f32_e32 v124, 0, v124
	v_max_f32_e32 v125, 0, v125
	v_max_f32_e32 v126, 0, v126
	v_max_f32_e32 v127, 0, v127
	v_pk_fma_f32 v[124:125], v[132:133], v[140:141], v[124:125] neg_lo:[1,0,0] neg_hi:[1,0,0]
	v_pk_fma_f32 v[126:127], v[134:135], v[142:143], v[126:127] neg_lo:[1,0,0] neg_hi:[1,0,0]
	v_and_b32_e32 v132, 0x7fffffff, v116
	v_and_b32_e32 v133, 0x7fffffff, v117
	v_and_b32_e32 v134, 0x7fffffff, v118
	v_and_b32_e32 v135, 0x7fffffff, v119
	v_pk_mul_f32 v[144:145], v[116:117], v[116:117]
	v_pk_mul_f32 v[146:147], v[118:119], v[118:119]
	v_pk_fma_f32 v[136:137], v[132:133], s[84:85], 1.0 op_sel_hi:[1,0,0]
	v_pk_fma_f32 v[138:139], v[134:135], s[84:85], 1.0 op_sel_hi:[1,0,0]
	v_pk_mul_f32 v[144:145], v[144:145], s[80:81] op_sel_hi:[1,0]
	v_pk_mul_f32 v[146:147], v[146:147], s[80:81] op_sel_hi:[1,0]
	v_rcp_f32_e32 v136, v136
	v_rcp_f32_e32 v137, v137
	v_rcp_f32_e32 v138, v138
	v_rcp_f32_e32 v139, v139
	v_exp_f32_e32 v144, v144
	v_exp_f32_e32 v145, v145
	v_exp_f32_e32 v146, v146
	v_exp_f32_e32 v147, v147
	v_pk_fma_f32 v[140:141], v[136:137], s[86:87], v[0:1] op_sel_hi:[1,0,0]
	v_pk_fma_f32 v[142:143], v[138:139], s[86:87], v[0:1] op_sel_hi:[1,0,0]
	v_pk_fma_f32 v[140:141], v[136:137], v[140:141], s[88:89] op_sel_hi:[1,1,0]
	v_pk_fma_f32 v[142:143], v[138:139], v[142:143], s[88:89] op_sel_hi:[1,1,0]
	v_pk_fma_f32 v[140:141], v[136:137], v[140:141], s[82:83] op_sel_hi:[1,1,0]
	v_pk_fma_f32 v[142:143], v[138:139], v[142:143], s[82:83] op_sel_hi:[1,1,0]
	v_pk_fma_f32 v[140:141], v[136:137], v[140:141], s[48:49] op_sel_hi:[1,1,0]
	v_pk_fma_f32 v[142:143], v[138:139], v[142:143], s[48:49] op_sel_hi:[1,1,0]
	v_pk_mul_f32 v[140:141], v[136:137], v[140:141]
	v_pk_mul_f32 v[142:143], v[138:139], v[142:143]
	v_pk_mul_f32 v[140:141], v[140:141], v[144:145]
	v_pk_mul_f32 v[142:143], v[142:143], v[146:147]
	v_max_f32_e32 v116, 0, v116
	v_max_f32_e32 v117, 0, v117
	v_max_f32_e32 v118, 0, v118
	v_max_f32_e32 v119, 0, v119
	v_pk_fma_f32 v[116:117], v[132:133], v[140:141], v[116:117] neg_lo:[1,0,0] neg_hi:[1,0,0]
	v_pk_fma_f32 v[118:119], v[134:135], v[142:143], v[118:119] neg_lo:[1,0,0] neg_hi:[1,0,0]
	v_cvt_pk_bf16_f32 v124, v124, v125
	v_cvt_pk_bf16_f32 v125, v126, v127
	v_cvt_pk_bf16_f32 v126, v116, v117
	v_cvt_pk_bf16_f32 v127, v118, v119
	global_store_dwordx4 v148, v[124:127], s[50:51] sc1
	v_and_b32_e32 v132, 0x7fffffff, v108
	v_and_b32_e32 v133, 0x7fffffff, v109
	v_and_b32_e32 v134, 0x7fffffff, v110
	v_and_b32_e32 v135, 0x7fffffff, v111
	v_pk_mul_f32 v[144:145], v[108:109], v[108:109]
	v_pk_mul_f32 v[146:147], v[110:111], v[110:111]
	v_pk_fma_f32 v[136:137], v[132:133], s[84:85], 1.0 op_sel_hi:[1,0,0]
	v_pk_fma_f32 v[138:139], v[134:135], s[84:85], 1.0 op_sel_hi:[1,0,0]
	v_pk_mul_f32 v[144:145], v[144:145], s[80:81] op_sel_hi:[1,0]
	v_pk_mul_f32 v[146:147], v[146:147], s[80:81] op_sel_hi:[1,0]
	v_rcp_f32_e32 v136, v136
	v_rcp_f32_e32 v137, v137
	v_rcp_f32_e32 v138, v138
	v_rcp_f32_e32 v139, v139
	v_exp_f32_e32 v144, v144
	v_exp_f32_e32 v145, v145
	v_exp_f32_e32 v146, v146
	v_exp_f32_e32 v147, v147
	v_pk_fma_f32 v[140:141], v[136:137], s[86:87], v[0:1] op_sel_hi:[1,0,0]
	v_pk_fma_f32 v[142:143], v[138:139], s[86:87], v[0:1] op_sel_hi:[1,0,0]
	v_pk_fma_f32 v[140:141], v[136:137], v[140:141], s[88:89] op_sel_hi:[1,1,0]
	v_pk_fma_f32 v[142:143], v[138:139], v[142:143], s[88:89] op_sel_hi:[1,1,0]
	v_pk_fma_f32 v[140:141], v[136:137], v[140:141], s[82:83] op_sel_hi:[1,1,0]
	v_pk_fma_f32 v[142:143], v[138:139], v[142:143], s[82:83] op_sel_hi:[1,1,0]
	v_pk_fma_f32 v[140:141], v[136:137], v[140:141], s[48:49] op_sel_hi:[1,1,0]
	v_pk_fma_f32 v[142:143], v[138:139], v[142:143], s[48:49] op_sel_hi:[1,1,0]
	v_pk_mul_f32 v[140:141], v[136:137], v[140:141]
	v_pk_mul_f32 v[142:143], v[138:139], v[142:143]
	v_pk_mul_f32 v[140:141], v[140:141], v[144:145]
	v_pk_mul_f32 v[142:143], v[142:143], v[146:147]
	v_max_f32_e32 v108, 0, v108
	v_max_f32_e32 v109, 0, v109
	v_max_f32_e32 v110, 0, v110
	v_max_f32_e32 v111, 0, v111
	v_pk_fma_f32 v[108:109], v[132:133], v[140:141], v[108:109] neg_lo:[1,0,0] neg_hi:[1,0,0]
	v_pk_fma_f32 v[110:111], v[134:135], v[142:143], v[110:111] neg_lo:[1,0,0] neg_hi:[1,0,0]
	v_and_b32_e32 v132, 0x7fffffff, v100
	v_and_b32_e32 v133, 0x7fffffff, v101
	v_and_b32_e32 v134, 0x7fffffff, v102
	v_and_b32_e32 v135, 0x7fffffff, v103
	v_pk_mul_f32 v[144:145], v[100:101], v[100:101]
	v_pk_mul_f32 v[146:147], v[102:103], v[102:103]
	v_pk_fma_f32 v[136:137], v[132:133], s[84:85], 1.0 op_sel_hi:[1,0,0]
	v_pk_fma_f32 v[138:139], v[134:135], s[84:85], 1.0 op_sel_hi:[1,0,0]
	v_pk_mul_f32 v[144:145], v[144:145], s[80:81] op_sel_hi:[1,0]
	v_pk_mul_f32 v[146:147], v[146:147], s[80:81] op_sel_hi:[1,0]
	v_rcp_f32_e32 v136, v136
	v_rcp_f32_e32 v137, v137
	v_rcp_f32_e32 v138, v138
	v_rcp_f32_e32 v139, v139
	v_exp_f32_e32 v144, v144
	v_exp_f32_e32 v145, v145
	v_exp_f32_e32 v146, v146
	v_exp_f32_e32 v147, v147
	v_pk_fma_f32 v[140:141], v[136:137], s[86:87], v[0:1] op_sel_hi:[1,0,0]
	v_pk_fma_f32 v[142:143], v[138:139], s[86:87], v[0:1] op_sel_hi:[1,0,0]
	v_pk_fma_f32 v[140:141], v[136:137], v[140:141], s[88:89] op_sel_hi:[1,1,0]
	v_pk_fma_f32 v[142:143], v[138:139], v[142:143], s[88:89] op_sel_hi:[1,1,0]
	v_pk_fma_f32 v[140:141], v[136:137], v[140:141], s[82:83] op_sel_hi:[1,1,0]
	v_pk_fma_f32 v[142:143], v[138:139], v[142:143], s[82:83] op_sel_hi:[1,1,0]
	v_pk_fma_f32 v[140:141], v[136:137], v[140:141], s[48:49] op_sel_hi:[1,1,0]
	v_pk_fma_f32 v[142:143], v[138:139], v[142:143], s[48:49] op_sel_hi:[1,1,0]
	v_pk_mul_f32 v[140:141], v[136:137], v[140:141]
	v_pk_mul_f32 v[142:143], v[138:139], v[142:143]
	v_pk_mul_f32 v[140:141], v[140:141], v[144:145]
	v_pk_mul_f32 v[142:143], v[142:143], v[146:147]
	v_max_f32_e32 v100, 0, v100
	v_max_f32_e32 v101, 0, v101
	v_max_f32_e32 v102, 0, v102
	v_max_f32_e32 v103, 0, v103
	v_pk_fma_f32 v[100:101], v[132:133], v[140:141], v[100:101] neg_lo:[1,0,0] neg_hi:[1,0,0]
	v_pk_fma_f32 v[102:103], v[134:135], v[142:143], v[102:103] neg_lo:[1,0,0] neg_hi:[1,0,0]
	v_cvt_pk_bf16_f32 v108, v108, v109
	v_cvt_pk_bf16_f32 v109, v110, v111
	v_cvt_pk_bf16_f32 v110, v100, v101
	v_cvt_pk_bf16_f32 v111, v102, v103
	global_store_dwordx4 v148, v[108:111], s[50:51] offset:256 sc1
	v_add_u32_e32 v148, s81, v148
	v_and_b32_e32 v132, 0x7fffffff, v96
	v_and_b32_e32 v133, 0x7fffffff, v97
	v_and_b32_e32 v134, 0x7fffffff, v98
	v_and_b32_e32 v135, 0x7fffffff, v99
	v_pk_mul_f32 v[144:145], v[96:97], v[96:97]
	v_pk_mul_f32 v[146:147], v[98:99], v[98:99]
	v_pk_fma_f32 v[136:137], v[132:133], s[84:85], 1.0 op_sel_hi:[1,0,0]
	v_pk_fma_f32 v[138:139], v[134:135], s[84:85], 1.0 op_sel_hi:[1,0,0]
	v_pk_mul_f32 v[144:145], v[144:145], s[80:81] op_sel_hi:[1,0]
	v_pk_mul_f32 v[146:147], v[146:147], s[80:81] op_sel_hi:[1,0]
	v_rcp_f32_e32 v136, v136
	v_rcp_f32_e32 v137, v137
	v_rcp_f32_e32 v138, v138
	v_rcp_f32_e32 v139, v139
	v_exp_f32_e32 v144, v144
	v_exp_f32_e32 v145, v145
	v_exp_f32_e32 v146, v146
	v_exp_f32_e32 v147, v147
	v_pk_fma_f32 v[140:141], v[136:137], s[86:87], v[0:1] op_sel_hi:[1,0,0]
	v_pk_fma_f32 v[142:143], v[138:139], s[86:87], v[0:1] op_sel_hi:[1,0,0]
	v_pk_fma_f32 v[140:141], v[136:137], v[140:141], s[88:89] op_sel_hi:[1,1,0]
	v_pk_fma_f32 v[142:143], v[138:139], v[142:143], s[88:89] op_sel_hi:[1,1,0]
	v_pk_fma_f32 v[140:141], v[136:137], v[140:141], s[82:83] op_sel_hi:[1,1,0]
	v_pk_fma_f32 v[142:143], v[138:139], v[142:143], s[82:83] op_sel_hi:[1,1,0]
	v_pk_fma_f32 v[140:141], v[136:137], v[140:141], s[48:49] op_sel_hi:[1,1,0]
	v_pk_fma_f32 v[142:143], v[138:139], v[142:143], s[48:49] op_sel_hi:[1,1,0]
	v_pk_mul_f32 v[140:141], v[136:137], v[140:141]
	v_pk_mul_f32 v[142:143], v[138:139], v[142:143]
	v_pk_mul_f32 v[140:141], v[140:141], v[144:145]
	v_pk_mul_f32 v[142:143], v[142:143], v[146:147]
	v_max_f32_e32 v96, 0, v96
	v_max_f32_e32 v97, 0, v97
	v_max_f32_e32 v98, 0, v98
	v_max_f32_e32 v99, 0, v99
	v_pk_fma_f32 v[96:97], v[132:133], v[140:141], v[96:97] neg_lo:[1,0,0] neg_hi:[1,0,0]
	v_pk_fma_f32 v[98:99], v[134:135], v[142:143], v[98:99] neg_lo:[1,0,0] neg_hi:[1,0,0]
	v_and_b32_e32 v132, 0x7fffffff, v88
	v_and_b32_e32 v133, 0x7fffffff, v89
	v_and_b32_e32 v134, 0x7fffffff, v90
	v_and_b32_e32 v135, 0x7fffffff, v91
	v_pk_mul_f32 v[144:145], v[88:89], v[88:89]
	v_pk_mul_f32 v[146:147], v[90:91], v[90:91]
	v_pk_fma_f32 v[136:137], v[132:133], s[84:85], 1.0 op_sel_hi:[1,0,0]
	v_pk_fma_f32 v[138:139], v[134:135], s[84:85], 1.0 op_sel_hi:[1,0,0]
	v_pk_mul_f32 v[144:145], v[144:145], s[80:81] op_sel_hi:[1,0]
	v_pk_mul_f32 v[146:147], v[146:147], s[80:81] op_sel_hi:[1,0]
	v_rcp_f32_e32 v136, v136
	v_rcp_f32_e32 v137, v137
	v_rcp_f32_e32 v138, v138
	v_rcp_f32_e32 v139, v139
	v_exp_f32_e32 v144, v144
	v_exp_f32_e32 v145, v145
	v_exp_f32_e32 v146, v146
	v_exp_f32_e32 v147, v147
	v_pk_fma_f32 v[140:141], v[136:137], s[86:87], v[0:1] op_sel_hi:[1,0,0]
	v_pk_fma_f32 v[142:143], v[138:139], s[86:87], v[0:1] op_sel_hi:[1,0,0]
	v_pk_fma_f32 v[140:141], v[136:137], v[140:141], s[88:89] op_sel_hi:[1,1,0]
	v_pk_fma_f32 v[142:143], v[138:139], v[142:143], s[88:89] op_sel_hi:[1,1,0]
	v_pk_fma_f32 v[140:141], v[136:137], v[140:141], s[82:83] op_sel_hi:[1,1,0]
	v_pk_fma_f32 v[142:143], v[138:139], v[142:143], s[82:83] op_sel_hi:[1,1,0]
	v_pk_fma_f32 v[140:141], v[136:137], v[140:141], s[48:49] op_sel_hi:[1,1,0]
	v_pk_fma_f32 v[142:143], v[138:139], v[142:143], s[48:49] op_sel_hi:[1,1,0]
	v_pk_mul_f32 v[140:141], v[136:137], v[140:141]
	v_pk_mul_f32 v[142:143], v[138:139], v[142:143]
	v_pk_mul_f32 v[140:141], v[140:141], v[144:145]
	v_pk_mul_f32 v[142:143], v[142:143], v[146:147]
	v_max_f32_e32 v88, 0, v88
	v_max_f32_e32 v89, 0, v89
	v_max_f32_e32 v90, 0, v90
	v_max_f32_e32 v91, 0, v91
	v_pk_fma_f32 v[88:89], v[132:133], v[140:141], v[88:89] neg_lo:[1,0,0] neg_hi:[1,0,0]
	v_pk_fma_f32 v[90:91], v[134:135], v[142:143], v[90:91] neg_lo:[1,0,0] neg_hi:[1,0,0]
	v_cvt_pk_bf16_f32 v96, v96, v97
	v_cvt_pk_bf16_f32 v97, v98, v99
	v_cvt_pk_bf16_f32 v98, v88, v89
	v_cvt_pk_bf16_f32 v99, v90, v91
	global_store_dwordx4 v148, v[96:99], s[50:51] sc1
	v_and_b32_e32 v132, 0x7fffffff, v80
	v_and_b32_e32 v133, 0x7fffffff, v81
	v_and_b32_e32 v134, 0x7fffffff, v82
	v_and_b32_e32 v135, 0x7fffffff, v83
	v_pk_mul_f32 v[144:145], v[80:81], v[80:81]
	v_pk_mul_f32 v[146:147], v[82:83], v[82:83]
	v_pk_fma_f32 v[136:137], v[132:133], s[84:85], 1.0 op_sel_hi:[1,0,0]
	v_pk_fma_f32 v[138:139], v[134:135], s[84:85], 1.0 op_sel_hi:[1,0,0]
	v_pk_mul_f32 v[144:145], v[144:145], s[80:81] op_sel_hi:[1,0]
	v_pk_mul_f32 v[146:147], v[146:147], s[80:81] op_sel_hi:[1,0]
	v_rcp_f32_e32 v136, v136
	v_rcp_f32_e32 v137, v137
	v_rcp_f32_e32 v138, v138
	v_rcp_f32_e32 v139, v139
	v_exp_f32_e32 v144, v144
	v_exp_f32_e32 v145, v145
	v_exp_f32_e32 v146, v146
	v_exp_f32_e32 v147, v147
	v_pk_fma_f32 v[140:141], v[136:137], s[86:87], v[0:1] op_sel_hi:[1,0,0]
	v_pk_fma_f32 v[142:143], v[138:139], s[86:87], v[0:1] op_sel_hi:[1,0,0]
	v_pk_fma_f32 v[140:141], v[136:137], v[140:141], s[88:89] op_sel_hi:[1,1,0]
	v_pk_fma_f32 v[142:143], v[138:139], v[142:143], s[88:89] op_sel_hi:[1,1,0]
	v_pk_fma_f32 v[140:141], v[136:137], v[140:141], s[82:83] op_sel_hi:[1,1,0]
	v_pk_fma_f32 v[142:143], v[138:139], v[142:143], s[82:83] op_sel_hi:[1,1,0]
	v_pk_fma_f32 v[140:141], v[136:137], v[140:141], s[48:49] op_sel_hi:[1,1,0]
	v_pk_fma_f32 v[142:143], v[138:139], v[142:143], s[48:49] op_sel_hi:[1,1,0]
	v_pk_mul_f32 v[140:141], v[136:137], v[140:141]
	v_pk_mul_f32 v[142:143], v[138:139], v[142:143]
	v_pk_mul_f32 v[140:141], v[140:141], v[144:145]
	v_pk_mul_f32 v[142:143], v[142:143], v[146:147]
	v_max_f32_e32 v80, 0, v80
	v_max_f32_e32 v81, 0, v81
	v_max_f32_e32 v82, 0, v82
	v_max_f32_e32 v83, 0, v83
	v_pk_fma_f32 v[80:81], v[132:133], v[140:141], v[80:81] neg_lo:[1,0,0] neg_hi:[1,0,0]
	v_pk_fma_f32 v[82:83], v[134:135], v[142:143], v[82:83] neg_lo:[1,0,0] neg_hi:[1,0,0]
	v_and_b32_e32 v132, 0x7fffffff, v72
	v_and_b32_e32 v133, 0x7fffffff, v73
	v_and_b32_e32 v134, 0x7fffffff, v74
	v_and_b32_e32 v135, 0x7fffffff, v75
	v_pk_mul_f32 v[144:145], v[72:73], v[72:73]
	v_pk_mul_f32 v[146:147], v[74:75], v[74:75]
	v_pk_fma_f32 v[136:137], v[132:133], s[84:85], 1.0 op_sel_hi:[1,0,0]
	v_pk_fma_f32 v[138:139], v[134:135], s[84:85], 1.0 op_sel_hi:[1,0,0]
	v_pk_mul_f32 v[144:145], v[144:145], s[80:81] op_sel_hi:[1,0]
	v_pk_mul_f32 v[146:147], v[146:147], s[80:81] op_sel_hi:[1,0]
	v_rcp_f32_e32 v136, v136
	v_rcp_f32_e32 v137, v137
	v_rcp_f32_e32 v138, v138
	v_rcp_f32_e32 v139, v139
	v_exp_f32_e32 v144, v144
	v_exp_f32_e32 v145, v145
	v_exp_f32_e32 v146, v146
	v_exp_f32_e32 v147, v147
	v_pk_fma_f32 v[140:141], v[136:137], s[86:87], v[0:1] op_sel_hi:[1,0,0]
	v_pk_fma_f32 v[142:143], v[138:139], s[86:87], v[0:1] op_sel_hi:[1,0,0]
	v_pk_fma_f32 v[140:141], v[136:137], v[140:141], s[88:89] op_sel_hi:[1,1,0]
	v_pk_fma_f32 v[142:143], v[138:139], v[142:143], s[88:89] op_sel_hi:[1,1,0]
	v_pk_fma_f32 v[140:141], v[136:137], v[140:141], s[82:83] op_sel_hi:[1,1,0]
	v_pk_fma_f32 v[142:143], v[138:139], v[142:143], s[82:83] op_sel_hi:[1,1,0]
	v_pk_fma_f32 v[140:141], v[136:137], v[140:141], s[48:49] op_sel_hi:[1,1,0]
	v_pk_fma_f32 v[142:143], v[138:139], v[142:143], s[48:49] op_sel_hi:[1,1,0]
	v_pk_mul_f32 v[140:141], v[136:137], v[140:141]
	v_pk_mul_f32 v[142:143], v[138:139], v[142:143]
	v_pk_mul_f32 v[140:141], v[140:141], v[144:145]
	v_pk_mul_f32 v[142:143], v[142:143], v[146:147]
	v_max_f32_e32 v72, 0, v72
	v_max_f32_e32 v73, 0, v73
	v_max_f32_e32 v74, 0, v74
	v_max_f32_e32 v75, 0, v75
	v_pk_fma_f32 v[72:73], v[132:133], v[140:141], v[72:73] neg_lo:[1,0,0] neg_hi:[1,0,0]
	v_pk_fma_f32 v[74:75], v[134:135], v[142:143], v[74:75] neg_lo:[1,0,0] neg_hi:[1,0,0]
	v_cvt_pk_bf16_f32 v80, v80, v81
	v_cvt_pk_bf16_f32 v81, v82, v83
	v_cvt_pk_bf16_f32 v82, v72, v73
	v_cvt_pk_bf16_f32 v83, v74, v75
	global_store_dwordx4 v148, v[80:83], s[50:51] offset:256 sc1
	v_add_u32_e32 v148, s81, v148
	v_and_b32_e32 v132, 0x7fffffff, v92
	v_and_b32_e32 v133, 0x7fffffff, v93
	v_and_b32_e32 v134, 0x7fffffff, v94
	v_and_b32_e32 v135, 0x7fffffff, v95
	v_pk_mul_f32 v[144:145], v[92:93], v[92:93]
	v_pk_mul_f32 v[146:147], v[94:95], v[94:95]
	v_pk_fma_f32 v[136:137], v[132:133], s[84:85], 1.0 op_sel_hi:[1,0,0]
	v_pk_fma_f32 v[138:139], v[134:135], s[84:85], 1.0 op_sel_hi:[1,0,0]
	v_pk_mul_f32 v[144:145], v[144:145], s[80:81] op_sel_hi:[1,0]
	v_pk_mul_f32 v[146:147], v[146:147], s[80:81] op_sel_hi:[1,0]
	v_rcp_f32_e32 v136, v136
	v_rcp_f32_e32 v137, v137
	v_rcp_f32_e32 v138, v138
	v_rcp_f32_e32 v139, v139
	v_exp_f32_e32 v144, v144
	v_exp_f32_e32 v145, v145
	v_exp_f32_e32 v146, v146
	v_exp_f32_e32 v147, v147
	v_pk_fma_f32 v[140:141], v[136:137], s[86:87], v[0:1] op_sel_hi:[1,0,0]
	v_pk_fma_f32 v[142:143], v[138:139], s[86:87], v[0:1] op_sel_hi:[1,0,0]
	v_pk_fma_f32 v[140:141], v[136:137], v[140:141], s[88:89] op_sel_hi:[1,1,0]
	v_pk_fma_f32 v[142:143], v[138:139], v[142:143], s[88:89] op_sel_hi:[1,1,0]
	v_pk_fma_f32 v[140:141], v[136:137], v[140:141], s[82:83] op_sel_hi:[1,1,0]
	v_pk_fma_f32 v[142:143], v[138:139], v[142:143], s[82:83] op_sel_hi:[1,1,0]
	v_pk_fma_f32 v[140:141], v[136:137], v[140:141], s[48:49] op_sel_hi:[1,1,0]
	v_pk_fma_f32 v[142:143], v[138:139], v[142:143], s[48:49] op_sel_hi:[1,1,0]
	v_pk_mul_f32 v[140:141], v[136:137], v[140:141]
	v_pk_mul_f32 v[142:143], v[138:139], v[142:143]
	v_pk_mul_f32 v[140:141], v[140:141], v[144:145]
	v_pk_mul_f32 v[142:143], v[142:143], v[146:147]
	v_max_f32_e32 v92, 0, v92
	v_max_f32_e32 v93, 0, v93
	v_max_f32_e32 v94, 0, v94
	v_max_f32_e32 v95, 0, v95
	v_pk_fma_f32 v[92:93], v[132:133], v[140:141], v[92:93] neg_lo:[1,0,0] neg_hi:[1,0,0]
	v_pk_fma_f32 v[94:95], v[134:135], v[142:143], v[94:95] neg_lo:[1,0,0] neg_hi:[1,0,0]
	v_and_b32_e32 v132, 0x7fffffff, v84
	v_and_b32_e32 v133, 0x7fffffff, v85
	v_and_b32_e32 v134, 0x7fffffff, v86
	v_and_b32_e32 v135, 0x7fffffff, v87
	v_pk_mul_f32 v[144:145], v[84:85], v[84:85]
	v_pk_mul_f32 v[146:147], v[86:87], v[86:87]
	v_pk_fma_f32 v[136:137], v[132:133], s[84:85], 1.0 op_sel_hi:[1,0,0]
	v_pk_fma_f32 v[138:139], v[134:135], s[84:85], 1.0 op_sel_hi:[1,0,0]
	v_pk_mul_f32 v[144:145], v[144:145], s[80:81] op_sel_hi:[1,0]
	v_pk_mul_f32 v[146:147], v[146:147], s[80:81] op_sel_hi:[1,0]
	v_rcp_f32_e32 v136, v136
	v_rcp_f32_e32 v137, v137
	v_rcp_f32_e32 v138, v138
	v_rcp_f32_e32 v139, v139
	v_exp_f32_e32 v144, v144
	v_exp_f32_e32 v145, v145
	v_exp_f32_e32 v146, v146
	v_exp_f32_e32 v147, v147
	v_pk_fma_f32 v[140:141], v[136:137], s[86:87], v[0:1] op_sel_hi:[1,0,0]
	v_pk_fma_f32 v[142:143], v[138:139], s[86:87], v[0:1] op_sel_hi:[1,0,0]
	v_pk_fma_f32 v[140:141], v[136:137], v[140:141], s[88:89] op_sel_hi:[1,1,0]
	v_pk_fma_f32 v[142:143], v[138:139], v[142:143], s[88:89] op_sel_hi:[1,1,0]
	v_pk_fma_f32 v[140:141], v[136:137], v[140:141], s[82:83] op_sel_hi:[1,1,0]
	v_pk_fma_f32 v[142:143], v[138:139], v[142:143], s[82:83] op_sel_hi:[1,1,0]
	v_pk_fma_f32 v[140:141], v[136:137], v[140:141], s[48:49] op_sel_hi:[1,1,0]
	v_pk_fma_f32 v[142:143], v[138:139], v[142:143], s[48:49] op_sel_hi:[1,1,0]
	v_pk_mul_f32 v[140:141], v[136:137], v[140:141]
	v_pk_mul_f32 v[142:143], v[138:139], v[142:143]
	v_pk_mul_f32 v[140:141], v[140:141], v[144:145]
	v_pk_mul_f32 v[142:143], v[142:143], v[146:147]
	v_max_f32_e32 v84, 0, v84
	v_max_f32_e32 v85, 0, v85
	v_max_f32_e32 v86, 0, v86
	v_max_f32_e32 v87, 0, v87
	v_pk_fma_f32 v[84:85], v[132:133], v[140:141], v[84:85] neg_lo:[1,0,0] neg_hi:[1,0,0]
	v_pk_fma_f32 v[86:87], v[134:135], v[142:143], v[86:87] neg_lo:[1,0,0] neg_hi:[1,0,0]
	v_cvt_pk_bf16_f32 v92, v92, v93
	v_cvt_pk_bf16_f32 v93, v94, v95
	v_cvt_pk_bf16_f32 v94, v84, v85
	v_cvt_pk_bf16_f32 v95, v86, v87
	global_store_dwordx4 v148, v[92:95], s[50:51] sc1
	v_and_b32_e32 v132, 0x7fffffff, v76
	v_and_b32_e32 v133, 0x7fffffff, v77
	v_and_b32_e32 v134, 0x7fffffff, v78
	v_and_b32_e32 v135, 0x7fffffff, v79
	v_pk_mul_f32 v[144:145], v[76:77], v[76:77]
	v_pk_mul_f32 v[146:147], v[78:79], v[78:79]
	v_pk_fma_f32 v[136:137], v[132:133], s[84:85], 1.0 op_sel_hi:[1,0,0]
	v_pk_fma_f32 v[138:139], v[134:135], s[84:85], 1.0 op_sel_hi:[1,0,0]
	v_pk_mul_f32 v[144:145], v[144:145], s[80:81] op_sel_hi:[1,0]
	v_pk_mul_f32 v[146:147], v[146:147], s[80:81] op_sel_hi:[1,0]
	v_rcp_f32_e32 v136, v136
	v_rcp_f32_e32 v137, v137
	v_rcp_f32_e32 v138, v138
	v_rcp_f32_e32 v139, v139
	v_exp_f32_e32 v144, v144
	v_exp_f32_e32 v145, v145
	v_exp_f32_e32 v146, v146
	v_exp_f32_e32 v147, v147
	v_pk_fma_f32 v[140:141], v[136:137], s[86:87], v[0:1] op_sel_hi:[1,0,0]
	v_pk_fma_f32 v[142:143], v[138:139], s[86:87], v[0:1] op_sel_hi:[1,0,0]
	v_pk_fma_f32 v[140:141], v[136:137], v[140:141], s[88:89] op_sel_hi:[1,1,0]
	v_pk_fma_f32 v[142:143], v[138:139], v[142:143], s[88:89] op_sel_hi:[1,1,0]
	v_pk_fma_f32 v[140:141], v[136:137], v[140:141], s[82:83] op_sel_hi:[1,1,0]
	v_pk_fma_f32 v[142:143], v[138:139], v[142:143], s[82:83] op_sel_hi:[1,1,0]
	v_pk_fma_f32 v[140:141], v[136:137], v[140:141], s[48:49] op_sel_hi:[1,1,0]
	v_pk_fma_f32 v[142:143], v[138:139], v[142:143], s[48:49] op_sel_hi:[1,1,0]
	v_pk_mul_f32 v[140:141], v[136:137], v[140:141]
	v_pk_mul_f32 v[142:143], v[138:139], v[142:143]
	v_pk_mul_f32 v[140:141], v[140:141], v[144:145]
	v_pk_mul_f32 v[142:143], v[142:143], v[146:147]
	v_max_f32_e32 v76, 0, v76
	v_max_f32_e32 v77, 0, v77
	v_max_f32_e32 v78, 0, v78
	v_max_f32_e32 v79, 0, v79
	v_pk_fma_f32 v[76:77], v[132:133], v[140:141], v[76:77] neg_lo:[1,0,0] neg_hi:[1,0,0]
	v_pk_fma_f32 v[78:79], v[134:135], v[142:143], v[78:79] neg_lo:[1,0,0] neg_hi:[1,0,0]
	v_and_b32_e32 v132, 0x7fffffff, v68
	v_and_b32_e32 v133, 0x7fffffff, v69
	v_and_b32_e32 v134, 0x7fffffff, v70
	v_and_b32_e32 v135, 0x7fffffff, v71
	v_pk_mul_f32 v[144:145], v[68:69], v[68:69]
	v_pk_mul_f32 v[146:147], v[70:71], v[70:71]
	v_pk_fma_f32 v[136:137], v[132:133], s[84:85], 1.0 op_sel_hi:[1,0,0]
	v_pk_fma_f32 v[138:139], v[134:135], s[84:85], 1.0 op_sel_hi:[1,0,0]
	v_pk_mul_f32 v[144:145], v[144:145], s[80:81] op_sel_hi:[1,0]
	v_pk_mul_f32 v[146:147], v[146:147], s[80:81] op_sel_hi:[1,0]
	v_rcp_f32_e32 v136, v136
	v_rcp_f32_e32 v137, v137
	v_rcp_f32_e32 v138, v138
	v_rcp_f32_e32 v139, v139
	v_exp_f32_e32 v144, v144
	v_exp_f32_e32 v145, v145
	v_exp_f32_e32 v146, v146
	v_exp_f32_e32 v147, v147
	v_pk_fma_f32 v[140:141], v[136:137], s[86:87], v[0:1] op_sel_hi:[1,0,0]
	v_pk_fma_f32 v[142:143], v[138:139], s[86:87], v[0:1] op_sel_hi:[1,0,0]
	v_pk_fma_f32 v[140:141], v[136:137], v[140:141], s[88:89] op_sel_hi:[1,1,0]
	v_pk_fma_f32 v[142:143], v[138:139], v[142:143], s[88:89] op_sel_hi:[1,1,0]
	v_pk_fma_f32 v[140:141], v[136:137], v[140:141], s[82:83] op_sel_hi:[1,1,0]
	v_pk_fma_f32 v[142:143], v[138:139], v[142:143], s[82:83] op_sel_hi:[1,1,0]
	v_pk_fma_f32 v[140:141], v[136:137], v[140:141], s[48:49] op_sel_hi:[1,1,0]
	v_pk_fma_f32 v[142:143], v[138:139], v[142:143], s[48:49] op_sel_hi:[1,1,0]
	v_pk_mul_f32 v[140:141], v[136:137], v[140:141]
	v_pk_mul_f32 v[142:143], v[138:139], v[142:143]
	v_pk_mul_f32 v[140:141], v[140:141], v[144:145]
	v_pk_mul_f32 v[142:143], v[142:143], v[146:147]
	v_max_f32_e32 v68, 0, v68
	v_max_f32_e32 v69, 0, v69
	v_max_f32_e32 v70, 0, v70
	v_max_f32_e32 v71, 0, v71
	v_pk_fma_f32 v[68:69], v[132:133], v[140:141], v[68:69] neg_lo:[1,0,0] neg_hi:[1,0,0]
	v_pk_fma_f32 v[70:71], v[134:135], v[142:143], v[70:71] neg_lo:[1,0,0] neg_hi:[1,0,0]
	v_cvt_pk_bf16_f32 v76, v76, v77
	v_cvt_pk_bf16_f32 v77, v78, v79
	v_cvt_pk_bf16_f32 v78, v68, v69
	v_cvt_pk_bf16_f32 v79, v70, v71
	global_store_dwordx4 v148, v[76:79], s[50:51] offset:256 sc1
	s_mul_i32 s30, s81, 5
	v_add_u32_e32 v148, s30, v148
	s_cmp_lg_u32 s49, 0
	s_cbranch_scc1 .LBB0_326
	v_and_b32_e32 v132, 0x7fffffff, v64
	v_and_b32_e32 v133, 0x7fffffff, v65
	v_and_b32_e32 v134, 0x7fffffff, v66
	v_and_b32_e32 v135, 0x7fffffff, v67
	v_pk_mul_f32 v[144:145], v[64:65], v[64:65]
	v_pk_mul_f32 v[146:147], v[66:67], v[66:67]
	v_pk_fma_f32 v[136:137], v[132:133], s[84:85], 1.0 op_sel_hi:[1,0,0]
	v_pk_fma_f32 v[138:139], v[134:135], s[84:85], 1.0 op_sel_hi:[1,0,0]
	v_pk_mul_f32 v[144:145], v[144:145], s[80:81] op_sel_hi:[1,0]
	v_pk_mul_f32 v[146:147], v[146:147], s[80:81] op_sel_hi:[1,0]
	v_rcp_f32_e32 v136, v136
	v_rcp_f32_e32 v137, v137
	v_rcp_f32_e32 v138, v138
	v_rcp_f32_e32 v139, v139
	v_exp_f32_e32 v144, v144
	v_exp_f32_e32 v145, v145
	v_exp_f32_e32 v146, v146
	v_exp_f32_e32 v147, v147
	v_pk_fma_f32 v[140:141], v[136:137], s[86:87], v[0:1] op_sel_hi:[1,0,0]
	v_pk_fma_f32 v[142:143], v[138:139], s[86:87], v[0:1] op_sel_hi:[1,0,0]
	v_pk_fma_f32 v[140:141], v[136:137], v[140:141], s[88:89] op_sel_hi:[1,1,0]
	v_pk_fma_f32 v[142:143], v[138:139], v[142:143], s[88:89] op_sel_hi:[1,1,0]
	v_pk_fma_f32 v[140:141], v[136:137], v[140:141], s[82:83] op_sel_hi:[1,1,0]
	v_pk_fma_f32 v[142:143], v[138:139], v[142:143], s[82:83] op_sel_hi:[1,1,0]
	v_pk_fma_f32 v[140:141], v[136:137], v[140:141], s[48:49] op_sel_hi:[1,1,0]
	v_pk_fma_f32 v[142:143], v[138:139], v[142:143], s[48:49] op_sel_hi:[1,1,0]
	v_pk_mul_f32 v[140:141], v[136:137], v[140:141]
	v_pk_mul_f32 v[142:143], v[138:139], v[142:143]
	v_pk_mul_f32 v[140:141], v[140:141], v[144:145]
	v_pk_mul_f32 v[142:143], v[142:143], v[146:147]
	v_max_f32_e32 v64, 0, v64
	v_max_f32_e32 v65, 0, v65
	v_max_f32_e32 v66, 0, v66
	v_max_f32_e32 v67, 0, v67
	v_pk_fma_f32 v[64:65], v[132:133], v[140:141], v[64:65] neg_lo:[1,0,0] neg_hi:[1,0,0]
	v_pk_fma_f32 v[66:67], v[134:135], v[142:143], v[66:67] neg_lo:[1,0,0] neg_hi:[1,0,0]
	v_and_b32_e32 v132, 0x7fffffff, v56
	v_and_b32_e32 v133, 0x7fffffff, v57
	v_and_b32_e32 v134, 0x7fffffff, v58
	v_and_b32_e32 v135, 0x7fffffff, v59
	v_pk_mul_f32 v[144:145], v[56:57], v[56:57]
	v_pk_mul_f32 v[146:147], v[58:59], v[58:59]
	v_pk_fma_f32 v[136:137], v[132:133], s[84:85], 1.0 op_sel_hi:[1,0,0]
	v_pk_fma_f32 v[138:139], v[134:135], s[84:85], 1.0 op_sel_hi:[1,0,0]
	v_pk_mul_f32 v[144:145], v[144:145], s[80:81] op_sel_hi:[1,0]
	v_pk_mul_f32 v[146:147], v[146:147], s[80:81] op_sel_hi:[1,0]
	v_rcp_f32_e32 v136, v136
	v_rcp_f32_e32 v137, v137
	v_rcp_f32_e32 v138, v138
	v_rcp_f32_e32 v139, v139
	v_exp_f32_e32 v144, v144
	v_exp_f32_e32 v145, v145
	v_exp_f32_e32 v146, v146
	v_exp_f32_e32 v147, v147
	v_pk_fma_f32 v[140:141], v[136:137], s[86:87], v[0:1] op_sel_hi:[1,0,0]
	v_pk_fma_f32 v[142:143], v[138:139], s[86:87], v[0:1] op_sel_hi:[1,0,0]
	v_pk_fma_f32 v[140:141], v[136:137], v[140:141], s[88:89] op_sel_hi:[1,1,0]
	v_pk_fma_f32 v[142:143], v[138:139], v[142:143], s[88:89] op_sel_hi:[1,1,0]
	v_pk_fma_f32 v[140:141], v[136:137], v[140:141], s[82:83] op_sel_hi:[1,1,0]
	v_pk_fma_f32 v[142:143], v[138:139], v[142:143], s[82:83] op_sel_hi:[1,1,0]
	v_pk_fma_f32 v[140:141], v[136:137], v[140:141], s[48:49] op_sel_hi:[1,1,0]
	v_pk_fma_f32 v[142:143], v[138:139], v[142:143], s[48:49] op_sel_hi:[1,1,0]
	v_pk_mul_f32 v[140:141], v[136:137], v[140:141]
	v_pk_mul_f32 v[142:143], v[138:139], v[142:143]
	v_pk_mul_f32 v[140:141], v[140:141], v[144:145]
	v_pk_mul_f32 v[142:143], v[142:143], v[146:147]
	v_max_f32_e32 v56, 0, v56
	v_max_f32_e32 v57, 0, v57
	v_max_f32_e32 v58, 0, v58
	v_max_f32_e32 v59, 0, v59
	v_pk_fma_f32 v[56:57], v[132:133], v[140:141], v[56:57] neg_lo:[1,0,0] neg_hi:[1,0,0]
	v_pk_fma_f32 v[58:59], v[134:135], v[142:143], v[58:59] neg_lo:[1,0,0] neg_hi:[1,0,0]
	v_cvt_pk_bf16_f32 v64, v64, v65
	v_cvt_pk_bf16_f32 v65, v66, v67
	v_cvt_pk_bf16_f32 v66, v56, v57
	v_cvt_pk_bf16_f32 v67, v58, v59
	global_store_dwordx4 v148, v[64:67], s[50:51] sc1
	v_and_b32_e32 v132, 0x7fffffff, v48
	v_and_b32_e32 v133, 0x7fffffff, v49
	v_and_b32_e32 v134, 0x7fffffff, v50
	v_and_b32_e32 v135, 0x7fffffff, v51
	v_pk_mul_f32 v[144:145], v[48:49], v[48:49]
	v_pk_mul_f32 v[146:147], v[50:51], v[50:51]
	v_pk_fma_f32 v[136:137], v[132:133], s[84:85], 1.0 op_sel_hi:[1,0,0]
	v_pk_fma_f32 v[138:139], v[134:135], s[84:85], 1.0 op_sel_hi:[1,0,0]
	v_pk_mul_f32 v[144:145], v[144:145], s[80:81] op_sel_hi:[1,0]
	v_pk_mul_f32 v[146:147], v[146:147], s[80:81] op_sel_hi:[1,0]
	v_rcp_f32_e32 v136, v136
	v_rcp_f32_e32 v137, v137
	v_rcp_f32_e32 v138, v138
	v_rcp_f32_e32 v139, v139
	v_exp_f32_e32 v144, v144
	v_exp_f32_e32 v145, v145
	v_exp_f32_e32 v146, v146
	v_exp_f32_e32 v147, v147
	v_pk_fma_f32 v[140:141], v[136:137], s[86:87], v[0:1] op_sel_hi:[1,0,0]
	v_pk_fma_f32 v[142:143], v[138:139], s[86:87], v[0:1] op_sel_hi:[1,0,0]
	v_pk_fma_f32 v[140:141], v[136:137], v[140:141], s[88:89] op_sel_hi:[1,1,0]
	v_pk_fma_f32 v[142:143], v[138:139], v[142:143], s[88:89] op_sel_hi:[1,1,0]
	v_pk_fma_f32 v[140:141], v[136:137], v[140:141], s[82:83] op_sel_hi:[1,1,0]
	v_pk_fma_f32 v[142:143], v[138:139], v[142:143], s[82:83] op_sel_hi:[1,1,0]
	v_pk_fma_f32 v[140:141], v[136:137], v[140:141], s[48:49] op_sel_hi:[1,1,0]
	v_pk_fma_f32 v[142:143], v[138:139], v[142:143], s[48:49] op_sel_hi:[1,1,0]
	v_pk_mul_f32 v[140:141], v[136:137], v[140:141]
	v_pk_mul_f32 v[142:143], v[138:139], v[142:143]
	v_pk_mul_f32 v[140:141], v[140:141], v[144:145]
	v_pk_mul_f32 v[142:143], v[142:143], v[146:147]
	v_max_f32_e32 v48, 0, v48
	v_max_f32_e32 v49, 0, v49
	v_max_f32_e32 v50, 0, v50
	v_max_f32_e32 v51, 0, v51
	v_pk_fma_f32 v[48:49], v[132:133], v[140:141], v[48:49] neg_lo:[1,0,0] neg_hi:[1,0,0]
	v_pk_fma_f32 v[50:51], v[134:135], v[142:143], v[50:51] neg_lo:[1,0,0] neg_hi:[1,0,0]
	v_and_b32_e32 v132, 0x7fffffff, v40
	v_and_b32_e32 v133, 0x7fffffff, v41
	v_and_b32_e32 v134, 0x7fffffff, v42
	v_and_b32_e32 v135, 0x7fffffff, v43
	v_pk_mul_f32 v[144:145], v[40:41], v[40:41]
	v_pk_mul_f32 v[146:147], v[42:43], v[42:43]
	v_pk_fma_f32 v[136:137], v[132:133], s[84:85], 1.0 op_sel_hi:[1,0,0]
	v_pk_fma_f32 v[138:139], v[134:135], s[84:85], 1.0 op_sel_hi:[1,0,0]
	v_pk_mul_f32 v[144:145], v[144:145], s[80:81] op_sel_hi:[1,0]
	v_pk_mul_f32 v[146:147], v[146:147], s[80:81] op_sel_hi:[1,0]
	v_rcp_f32_e32 v136, v136
	v_rcp_f32_e32 v137, v137
	v_rcp_f32_e32 v138, v138
	v_rcp_f32_e32 v139, v139
	v_exp_f32_e32 v144, v144
	v_exp_f32_e32 v145, v145
	v_exp_f32_e32 v146, v146
	v_exp_f32_e32 v147, v147
	v_pk_fma_f32 v[140:141], v[136:137], s[86:87], v[0:1] op_sel_hi:[1,0,0]
	v_pk_fma_f32 v[142:143], v[138:139], s[86:87], v[0:1] op_sel_hi:[1,0,0]
	v_pk_fma_f32 v[140:141], v[136:137], v[140:141], s[88:89] op_sel_hi:[1,1,0]
	v_pk_fma_f32 v[142:143], v[138:139], v[142:143], s[88:89] op_sel_hi:[1,1,0]
	v_pk_fma_f32 v[140:141], v[136:137], v[140:141], s[82:83] op_sel_hi:[1,1,0]
	v_pk_fma_f32 v[142:143], v[138:139], v[142:143], s[82:83] op_sel_hi:[1,1,0]
	v_pk_fma_f32 v[140:141], v[136:137], v[140:141], s[48:49] op_sel_hi:[1,1,0]
	v_pk_fma_f32 v[142:143], v[138:139], v[142:143], s[48:49] op_sel_hi:[1,1,0]
	v_pk_mul_f32 v[140:141], v[136:137], v[140:141]
	v_pk_mul_f32 v[142:143], v[138:139], v[142:143]
	v_pk_mul_f32 v[140:141], v[140:141], v[144:145]
	v_pk_mul_f32 v[142:143], v[142:143], v[146:147]
	v_max_f32_e32 v40, 0, v40
	v_max_f32_e32 v41, 0, v41
	v_max_f32_e32 v42, 0, v42
	v_max_f32_e32 v43, 0, v43
	v_pk_fma_f32 v[40:41], v[132:133], v[140:141], v[40:41] neg_lo:[1,0,0] neg_hi:[1,0,0]
	v_pk_fma_f32 v[42:43], v[134:135], v[142:143], v[42:43] neg_lo:[1,0,0] neg_hi:[1,0,0]
	v_cvt_pk_bf16_f32 v48, v48, v49
	v_cvt_pk_bf16_f32 v49, v50, v51
	v_cvt_pk_bf16_f32 v50, v40, v41
	v_cvt_pk_bf16_f32 v51, v42, v43
	global_store_dwordx4 v148, v[48:51], s[50:51] offset:256 sc1
	v_add_u32_e32 v148, s81, v148
	v_and_b32_e32 v132, 0x7fffffff, v60
	v_and_b32_e32 v133, 0x7fffffff, v61
	v_and_b32_e32 v134, 0x7fffffff, v62
	v_and_b32_e32 v135, 0x7fffffff, v63
	v_pk_mul_f32 v[144:145], v[60:61], v[60:61]
	v_pk_mul_f32 v[146:147], v[62:63], v[62:63]
	v_pk_fma_f32 v[136:137], v[132:133], s[84:85], 1.0 op_sel_hi:[1,0,0]
	v_pk_fma_f32 v[138:139], v[134:135], s[84:85], 1.0 op_sel_hi:[1,0,0]
	v_pk_mul_f32 v[144:145], v[144:145], s[80:81] op_sel_hi:[1,0]
	v_pk_mul_f32 v[146:147], v[146:147], s[80:81] op_sel_hi:[1,0]
	v_rcp_f32_e32 v136, v136
	v_rcp_f32_e32 v137, v137
	v_rcp_f32_e32 v138, v138
	v_rcp_f32_e32 v139, v139
	v_exp_f32_e32 v144, v144
	v_exp_f32_e32 v145, v145
	v_exp_f32_e32 v146, v146
	v_exp_f32_e32 v147, v147
	v_pk_fma_f32 v[140:141], v[136:137], s[86:87], v[0:1] op_sel_hi:[1,0,0]
	v_pk_fma_f32 v[142:143], v[138:139], s[86:87], v[0:1] op_sel_hi:[1,0,0]
	v_pk_fma_f32 v[140:141], v[136:137], v[140:141], s[88:89] op_sel_hi:[1,1,0]
	v_pk_fma_f32 v[142:143], v[138:139], v[142:143], s[88:89] op_sel_hi:[1,1,0]
	v_pk_fma_f32 v[140:141], v[136:137], v[140:141], s[82:83] op_sel_hi:[1,1,0]
	v_pk_fma_f32 v[142:143], v[138:139], v[142:143], s[82:83] op_sel_hi:[1,1,0]
	v_pk_fma_f32 v[140:141], v[136:137], v[140:141], s[48:49] op_sel_hi:[1,1,0]
	v_pk_fma_f32 v[142:143], v[138:139], v[142:143], s[48:49] op_sel_hi:[1,1,0]
	v_pk_mul_f32 v[140:141], v[136:137], v[140:141]
	v_pk_mul_f32 v[142:143], v[138:139], v[142:143]
	v_pk_mul_f32 v[140:141], v[140:141], v[144:145]
	v_pk_mul_f32 v[142:143], v[142:143], v[146:147]
	v_max_f32_e32 v60, 0, v60
	v_max_f32_e32 v61, 0, v61
	v_max_f32_e32 v62, 0, v62
	v_max_f32_e32 v63, 0, v63
	v_pk_fma_f32 v[60:61], v[132:133], v[140:141], v[60:61] neg_lo:[1,0,0] neg_hi:[1,0,0]
	v_pk_fma_f32 v[62:63], v[134:135], v[142:143], v[62:63] neg_lo:[1,0,0] neg_hi:[1,0,0]
	v_and_b32_e32 v132, 0x7fffffff, v52
	v_and_b32_e32 v133, 0x7fffffff, v53
	v_and_b32_e32 v134, 0x7fffffff, v54
	v_and_b32_e32 v135, 0x7fffffff, v55
	v_pk_mul_f32 v[144:145], v[52:53], v[52:53]
	v_pk_mul_f32 v[146:147], v[54:55], v[54:55]
	v_pk_fma_f32 v[136:137], v[132:133], s[84:85], 1.0 op_sel_hi:[1,0,0]
	v_pk_fma_f32 v[138:139], v[134:135], s[84:85], 1.0 op_sel_hi:[1,0,0]
	v_pk_mul_f32 v[144:145], v[144:145], s[80:81] op_sel_hi:[1,0]
	v_pk_mul_f32 v[146:147], v[146:147], s[80:81] op_sel_hi:[1,0]
	v_rcp_f32_e32 v136, v136
	v_rcp_f32_e32 v137, v137
	v_rcp_f32_e32 v138, v138
	v_rcp_f32_e32 v139, v139
	v_exp_f32_e32 v144, v144
	v_exp_f32_e32 v145, v145
	v_exp_f32_e32 v146, v146
	v_exp_f32_e32 v147, v147
	v_pk_fma_f32 v[140:141], v[136:137], s[86:87], v[0:1] op_sel_hi:[1,0,0]
	v_pk_fma_f32 v[142:143], v[138:139], s[86:87], v[0:1] op_sel_hi:[1,0,0]
	v_pk_fma_f32 v[140:141], v[136:137], v[140:141], s[88:89] op_sel_hi:[1,1,0]
	v_pk_fma_f32 v[142:143], v[138:139], v[142:143], s[88:89] op_sel_hi:[1,1,0]
	v_pk_fma_f32 v[140:141], v[136:137], v[140:141], s[82:83] op_sel_hi:[1,1,0]
	v_pk_fma_f32 v[142:143], v[138:139], v[142:143], s[82:83] op_sel_hi:[1,1,0]
	v_pk_fma_f32 v[140:141], v[136:137], v[140:141], s[48:49] op_sel_hi:[1,1,0]
	v_pk_fma_f32 v[142:143], v[138:139], v[142:143], s[48:49] op_sel_hi:[1,1,0]
	v_pk_mul_f32 v[140:141], v[136:137], v[140:141]
	v_pk_mul_f32 v[142:143], v[138:139], v[142:143]
	v_pk_mul_f32 v[140:141], v[140:141], v[144:145]
	v_pk_mul_f32 v[142:143], v[142:143], v[146:147]
	v_max_f32_e32 v52, 0, v52
	v_max_f32_e32 v53, 0, v53
	v_max_f32_e32 v54, 0, v54
	v_max_f32_e32 v55, 0, v55
	v_pk_fma_f32 v[52:53], v[132:133], v[140:141], v[52:53] neg_lo:[1,0,0] neg_hi:[1,0,0]
	v_pk_fma_f32 v[54:55], v[134:135], v[142:143], v[54:55] neg_lo:[1,0,0] neg_hi:[1,0,0]
	v_cvt_pk_bf16_f32 v60, v60, v61
	v_cvt_pk_bf16_f32 v61, v62, v63
	v_cvt_pk_bf16_f32 v62, v52, v53
	v_cvt_pk_bf16_f32 v63, v54, v55
	global_store_dwordx4 v148, v[60:63], s[50:51] sc1
	v_and_b32_e32 v132, 0x7fffffff, v44
	v_and_b32_e32 v133, 0x7fffffff, v45
	v_and_b32_e32 v134, 0x7fffffff, v46
	v_and_b32_e32 v135, 0x7fffffff, v47
	v_pk_mul_f32 v[144:145], v[44:45], v[44:45]
	v_pk_mul_f32 v[146:147], v[46:47], v[46:47]
	v_pk_fma_f32 v[136:137], v[132:133], s[84:85], 1.0 op_sel_hi:[1,0,0]
	v_pk_fma_f32 v[138:139], v[134:135], s[84:85], 1.0 op_sel_hi:[1,0,0]
	v_pk_mul_f32 v[144:145], v[144:145], s[80:81] op_sel_hi:[1,0]
	v_pk_mul_f32 v[146:147], v[146:147], s[80:81] op_sel_hi:[1,0]
	v_rcp_f32_e32 v136, v136
	v_rcp_f32_e32 v137, v137
	v_rcp_f32_e32 v138, v138
	v_rcp_f32_e32 v139, v139
	v_exp_f32_e32 v144, v144
	v_exp_f32_e32 v145, v145
	v_exp_f32_e32 v146, v146
	v_exp_f32_e32 v147, v147
	v_pk_fma_f32 v[140:141], v[136:137], s[86:87], v[0:1] op_sel_hi:[1,0,0]
	v_pk_fma_f32 v[142:143], v[138:139], s[86:87], v[0:1] op_sel_hi:[1,0,0]
	v_pk_fma_f32 v[140:141], v[136:137], v[140:141], s[88:89] op_sel_hi:[1,1,0]
	v_pk_fma_f32 v[142:143], v[138:139], v[142:143], s[88:89] op_sel_hi:[1,1,0]
	v_pk_fma_f32 v[140:141], v[136:137], v[140:141], s[82:83] op_sel_hi:[1,1,0]
	v_pk_fma_f32 v[142:143], v[138:139], v[142:143], s[82:83] op_sel_hi:[1,1,0]
	v_pk_fma_f32 v[140:141], v[136:137], v[140:141], s[48:49] op_sel_hi:[1,1,0]
	v_pk_fma_f32 v[142:143], v[138:139], v[142:143], s[48:49] op_sel_hi:[1,1,0]
	v_pk_mul_f32 v[140:141], v[136:137], v[140:141]
	v_pk_mul_f32 v[142:143], v[138:139], v[142:143]
	v_pk_mul_f32 v[140:141], v[140:141], v[144:145]
	v_pk_mul_f32 v[142:143], v[142:143], v[146:147]
	v_max_f32_e32 v44, 0, v44
	v_max_f32_e32 v45, 0, v45
	v_max_f32_e32 v46, 0, v46
	v_max_f32_e32 v47, 0, v47
	v_pk_fma_f32 v[44:45], v[132:133], v[140:141], v[44:45] neg_lo:[1,0,0] neg_hi:[1,0,0]
	v_pk_fma_f32 v[46:47], v[134:135], v[142:143], v[46:47] neg_lo:[1,0,0] neg_hi:[1,0,0]
	v_and_b32_e32 v132, 0x7fffffff, v36
	v_and_b32_e32 v133, 0x7fffffff, v37
	v_and_b32_e32 v134, 0x7fffffff, v38
	v_and_b32_e32 v135, 0x7fffffff, v39
	v_pk_mul_f32 v[144:145], v[36:37], v[36:37]
	v_pk_mul_f32 v[146:147], v[38:39], v[38:39]
	v_pk_fma_f32 v[136:137], v[132:133], s[84:85], 1.0 op_sel_hi:[1,0,0]
	v_pk_fma_f32 v[138:139], v[134:135], s[84:85], 1.0 op_sel_hi:[1,0,0]
	v_pk_mul_f32 v[144:145], v[144:145], s[80:81] op_sel_hi:[1,0]
	v_pk_mul_f32 v[146:147], v[146:147], s[80:81] op_sel_hi:[1,0]
	v_rcp_f32_e32 v136, v136
	v_rcp_f32_e32 v137, v137
	v_rcp_f32_e32 v138, v138
	v_rcp_f32_e32 v139, v139
	v_exp_f32_e32 v144, v144
	v_exp_f32_e32 v145, v145
	v_exp_f32_e32 v146, v146
	v_exp_f32_e32 v147, v147
	v_pk_fma_f32 v[140:141], v[136:137], s[86:87], v[0:1] op_sel_hi:[1,0,0]
	v_pk_fma_f32 v[142:143], v[138:139], s[86:87], v[0:1] op_sel_hi:[1,0,0]
	v_pk_fma_f32 v[140:141], v[136:137], v[140:141], s[88:89] op_sel_hi:[1,1,0]
	v_pk_fma_f32 v[142:143], v[138:139], v[142:143], s[88:89] op_sel_hi:[1,1,0]
	v_pk_fma_f32 v[140:141], v[136:137], v[140:141], s[82:83] op_sel_hi:[1,1,0]
	v_pk_fma_f32 v[142:143], v[138:139], v[142:143], s[82:83] op_sel_hi:[1,1,0]
	v_pk_fma_f32 v[140:141], v[136:137], v[140:141], s[48:49] op_sel_hi:[1,1,0]
	v_pk_fma_f32 v[142:143], v[138:139], v[142:143], s[48:49] op_sel_hi:[1,1,0]
	v_pk_mul_f32 v[140:141], v[136:137], v[140:141]
	v_pk_mul_f32 v[142:143], v[138:139], v[142:143]
	v_pk_mul_f32 v[140:141], v[140:141], v[144:145]
	v_pk_mul_f32 v[142:143], v[142:143], v[146:147]
	v_max_f32_e32 v36, 0, v36
	v_max_f32_e32 v37, 0, v37
	v_max_f32_e32 v38, 0, v38
	v_max_f32_e32 v39, 0, v39
	v_pk_fma_f32 v[36:37], v[132:133], v[140:141], v[36:37] neg_lo:[1,0,0] neg_hi:[1,0,0]
	v_pk_fma_f32 v[38:39], v[134:135], v[142:143], v[38:39] neg_lo:[1,0,0] neg_hi:[1,0,0]
	v_cvt_pk_bf16_f32 v44, v44, v45
	v_cvt_pk_bf16_f32 v45, v46, v47
	v_cvt_pk_bf16_f32 v46, v36, v37
	v_cvt_pk_bf16_f32 v47, v38, v39
	global_store_dwordx4 v148, v[44:47], s[50:51] offset:256 sc1
	v_add_u32_e32 v148, s81, v148
	v_and_b32_e32 v132, 0x7fffffff, v32
	v_and_b32_e32 v133, 0x7fffffff, v33
	v_and_b32_e32 v134, 0x7fffffff, v34
	v_and_b32_e32 v135, 0x7fffffff, v35
	v_pk_mul_f32 v[144:145], v[32:33], v[32:33]
	v_pk_mul_f32 v[146:147], v[34:35], v[34:35]
	v_pk_fma_f32 v[136:137], v[132:133], s[84:85], 1.0 op_sel_hi:[1,0,0]
	v_pk_fma_f32 v[138:139], v[134:135], s[84:85], 1.0 op_sel_hi:[1,0,0]
	v_pk_mul_f32 v[144:145], v[144:145], s[80:81] op_sel_hi:[1,0]
	v_pk_mul_f32 v[146:147], v[146:147], s[80:81] op_sel_hi:[1,0]
	v_rcp_f32_e32 v136, v136
	v_rcp_f32_e32 v137, v137
	v_rcp_f32_e32 v138, v138
	v_rcp_f32_e32 v139, v139
	v_exp_f32_e32 v144, v144
	v_exp_f32_e32 v145, v145
	v_exp_f32_e32 v146, v146
	v_exp_f32_e32 v147, v147
	v_pk_fma_f32 v[140:141], v[136:137], s[86:87], v[0:1] op_sel_hi:[1,0,0]
	v_pk_fma_f32 v[142:143], v[138:139], s[86:87], v[0:1] op_sel_hi:[1,0,0]
	v_pk_fma_f32 v[140:141], v[136:137], v[140:141], s[88:89] op_sel_hi:[1,1,0]
	v_pk_fma_f32 v[142:143], v[138:139], v[142:143], s[88:89] op_sel_hi:[1,1,0]
	v_pk_fma_f32 v[140:141], v[136:137], v[140:141], s[82:83] op_sel_hi:[1,1,0]
	v_pk_fma_f32 v[142:143], v[138:139], v[142:143], s[82:83] op_sel_hi:[1,1,0]
	v_pk_fma_f32 v[140:141], v[136:137], v[140:141], s[48:49] op_sel_hi:[1,1,0]
	v_pk_fma_f32 v[142:143], v[138:139], v[142:143], s[48:49] op_sel_hi:[1,1,0]
	v_pk_mul_f32 v[140:141], v[136:137], v[140:141]
	v_pk_mul_f32 v[142:143], v[138:139], v[142:143]
	v_pk_mul_f32 v[140:141], v[140:141], v[144:145]
	v_pk_mul_f32 v[142:143], v[142:143], v[146:147]
	v_max_f32_e32 v32, 0, v32
	v_max_f32_e32 v33, 0, v33
	v_max_f32_e32 v34, 0, v34
	v_max_f32_e32 v35, 0, v35
	v_pk_fma_f32 v[32:33], v[132:133], v[140:141], v[32:33] neg_lo:[1,0,0] neg_hi:[1,0,0]
	v_pk_fma_f32 v[34:35], v[134:135], v[142:143], v[34:35] neg_lo:[1,0,0] neg_hi:[1,0,0]
	v_and_b32_e32 v132, 0x7fffffff, v24
	v_and_b32_e32 v133, 0x7fffffff, v25
	v_and_b32_e32 v134, 0x7fffffff, v26
	v_and_b32_e32 v135, 0x7fffffff, v27
	v_pk_mul_f32 v[144:145], v[24:25], v[24:25]
	v_pk_mul_f32 v[146:147], v[26:27], v[26:27]
	v_pk_fma_f32 v[136:137], v[132:133], s[84:85], 1.0 op_sel_hi:[1,0,0]
	v_pk_fma_f32 v[138:139], v[134:135], s[84:85], 1.0 op_sel_hi:[1,0,0]
	v_pk_mul_f32 v[144:145], v[144:145], s[80:81] op_sel_hi:[1,0]
	v_pk_mul_f32 v[146:147], v[146:147], s[80:81] op_sel_hi:[1,0]
	v_rcp_f32_e32 v136, v136
	v_rcp_f32_e32 v137, v137
	v_rcp_f32_e32 v138, v138
	v_rcp_f32_e32 v139, v139
	v_exp_f32_e32 v144, v144
	v_exp_f32_e32 v145, v145
	v_exp_f32_e32 v146, v146
	v_exp_f32_e32 v147, v147
	v_pk_fma_f32 v[140:141], v[136:137], s[86:87], v[0:1] op_sel_hi:[1,0,0]
	v_pk_fma_f32 v[142:143], v[138:139], s[86:87], v[0:1] op_sel_hi:[1,0,0]
	v_pk_fma_f32 v[140:141], v[136:137], v[140:141], s[88:89] op_sel_hi:[1,1,0]
	v_pk_fma_f32 v[142:143], v[138:139], v[142:143], s[88:89] op_sel_hi:[1,1,0]
	v_pk_fma_f32 v[140:141], v[136:137], v[140:141], s[82:83] op_sel_hi:[1,1,0]
	v_pk_fma_f32 v[142:143], v[138:139], v[142:143], s[82:83] op_sel_hi:[1,1,0]
	v_pk_fma_f32 v[140:141], v[136:137], v[140:141], s[48:49] op_sel_hi:[1,1,0]
	v_pk_fma_f32 v[142:143], v[138:139], v[142:143], s[48:49] op_sel_hi:[1,1,0]
	v_pk_mul_f32 v[140:141], v[136:137], v[140:141]
	v_pk_mul_f32 v[142:143], v[138:139], v[142:143]
	v_pk_mul_f32 v[140:141], v[140:141], v[144:145]
	v_pk_mul_f32 v[142:143], v[142:143], v[146:147]
	v_max_f32_e32 v24, 0, v24
	v_max_f32_e32 v25, 0, v25
	v_max_f32_e32 v26, 0, v26
	v_max_f32_e32 v27, 0, v27
	v_pk_fma_f32 v[24:25], v[132:133], v[140:141], v[24:25] neg_lo:[1,0,0] neg_hi:[1,0,0]
	v_pk_fma_f32 v[26:27], v[134:135], v[142:143], v[26:27] neg_lo:[1,0,0] neg_hi:[1,0,0]
	v_cvt_pk_bf16_f32 v32, v32, v33
	v_cvt_pk_bf16_f32 v33, v34, v35
	v_cvt_pk_bf16_f32 v34, v24, v25
	v_cvt_pk_bf16_f32 v35, v26, v27
	global_store_dwordx4 v148, v[32:35], s[50:51] sc1
	v_and_b32_e32 v132, 0x7fffffff, v16
	v_and_b32_e32 v133, 0x7fffffff, v17
	v_and_b32_e32 v134, 0x7fffffff, v18
	v_and_b32_e32 v135, 0x7fffffff, v19
	v_pk_mul_f32 v[144:145], v[16:17], v[16:17]
	v_pk_mul_f32 v[146:147], v[18:19], v[18:19]
	v_pk_fma_f32 v[136:137], v[132:133], s[84:85], 1.0 op_sel_hi:[1,0,0]
	v_pk_fma_f32 v[138:139], v[134:135], s[84:85], 1.0 op_sel_hi:[1,0,0]
	v_pk_mul_f32 v[144:145], v[144:145], s[80:81] op_sel_hi:[1,0]
	v_pk_mul_f32 v[146:147], v[146:147], s[80:81] op_sel_hi:[1,0]
	v_rcp_f32_e32 v136, v136
	v_rcp_f32_e32 v137, v137
	v_rcp_f32_e32 v138, v138
	v_rcp_f32_e32 v139, v139
	v_exp_f32_e32 v144, v144
	v_exp_f32_e32 v145, v145
	v_exp_f32_e32 v146, v146
	v_exp_f32_e32 v147, v147
	v_pk_fma_f32 v[140:141], v[136:137], s[86:87], v[0:1] op_sel_hi:[1,0,0]
	v_pk_fma_f32 v[142:143], v[138:139], s[86:87], v[0:1] op_sel_hi:[1,0,0]
	v_pk_fma_f32 v[140:141], v[136:137], v[140:141], s[88:89] op_sel_hi:[1,1,0]
	v_pk_fma_f32 v[142:143], v[138:139], v[142:143], s[88:89] op_sel_hi:[1,1,0]
	v_pk_fma_f32 v[140:141], v[136:137], v[140:141], s[82:83] op_sel_hi:[1,1,0]
	v_pk_fma_f32 v[142:143], v[138:139], v[142:143], s[82:83] op_sel_hi:[1,1,0]
	v_pk_fma_f32 v[140:141], v[136:137], v[140:141], s[48:49] op_sel_hi:[1,1,0]
	v_pk_fma_f32 v[142:143], v[138:139], v[142:143], s[48:49] op_sel_hi:[1,1,0]
	v_pk_mul_f32 v[140:141], v[136:137], v[140:141]
	v_pk_mul_f32 v[142:143], v[138:139], v[142:143]
	v_pk_mul_f32 v[140:141], v[140:141], v[144:145]
	v_pk_mul_f32 v[142:143], v[142:143], v[146:147]
	v_max_f32_e32 v16, 0, v16
	v_max_f32_e32 v17, 0, v17
	v_max_f32_e32 v18, 0, v18
	v_max_f32_e32 v19, 0, v19
	v_pk_fma_f32 v[16:17], v[132:133], v[140:141], v[16:17] neg_lo:[1,0,0] neg_hi:[1,0,0]
	v_pk_fma_f32 v[18:19], v[134:135], v[142:143], v[18:19] neg_lo:[1,0,0] neg_hi:[1,0,0]
	v_and_b32_e32 v132, 0x7fffffff, v8
	v_and_b32_e32 v133, 0x7fffffff, v9
	v_and_b32_e32 v134, 0x7fffffff, v10
	v_and_b32_e32 v135, 0x7fffffff, v11
	v_pk_mul_f32 v[144:145], v[8:9], v[8:9]
	v_pk_mul_f32 v[146:147], v[10:11], v[10:11]
	v_pk_fma_f32 v[136:137], v[132:133], s[84:85], 1.0 op_sel_hi:[1,0,0]
	v_pk_fma_f32 v[138:139], v[134:135], s[84:85], 1.0 op_sel_hi:[1,0,0]
	v_pk_mul_f32 v[144:145], v[144:145], s[80:81] op_sel_hi:[1,0]
	v_pk_mul_f32 v[146:147], v[146:147], s[80:81] op_sel_hi:[1,0]
	v_rcp_f32_e32 v136, v136
	v_rcp_f32_e32 v137, v137
	v_rcp_f32_e32 v138, v138
	v_rcp_f32_e32 v139, v139
	v_exp_f32_e32 v144, v144
	v_exp_f32_e32 v145, v145
	v_exp_f32_e32 v146, v146
	v_exp_f32_e32 v147, v147
	v_pk_fma_f32 v[140:141], v[136:137], s[86:87], v[0:1] op_sel_hi:[1,0,0]
	v_pk_fma_f32 v[142:143], v[138:139], s[86:87], v[0:1] op_sel_hi:[1,0,0]
	v_pk_fma_f32 v[140:141], v[136:137], v[140:141], s[88:89] op_sel_hi:[1,1,0]
	v_pk_fma_f32 v[142:143], v[138:139], v[142:143], s[88:89] op_sel_hi:[1,1,0]
	v_pk_fma_f32 v[140:141], v[136:137], v[140:141], s[82:83] op_sel_hi:[1,1,0]
	v_pk_fma_f32 v[142:143], v[138:139], v[142:143], s[82:83] op_sel_hi:[1,1,0]
	v_pk_fma_f32 v[140:141], v[136:137], v[140:141], s[48:49] op_sel_hi:[1,1,0]
	v_pk_fma_f32 v[142:143], v[138:139], v[142:143], s[48:49] op_sel_hi:[1,1,0]
	v_pk_mul_f32 v[140:141], v[136:137], v[140:141]
	v_pk_mul_f32 v[142:143], v[138:139], v[142:143]
	v_pk_mul_f32 v[140:141], v[140:141], v[144:145]
	v_pk_mul_f32 v[142:143], v[142:143], v[146:147]
	v_max_f32_e32 v8, 0, v8
	v_max_f32_e32 v9, 0, v9
	v_max_f32_e32 v10, 0, v10
	v_max_f32_e32 v11, 0, v11
	v_pk_fma_f32 v[8:9], v[132:133], v[140:141], v[8:9] neg_lo:[1,0,0] neg_hi:[1,0,0]
	v_pk_fma_f32 v[10:11], v[134:135], v[142:143], v[10:11] neg_lo:[1,0,0] neg_hi:[1,0,0]
	v_cvt_pk_bf16_f32 v16, v16, v17
	v_cvt_pk_bf16_f32 v17, v18, v19
	v_cvt_pk_bf16_f32 v18, v8, v9
	v_cvt_pk_bf16_f32 v19, v10, v11
	global_store_dwordx4 v148, v[16:19], s[50:51] offset:256 sc1
	v_add_u32_e32 v148, s81, v148
	v_and_b32_e32 v132, 0x7fffffff, v28
	v_and_b32_e32 v133, 0x7fffffff, v29
	v_and_b32_e32 v134, 0x7fffffff, v30
	v_and_b32_e32 v135, 0x7fffffff, v31
	v_pk_mul_f32 v[144:145], v[28:29], v[28:29]
	v_pk_mul_f32 v[146:147], v[30:31], v[30:31]
	v_pk_fma_f32 v[136:137], v[132:133], s[84:85], 1.0 op_sel_hi:[1,0,0]
	v_pk_fma_f32 v[138:139], v[134:135], s[84:85], 1.0 op_sel_hi:[1,0,0]
	v_pk_mul_f32 v[144:145], v[144:145], s[80:81] op_sel_hi:[1,0]
	v_pk_mul_f32 v[146:147], v[146:147], s[80:81] op_sel_hi:[1,0]
	v_rcp_f32_e32 v136, v136
	v_rcp_f32_e32 v137, v137
	v_rcp_f32_e32 v138, v138
	v_rcp_f32_e32 v139, v139
	v_exp_f32_e32 v144, v144
	v_exp_f32_e32 v145, v145
	v_exp_f32_e32 v146, v146
	v_exp_f32_e32 v147, v147
	v_pk_fma_f32 v[140:141], v[136:137], s[86:87], v[0:1] op_sel_hi:[1,0,0]
	v_pk_fma_f32 v[142:143], v[138:139], s[86:87], v[0:1] op_sel_hi:[1,0,0]
	v_pk_fma_f32 v[140:141], v[136:137], v[140:141], s[88:89] op_sel_hi:[1,1,0]
	v_pk_fma_f32 v[142:143], v[138:139], v[142:143], s[88:89] op_sel_hi:[1,1,0]
	v_pk_fma_f32 v[140:141], v[136:137], v[140:141], s[82:83] op_sel_hi:[1,1,0]
	v_pk_fma_f32 v[142:143], v[138:139], v[142:143], s[82:83] op_sel_hi:[1,1,0]
	v_pk_fma_f32 v[140:141], v[136:137], v[140:141], s[48:49] op_sel_hi:[1,1,0]
	v_pk_fma_f32 v[142:143], v[138:139], v[142:143], s[48:49] op_sel_hi:[1,1,0]
	v_pk_mul_f32 v[140:141], v[136:137], v[140:141]
	v_pk_mul_f32 v[142:143], v[138:139], v[142:143]
	v_pk_mul_f32 v[140:141], v[140:141], v[144:145]
	v_pk_mul_f32 v[142:143], v[142:143], v[146:147]
	v_max_f32_e32 v28, 0, v28
	v_max_f32_e32 v29, 0, v29
	v_max_f32_e32 v30, 0, v30
	v_max_f32_e32 v31, 0, v31
	v_pk_fma_f32 v[28:29], v[132:133], v[140:141], v[28:29] neg_lo:[1,0,0] neg_hi:[1,0,0]
	v_pk_fma_f32 v[30:31], v[134:135], v[142:143], v[30:31] neg_lo:[1,0,0] neg_hi:[1,0,0]
	v_and_b32_e32 v132, 0x7fffffff, v20
	v_and_b32_e32 v133, 0x7fffffff, v21
	v_and_b32_e32 v134, 0x7fffffff, v22
	v_and_b32_e32 v135, 0x7fffffff, v23
	v_pk_mul_f32 v[144:145], v[20:21], v[20:21]
	v_pk_mul_f32 v[146:147], v[22:23], v[22:23]
	v_pk_fma_f32 v[136:137], v[132:133], s[84:85], 1.0 op_sel_hi:[1,0,0]
	v_pk_fma_f32 v[138:139], v[134:135], s[84:85], 1.0 op_sel_hi:[1,0,0]
	v_pk_mul_f32 v[144:145], v[144:145], s[80:81] op_sel_hi:[1,0]
	v_pk_mul_f32 v[146:147], v[146:147], s[80:81] op_sel_hi:[1,0]
	v_rcp_f32_e32 v136, v136
	v_rcp_f32_e32 v137, v137
	v_rcp_f32_e32 v138, v138
	v_rcp_f32_e32 v139, v139
	v_exp_f32_e32 v144, v144
	v_exp_f32_e32 v145, v145
	v_exp_f32_e32 v146, v146
	v_exp_f32_e32 v147, v147
	v_pk_fma_f32 v[140:141], v[136:137], s[86:87], v[0:1] op_sel_hi:[1,0,0]
	v_pk_fma_f32 v[142:143], v[138:139], s[86:87], v[0:1] op_sel_hi:[1,0,0]
	v_pk_fma_f32 v[140:141], v[136:137], v[140:141], s[88:89] op_sel_hi:[1,1,0]
	v_pk_fma_f32 v[142:143], v[138:139], v[142:143], s[88:89] op_sel_hi:[1,1,0]
	v_pk_fma_f32 v[140:141], v[136:137], v[140:141], s[82:83] op_sel_hi:[1,1,0]
	v_pk_fma_f32 v[142:143], v[138:139], v[142:143], s[82:83] op_sel_hi:[1,1,0]
	v_pk_fma_f32 v[140:141], v[136:137], v[140:141], s[48:49] op_sel_hi:[1,1,0]
	v_pk_fma_f32 v[142:143], v[138:139], v[142:143], s[48:49] op_sel_hi:[1,1,0]
	v_pk_mul_f32 v[140:141], v[136:137], v[140:141]
	v_pk_mul_f32 v[142:143], v[138:139], v[142:143]
	v_pk_mul_f32 v[140:141], v[140:141], v[144:145]
	v_pk_mul_f32 v[142:143], v[142:143], v[146:147]
	v_max_f32_e32 v20, 0, v20
	v_max_f32_e32 v21, 0, v21
	v_max_f32_e32 v22, 0, v22
	v_max_f32_e32 v23, 0, v23
	v_pk_fma_f32 v[20:21], v[132:133], v[140:141], v[20:21] neg_lo:[1,0,0] neg_hi:[1,0,0]
	v_pk_fma_f32 v[22:23], v[134:135], v[142:143], v[22:23] neg_lo:[1,0,0] neg_hi:[1,0,0]
	v_cvt_pk_bf16_f32 v28, v28, v29
	v_cvt_pk_bf16_f32 v29, v30, v31
	v_cvt_pk_bf16_f32 v30, v20, v21
	v_cvt_pk_bf16_f32 v31, v22, v23
	global_store_dwordx4 v148, v[28:31], s[50:51] sc1
	v_and_b32_e32 v132, 0x7fffffff, v12
	v_and_b32_e32 v133, 0x7fffffff, v13
	v_and_b32_e32 v134, 0x7fffffff, v14
	v_and_b32_e32 v135, 0x7fffffff, v15
	v_pk_mul_f32 v[144:145], v[12:13], v[12:13]
	v_pk_mul_f32 v[146:147], v[14:15], v[14:15]
	v_pk_fma_f32 v[136:137], v[132:133], s[84:85], 1.0 op_sel_hi:[1,0,0]
	v_pk_fma_f32 v[138:139], v[134:135], s[84:85], 1.0 op_sel_hi:[1,0,0]
	v_pk_mul_f32 v[144:145], v[144:145], s[80:81] op_sel_hi:[1,0]
	v_pk_mul_f32 v[146:147], v[146:147], s[80:81] op_sel_hi:[1,0]
	v_rcp_f32_e32 v136, v136
	v_rcp_f32_e32 v137, v137
	v_rcp_f32_e32 v138, v138
	v_rcp_f32_e32 v139, v139
	v_exp_f32_e32 v144, v144
	v_exp_f32_e32 v145, v145
	v_exp_f32_e32 v146, v146
	v_exp_f32_e32 v147, v147
	v_pk_fma_f32 v[140:141], v[136:137], s[86:87], v[0:1] op_sel_hi:[1,0,0]
	v_pk_fma_f32 v[142:143], v[138:139], s[86:87], v[0:1] op_sel_hi:[1,0,0]
	v_pk_fma_f32 v[140:141], v[136:137], v[140:141], s[88:89] op_sel_hi:[1,1,0]
	v_pk_fma_f32 v[142:143], v[138:139], v[142:143], s[88:89] op_sel_hi:[1,1,0]
	v_pk_fma_f32 v[140:141], v[136:137], v[140:141], s[82:83] op_sel_hi:[1,1,0]
	v_pk_fma_f32 v[142:143], v[138:139], v[142:143], s[82:83] op_sel_hi:[1,1,0]
	v_pk_fma_f32 v[140:141], v[136:137], v[140:141], s[48:49] op_sel_hi:[1,1,0]
	v_pk_fma_f32 v[142:143], v[138:139], v[142:143], s[48:49] op_sel_hi:[1,1,0]
	v_pk_mul_f32 v[140:141], v[136:137], v[140:141]
	v_pk_mul_f32 v[142:143], v[138:139], v[142:143]
	v_pk_mul_f32 v[140:141], v[140:141], v[144:145]
	v_pk_mul_f32 v[142:143], v[142:143], v[146:147]
	v_max_f32_e32 v12, 0, v12
	v_max_f32_e32 v13, 0, v13
	v_max_f32_e32 v14, 0, v14
	v_max_f32_e32 v15, 0, v15
	v_pk_fma_f32 v[12:13], v[132:133], v[140:141], v[12:13] neg_lo:[1,0,0] neg_hi:[1,0,0]
	v_pk_fma_f32 v[14:15], v[134:135], v[142:143], v[14:15] neg_lo:[1,0,0] neg_hi:[1,0,0]
	v_and_b32_e32 v132, 0x7fffffff, v4
	v_and_b32_e32 v133, 0x7fffffff, v5
	v_and_b32_e32 v134, 0x7fffffff, v6
	v_and_b32_e32 v135, 0x7fffffff, v7
	v_pk_mul_f32 v[144:145], v[4:5], v[4:5]
	v_pk_mul_f32 v[146:147], v[6:7], v[6:7]
	v_pk_fma_f32 v[136:137], v[132:133], s[84:85], 1.0 op_sel_hi:[1,0,0]
	v_pk_fma_f32 v[138:139], v[134:135], s[84:85], 1.0 op_sel_hi:[1,0,0]
	v_pk_mul_f32 v[144:145], v[144:145], s[80:81] op_sel_hi:[1,0]
	v_pk_mul_f32 v[146:147], v[146:147], s[80:81] op_sel_hi:[1,0]
	v_rcp_f32_e32 v136, v136
	v_rcp_f32_e32 v137, v137
	v_rcp_f32_e32 v138, v138
	v_rcp_f32_e32 v139, v139
	v_exp_f32_e32 v144, v144
	v_exp_f32_e32 v145, v145
	v_exp_f32_e32 v146, v146
	v_exp_f32_e32 v147, v147
	v_pk_fma_f32 v[140:141], v[136:137], s[86:87], v[0:1] op_sel_hi:[1,0,0]
	v_pk_fma_f32 v[142:143], v[138:139], s[86:87], v[0:1] op_sel_hi:[1,0,0]
	v_pk_fma_f32 v[140:141], v[136:137], v[140:141], s[88:89] op_sel_hi:[1,1,0]
	v_pk_fma_f32 v[142:143], v[138:139], v[142:143], s[88:89] op_sel_hi:[1,1,0]
	v_pk_fma_f32 v[140:141], v[136:137], v[140:141], s[82:83] op_sel_hi:[1,1,0]
	v_pk_fma_f32 v[142:143], v[138:139], v[142:143], s[82:83] op_sel_hi:[1,1,0]
	v_pk_fma_f32 v[140:141], v[136:137], v[140:141], s[48:49] op_sel_hi:[1,1,0]
	v_pk_fma_f32 v[142:143], v[138:139], v[142:143], s[48:49] op_sel_hi:[1,1,0]
	v_pk_mul_f32 v[140:141], v[136:137], v[140:141]
	v_pk_mul_f32 v[142:143], v[138:139], v[142:143]
	v_pk_mul_f32 v[140:141], v[140:141], v[144:145]
	v_pk_mul_f32 v[142:143], v[142:143], v[146:147]
	v_max_f32_e32 v4, 0, v4
	v_max_f32_e32 v5, 0, v5
	v_max_f32_e32 v6, 0, v6
	v_max_f32_e32 v7, 0, v7
	v_pk_fma_f32 v[4:5], v[132:133], v[140:141], v[4:5] neg_lo:[1,0,0] neg_hi:[1,0,0]
	v_pk_fma_f32 v[6:7], v[134:135], v[142:143], v[6:7] neg_lo:[1,0,0] neg_hi:[1,0,0]
	v_cvt_pk_bf16_f32 v12, v12, v13
	v_cvt_pk_bf16_f32 v13, v14, v15
	v_cvt_pk_bf16_f32 v14, v4, v5
	v_cvt_pk_bf16_f32 v15, v6, v7
	global_store_dwordx4 v148, v[12:15], s[50:51] offset:256 sc1
	s_branch .LBB0_326
.Lepi_plain_e:
	s_lshl_b32 s30, s48, 8
	s_cmp_eq_u32 s57, 2
	s_cselect_b32 s47, 0x80, 0
	s_add_i32 s30, s30, s60
	s_add_i32 s30, s30, s47
	s_cmp_lg_u32 s57, 0
	s_cselect_b32 s47, 1, 0
	v_readlane_b32 s50, v240, 9
	v_readlane_b32 s51, v240, 10
	s_movk_i32 s82, 0x1400
	s_lshl_b32 s83, s71, 9
	s_cmp_eq_u32 s73, 4
	s_cselect_b32 s81, 0x800, 0
	s_add_i32 s83, s83, s81
	s_cmp_eq_u32 s73, 0
	s_cbranch_scc0 .Lepi_plain_go_e
	s_mov_b64 s[50:51], s[26:27]
	s_movk_i32 s82, 0xc00
.Lepi_plain_go_e:
	v_add_u32_e32 v133, s30, v232
	v_lshl_add_u32 v134, v234, 1, s83
	v_mad_u32_u24 v132, v133, s82, v134
	s_lshl_b32 s81, s82, 4
	s_mov_b32 s80, 0x3e38aa3b
	s_mov_b32 s83, 0x3e38aa3b
	s_cmp_eq_u32 s73, 0
	s_cbranch_scc0 .Lepi_plain_ns_e
	v_pk_mul_f32 v[128:129], v[128:129], s[80:81] op_sel_hi:[1,0]
	v_pk_mul_f32 v[130:131], v[130:131], s[80:81] op_sel_hi:[1,0]
	v_pk_mul_f32 v[120:121], v[120:121], s[80:81] op_sel_hi:[1,0]
	v_pk_mul_f32 v[122:123], v[122:123], s[80:81] op_sel_hi:[1,0]
	v_cvt_pk_bf16_f32 v136, v128, v129
	v_cvt_pk_bf16_f32 v137, v130, v131
	v_cvt_pk_bf16_f32 v138, v120, v121
	v_cvt_pk_bf16_f32 v139, v122, v123
	global_store_dwordx4 v132, v[136:139], s[50:51]
	v_pk_mul_f32 v[112:113], v[112:113], s[80:81] op_sel_hi:[1,0]
	v_pk_mul_f32 v[114:115], v[114:115], s[80:81] op_sel_hi:[1,0]
	v_pk_mul_f32 v[104:105], v[104:105], s[80:81] op_sel_hi:[1,0]
	v_pk_mul_f32 v[106:107], v[106:107], s[80:81] op_sel_hi:[1,0]
	v_cvt_pk_bf16_f32 v140, v112, v113
	v_cvt_pk_bf16_f32 v141, v114, v115
	v_cvt_pk_bf16_f32 v142, v104, v105
	v_cvt_pk_bf16_f32 v143, v106, v107
	global_store_dwordx4 v132, v[140:143], s[50:51] offset:256
	v_add_u32_e32 v132, s81, v132
	v_pk_mul_f32 v[124:125], v[124:125], s[80:81] op_sel_hi:[1,0]
	v_pk_mul_f32 v[126:127], v[126:127], s[80:81] op_sel_hi:[1,0]
	v_pk_mul_f32 v[116:117], v[116:117], s[80:81] op_sel_hi:[1,0]
	v_pk_mul_f32 v[118:119], v[118:119], s[80:81] op_sel_hi:[1,0]
	v_cvt_pk_bf16_f32 v136, v124, v125
	v_cvt_pk_bf16_f32 v137, v126, v127
	v_cvt_pk_bf16_f32 v138, v116, v117
	v_cvt_pk_bf16_f32 v139, v118, v119
	global_store_dwordx4 v132, v[136:139], s[50:51]
	v_pk_mul_f32 v[108:109], v[108:109], s[80:81] op_sel_hi:[1,0]
	v_pk_mul_f32 v[110:111], v[110:111], s[80:81] op_sel_hi:[1,0]
	v_pk_mul_f32 v[100:101], v[100:101], s[80:81] op_sel_hi:[1,0]
	v_pk_mul_f32 v[102:103], v[102:103], s[80:81] op_sel_hi:[1,0]
	v_cvt_pk_bf16_f32 v140, v108, v109
	v_cvt_pk_bf16_f32 v141, v110, v111
	v_cvt_pk_bf16_f32 v142, v100, v101
	v_cvt_pk_bf16_f32 v143, v102, v103
	global_store_dwordx4 v132, v[140:143], s[50:51] offset:256
	v_add_u32_e32 v132, s81, v132
	v_pk_mul_f32 v[96:97], v[96:97], s[80:81] op_sel_hi:[1,0]
	v_pk_mul_f32 v[98:99], v[98:99], s[80:81] op_sel_hi:[1,0]
	v_pk_mul_f32 v[88:89], v[88:89], s[80:81] op_sel_hi:[1,0]
	v_pk_mul_f32 v[90:91], v[90:91], s[80:81] op_sel_hi:[1,0]
	v_cvt_pk_bf16_f32 v136, v96, v97
	v_cvt_pk_bf16_f32 v137, v98, v99
	v_cvt_pk_bf16_f32 v138, v88, v89
	v_cvt_pk_bf16_f32 v139, v90, v91
	global_store_dwordx4 v132, v[136:139], s[50:51]
	v_pk_mul_f32 v[80:81], v[80:81], s[80:81] op_sel_hi:[1,0]
	v_pk_mul_f32 v[82:83], v[82:83], s[80:81] op_sel_hi:[1,0]
	v_pk_mul_f32 v[72:73], v[72:73], s[80:81] op_sel_hi:[1,0]
	v_pk_mul_f32 v[74:75], v[74:75], s[80:81] op_sel_hi:[1,0]
	v_cvt_pk_bf16_f32 v140, v80, v81
	v_cvt_pk_bf16_f32 v141, v82, v83
	v_cvt_pk_bf16_f32 v142, v72, v73
	v_cvt_pk_bf16_f32 v143, v74, v75
	global_store_dwordx4 v132, v[140:143], s[50:51] offset:256
	v_add_u32_e32 v132, s81, v132
	v_pk_mul_f32 v[92:93], v[92:93], s[80:81] op_sel_hi:[1,0]
	v_pk_mul_f32 v[94:95], v[94:95], s[80:81] op_sel_hi:[1,0]
	v_pk_mul_f32 v[84:85], v[84:85], s[80:81] op_sel_hi:[1,0]
	v_pk_mul_f32 v[86:87], v[86:87], s[80:81] op_sel_hi:[1,0]
	v_cvt_pk_bf16_f32 v136, v92, v93
	v_cvt_pk_bf16_f32 v137, v94, v95
	v_cvt_pk_bf16_f32 v138, v84, v85
	v_cvt_pk_bf16_f32 v139, v86, v87
	global_store_dwordx4 v132, v[136:139], s[50:51]
	v_pk_mul_f32 v[76:77], v[76:77], s[80:81] op_sel_hi:[1,0]
	v_pk_mul_f32 v[78:79], v[78:79], s[80:81] op_sel_hi:[1,0]
	v_pk_mul_f32 v[68:69], v[68:69], s[80:81] op_sel_hi:[1,0]
	v_pk_mul_f32 v[70:71], v[70:71], s[80:81] op_sel_hi:[1,0]
	v_cvt_pk_bf16_f32 v140, v76, v77
	v_cvt_pk_bf16_f32 v141, v78, v79
	v_cvt_pk_bf16_f32 v142, v68, v69
	v_cvt_pk_bf16_f32 v143, v70, v71
	global_store_dwordx4 v132, v[140:143], s[50:51] offset:256
	s_mul_i32 s30, s81, 5
	v_add_u32_e32 v132, s30, v132
	s_cmp_lg_u32 s47, 0
	s_cbranch_scc1 .LBB0_326
	v_pk_mul_f32 v[64:65], v[64:65], s[80:81] op_sel_hi:[1,0]
	v_pk_mul_f32 v[66:67], v[66:67], s[80:81] op_sel_hi:[1,0]
	v_pk_mul_f32 v[56:57], v[56:57], s[80:81] op_sel_hi:[1,0]
	v_pk_mul_f32 v[58:59], v[58:59], s[80:81] op_sel_hi:[1,0]
	v_cvt_pk_bf16_f32 v136, v64, v65
	v_cvt_pk_bf16_f32 v137, v66, v67
	v_cvt_pk_bf16_f32 v138, v56, v57
	v_cvt_pk_bf16_f32 v139, v58, v59
	global_store_dwordx4 v132, v[136:139], s[50:51]
	v_pk_mul_f32 v[48:49], v[48:49], s[80:81] op_sel_hi:[1,0]
	v_pk_mul_f32 v[50:51], v[50:51], s[80:81] op_sel_hi:[1,0]
	v_pk_mul_f32 v[40:41], v[40:41], s[80:81] op_sel_hi:[1,0]
	v_pk_mul_f32 v[42:43], v[42:43], s[80:81] op_sel_hi:[1,0]
	v_cvt_pk_bf16_f32 v140, v48, v49
	v_cvt_pk_bf16_f32 v141, v50, v51
	v_cvt_pk_bf16_f32 v142, v40, v41
	v_cvt_pk_bf16_f32 v143, v42, v43
	global_store_dwordx4 v132, v[140:143], s[50:51] offset:256
	v_add_u32_e32 v132, s81, v132
	v_pk_mul_f32 v[60:61], v[60:61], s[80:81] op_sel_hi:[1,0]
	v_pk_mul_f32 v[62:63], v[62:63], s[80:81] op_sel_hi:[1,0]
	v_pk_mul_f32 v[52:53], v[52:53], s[80:81] op_sel_hi:[1,0]
	v_pk_mul_f32 v[54:55], v[54:55], s[80:81] op_sel_hi:[1,0]
	v_cvt_pk_bf16_f32 v136, v60, v61
	v_cvt_pk_bf16_f32 v137, v62, v63
	v_cvt_pk_bf16_f32 v138, v52, v53
	v_cvt_pk_bf16_f32 v139, v54, v55
	global_store_dwordx4 v132, v[136:139], s[50:51]
	v_pk_mul_f32 v[44:45], v[44:45], s[80:81] op_sel_hi:[1,0]
	v_pk_mul_f32 v[46:47], v[46:47], s[80:81] op_sel_hi:[1,0]
	v_pk_mul_f32 v[36:37], v[36:37], s[80:81] op_sel_hi:[1,0]
	v_pk_mul_f32 v[38:39], v[38:39], s[80:81] op_sel_hi:[1,0]
	v_cvt_pk_bf16_f32 v140, v44, v45
	v_cvt_pk_bf16_f32 v141, v46, v47
	v_cvt_pk_bf16_f32 v142, v36, v37
	v_cvt_pk_bf16_f32 v143, v38, v39
	global_store_dwordx4 v132, v[140:143], s[50:51] offset:256
	v_add_u32_e32 v132, s81, v132
	v_pk_mul_f32 v[32:33], v[32:33], s[80:81] op_sel_hi:[1,0]
	v_pk_mul_f32 v[34:35], v[34:35], s[80:81] op_sel_hi:[1,0]
	v_pk_mul_f32 v[24:25], v[24:25], s[80:81] op_sel_hi:[1,0]
	v_pk_mul_f32 v[26:27], v[26:27], s[80:81] op_sel_hi:[1,0]
	v_cvt_pk_bf16_f32 v136, v32, v33
	v_cvt_pk_bf16_f32 v137, v34, v35
	v_cvt_pk_bf16_f32 v138, v24, v25
	v_cvt_pk_bf16_f32 v139, v26, v27
	global_store_dwordx4 v132, v[136:139], s[50:51]
	v_pk_mul_f32 v[16:17], v[16:17], s[80:81] op_sel_hi:[1,0]
	v_pk_mul_f32 v[18:19], v[18:19], s[80:81] op_sel_hi:[1,0]
	v_pk_mul_f32 v[8:9], v[8:9], s[80:81] op_sel_hi:[1,0]
	v_pk_mul_f32 v[10:11], v[10:11], s[80:81] op_sel_hi:[1,0]
	v_cvt_pk_bf16_f32 v140, v16, v17
	v_cvt_pk_bf16_f32 v141, v18, v19
	v_cvt_pk_bf16_f32 v142, v8, v9
	v_cvt_pk_bf16_f32 v143, v10, v11
	global_store_dwordx4 v132, v[140:143], s[50:51] offset:256
	v_add_u32_e32 v132, s81, v132
	v_pk_mul_f32 v[28:29], v[28:29], s[80:81] op_sel_hi:[1,0]
	v_pk_mul_f32 v[30:31], v[30:31], s[80:81] op_sel_hi:[1,0]
	v_pk_mul_f32 v[20:21], v[20:21], s[80:81] op_sel_hi:[1,0]
	v_pk_mul_f32 v[22:23], v[22:23], s[80:81] op_sel_hi:[1,0]
	v_cvt_pk_bf16_f32 v136, v28, v29
	v_cvt_pk_bf16_f32 v137, v30, v31
	v_cvt_pk_bf16_f32 v138, v20, v21
	v_cvt_pk_bf16_f32 v139, v22, v23
	global_store_dwordx4 v132, v[136:139], s[50:51]
	v_pk_mul_f32 v[12:13], v[12:13], s[80:81] op_sel_hi:[1,0]
	v_pk_mul_f32 v[14:15], v[14:15], s[80:81] op_sel_hi:[1,0]
	v_pk_mul_f32 v[4:5], v[4:5], s[80:81] op_sel_hi:[1,0]
	v_pk_mul_f32 v[6:7], v[6:7], s[80:81] op_sel_hi:[1,0]
	v_cvt_pk_bf16_f32 v140, v12, v13
	v_cvt_pk_bf16_f32 v141, v14, v15
	v_cvt_pk_bf16_f32 v142, v4, v5
	v_cvt_pk_bf16_f32 v143, v6, v7
	global_store_dwordx4 v132, v[140:143], s[50:51] offset:256
	s_branch .LBB0_326
.Lepi_plain_ns_e:
	v_cvt_pk_bf16_f32 v136, v128, v129
	v_cvt_pk_bf16_f32 v137, v130, v131
	v_cvt_pk_bf16_f32 v138, v120, v121
	v_cvt_pk_bf16_f32 v139, v122, v123
	global_store_dwordx4 v132, v[136:139], s[50:51]
	v_cvt_pk_bf16_f32 v140, v112, v113
	v_cvt_pk_bf16_f32 v141, v114, v115
	v_cvt_pk_bf16_f32 v142, v104, v105
	v_cvt_pk_bf16_f32 v143, v106, v107
	global_store_dwordx4 v132, v[140:143], s[50:51] offset:256
	v_add_u32_e32 v132, s81, v132
	v_cvt_pk_bf16_f32 v136, v124, v125
	v_cvt_pk_bf16_f32 v137, v126, v127
	v_cvt_pk_bf16_f32 v138, v116, v117
	v_cvt_pk_bf16_f32 v139, v118, v119
	global_store_dwordx4 v132, v[136:139], s[50:51]
	v_cvt_pk_bf16_f32 v140, v108, v109
	v_cvt_pk_bf16_f32 v141, v110, v111
	v_cvt_pk_bf16_f32 v142, v100, v101
	v_cvt_pk_bf16_f32 v143, v102, v103
	global_store_dwordx4 v132, v[140:143], s[50:51] offset:256
	v_add_u32_e32 v132, s81, v132
	v_cvt_pk_bf16_f32 v136, v96, v97
	v_cvt_pk_bf16_f32 v137, v98, v99
	v_cvt_pk_bf16_f32 v138, v88, v89
	v_cvt_pk_bf16_f32 v139, v90, v91
	global_store_dwordx4 v132, v[136:139], s[50:51]
	v_cvt_pk_bf16_f32 v140, v80, v81
	v_cvt_pk_bf16_f32 v141, v82, v83
	v_cvt_pk_bf16_f32 v142, v72, v73
	v_cvt_pk_bf16_f32 v143, v74, v75
	global_store_dwordx4 v132, v[140:143], s[50:51] offset:256
	v_add_u32_e32 v132, s81, v132
	v_cvt_pk_bf16_f32 v136, v92, v93
	v_cvt_pk_bf16_f32 v137, v94, v95
	v_cvt_pk_bf16_f32 v138, v84, v85
	v_cvt_pk_bf16_f32 v139, v86, v87
	global_store_dwordx4 v132, v[136:139], s[50:51]
	v_cvt_pk_bf16_f32 v140, v76, v77
	v_cvt_pk_bf16_f32 v141, v78, v79
	v_cvt_pk_bf16_f32 v142, v68, v69
	v_cvt_pk_bf16_f32 v143, v70, v71
	global_store_dwordx4 v132, v[140:143], s[50:51] offset:256
	s_mul_i32 s30, s81, 5
	v_add_u32_e32 v132, s30, v132
	s_cmp_lg_u32 s47, 0
	s_cbranch_scc1 .LBB0_326
	v_cvt_pk_bf16_f32 v136, v64, v65
	v_cvt_pk_bf16_f32 v137, v66, v67
	v_cvt_pk_bf16_f32 v138, v56, v57
	v_cvt_pk_bf16_f32 v139, v58, v59
	global_store_dwordx4 v132, v[136:139], s[50:51]
	v_cvt_pk_bf16_f32 v140, v48, v49
	v_cvt_pk_bf16_f32 v141, v50, v51
	v_cvt_pk_bf16_f32 v142, v40, v41
	v_cvt_pk_bf16_f32 v143, v42, v43
	global_store_dwordx4 v132, v[140:143], s[50:51] offset:256
	v_add_u32_e32 v132, s81, v132
	v_cvt_pk_bf16_f32 v136, v60, v61
	v_cvt_pk_bf16_f32 v137, v62, v63
	v_cvt_pk_bf16_f32 v138, v52, v53
	v_cvt_pk_bf16_f32 v139, v54, v55
	global_store_dwordx4 v132, v[136:139], s[50:51]
	v_cvt_pk_bf16_f32 v140, v44, v45
	v_cvt_pk_bf16_f32 v141, v46, v47
	v_cvt_pk_bf16_f32 v142, v36, v37
	v_cvt_pk_bf16_f32 v143, v38, v39
	global_store_dwordx4 v132, v[140:143], s[50:51] offset:256
	v_add_u32_e32 v132, s81, v132
	v_cvt_pk_bf16_f32 v136, v32, v33
	v_cvt_pk_bf16_f32 v137, v34, v35
	v_cvt_pk_bf16_f32 v138, v24, v25
	v_cvt_pk_bf16_f32 v139, v26, v27
	global_store_dwordx4 v132, v[136:139], s[50:51]
	v_cvt_pk_bf16_f32 v140, v16, v17
	v_cvt_pk_bf16_f32 v141, v18, v19
	v_cvt_pk_bf16_f32 v142, v8, v9
	v_cvt_pk_bf16_f32 v143, v10, v11
	global_store_dwordx4 v132, v[140:143], s[50:51] offset:256
	v_add_u32_e32 v132, s81, v132
	v_cvt_pk_bf16_f32 v136, v28, v29
	v_cvt_pk_bf16_f32 v137, v30, v31
	v_cvt_pk_bf16_f32 v138, v20, v21
	v_cvt_pk_bf16_f32 v139, v22, v23
	global_store_dwordx4 v132, v[136:139], s[50:51]
	v_cvt_pk_bf16_f32 v140, v12, v13
	v_cvt_pk_bf16_f32 v141, v14, v15
	v_cvt_pk_bf16_f32 v142, v4, v5
	v_cvt_pk_bf16_f32 v143, v6, v7
	global_store_dwordx4 v132, v[140:143], s[50:51] offset:256
	s_branch .LBB0_326

.Lepi_silu_go_e:
	v_add_u32_e32 v133, s30, v232
	v_lshl_add_u32 v134, v234, 1, s83
	v_mad_u32_u24 v148, v133, s82, v134
	s_lshl_b32 s81, s82, 4
	s_mov_b32 s80, 0xbfb8aa3b
	v_pk_mul_f32 v[132:133], v[128:129], s[80:81] op_sel_hi:[1,0]
	v_pk_mul_f32 v[134:135], v[130:131], s[80:81] op_sel_hi:[1,0]
	v_pk_mul_f32 v[136:137], v[120:121], s[80:81] op_sel_hi:[1,0]
	v_pk_mul_f32 v[138:139], v[122:123], s[80:81] op_sel_hi:[1,0]
	v_exp_f32_e32 v132, v132
	v_exp_f32_e32 v133, v133
	v_exp_f32_e32 v134, v134
	v_exp_f32_e32 v135, v135
	v_exp_f32_e32 v136, v136
	v_exp_f32_e32 v137, v137
	v_exp_f32_e32 v138, v138
	v_exp_f32_e32 v139, v139
	v_pk_add_f32 v[132:133], v[132:133], 1.0 op_sel_hi:[1,0]
	v_pk_add_f32 v[134:135], v[134:135], 1.0 op_sel_hi:[1,0]
	v_pk_add_f32 v[136:137], v[136:137], 1.0 op_sel_hi:[1,0]
	v_pk_add_f32 v[138:139], v[138:139], 1.0 op_sel_hi:[1,0]
	v_rcp_f32_e32 v132, v132
	v_rcp_f32_e32 v133, v133
	v_rcp_f32_e32 v134, v134
	v_rcp_f32_e32 v135, v135
	v_rcp_f32_e32 v136, v136
	v_rcp_f32_e32 v137, v137
	v_rcp_f32_e32 v138, v138
	v_rcp_f32_e32 v139, v139
	v_pk_mul_f32 v[128:129], v[128:129], v[132:133]
	v_pk_mul_f32 v[130:131], v[130:131], v[134:135]
	v_pk_mul_f32 v[120:121], v[120:121], v[136:137]
	v_pk_mul_f32 v[122:123], v[122:123], v[138:139]
	v_cvt_pk_bf16_f32 v128, v128, v129
	v_cvt_pk_bf16_f32 v129, v130, v131
	v_cvt_pk_bf16_f32 v130, v120, v121
	v_cvt_pk_bf16_f32 v131, v122, v123
	global_store_dwordx4 v148, v[128:131], s[50:51]
	v_pk_mul_f32 v[132:133], v[112:113], s[80:81] op_sel_hi:[1,0]
	v_pk_mul_f32 v[134:135], v[114:115], s[80:81] op_sel_hi:[1,0]
	v_pk_mul_f32 v[136:137], v[104:105], s[80:81] op_sel_hi:[1,0]
	v_pk_mul_f32 v[138:139], v[106:107], s[80:81] op_sel_hi:[1,0]
	v_exp_f32_e32 v132, v132
	v_exp_f32_e32 v133, v133
	v_exp_f32_e32 v134, v134
	v_exp_f32_e32 v135, v135
	v_exp_f32_e32 v136, v136
	v_exp_f32_e32 v137, v137
	v_exp_f32_e32 v138, v138
	v_exp_f32_e32 v139, v139
	v_pk_add_f32 v[132:133], v[132:133], 1.0 op_sel_hi:[1,0]
	v_pk_add_f32 v[134:135], v[134:135], 1.0 op_sel_hi:[1,0]
	v_pk_add_f32 v[136:137], v[136:137], 1.0 op_sel_hi:[1,0]
	v_pk_add_f32 v[138:139], v[138:139], 1.0 op_sel_hi:[1,0]
	v_rcp_f32_e32 v132, v132
	v_rcp_f32_e32 v133, v133
	v_rcp_f32_e32 v134, v134
	v_rcp_f32_e32 v135, v135
	v_rcp_f32_e32 v136, v136
	v_rcp_f32_e32 v137, v137
	v_rcp_f32_e32 v138, v138
	v_rcp_f32_e32 v139, v139
	v_pk_mul_f32 v[112:113], v[112:113], v[132:133]
	v_pk_mul_f32 v[114:115], v[114:115], v[134:135]
	v_pk_mul_f32 v[104:105], v[104:105], v[136:137]
	v_pk_mul_f32 v[106:107], v[106:107], v[138:139]
	v_cvt_pk_bf16_f32 v112, v112, v113
	v_cvt_pk_bf16_f32 v113, v114, v115
	v_cvt_pk_bf16_f32 v114, v104, v105
	v_cvt_pk_bf16_f32 v115, v106, v107
	global_store_dwordx4 v148, v[112:115], s[50:51] offset:256
	v_add_u32_e32 v148, s81, v148
	v_pk_mul_f32 v[132:133], v[124:125], s[80:81] op_sel_hi:[1,0]
	v_pk_mul_f32 v[134:135], v[126:127], s[80:81] op_sel_hi:[1,0]
	v_pk_mul_f32 v[136:137], v[116:117], s[80:81] op_sel_hi:[1,0]
	v_pk_mul_f32 v[138:139], v[118:119], s[80:81] op_sel_hi:[1,0]
	v_exp_f32_e32 v132, v132
	v_exp_f32_e32 v133, v133
	v_exp_f32_e32 v134, v134
	v_exp_f32_e32 v135, v135
	v_exp_f32_e32 v136, v136
	v_exp_f32_e32 v137, v137
	v_exp_f32_e32 v138, v138
	v_exp_f32_e32 v139, v139
	v_pk_add_f32 v[132:133], v[132:133], 1.0 op_sel_hi:[1,0]
	v_pk_add_f32 v[134:135], v[134:135], 1.0 op_sel_hi:[1,0]
	v_pk_add_f32 v[136:137], v[136:137], 1.0 op_sel_hi:[1,0]
	v_pk_add_f32 v[138:139], v[138:139], 1.0 op_sel_hi:[1,0]
	v_rcp_f32_e32 v132, v132
	v_rcp_f32_e32 v133, v133
	v_rcp_f32_e32 v134, v134
	v_rcp_f32_e32 v135, v135
	v_rcp_f32_e32 v136, v136
	v_rcp_f32_e32 v137, v137
	v_rcp_f32_e32 v138, v138
	v_rcp_f32_e32 v139, v139
	v_pk_mul_f32 v[124:125], v[124:125], v[132:133]
	v_pk_mul_f32 v[126:127], v[126:127], v[134:135]
	v_pk_mul_f32 v[116:117], v[116:117], v[136:137]
	v_pk_mul_f32 v[118:119], v[118:119], v[138:139]
	v_cvt_pk_bf16_f32 v124, v124, v125
	v_cvt_pk_bf16_f32 v125, v126, v127
	v_cvt_pk_bf16_f32 v126, v116, v117
	v_cvt_pk_bf16_f32 v127, v118, v119
	global_store_dwordx4 v148, v[124:127], s[50:51]
	v_pk_mul_f32 v[132:133], v[108:109], s[80:81] op_sel_hi:[1,0]
	v_pk_mul_f32 v[134:135], v[110:111], s[80:81] op_sel_hi:[1,0]
	v_pk_mul_f32 v[136:137], v[100:101], s[80:81] op_sel_hi:[1,0]
	v_pk_mul_f32 v[138:139], v[102:103], s[80:81] op_sel_hi:[1,0]
	v_exp_f32_e32 v132, v132
	v_exp_f32_e32 v133, v133
	v_exp_f32_e32 v134, v134
	v_exp_f32_e32 v135, v135
	v_exp_f32_e32 v136, v136
	v_exp_f32_e32 v137, v137
	v_exp_f32_e32 v138, v138
	v_exp_f32_e32 v139, v139
	v_pk_add_f32 v[132:133], v[132:133], 1.0 op_sel_hi:[1,0]
	v_pk_add_f32 v[134:135], v[134:135], 1.0 op_sel_hi:[1,0]
	v_pk_add_f32 v[136:137], v[136:137], 1.0 op_sel_hi:[1,0]
	v_pk_add_f32 v[138:139], v[138:139], 1.0 op_sel_hi:[1,0]
	v_rcp_f32_e32 v132, v132
	v_rcp_f32_e32 v133, v133
	v_rcp_f32_e32 v134, v134
	v_rcp_f32_e32 v135, v135
	v_rcp_f32_e32 v136, v136
	v_rcp_f32_e32 v137, v137
	v_rcp_f32_e32 v138, v138
	v_rcp_f32_e32 v139, v139
	v_pk_mul_f32 v[108:109], v[108:109], v[132:133]
	v_pk_mul_f32 v[110:111], v[110:111], v[134:135]
	v_pk_mul_f32 v[100:101], v[100:101], v[136:137]
	v_pk_mul_f32 v[102:103], v[102:103], v[138:139]
	v_cvt_pk_bf16_f32 v108, v108, v109
	v_cvt_pk_bf16_f32 v109, v110, v111
	v_cvt_pk_bf16_f32 v110, v100, v101
	v_cvt_pk_bf16_f32 v111, v102, v103
	global_store_dwordx4 v148, v[108:111], s[50:51] offset:256
	v_add_u32_e32 v148, s81, v148
	v_pk_mul_f32 v[132:133], v[96:97], s[80:81] op_sel_hi:[1,0]
	v_pk_mul_f32 v[134:135], v[98:99], s[80:81] op_sel_hi:[1,0]
	v_pk_mul_f32 v[136:137], v[88:89], s[80:81] op_sel_hi:[1,0]
	v_pk_mul_f32 v[138:139], v[90:91], s[80:81] op_sel_hi:[1,0]
	v_exp_f32_e32 v132, v132
	v_exp_f32_e32 v133, v133
	v_exp_f32_e32 v134, v134
	v_exp_f32_e32 v135, v135
	v_exp_f32_e32 v136, v136
	v_exp_f32_e32 v137, v137
	v_exp_f32_e32 v138, v138
	v_exp_f32_e32 v139, v139
	v_pk_add_f32 v[132:133], v[132:133], 1.0 op_sel_hi:[1,0]
	v_pk_add_f32 v[134:135], v[134:135], 1.0 op_sel_hi:[1,0]
	v_pk_add_f32 v[136:137], v[136:137], 1.0 op_sel_hi:[1,0]
	v_pk_add_f32 v[138:139], v[138:139], 1.0 op_sel_hi:[1,0]
	v_rcp_f32_e32 v132, v132
	v_rcp_f32_e32 v133, v133
	v_rcp_f32_e32 v134, v134
	v_rcp_f32_e32 v135, v135
	v_rcp_f32_e32 v136, v136
	v_rcp_f32_e32 v137, v137
	v_rcp_f32_e32 v138, v138
	v_rcp_f32_e32 v139, v139
	v_pk_mul_f32 v[96:97], v[96:97], v[132:133]
	v_pk_mul_f32 v[98:99], v[98:99], v[134:135]
	v_pk_mul_f32 v[88:89], v[88:89], v[136:137]
	v_pk_mul_f32 v[90:91], v[90:91], v[138:139]
	v_cvt_pk_bf16_f32 v96, v96, v97
	v_cvt_pk_bf16_f32 v97, v98, v99
	v_cvt_pk_bf16_f32 v98, v88, v89
	v_cvt_pk_bf16_f32 v99, v90, v91
	global_store_dwordx4 v148, v[96:99], s[50:51]
	v_pk_mul_f32 v[132:133], v[80:81], s[80:81] op_sel_hi:[1,0]
	v_pk_mul_f32 v[134:135], v[82:83], s[80:81] op_sel_hi:[1,0]
	v_pk_mul_f32 v[136:137], v[72:73], s[80:81] op_sel_hi:[1,0]
	v_pk_mul_f32 v[138:139], v[74:75], s[80:81] op_sel_hi:[1,0]
	v_exp_f32_e32 v132, v132
	v_exp_f32_e32 v133, v133
	v_exp_f32_e32 v134, v134
	v_exp_f32_e32 v135, v135
	v_exp_f32_e32 v136, v136
	v_exp_f32_e32 v137, v137
	v_exp_f32_e32 v138, v138
	v_exp_f32_e32 v139, v139
	v_pk_add_f32 v[132:133], v[132:133], 1.0 op_sel_hi:[1,0]
	v_pk_add_f32 v[134:135], v[134:135], 1.0 op_sel_hi:[1,0]
	v_pk_add_f32 v[136:137], v[136:137], 1.0 op_sel_hi:[1,0]
	v_pk_add_f32 v[138:139], v[138:139], 1.0 op_sel_hi:[1,0]
	v_rcp_f32_e32 v132, v132
	v_rcp_f32_e32 v133, v133
	v_rcp_f32_e32 v134, v134
	v_rcp_f32_e32 v135, v135
	v_rcp_f32_e32 v136, v136
	v_rcp_f32_e32 v137, v137
	v_rcp_f32_e32 v138, v138
	v_rcp_f32_e32 v139, v139
	v_pk_mul_f32 v[80:81], v[80:81], v[132:133]
	v_pk_mul_f32 v[82:83], v[82:83], v[134:135]
	v_pk_mul_f32 v[72:73], v[72:73], v[136:137]
	v_pk_mul_f32 v[74:75], v[74:75], v[138:139]
	v_cvt_pk_bf16_f32 v80, v80, v81
	v_cvt_pk_bf16_f32 v81, v82, v83
	v_cvt_pk_bf16_f32 v82, v72, v73
	v_cvt_pk_bf16_f32 v83, v74, v75
	global_store_dwordx4 v148, v[80:83], s[50:51] offset:256
	v_add_u32_e32 v148, s81, v148
	v_pk_mul_f32 v[132:133], v[92:93], s[80:81] op_sel_hi:[1,0]
	v_pk_mul_f32 v[134:135], v[94:95], s[80:81] op_sel_hi:[1,0]
	v_pk_mul_f32 v[136:137], v[84:85], s[80:81] op_sel_hi:[1,0]
	v_pk_mul_f32 v[138:139], v[86:87], s[80:81] op_sel_hi:[1,0]
	v_exp_f32_e32 v132, v132
	v_exp_f32_e32 v133, v133
	v_exp_f32_e32 v134, v134
	v_exp_f32_e32 v135, v135
	v_exp_f32_e32 v136, v136
	v_exp_f32_e32 v137, v137
	v_exp_f32_e32 v138, v138
	v_exp_f32_e32 v139, v139
	v_pk_add_f32 v[132:133], v[132:133], 1.0 op_sel_hi:[1,0]
	v_pk_add_f32 v[134:135], v[134:135], 1.0 op_sel_hi:[1,0]
	v_pk_add_f32 v[136:137], v[136:137], 1.0 op_sel_hi:[1,0]
	v_pk_add_f32 v[138:139], v[138:139], 1.0 op_sel_hi:[1,0]
	v_rcp_f32_e32 v132, v132
	v_rcp_f32_e32 v133, v133
	v_rcp_f32_e32 v134, v134
	v_rcp_f32_e32 v135, v135
	v_rcp_f32_e32 v136, v136
	v_rcp_f32_e32 v137, v137
	v_rcp_f32_e32 v138, v138
	v_rcp_f32_e32 v139, v139
	v_pk_mul_f32 v[92:93], v[92:93], v[132:133]
	v_pk_mul_f32 v[94:95], v[94:95], v[134:135]
	v_pk_mul_f32 v[84:85], v[84:85], v[136:137]
	v_pk_mul_f32 v[86:87], v[86:87], v[138:139]
	v_cvt_pk_bf16_f32 v92, v92, v93
	v_cvt_pk_bf16_f32 v93, v94, v95
	v_cvt_pk_bf16_f32 v94, v84, v85
	v_cvt_pk_bf16_f32 v95, v86, v87
	global_store_dwordx4 v148, v[92:95], s[50:51]
	v_pk_mul_f32 v[132:133], v[76:77], s[80:81] op_sel_hi:[1,0]
	v_pk_mul_f32 v[134:135], v[78:79], s[80:81] op_sel_hi:[1,0]
	v_pk_mul_f32 v[136:137], v[68:69], s[80:81] op_sel_hi:[1,0]
	v_pk_mul_f32 v[138:139], v[70:71], s[80:81] op_sel_hi:[1,0]
	v_exp_f32_e32 v132, v132
	v_exp_f32_e32 v133, v133
	v_exp_f32_e32 v134, v134
	v_exp_f32_e32 v135, v135
	v_exp_f32_e32 v136, v136
	v_exp_f32_e32 v137, v137
	v_exp_f32_e32 v138, v138
	v_exp_f32_e32 v139, v139
	v_pk_add_f32 v[132:133], v[132:133], 1.0 op_sel_hi:[1,0]
	v_pk_add_f32 v[134:135], v[134:135], 1.0 op_sel_hi:[1,0]
	v_pk_add_f32 v[136:137], v[136:137], 1.0 op_sel_hi:[1,0]
	v_pk_add_f32 v[138:139], v[138:139], 1.0 op_sel_hi:[1,0]
	v_rcp_f32_e32 v132, v132
	v_rcp_f32_e32 v133, v133
	v_rcp_f32_e32 v134, v134
	v_rcp_f32_e32 v135, v135
	v_rcp_f32_e32 v136, v136
	v_rcp_f32_e32 v137, v137
	v_rcp_f32_e32 v138, v138
	v_rcp_f32_e32 v139, v139
	v_pk_mul_f32 v[76:77], v[76:77], v[132:133]
	v_pk_mul_f32 v[78:79], v[78:79], v[134:135]
	v_pk_mul_f32 v[68:69], v[68:69], v[136:137]
	v_pk_mul_f32 v[70:71], v[70:71], v[138:139]
	v_cvt_pk_bf16_f32 v76, v76, v77
	v_cvt_pk_bf16_f32 v77, v78, v79
	v_cvt_pk_bf16_f32 v78, v68, v69
	v_cvt_pk_bf16_f32 v79, v70, v71
	global_store_dwordx4 v148, v[76:79], s[50:51] offset:256
	s_mul_i32 s30, s81, 5
	v_add_u32_e32 v148, s30, v148
	s_cmp_lg_u32 s49, 0
	s_cbranch_scc1 .LBB0_326
	v_pk_mul_f32 v[132:133], v[64:65], s[80:81] op_sel_hi:[1,0]
	v_pk_mul_f32 v[134:135], v[66:67], s[80:81] op_sel_hi:[1,0]
	v_pk_mul_f32 v[136:137], v[56:57], s[80:81] op_sel_hi:[1,0]
	v_pk_mul_f32 v[138:139], v[58:59], s[80:81] op_sel_hi:[1,0]
	v_exp_f32_e32 v132, v132
	v_exp_f32_e32 v133, v133
	v_exp_f32_e32 v134, v134
	v_exp_f32_e32 v135, v135
	v_exp_f32_e32 v136, v136
	v_exp_f32_e32 v137, v137
	v_exp_f32_e32 v138, v138
	v_exp_f32_e32 v139, v139
	v_pk_add_f32 v[132:133], v[132:133], 1.0 op_sel_hi:[1,0]
	v_pk_add_f32 v[134:135], v[134:135], 1.0 op_sel_hi:[1,0]
	v_pk_add_f32 v[136:137], v[136:137], 1.0 op_sel_hi:[1,0]
	v_pk_add_f32 v[138:139], v[138:139], 1.0 op_sel_hi:[1,0]
	v_rcp_f32_e32 v132, v132
	v_rcp_f32_e32 v133, v133
	v_rcp_f32_e32 v134, v134
	v_rcp_f32_e32 v135, v135
	v_rcp_f32_e32 v136, v136
	v_rcp_f32_e32 v137, v137
	v_rcp_f32_e32 v138, v138
	v_rcp_f32_e32 v139, v139
	v_pk_mul_f32 v[64:65], v[64:65], v[132:133]
	v_pk_mul_f32 v[66:67], v[66:67], v[134:135]
	v_pk_mul_f32 v[56:57], v[56:57], v[136:137]
	v_pk_mul_f32 v[58:59], v[58:59], v[138:139]
	v_cvt_pk_bf16_f32 v64, v64, v65
	v_cvt_pk_bf16_f32 v65, v66, v67
	v_cvt_pk_bf16_f32 v66, v56, v57
	v_cvt_pk_bf16_f32 v67, v58, v59
	global_store_dwordx4 v148, v[64:67], s[50:51]
	v_pk_mul_f32 v[132:133], v[48:49], s[80:81] op_sel_hi:[1,0]
	v_pk_mul_f32 v[134:135], v[50:51], s[80:81] op_sel_hi:[1,0]
	v_pk_mul_f32 v[136:137], v[40:41], s[80:81] op_sel_hi:[1,0]
	v_pk_mul_f32 v[138:139], v[42:43], s[80:81] op_sel_hi:[1,0]
	v_exp_f32_e32 v132, v132
	v_exp_f32_e32 v133, v133
	v_exp_f32_e32 v134, v134
	v_exp_f32_e32 v135, v135
	v_exp_f32_e32 v136, v136
	v_exp_f32_e32 v137, v137
	v_exp_f32_e32 v138, v138
	v_exp_f32_e32 v139, v139
	v_pk_add_f32 v[132:133], v[132:133], 1.0 op_sel_hi:[1,0]
	v_pk_add_f32 v[134:135], v[134:135], 1.0 op_sel_hi:[1,0]
	v_pk_add_f32 v[136:137], v[136:137], 1.0 op_sel_hi:[1,0]
	v_pk_add_f32 v[138:139], v[138:139], 1.0 op_sel_hi:[1,0]
	v_rcp_f32_e32 v132, v132
	v_rcp_f32_e32 v133, v133
	v_rcp_f32_e32 v134, v134
	v_rcp_f32_e32 v135, v135
	v_rcp_f32_e32 v136, v136
	v_rcp_f32_e32 v137, v137
	v_rcp_f32_e32 v138, v138
	v_rcp_f32_e32 v139, v139
	v_pk_mul_f32 v[48:49], v[48:49], v[132:133]
	v_pk_mul_f32 v[50:51], v[50:51], v[134:135]
	v_pk_mul_f32 v[40:41], v[40:41], v[136:137]
	v_pk_mul_f32 v[42:43], v[42:43], v[138:139]
	v_cvt_pk_bf16_f32 v48, v48, v49
	v_cvt_pk_bf16_f32 v49, v50, v51
	v_cvt_pk_bf16_f32 v50, v40, v41
	v_cvt_pk_bf16_f32 v51, v42, v43
	global_store_dwordx4 v148, v[48:51], s[50:51] offset:256
	v_add_u32_e32 v148, s81, v148
	v_pk_mul_f32 v[132:133], v[60:61], s[80:81] op_sel_hi:[1,0]
	v_pk_mul_f32 v[134:135], v[62:63], s[80:81] op_sel_hi:[1,0]
	v_pk_mul_f32 v[136:137], v[52:53], s[80:81] op_sel_hi:[1,0]
	v_pk_mul_f32 v[138:139], v[54:55], s[80:81] op_sel_hi:[1,0]
	v_exp_f32_e32 v132, v132
	v_exp_f32_e32 v133, v133
	v_exp_f32_e32 v134, v134
	v_exp_f32_e32 v135, v135
	v_exp_f32_e32 v136, v136
	v_exp_f32_e32 v137, v137
	v_exp_f32_e32 v138, v138
	v_exp_f32_e32 v139, v139
	v_pk_add_f32 v[132:133], v[132:133], 1.0 op_sel_hi:[1,0]
	v_pk_add_f32 v[134:135], v[134:135], 1.0 op_sel_hi:[1,0]
	v_pk_add_f32 v[136:137], v[136:137], 1.0 op_sel_hi:[1,0]
	v_pk_add_f32 v[138:139], v[138:139], 1.0 op_sel_hi:[1,0]
	v_rcp_f32_e32 v132, v132
	v_rcp_f32_e32 v133, v133
	v_rcp_f32_e32 v134, v134
	v_rcp_f32_e32 v135, v135
	v_rcp_f32_e32 v136, v136
	v_rcp_f32_e32 v137, v137
	v_rcp_f32_e32 v138, v138
	v_rcp_f32_e32 v139, v139
	v_pk_mul_f32 v[60:61], v[60:61], v[132:133]
	v_pk_mul_f32 v[62:63], v[62:63], v[134:135]
	v_pk_mul_f32 v[52:53], v[52:53], v[136:137]
	v_pk_mul_f32 v[54:55], v[54:55], v[138:139]
	v_cvt_pk_bf16_f32 v60, v60, v61
	v_cvt_pk_bf16_f32 v61, v62, v63
	v_cvt_pk_bf16_f32 v62, v52, v53
	v_cvt_pk_bf16_f32 v63, v54, v55
	global_store_dwordx4 v148, v[60:63], s[50:51]
	v_pk_mul_f32 v[132:133], v[44:45], s[80:81] op_sel_hi:[1,0]
	v_pk_mul_f32 v[134:135], v[46:47], s[80:81] op_sel_hi:[1,0]
	v_pk_mul_f32 v[136:137], v[36:37], s[80:81] op_sel_hi:[1,0]
	v_pk_mul_f32 v[138:139], v[38:39], s[80:81] op_sel_hi:[1,0]
	v_exp_f32_e32 v132, v132
	v_exp_f32_e32 v133, v133
	v_exp_f32_e32 v134, v134
	v_exp_f32_e32 v135, v135
	v_exp_f32_e32 v136, v136
	v_exp_f32_e32 v137, v137
	v_exp_f32_e32 v138, v138
	v_exp_f32_e32 v139, v139
	v_pk_add_f32 v[132:133], v[132:133], 1.0 op_sel_hi:[1,0]
	v_pk_add_f32 v[134:135], v[134:135], 1.0 op_sel_hi:[1,0]
	v_pk_add_f32 v[136:137], v[136:137], 1.0 op_sel_hi:[1,0]
	v_pk_add_f32 v[138:139], v[138:139], 1.0 op_sel_hi:[1,0]
	v_rcp_f32_e32 v132, v132
	v_rcp_f32_e32 v133, v133
	v_rcp_f32_e32 v134, v134
	v_rcp_f32_e32 v135, v135
	v_rcp_f32_e32 v136, v136
	v_rcp_f32_e32 v137, v137
	v_rcp_f32_e32 v138, v138
	v_rcp_f32_e32 v139, v139
	v_pk_mul_f32 v[44:45], v[44:45], v[132:133]
	v_pk_mul_f32 v[46:47], v[46:47], v[134:135]
	v_pk_mul_f32 v[36:37], v[36:37], v[136:137]
	v_pk_mul_f32 v[38:39], v[38:39], v[138:139]
	v_cvt_pk_bf16_f32 v44, v44, v45
	v_cvt_pk_bf16_f32 v45, v46, v47
	v_cvt_pk_bf16_f32 v46, v36, v37
	v_cvt_pk_bf16_f32 v47, v38, v39
	global_store_dwordx4 v148, v[44:47], s[50:51] offset:256
	v_add_u32_e32 v148, s81, v148
	v_pk_mul_f32 v[132:133], v[32:33], s[80:81] op_sel_hi:[1,0]
	v_pk_mul_f32 v[134:135], v[34:35], s[80:81] op_sel_hi:[1,0]
	v_pk_mul_f32 v[136:137], v[24:25], s[80:81] op_sel_hi:[1,0]
	v_pk_mul_f32 v[138:139], v[26:27], s[80:81] op_sel_hi:[1,0]
	v_exp_f32_e32 v132, v132
	v_exp_f32_e32 v133, v133
	v_exp_f32_e32 v134, v134
	v_exp_f32_e32 v135, v135
	v_exp_f32_e32 v136, v136
	v_exp_f32_e32 v137, v137
	v_exp_f32_e32 v138, v138
	v_exp_f32_e32 v139, v139
	v_pk_add_f32 v[132:133], v[132:133], 1.0 op_sel_hi:[1,0]
	v_pk_add_f32 v[134:135], v[134:135], 1.0 op_sel_hi:[1,0]
	v_pk_add_f32 v[136:137], v[136:137], 1.0 op_sel_hi:[1,0]
	v_pk_add_f32 v[138:139], v[138:139], 1.0 op_sel_hi:[1,0]
	v_rcp_f32_e32 v132, v132
	v_rcp_f32_e32 v133, v133
	v_rcp_f32_e32 v134, v134
	v_rcp_f32_e32 v135, v135
	v_rcp_f32_e32 v136, v136
	v_rcp_f32_e32 v137, v137
	v_rcp_f32_e32 v138, v138
	v_rcp_f32_e32 v139, v139
	v_pk_mul_f32 v[32:33], v[32:33], v[132:133]
	v_pk_mul_f32 v[34:35], v[34:35], v[134:135]
	v_pk_mul_f32 v[24:25], v[24:25], v[136:137]
	v_pk_mul_f32 v[26:27], v[26:27], v[138:139]
	v_cvt_pk_bf16_f32 v32, v32, v33
	v_cvt_pk_bf16_f32 v33, v34, v35
	v_cvt_pk_bf16_f32 v34, v24, v25
	v_cvt_pk_bf16_f32 v35, v26, v27
	global_store_dwordx4 v148, v[32:35], s[50:51]
	v_pk_mul_f32 v[132:133], v[16:17], s[80:81] op_sel_hi:[1,0]
	v_pk_mul_f32 v[134:135], v[18:19], s[80:81] op_sel_hi:[1,0]
	v_pk_mul_f32 v[136:137], v[8:9], s[80:81] op_sel_hi:[1,0]
	v_pk_mul_f32 v[138:139], v[10:11], s[80:81] op_sel_hi:[1,0]
	v_exp_f32_e32 v132, v132
	v_exp_f32_e32 v133, v133
	v_exp_f32_e32 v134, v134
	v_exp_f32_e32 v135, v135
	v_exp_f32_e32 v136, v136
	v_exp_f32_e32 v137, v137
	v_exp_f32_e32 v138, v138
	v_exp_f32_e32 v139, v139
	v_pk_add_f32 v[132:133], v[132:133], 1.0 op_sel_hi:[1,0]
	v_pk_add_f32 v[134:135], v[134:135], 1.0 op_sel_hi:[1,0]
	v_pk_add_f32 v[136:137], v[136:137], 1.0 op_sel_hi:[1,0]
	v_pk_add_f32 v[138:139], v[138:139], 1.0 op_sel_hi:[1,0]
	v_rcp_f32_e32 v132, v132
	v_rcp_f32_e32 v133, v133
	v_rcp_f32_e32 v134, v134
	v_rcp_f32_e32 v135, v135
	v_rcp_f32_e32 v136, v136
	v_rcp_f32_e32 v137, v137
	v_rcp_f32_e32 v138, v138
	v_rcp_f32_e32 v139, v139
	v_pk_mul_f32 v[16:17], v[16:17], v[132:133]
	v_pk_mul_f32 v[18:19], v[18:19], v[134:135]
	v_pk_mul_f32 v[8:9], v[8:9], v[136:137]
	v_pk_mul_f32 v[10:11], v[10:11], v[138:139]
	v_cvt_pk_bf16_f32 v16, v16, v17
	v_cvt_pk_bf16_f32 v17, v18, v19
	v_cvt_pk_bf16_f32 v18, v8, v9
	v_cvt_pk_bf16_f32 v19, v10, v11
	global_store_dwordx4 v148, v[16:19], s[50:51] offset:256
	v_add_u32_e32 v148, s81, v148
	v_pk_mul_f32 v[132:133], v[28:29], s[80:81] op_sel_hi:[1,0]
	v_pk_mul_f32 v[134:135], v[30:31], s[80:81] op_sel_hi:[1,0]
	v_pk_mul_f32 v[136:137], v[20:21], s[80:81] op_sel_hi:[1,0]
	v_pk_mul_f32 v[138:139], v[22:23], s[80:81] op_sel_hi:[1,0]
	v_exp_f32_e32 v132, v132
	v_exp_f32_e32 v133, v133
	v_exp_f32_e32 v134, v134
	v_exp_f32_e32 v135, v135
	v_exp_f32_e32 v136, v136
	v_exp_f32_e32 v137, v137
	v_exp_f32_e32 v138, v138
	v_exp_f32_e32 v139, v139
	v_pk_add_f32 v[132:133], v[132:133], 1.0 op_sel_hi:[1,0]
	v_pk_add_f32 v[134:135], v[134:135], 1.0 op_sel_hi:[1,0]
	v_pk_add_f32 v[136:137], v[136:137], 1.0 op_sel_hi:[1,0]
	v_pk_add_f32 v[138:139], v[138:139], 1.0 op_sel_hi:[1,0]
	v_rcp_f32_e32 v132, v132
	v_rcp_f32_e32 v133, v133
	v_rcp_f32_e32 v134, v134
	v_rcp_f32_e32 v135, v135
	v_rcp_f32_e32 v136, v136
	v_rcp_f32_e32 v137, v137
	v_rcp_f32_e32 v138, v138
	v_rcp_f32_e32 v139, v139
	v_pk_mul_f32 v[28:29], v[28:29], v[132:133]
	v_pk_mul_f32 v[30:31], v[30:31], v[134:135]
	v_pk_mul_f32 v[20:21], v[20:21], v[136:137]
	v_pk_mul_f32 v[22:23], v[22:23], v[138:139]
	v_cvt_pk_bf16_f32 v28, v28, v29
	v_cvt_pk_bf16_f32 v29, v30, v31
	v_cvt_pk_bf16_f32 v30, v20, v21
	v_cvt_pk_bf16_f32 v31, v22, v23
	global_store_dwordx4 v148, v[28:31], s[50:51]
	v_pk_mul_f32 v[132:133], v[12:13], s[80:81] op_sel_hi:[1,0]
	v_pk_mul_f32 v[134:135], v[14:15], s[80:81] op_sel_hi:[1,0]
	v_pk_mul_f32 v[136:137], v[4:5], s[80:81] op_sel_hi:[1,0]
	v_pk_mul_f32 v[138:139], v[6:7], s[80:81] op_sel_hi:[1,0]
	v_exp_f32_e32 v132, v132
	v_exp_f32_e32 v133, v133
	v_exp_f32_e32 v134, v134
	v_exp_f32_e32 v135, v135
	v_exp_f32_e32 v136, v136
	v_exp_f32_e32 v137, v137
	v_exp_f32_e32 v138, v138
	v_exp_f32_e32 v139, v139
	v_pk_add_f32 v[132:133], v[132:133], 1.0 op_sel_hi:[1,0]
	v_pk_add_f32 v[134:135], v[134:135], 1.0 op_sel_hi:[1,0]
	v_pk_add_f32 v[136:137], v[136:137], 1.0 op_sel_hi:[1,0]
	v_pk_add_f32 v[138:139], v[138:139], 1.0 op_sel_hi:[1,0]
	v_rcp_f32_e32 v132, v132
	v_rcp_f32_e32 v133, v133
	v_rcp_f32_e32 v134, v134
	v_rcp_f32_e32 v135, v135
	v_rcp_f32_e32 v136, v136
	v_rcp_f32_e32 v137, v137
	v_rcp_f32_e32 v138, v138
	v_rcp_f32_e32 v139, v139
	v_pk_mul_f32 v[12:13], v[12:13], v[132:133]
	v_pk_mul_f32 v[14:15], v[14:15], v[134:135]
	v_pk_mul_f32 v[4:5], v[4:5], v[136:137]
	v_pk_mul_f32 v[6:7], v[6:7], v[138:139]
	v_cvt_pk_bf16_f32 v12, v12, v13
	v_cvt_pk_bf16_f32 v13, v14, v15
	v_cvt_pk_bf16_f32 v14, v4, v5
	v_cvt_pk_bf16_f32 v15, v6, v7
	global_store_dwordx4 v148, v[12:15], s[50:51] offset:256
	s_branch .LBB0_326
.Lepi_gelu_e:
	s_lshl_b32 s30, s48, 8
	s_cmp_eq_u32 s57, 2
	s_cselect_b32 s47, 0x80, 0
	s_add_i32 s30, s30, s60
	s_add_i32 s30, s30, s47
	s_cmp_lg_u32 s57, 0
	s_cselect_b32 s49, 1, 0
	v_readlane_b32 s50, v240, 9
	v_readlane_b32 s51, v240, 10
	s_movk_i32 s82, 0x1400
	s_lshl_b32 s83, s71, 9
	s_movk_i32 s81, 0xc00
	s_cmp_eq_u32 s73, 7
	s_cselect_b32 s81, 0x1000, s81
	s_add_i32 s83, s83, s81
	v_add_u32_e32 v133, s30, v232
	v_lshl_add_u32 v134, v234, 1, s83
	v_mad_u32_u24 v148, v133, s82, v134
	s_lshl_b32 s81, s82, 4
	s_lshl_b32 s30, s71, 2
	s_add_i32 s30, s30, s16
	s_lshl_b32 s30, s30, 3
	v_lshl_add_u32 v149, v133, 6, s30
	v_xor_b32_e32 v150, 16, v230
	v_xor_b32_e32 v151, 32, v230
	v_lshlrev_b32_e32 v150, 2, v150
	v_lshlrev_b32_e32 v151, 2, v151
	s_mov_b32 s80, 0xbf38aa3b
	s_mov_b32 s82, 0xbe11a98e
	s_mov_b32 s84, 0x3e6d3388
	s_mov_b32 s86, 0x3f07dc22
	s_mov_b32 s88, 0x3f35f0e3
	s_mov_b32 s48, 0x3e027906
	v_mov_b32_e32 v0, 0xbf3a00e3
	s_cmp_eq_u32 s73, 7
	s_cbranch_scc0 .Lepi_gelu6_e
	v_and_b32_e32 v132, 0x7fffffff, v128
	v_and_b32_e32 v133, 0x7fffffff, v129
	v_and_b32_e32 v134, 0x7fffffff, v130
	v_and_b32_e32 v135, 0x7fffffff, v131
	v_pk_mul_f32 v[144:145], v[128:129], v[128:129]
	v_pk_mul_f32 v[146:147], v[130:131], v[130:131]
	v_pk_fma_f32 v[136:137], v[132:133], s[84:85], 1.0 op_sel_hi:[1,0,0]
	v_pk_fma_f32 v[138:139], v[134:135], s[84:85], 1.0 op_sel_hi:[1,0,0]
	v_pk_mul_f32 v[144:145], v[144:145], s[80:81] op_sel_hi:[1,0]
	v_pk_mul_f32 v[146:147], v[146:147], s[80:81] op_sel_hi:[1,0]
	v_rcp_f32_e32 v136, v136
	v_rcp_f32_e32 v137, v137
	v_rcp_f32_e32 v138, v138
	v_rcp_f32_e32 v139, v139
	v_exp_f32_e32 v144, v144
	v_exp_f32_e32 v145, v145
	v_exp_f32_e32 v146, v146
	v_exp_f32_e32 v147, v147
	v_pk_fma_f32 v[140:141], v[136:137], s[86:87], v[0:1] op_sel_hi:[1,0,0]
	v_pk_fma_f32 v[142:143], v[138:139], s[86:87], v[0:1] op_sel_hi:[1,0,0]
	v_pk_fma_f32 v[140:141], v[136:137], v[140:141], s[88:89] op_sel_hi:[1,1,0]
	v_pk_fma_f32 v[142:143], v[138:139], v[142:143], s[88:89] op_sel_hi:[1,1,0]
	v_pk_fma_f32 v[140:141], v[136:137], v[140:141], s[82:83] op_sel_hi:[1,1,0]
	v_pk_fma_f32 v[142:143], v[138:139], v[142:143], s[82:83] op_sel_hi:[1,1,0]
	v_pk_fma_f32 v[140:141], v[136:137], v[140:141], s[48:49] op_sel_hi:[1,1,0]
	v_pk_fma_f32 v[142:143], v[138:139], v[142:143], s[48:49] op_sel_hi:[1,1,0]
	v_pk_mul_f32 v[140:141], v[136:137], v[140:141]
	v_pk_mul_f32 v[142:143], v[138:139], v[142:143]
	v_pk_mul_f32 v[140:141], v[140:141], v[144:145]
	v_pk_mul_f32 v[142:143], v[142:143], v[146:147]
	v_max_f32_e32 v128, 0, v128
	v_max_f32_e32 v129, 0, v129
	v_max_f32_e32 v130, 0, v130
	v_max_f32_e32 v131, 0, v131
	v_pk_fma_f32 v[128:129], v[132:133], v[140:141], v[128:129] neg_lo:[1,0,0] neg_hi:[1,0,0]
	v_pk_fma_f32 v[130:131], v[134:135], v[142:143], v[130:131] neg_lo:[1,0,0] neg_hi:[1,0,0]
	v_pk_add_f32 v[2:3], v[128:129], v[130:131]
	v_pk_mul_f32 v[152:153], v[128:129], v[128:129]
	v_pk_fma_f32 v[152:153], v[130:131], v[130:131], v[152:153]
	v_and_b32_e32 v132, 0x7fffffff, v120
	v_and_b32_e32 v133, 0x7fffffff, v121
	v_and_b32_e32 v134, 0x7fffffff, v122
	v_and_b32_e32 v135, 0x7fffffff, v123
	v_pk_mul_f32 v[144:145], v[120:121], v[120:121]
	v_pk_mul_f32 v[146:147], v[122:123], v[122:123]
	v_pk_fma_f32 v[136:137], v[132:133], s[84:85], 1.0 op_sel_hi:[1,0,0]
	v_pk_fma_f32 v[138:139], v[134:135], s[84:85], 1.0 op_sel_hi:[1,0,0]
	v_pk_mul_f32 v[144:145], v[144:145], s[80:81] op_sel_hi:[1,0]
	v_pk_mul_f32 v[146:147], v[146:147], s[80:81] op_sel_hi:[1,0]
	v_rcp_f32_e32 v136, v136
	v_rcp_f32_e32 v137, v137
	v_rcp_f32_e32 v138, v138
	v_rcp_f32_e32 v139, v139
	v_exp_f32_e32 v144, v144
	v_exp_f32_e32 v145, v145
	v_exp_f32_e32 v146, v146
	v_exp_f32_e32 v147, v147
	v_pk_fma_f32 v[140:141], v[136:137], s[86:87], v[0:1] op_sel_hi:[1,0,0]
	v_pk_fma_f32 v[142:143], v[138:139], s[86:87], v[0:1] op_sel_hi:[1,0,0]
	v_pk_fma_f32 v[140:141], v[136:137], v[140:141], s[88:89] op_sel_hi:[1,1,0]
	v_pk_fma_f32 v[142:143], v[138:139], v[142:143], s[88:89] op_sel_hi:[1,1,0]
	v_pk_fma_f32 v[140:141], v[136:137], v[140:141], s[82:83] op_sel_hi:[1,1,0]
	v_pk_fma_f32 v[142:143], v[138:139], v[142:143], s[82:83] op_sel_hi:[1,1,0]
	v_pk_fma_f32 v[140:141], v[136:137], v[140:141], s[48:49] op_sel_hi:[1,1,0]
	v_pk_fma_f32 v[142:143], v[138:139], v[142:143], s[48:49] op_sel_hi:[1,1,0]
	v_pk_mul_f32 v[140:141], v[136:137], v[140:141]
	v_pk_mul_f32 v[142:143], v[138:139], v[142:143]
	v_pk_mul_f32 v[140:141], v[140:141], v[144:145]
	v_pk_mul_f32 v[142:143], v[142:143], v[146:147]
	v_max_f32_e32 v120, 0, v120
	v_max_f32_e32 v121, 0, v121
	v_max_f32_e32 v122, 0, v122
	v_max_f32_e32 v123, 0, v123
	v_pk_fma_f32 v[120:121], v[132:133], v[140:141], v[120:121] neg_lo:[1,0,0] neg_hi:[1,0,0]
	v_pk_fma_f32 v[122:123], v[134:135], v[142:143], v[122:123] neg_lo:[1,0,0] neg_hi:[1,0,0]
	v_pk_add_f32 v[2:3], v[2:3], v[120:121]
	v_pk_fma_f32 v[152:153], v[120:121], v[120:121], v[152:153]
	v_pk_add_f32 v[2:3], v[2:3], v[122:123]
	v_pk_fma_f32 v[152:153], v[122:123], v[122:123], v[152:153]
	v_cvt_pk_bf16_f32 v128, v128, v129
	v_cvt_pk_bf16_f32 v129, v130, v131
	v_cvt_pk_bf16_f32 v130, v120, v121
	v_cvt_pk_bf16_f32 v131, v122, v123
	global_store_dwordx4 v148, v[128:131], s[50:51]
	v_and_b32_e32 v132, 0x7fffffff, v112
	v_and_b32_e32 v133, 0x7fffffff, v113
	v_and_b32_e32 v134, 0x7fffffff, v114
	v_and_b32_e32 v135, 0x7fffffff, v115
	v_pk_mul_f32 v[144:145], v[112:113], v[112:113]
	v_pk_mul_f32 v[146:147], v[114:115], v[114:115]
	v_pk_fma_f32 v[136:137], v[132:133], s[84:85], 1.0 op_sel_hi:[1,0,0]
	v_pk_fma_f32 v[138:139], v[134:135], s[84:85], 1.0 op_sel_hi:[1,0,0]
	v_pk_mul_f32 v[144:145], v[144:145], s[80:81] op_sel_hi:[1,0]
	v_pk_mul_f32 v[146:147], v[146:147], s[80:81] op_sel_hi:[1,0]
	v_rcp_f32_e32 v136, v136
	v_rcp_f32_e32 v137, v137
	v_rcp_f32_e32 v138, v138
	v_rcp_f32_e32 v139, v139
	v_exp_f32_e32 v144, v144
	v_exp_f32_e32 v145, v145
	v_exp_f32_e32 v146, v146
	v_exp_f32_e32 v147, v147
	v_pk_fma_f32 v[140:141], v[136:137], s[86:87], v[0:1] op_sel_hi:[1,0,0]
	v_pk_fma_f32 v[142:143], v[138:139], s[86:87], v[0:1] op_sel_hi:[1,0,0]
	v_pk_fma_f32 v[140:141], v[136:137], v[140:141], s[88:89] op_sel_hi:[1,1,0]
	v_pk_fma_f32 v[142:143], v[138:139], v[142:143], s[88:89] op_sel_hi:[1,1,0]
	v_pk_fma_f32 v[140:141], v[136:137], v[140:141], s[82:83] op_sel_hi:[1,1,0]
	v_pk_fma_f32 v[142:143], v[138:139], v[142:143], s[82:83] op_sel_hi:[1,1,0]
	v_pk_fma_f32 v[140:141], v[136:137], v[140:141], s[48:49] op_sel_hi:[1,1,0]
	v_pk_fma_f32 v[142:143], v[138:139], v[142:143], s[48:49] op_sel_hi:[1,1,0]
	v_pk_mul_f32 v[140:141], v[136:137], v[140:141]
	v_pk_mul_f32 v[142:143], v[138:139], v[142:143]
	v_pk_mul_f32 v[140:141], v[140:141], v[144:145]
	v_pk_mul_f32 v[142:143], v[142:143], v[146:147]
	v_max_f32_e32 v112, 0, v112
	v_max_f32_e32 v113, 0, v113
	v_max_f32_e32 v114, 0, v114
	v_max_f32_e32 v115, 0, v115
	v_pk_fma_f32 v[112:113], v[132:133], v[140:141], v[112:113] neg_lo:[1,0,0] neg_hi:[1,0,0]
	v_pk_fma_f32 v[114:115], v[134:135], v[142:143], v[114:115] neg_lo:[1,0,0] neg_hi:[1,0,0]
	v_pk_add_f32 v[2:3], v[2:3], v[112:113]
	v_pk_fma_f32 v[152:153], v[112:113], v[112:113], v[152:153]
	v_pk_add_f32 v[2:3], v[2:3], v[114:115]
	v_pk_fma_f32 v[152:153], v[114:115], v[114:115], v[152:153]
	v_and_b32_e32 v132, 0x7fffffff, v104
	v_and_b32_e32 v133, 0x7fffffff, v105
	v_and_b32_e32 v134, 0x7fffffff, v106
	v_and_b32_e32 v135, 0x7fffffff, v107
	v_pk_mul_f32 v[144:145], v[104:105], v[104:105]
	v_pk_mul_f32 v[146:147], v[106:107], v[106:107]
	v_pk_fma_f32 v[136:137], v[132:133], s[84:85], 1.0 op_sel_hi:[1,0,0]
	v_pk_fma_f32 v[138:139], v[134:135], s[84:85], 1.0 op_sel_hi:[1,0,0]
	v_pk_mul_f32 v[144:145], v[144:145], s[80:81] op_sel_hi:[1,0]
	v_pk_mul_f32 v[146:147], v[146:147], s[80:81] op_sel_hi:[1,0]
	v_rcp_f32_e32 v136, v136
	v_rcp_f32_e32 v137, v137
	v_rcp_f32_e32 v138, v138
	v_rcp_f32_e32 v139, v139
	v_exp_f32_e32 v144, v144
	v_exp_f32_e32 v145, v145
	v_exp_f32_e32 v146, v146
	v_exp_f32_e32 v147, v147
	v_pk_fma_f32 v[140:141], v[136:137], s[86:87], v[0:1] op_sel_hi:[1,0,0]
	v_pk_fma_f32 v[142:143], v[138:139], s[86:87], v[0:1] op_sel_hi:[1,0,0]
	v_pk_fma_f32 v[140:141], v[136:137], v[140:141], s[88:89] op_sel_hi:[1,1,0]
	v_pk_fma_f32 v[142:143], v[138:139], v[142:143], s[88:89] op_sel_hi:[1,1,0]
	v_pk_fma_f32 v[140:141], v[136:137], v[140:141], s[82:83] op_sel_hi:[1,1,0]
	v_pk_fma_f32 v[142:143], v[138:139], v[142:143], s[82:83] op_sel_hi:[1,1,0]
	v_pk_fma_f32 v[140:141], v[136:137], v[140:141], s[48:49] op_sel_hi:[1,1,0]
	v_pk_fma_f32 v[142:143], v[138:139], v[142:143], s[48:49] op_sel_hi:[1,1,0]
	v_pk_mul_f32 v[140:141], v[136:137], v[140:141]
	v_pk_mul_f32 v[142:143], v[138:139], v[142:143]
	v_pk_mul_f32 v[140:141], v[140:141], v[144:145]
	v_pk_mul_f32 v[142:143], v[142:143], v[146:147]
	v_max_f32_e32 v104, 0, v104
	v_max_f32_e32 v105, 0, v105
	v_max_f32_e32 v106, 0, v106
	v_max_f32_e32 v107, 0, v107
	v_pk_fma_f32 v[104:105], v[132:133], v[140:141], v[104:105] neg_lo:[1,0,0] neg_hi:[1,0,0]
	v_pk_fma_f32 v[106:107], v[134:135], v[142:143], v[106:107] neg_lo:[1,0,0] neg_hi:[1,0,0]
	v_pk_add_f32 v[2:3], v[2:3], v[104:105]
	v_pk_fma_f32 v[152:153], v[104:105], v[104:105], v[152:153]
	v_pk_add_f32 v[2:3], v[2:3], v[106:107]
	v_pk_fma_f32 v[152:153], v[106:107], v[106:107], v[152:153]
	v_cvt_pk_bf16_f32 v112, v112, v113
	v_cvt_pk_bf16_f32 v113, v114, v115
	v_cvt_pk_bf16_f32 v114, v104, v105
	v_cvt_pk_bf16_f32 v115, v106, v107
	global_store_dwordx4 v148, v[112:115], s[50:51] offset:256
	v_add_f32_e32 v2, v2, v3
	v_add_f32_e32 v3, v152, v153
	ds_bpermute_b32 v132, v150, v2
	ds_bpermute_b32 v133, v150, v3
	s_waitcnt lgkmcnt(0)
	v_pk_add_f32 v[2:3], v[2:3], v[132:133]
	ds_bpermute_b32 v132, v151, v2
	ds_bpermute_b32 v133, v151, v3
	s_waitcnt lgkmcnt(0)
	v_pk_add_f32 v[2:3], v[2:3], v[132:133]
	s_and_saveexec_b64 s[46:47], s[38:39]
	global_store_dwordx2 v149, v[2:3], s[66:67]
	s_mov_b64 exec, s[46:47]
	v_add_u32_e32 v148, s81, v148
	v_add_u32_e32 v149, 0x400, v149
	v_and_b32_e32 v132, 0x7fffffff, v124
	v_and_b32_e32 v133, 0x7fffffff, v125
	v_and_b32_e32 v134, 0x7fffffff, v126
	v_and_b32_e32 v135, 0x7fffffff, v127
	v_pk_mul_f32 v[144:145], v[124:125], v[124:125]
	v_pk_mul_f32 v[146:147], v[126:127], v[126:127]
	v_pk_fma_f32 v[136:137], v[132:133], s[84:85], 1.0 op_sel_hi:[1,0,0]
	v_pk_fma_f32 v[138:139], v[134:135], s[84:85], 1.0 op_sel_hi:[1,0,0]
	v_pk_mul_f32 v[144:145], v[144:145], s[80:81] op_sel_hi:[1,0]
	v_pk_mul_f32 v[146:147], v[146:147], s[80:81] op_sel_hi:[1,0]
	v_rcp_f32_e32 v136, v136
	v_rcp_f32_e32 v137, v137
	v_rcp_f32_e32 v138, v138
	v_rcp_f32_e32 v139, v139
	v_exp_f32_e32 v144, v144
	v_exp_f32_e32 v145, v145
	v_exp_f32_e32 v146, v146
	v_exp_f32_e32 v147, v147
	v_pk_fma_f32 v[140:141], v[136:137], s[86:87], v[0:1] op_sel_hi:[1,0,0]
	v_pk_fma_f32 v[142:143], v[138:139], s[86:87], v[0:1] op_sel_hi:[1,0,0]
	v_pk_fma_f32 v[140:141], v[136:137], v[140:141], s[88:89] op_sel_hi:[1,1,0]
	v_pk_fma_f32 v[142:143], v[138:139], v[142:143], s[88:89] op_sel_hi:[1,1,0]
	v_pk_fma_f32 v[140:141], v[136:137], v[140:141], s[82:83] op_sel_hi:[1,1,0]
	v_pk_fma_f32 v[142:143], v[138:139], v[142:143], s[82:83] op_sel_hi:[1,1,0]
	v_pk_fma_f32 v[140:141], v[136:137], v[140:141], s[48:49] op_sel_hi:[1,1,0]
	v_pk_fma_f32 v[142:143], v[138:139], v[142:143], s[48:49] op_sel_hi:[1,1,0]
	v_pk_mul_f32 v[140:141], v[136:137], v[140:141]
	v_pk_mul_f32 v[142:143], v[138:139], v[142:143]
	v_pk_mul_f32 v[140:141], v[140:141], v[144:145]
	v_pk_mul_f32 v[142:143], v[142:143], v[146:147]
	v_max_f32_e32 v124, 0, v124
	v_max_f32_e32 v125, 0, v125
	v_max_f32_e32 v126, 0, v126
	v_max_f32_e32 v127, 0, v127
	v_pk_fma_f32 v[124:125], v[132:133], v[140:141], v[124:125] neg_lo:[1,0,0] neg_hi:[1,0,0]
	v_pk_fma_f32 v[126:127], v[134:135], v[142:143], v[126:127] neg_lo:[1,0,0] neg_hi:[1,0,0]
	v_pk_add_f32 v[2:3], v[124:125], v[126:127]
	v_pk_mul_f32 v[152:153], v[124:125], v[124:125]
	v_pk_fma_f32 v[152:153], v[126:127], v[126:127], v[152:153]
	v_and_b32_e32 v132, 0x7fffffff, v116
	v_and_b32_e32 v133, 0x7fffffff, v117
	v_and_b32_e32 v134, 0x7fffffff, v118
	v_and_b32_e32 v135, 0x7fffffff, v119
	v_pk_mul_f32 v[144:145], v[116:117], v[116:117]
	v_pk_mul_f32 v[146:147], v[118:119], v[118:119]
	v_pk_fma_f32 v[136:137], v[132:133], s[84:85], 1.0 op_sel_hi:[1,0,0]
	v_pk_fma_f32 v[138:139], v[134:135], s[84:85], 1.0 op_sel_hi:[1,0,0]
	v_pk_mul_f32 v[144:145], v[144:145], s[80:81] op_sel_hi:[1,0]
	v_pk_mul_f32 v[146:147], v[146:147], s[80:81] op_sel_hi:[1,0]
	v_rcp_f32_e32 v136, v136
	v_rcp_f32_e32 v137, v137
	v_rcp_f32_e32 v138, v138
	v_rcp_f32_e32 v139, v139
	v_exp_f32_e32 v144, v144
	v_exp_f32_e32 v145, v145
	v_exp_f32_e32 v146, v146
	v_exp_f32_e32 v147, v147
	v_pk_fma_f32 v[140:141], v[136:137], s[86:87], v[0:1] op_sel_hi:[1,0,0]
	v_pk_fma_f32 v[142:143], v[138:139], s[86:87], v[0:1] op_sel_hi:[1,0,0]
	v_pk_fma_f32 v[140:141], v[136:137], v[140:141], s[88:89] op_sel_hi:[1,1,0]
	v_pk_fma_f32 v[142:143], v[138:139], v[142:143], s[88:89] op_sel_hi:[1,1,0]
	v_pk_fma_f32 v[140:141], v[136:137], v[140:141], s[82:83] op_sel_hi:[1,1,0]
	v_pk_fma_f32 v[142:143], v[138:139], v[142:143], s[82:83] op_sel_hi:[1,1,0]
	v_pk_fma_f32 v[140:141], v[136:137], v[140:141], s[48:49] op_sel_hi:[1,1,0]
	v_pk_fma_f32 v[142:143], v[138:139], v[142:143], s[48:49] op_sel_hi:[1,1,0]
	v_pk_mul_f32 v[140:141], v[136:137], v[140:141]
	v_pk_mul_f32 v[142:143], v[138:139], v[142:143]
	v_pk_mul_f32 v[140:141], v[140:141], v[144:145]
	v_pk_mul_f32 v[142:143], v[142:143], v[146:147]
	v_max_f32_e32 v116, 0, v116
	v_max_f32_e32 v117, 0, v117
	v_max_f32_e32 v118, 0, v118
	v_max_f32_e32 v119, 0, v119
	v_pk_fma_f32 v[116:117], v[132:133], v[140:141], v[116:117] neg_lo:[1,0,0] neg_hi:[1,0,0]
	v_pk_fma_f32 v[118:119], v[134:135], v[142:143], v[118:119] neg_lo:[1,0,0] neg_hi:[1,0,0]
	v_pk_add_f32 v[2:3], v[2:3], v[116:117]
	v_pk_fma_f32 v[152:153], v[116:117], v[116:117], v[152:153]
	v_pk_add_f32 v[2:3], v[2:3], v[118:119]
	v_pk_fma_f32 v[152:153], v[118:119], v[118:119], v[152:153]
	v_cvt_pk_bf16_f32 v124, v124, v125
	v_cvt_pk_bf16_f32 v125, v126, v127
	v_cvt_pk_bf16_f32 v126, v116, v117
	v_cvt_pk_bf16_f32 v127, v118, v119
	global_store_dwordx4 v148, v[124:127], s[50:51]
	v_and_b32_e32 v132, 0x7fffffff, v108
	v_and_b32_e32 v133, 0x7fffffff, v109
	v_and_b32_e32 v134, 0x7fffffff, v110
	v_and_b32_e32 v135, 0x7fffffff, v111
	v_pk_mul_f32 v[144:145], v[108:109], v[108:109]
	v_pk_mul_f32 v[146:147], v[110:111], v[110:111]
	v_pk_fma_f32 v[136:137], v[132:133], s[84:85], 1.0 op_sel_hi:[1,0,0]
	v_pk_fma_f32 v[138:139], v[134:135], s[84:85], 1.0 op_sel_hi:[1,0,0]
	v_pk_mul_f32 v[144:145], v[144:145], s[80:81] op_sel_hi:[1,0]
	v_pk_mul_f32 v[146:147], v[146:147], s[80:81] op_sel_hi:[1,0]
	v_rcp_f32_e32 v136, v136
	v_rcp_f32_e32 v137, v137
	v_rcp_f32_e32 v138, v138
	v_rcp_f32_e32 v139, v139
	v_exp_f32_e32 v144, v144
	v_exp_f32_e32 v145, v145
	v_exp_f32_e32 v146, v146
	v_exp_f32_e32 v147, v147
	v_pk_fma_f32 v[140:141], v[136:137], s[86:87], v[0:1] op_sel_hi:[1,0,0]
	v_pk_fma_f32 v[142:143], v[138:139], s[86:87], v[0:1] op_sel_hi:[1,0,0]
	v_pk_fma_f32 v[140:141], v[136:137], v[140:141], s[88:89] op_sel_hi:[1,1,0]
	v_pk_fma_f32 v[142:143], v[138:139], v[142:143], s[88:89] op_sel_hi:[1,1,0]
	v_pk_fma_f32 v[140:141], v[136:137], v[140:141], s[82:83] op_sel_hi:[1,1,0]
	v_pk_fma_f32 v[142:143], v[138:139], v[142:143], s[82:83] op_sel_hi:[1,1,0]
	v_pk_fma_f32 v[140:141], v[136:137], v[140:141], s[48:49] op_sel_hi:[1,1,0]
	v_pk_fma_f32 v[142:143], v[138:139], v[142:143], s[48:49] op_sel_hi:[1,1,0]
	v_pk_mul_f32 v[140:141], v[136:137], v[140:141]
	v_pk_mul_f32 v[142:143], v[138:139], v[142:143]
	v_pk_mul_f32 v[140:141], v[140:141], v[144:145]
	v_pk_mul_f32 v[142:143], v[142:143], v[146:147]
	v_max_f32_e32 v108, 0, v108
	v_max_f32_e32 v109, 0, v109
	v_max_f32_e32 v110, 0, v110
	v_max_f32_e32 v111, 0, v111
	v_pk_fma_f32 v[108:109], v[132:133], v[140:141], v[108:109] neg_lo:[1,0,0] neg_hi:[1,0,0]
	v_pk_fma_f32 v[110:111], v[134:135], v[142:143], v[110:111] neg_lo:[1,0,0] neg_hi:[1,0,0]
	v_pk_add_f32 v[2:3], v[2:3], v[108:109]
	v_pk_fma_f32 v[152:153], v[108:109], v[108:109], v[152:153]
	v_pk_add_f32 v[2:3], v[2:3], v[110:111]
	v_pk_fma_f32 v[152:153], v[110:111], v[110:111], v[152:153]
	v_and_b32_e32 v132, 0x7fffffff, v100
	v_and_b32_e32 v133, 0x7fffffff, v101
	v_and_b32_e32 v134, 0x7fffffff, v102
	v_and_b32_e32 v135, 0x7fffffff, v103
	v_pk_mul_f32 v[144:145], v[100:101], v[100:101]
	v_pk_mul_f32 v[146:147], v[102:103], v[102:103]
	v_pk_fma_f32 v[136:137], v[132:133], s[84:85], 1.0 op_sel_hi:[1,0,0]
	v_pk_fma_f32 v[138:139], v[134:135], s[84:85], 1.0 op_sel_hi:[1,0,0]
	v_pk_mul_f32 v[144:145], v[144:145], s[80:81] op_sel_hi:[1,0]
	v_pk_mul_f32 v[146:147], v[146:147], s[80:81] op_sel_hi:[1,0]
	v_rcp_f32_e32 v136, v136
	v_rcp_f32_e32 v137, v137
	v_rcp_f32_e32 v138, v138
	v_rcp_f32_e32 v139, v139
	v_exp_f32_e32 v144, v144
	v_exp_f32_e32 v145, v145
	v_exp_f32_e32 v146, v146
	v_exp_f32_e32 v147, v147
	v_pk_fma_f32 v[140:141], v[136:137], s[86:87], v[0:1] op_sel_hi:[1,0,0]
	v_pk_fma_f32 v[142:143], v[138:139], s[86:87], v[0:1] op_sel_hi:[1,0,0]
	v_pk_fma_f32 v[140:141], v[136:137], v[140:141], s[88:89] op_sel_hi:[1,1,0]
	v_pk_fma_f32 v[142:143], v[138:139], v[142:143], s[88:89] op_sel_hi:[1,1,0]
	v_pk_fma_f32 v[140:141], v[136:137], v[140:141], s[82:83] op_sel_hi:[1,1,0]
	v_pk_fma_f32 v[142:143], v[138:139], v[142:143], s[82:83] op_sel_hi:[1,1,0]
	v_pk_fma_f32 v[140:141], v[136:137], v[140:141], s[48:49] op_sel_hi:[1,1,0]
	v_pk_fma_f32 v[142:143], v[138:139], v[142:143], s[48:49] op_sel_hi:[1,1,0]
	v_pk_mul_f32 v[140:141], v[136:137], v[140:141]
	v_pk_mul_f32 v[142:143], v[138:139], v[142:143]
	v_pk_mul_f32 v[140:141], v[140:141], v[144:145]
	v_pk_mul_f32 v[142:143], v[142:143], v[146:147]
	v_max_f32_e32 v100, 0, v100
	v_max_f32_e32 v101, 0, v101
	v_max_f32_e32 v102, 0, v102
	v_max_f32_e32 v103, 0, v103
	v_pk_fma_f32 v[100:101], v[132:133], v[140:141], v[100:101] neg_lo:[1,0,0] neg_hi:[1,0,0]
	v_pk_fma_f32 v[102:103], v[134:135], v[142:143], v[102:103] neg_lo:[1,0,0] neg_hi:[1,0,0]
	v_pk_add_f32 v[2:3], v[2:3], v[100:101]
	v_pk_fma_f32 v[152:153], v[100:101], v[100:101], v[152:153]
	v_pk_add_f32 v[2:3], v[2:3], v[102:103]
	v_pk_fma_f32 v[152:153], v[102:103], v[102:103], v[152:153]
	v_cvt_pk_bf16_f32 v108, v108, v109
	v_cvt_pk_bf16_f32 v109, v110, v111
	v_cvt_pk_bf16_f32 v110, v100, v101
	v_cvt_pk_bf16_f32 v111, v102, v103
	global_store_dwordx4 v148, v[108:111], s[50:51] offset:256
	v_add_f32_e32 v2, v2, v3
	v_add_f32_e32 v3, v152, v153
	ds_bpermute_b32 v132, v150, v2
	ds_bpermute_b32 v133, v150, v3
	s_waitcnt lgkmcnt(0)
	v_pk_add_f32 v[2:3], v[2:3], v[132:133]
	ds_bpermute_b32 v132, v151, v2
	ds_bpermute_b32 v133, v151, v3
	s_waitcnt lgkmcnt(0)
	v_pk_add_f32 v[2:3], v[2:3], v[132:133]
	s_and_saveexec_b64 s[46:47], s[38:39]
	global_store_dwordx2 v149, v[2:3], s[66:67]
	s_mov_b64 exec, s[46:47]
	v_add_u32_e32 v148, s81, v148
	v_add_u32_e32 v149, 0x400, v149
	v_and_b32_e32 v132, 0x7fffffff, v96
	v_and_b32_e32 v133, 0x7fffffff, v97
	v_and_b32_e32 v134, 0x7fffffff, v98
	v_and_b32_e32 v135, 0x7fffffff, v99
	v_pk_mul_f32 v[144:145], v[96:97], v[96:97]
	v_pk_mul_f32 v[146:147], v[98:99], v[98:99]
	v_pk_fma_f32 v[136:137], v[132:133], s[84:85], 1.0 op_sel_hi:[1,0,0]
	v_pk_fma_f32 v[138:139], v[134:135], s[84:85], 1.0 op_sel_hi:[1,0,0]
	v_pk_mul_f32 v[144:145], v[144:145], s[80:81] op_sel_hi:[1,0]
	v_pk_mul_f32 v[146:147], v[146:147], s[80:81] op_sel_hi:[1,0]
	v_rcp_f32_e32 v136, v136
	v_rcp_f32_e32 v137, v137
	v_rcp_f32_e32 v138, v138
	v_rcp_f32_e32 v139, v139
	v_exp_f32_e32 v144, v144
	v_exp_f32_e32 v145, v145
	v_exp_f32_e32 v146, v146
	v_exp_f32_e32 v147, v147
	v_pk_fma_f32 v[140:141], v[136:137], s[86:87], v[0:1] op_sel_hi:[1,0,0]
	v_pk_fma_f32 v[142:143], v[138:139], s[86:87], v[0:1] op_sel_hi:[1,0,0]
	v_pk_fma_f32 v[140:141], v[136:137], v[140:141], s[88:89] op_sel_hi:[1,1,0]
	v_pk_fma_f32 v[142:143], v[138:139], v[142:143], s[88:89] op_sel_hi:[1,1,0]
	v_pk_fma_f32 v[140:141], v[136:137], v[140:141], s[82:83] op_sel_hi:[1,1,0]
	v_pk_fma_f32 v[142:143], v[138:139], v[142:143], s[82:83] op_sel_hi:[1,1,0]
	v_pk_fma_f32 v[140:141], v[136:137], v[140:141], s[48:49] op_sel_hi:[1,1,0]
	v_pk_fma_f32 v[142:143], v[138:139], v[142:143], s[48:49] op_sel_hi:[1,1,0]
	v_pk_mul_f32 v[140:141], v[136:137], v[140:141]
	v_pk_mul_f32 v[142:143], v[138:139], v[142:143]
	v_pk_mul_f32 v[140:141], v[140:141], v[144:145]
	v_pk_mul_f32 v[142:143], v[142:143], v[146:147]
	v_max_f32_e32 v96, 0, v96
	v_max_f32_e32 v97, 0, v97
	v_max_f32_e32 v98, 0, v98
	v_max_f32_e32 v99, 0, v99
	v_pk_fma_f32 v[96:97], v[132:133], v[140:141], v[96:97] neg_lo:[1,0,0] neg_hi:[1,0,0]
	v_pk_fma_f32 v[98:99], v[134:135], v[142:143], v[98:99] neg_lo:[1,0,0] neg_hi:[1,0,0]
	v_pk_add_f32 v[2:3], v[96:97], v[98:99]
	v_pk_mul_f32 v[152:153], v[96:97], v[96:97]
	v_pk_fma_f32 v[152:153], v[98:99], v[98:99], v[152:153]
	v_and_b32_e32 v132, 0x7fffffff, v88
	v_and_b32_e32 v133, 0x7fffffff, v89
	v_and_b32_e32 v134, 0x7fffffff, v90
	v_and_b32_e32 v135, 0x7fffffff, v91
	v_pk_mul_f32 v[144:145], v[88:89], v[88:89]
	v_pk_mul_f32 v[146:147], v[90:91], v[90:91]
	v_pk_fma_f32 v[136:137], v[132:133], s[84:85], 1.0 op_sel_hi:[1,0,0]
	v_pk_fma_f32 v[138:139], v[134:135], s[84:85], 1.0 op_sel_hi:[1,0,0]
	v_pk_mul_f32 v[144:145], v[144:145], s[80:81] op_sel_hi:[1,0]
	v_pk_mul_f32 v[146:147], v[146:147], s[80:81] op_sel_hi:[1,0]
	v_rcp_f32_e32 v136, v136
	v_rcp_f32_e32 v137, v137
	v_rcp_f32_e32 v138, v138
	v_rcp_f32_e32 v139, v139
	v_exp_f32_e32 v144, v144
	v_exp_f32_e32 v145, v145
	v_exp_f32_e32 v146, v146
	v_exp_f32_e32 v147, v147
	v_pk_fma_f32 v[140:141], v[136:137], s[86:87], v[0:1] op_sel_hi:[1,0,0]
	v_pk_fma_f32 v[142:143], v[138:139], s[86:87], v[0:1] op_sel_hi:[1,0,0]
	v_pk_fma_f32 v[140:141], v[136:137], v[140:141], s[88:89] op_sel_hi:[1,1,0]
	v_pk_fma_f32 v[142:143], v[138:139], v[142:143], s[88:89] op_sel_hi:[1,1,0]
	v_pk_fma_f32 v[140:141], v[136:137], v[140:141], s[82:83] op_sel_hi:[1,1,0]
	v_pk_fma_f32 v[142:143], v[138:139], v[142:143], s[82:83] op_sel_hi:[1,1,0]
	v_pk_fma_f32 v[140:141], v[136:137], v[140:141], s[48:49] op_sel_hi:[1,1,0]
	v_pk_fma_f32 v[142:143], v[138:139], v[142:143], s[48:49] op_sel_hi:[1,1,0]
	v_pk_mul_f32 v[140:141], v[136:137], v[140:141]
	v_pk_mul_f32 v[142:143], v[138:139], v[142:143]
	v_pk_mul_f32 v[140:141], v[140:141], v[144:145]
	v_pk_mul_f32 v[142:143], v[142:143], v[146:147]
	v_max_f32_e32 v88, 0, v88
	v_max_f32_e32 v89, 0, v89
	v_max_f32_e32 v90, 0, v90
	v_max_f32_e32 v91, 0, v91
	v_pk_fma_f32 v[88:89], v[132:133], v[140:141], v[88:89] neg_lo:[1,0,0] neg_hi:[1,0,0]
	v_pk_fma_f32 v[90:91], v[134:135], v[142:143], v[90:91] neg_lo:[1,0,0] neg_hi:[1,0,0]
	v_pk_add_f32 v[2:3], v[2:3], v[88:89]
	v_pk_fma_f32 v[152:153], v[88:89], v[88:89], v[152:153]
	v_pk_add_f32 v[2:3], v[2:3], v[90:91]
	v_pk_fma_f32 v[152:153], v[90:91], v[90:91], v[152:153]
	v_cvt_pk_bf16_f32 v96, v96, v97
	v_cvt_pk_bf16_f32 v97, v98, v99
	v_cvt_pk_bf16_f32 v98, v88, v89
	v_cvt_pk_bf16_f32 v99, v90, v91
	global_store_dwordx4 v148, v[96:99], s[50:51]
	v_and_b32_e32 v132, 0x7fffffff, v80
	v_and_b32_e32 v133, 0x7fffffff, v81
	v_and_b32_e32 v134, 0x7fffffff, v82
	v_and_b32_e32 v135, 0x7fffffff, v83
	v_pk_mul_f32 v[144:145], v[80:81], v[80:81]
	v_pk_mul_f32 v[146:147], v[82:83], v[82:83]
	v_pk_fma_f32 v[136:137], v[132:133], s[84:85], 1.0 op_sel_hi:[1,0,0]
	v_pk_fma_f32 v[138:139], v[134:135], s[84:85], 1.0 op_sel_hi:[1,0,0]
	v_pk_mul_f32 v[144:145], v[144:145], s[80:81] op_sel_hi:[1,0]
	v_pk_mul_f32 v[146:147], v[146:147], s[80:81] op_sel_hi:[1,0]
	v_rcp_f32_e32 v136, v136
	v_rcp_f32_e32 v137, v137
	v_rcp_f32_e32 v138, v138
	v_rcp_f32_e32 v139, v139
	v_exp_f32_e32 v144, v144
	v_exp_f32_e32 v145, v145
	v_exp_f32_e32 v146, v146
	v_exp_f32_e32 v147, v147
	v_pk_fma_f32 v[140:141], v[136:137], s[86:87], v[0:1] op_sel_hi:[1,0,0]
	v_pk_fma_f32 v[142:143], v[138:139], s[86:87], v[0:1] op_sel_hi:[1,0,0]
	v_pk_fma_f32 v[140:141], v[136:137], v[140:141], s[88:89] op_sel_hi:[1,1,0]
	v_pk_fma_f32 v[142:143], v[138:139], v[142:143], s[88:89] op_sel_hi:[1,1,0]
	v_pk_fma_f32 v[140:141], v[136:137], v[140:141], s[82:83] op_sel_hi:[1,1,0]
	v_pk_fma_f32 v[142:143], v[138:139], v[142:143], s[82:83] op_sel_hi:[1,1,0]
	v_pk_fma_f32 v[140:141], v[136:137], v[140:141], s[48:49] op_sel_hi:[1,1,0]
	v_pk_fma_f32 v[142:143], v[138:139], v[142:143], s[48:49] op_sel_hi:[1,1,0]
	v_pk_mul_f32 v[140:141], v[136:137], v[140:141]
	v_pk_mul_f32 v[142:143], v[138:139], v[142:143]
	v_pk_mul_f32 v[140:141], v[140:141], v[144:145]
	v_pk_mul_f32 v[142:143], v[142:143], v[146:147]
	v_max_f32_e32 v80, 0, v80
	v_max_f32_e32 v81, 0, v81
	v_max_f32_e32 v82, 0, v82
	v_max_f32_e32 v83, 0, v83
	v_pk_fma_f32 v[80:81], v[132:133], v[140:141], v[80:81] neg_lo:[1,0,0] neg_hi:[1,0,0]
	v_pk_fma_f32 v[82:83], v[134:135], v[142:143], v[82:83] neg_lo:[1,0,0] neg_hi:[1,0,0]
	v_pk_add_f32 v[2:3], v[2:3], v[80:81]
	v_pk_fma_f32 v[152:153], v[80:81], v[80:81], v[152:153]
	v_pk_add_f32 v[2:3], v[2:3], v[82:83]
	v_pk_fma_f32 v[152:153], v[82:83], v[82:83], v[152:153]
	v_and_b32_e32 v132, 0x7fffffff, v72
	v_and_b32_e32 v133, 0x7fffffff, v73
	v_and_b32_e32 v134, 0x7fffffff, v74
	v_and_b32_e32 v135, 0x7fffffff, v75
	v_pk_mul_f32 v[144:145], v[72:73], v[72:73]
	v_pk_mul_f32 v[146:147], v[74:75], v[74:75]
	v_pk_fma_f32 v[136:137], v[132:133], s[84:85], 1.0 op_sel_hi:[1,0,0]
	v_pk_fma_f32 v[138:139], v[134:135], s[84:85], 1.0 op_sel_hi:[1,0,0]
	v_pk_mul_f32 v[144:145], v[144:145], s[80:81] op_sel_hi:[1,0]
	v_pk_mul_f32 v[146:147], v[146:147], s[80:81] op_sel_hi:[1,0]
	v_rcp_f32_e32 v136, v136
	v_rcp_f32_e32 v137, v137
	v_rcp_f32_e32 v138, v138
	v_rcp_f32_e32 v139, v139
	v_exp_f32_e32 v144, v144
	v_exp_f32_e32 v145, v145
	v_exp_f32_e32 v146, v146
	v_exp_f32_e32 v147, v147
	v_pk_fma_f32 v[140:141], v[136:137], s[86:87], v[0:1] op_sel_hi:[1,0,0]
	v_pk_fma_f32 v[142:143], v[138:139], s[86:87], v[0:1] op_sel_hi:[1,0,0]
	v_pk_fma_f32 v[140:141], v[136:137], v[140:141], s[88:89] op_sel_hi:[1,1,0]
	v_pk_fma_f32 v[142:143], v[138:139], v[142:143], s[88:89] op_sel_hi:[1,1,0]
	v_pk_fma_f32 v[140:141], v[136:137], v[140:141], s[82:83] op_sel_hi:[1,1,0]
	v_pk_fma_f32 v[142:143], v[138:139], v[142:143], s[82:83] op_sel_hi:[1,1,0]
	v_pk_fma_f32 v[140:141], v[136:137], v[140:141], s[48:49] op_sel_hi:[1,1,0]
	v_pk_fma_f32 v[142:143], v[138:139], v[142:143], s[48:49] op_sel_hi:[1,1,0]
	v_pk_mul_f32 v[140:141], v[136:137], v[140:141]
	v_pk_mul_f32 v[142:143], v[138:139], v[142:143]
	v_pk_mul_f32 v[140:141], v[140:141], v[144:145]
	v_pk_mul_f32 v[142:143], v[142:143], v[146:147]
	v_max_f32_e32 v72, 0, v72
	v_max_f32_e32 v73, 0, v73
	v_max_f32_e32 v74, 0, v74
	v_max_f32_e32 v75, 0, v75
	v_pk_fma_f32 v[72:73], v[132:133], v[140:141], v[72:73] neg_lo:[1,0,0] neg_hi:[1,0,0]
	v_pk_fma_f32 v[74:75], v[134:135], v[142:143], v[74:75] neg_lo:[1,0,0] neg_hi:[1,0,0]
	v_pk_add_f32 v[2:3], v[2:3], v[72:73]
	v_pk_fma_f32 v[152:153], v[72:73], v[72:73], v[152:153]
	v_pk_add_f32 v[2:3], v[2:3], v[74:75]
	v_pk_fma_f32 v[152:153], v[74:75], v[74:75], v[152:153]
	v_cvt_pk_bf16_f32 v80, v80, v81
	v_cvt_pk_bf16_f32 v81, v82, v83
	v_cvt_pk_bf16_f32 v82, v72, v73
	v_cvt_pk_bf16_f32 v83, v74, v75
	global_store_dwordx4 v148, v[80:83], s[50:51] offset:256
	v_add_f32_e32 v2, v2, v3
	v_add_f32_e32 v3, v152, v153
	ds_bpermute_b32 v132, v150, v2
	ds_bpermute_b32 v133, v150, v3
	s_waitcnt lgkmcnt(0)
	v_pk_add_f32 v[2:3], v[2:3], v[132:133]
	ds_bpermute_b32 v132, v151, v2
	ds_bpermute_b32 v133, v151, v3
	s_waitcnt lgkmcnt(0)
	v_pk_add_f32 v[2:3], v[2:3], v[132:133]
	s_and_saveexec_b64 s[46:47], s[38:39]
	global_store_dwordx2 v149, v[2:3], s[66:67]
	s_mov_b64 exec, s[46:47]
	v_add_u32_e32 v148, s81, v148
	v_add_u32_e32 v149, 0x400, v149
	v_and_b32_e32 v132, 0x7fffffff, v92
	v_and_b32_e32 v133, 0x7fffffff, v93
	v_and_b32_e32 v134, 0x7fffffff, v94
	v_and_b32_e32 v135, 0x7fffffff, v95
	v_pk_mul_f32 v[144:145], v[92:93], v[92:93]
	v_pk_mul_f32 v[146:147], v[94:95], v[94:95]
	v_pk_fma_f32 v[136:137], v[132:133], s[84:85], 1.0 op_sel_hi:[1,0,0]
	v_pk_fma_f32 v[138:139], v[134:135], s[84:85], 1.0 op_sel_hi:[1,0,0]
	v_pk_mul_f32 v[144:145], v[144:145], s[80:81] op_sel_hi:[1,0]
	v_pk_mul_f32 v[146:147], v[146:147], s[80:81] op_sel_hi:[1,0]
	v_rcp_f32_e32 v136, v136
	v_rcp_f32_e32 v137, v137
	v_rcp_f32_e32 v138, v138
	v_rcp_f32_e32 v139, v139
	v_exp_f32_e32 v144, v144
	v_exp_f32_e32 v145, v145
	v_exp_f32_e32 v146, v146
	v_exp_f32_e32 v147, v147
	v_pk_fma_f32 v[140:141], v[136:137], s[86:87], v[0:1] op_sel_hi:[1,0,0]
	v_pk_fma_f32 v[142:143], v[138:139], s[86:87], v[0:1] op_sel_hi:[1,0,0]
	v_pk_fma_f32 v[140:141], v[136:137], v[140:141], s[88:89] op_sel_hi:[1,1,0]
	v_pk_fma_f32 v[142:143], v[138:139], v[142:143], s[88:89] op_sel_hi:[1,1,0]
	v_pk_fma_f32 v[140:141], v[136:137], v[140:141], s[82:83] op_sel_hi:[1,1,0]
	v_pk_fma_f32 v[142:143], v[138:139], v[142:143], s[82:83] op_sel_hi:[1,1,0]
	v_pk_fma_f32 v[140:141], v[136:137], v[140:141], s[48:49] op_sel_hi:[1,1,0]
	v_pk_fma_f32 v[142:143], v[138:139], v[142:143], s[48:49] op_sel_hi:[1,1,0]
	v_pk_mul_f32 v[140:141], v[136:137], v[140:141]
	v_pk_mul_f32 v[142:143], v[138:139], v[142:143]
	v_pk_mul_f32 v[140:141], v[140:141], v[144:145]
	v_pk_mul_f32 v[142:143], v[142:143], v[146:147]
	v_max_f32_e32 v92, 0, v92
	v_max_f32_e32 v93, 0, v93
	v_max_f32_e32 v94, 0, v94
	v_max_f32_e32 v95, 0, v95
	v_pk_fma_f32 v[92:93], v[132:133], v[140:141], v[92:93] neg_lo:[1,0,0] neg_hi:[1,0,0]
	v_pk_fma_f32 v[94:95], v[134:135], v[142:143], v[94:95] neg_lo:[1,0,0] neg_hi:[1,0,0]
	v_pk_add_f32 v[2:3], v[92:93], v[94:95]
	v_pk_mul_f32 v[152:153], v[92:93], v[92:93]
	v_pk_fma_f32 v[152:153], v[94:95], v[94:95], v[152:153]
	v_and_b32_e32 v132, 0x7fffffff, v84
	v_and_b32_e32 v133, 0x7fffffff, v85
	v_and_b32_e32 v134, 0x7fffffff, v86
	v_and_b32_e32 v135, 0x7fffffff, v87
	v_pk_mul_f32 v[144:145], v[84:85], v[84:85]
	v_pk_mul_f32 v[146:147], v[86:87], v[86:87]
	v_pk_fma_f32 v[136:137], v[132:133], s[84:85], 1.0 op_sel_hi:[1,0,0]
	v_pk_fma_f32 v[138:139], v[134:135], s[84:85], 1.0 op_sel_hi:[1,0,0]
	v_pk_mul_f32 v[144:145], v[144:145], s[80:81] op_sel_hi:[1,0]
	v_pk_mul_f32 v[146:147], v[146:147], s[80:81] op_sel_hi:[1,0]
	v_rcp_f32_e32 v136, v136
	v_rcp_f32_e32 v137, v137
	v_rcp_f32_e32 v138, v138
	v_rcp_f32_e32 v139, v139
	v_exp_f32_e32 v144, v144
	v_exp_f32_e32 v145, v145
	v_exp_f32_e32 v146, v146
	v_exp_f32_e32 v147, v147
	v_pk_fma_f32 v[140:141], v[136:137], s[86:87], v[0:1] op_sel_hi:[1,0,0]
	v_pk_fma_f32 v[142:143], v[138:139], s[86:87], v[0:1] op_sel_hi:[1,0,0]
	v_pk_fma_f32 v[140:141], v[136:137], v[140:141], s[88:89] op_sel_hi:[1,1,0]
	v_pk_fma_f32 v[142:143], v[138:139], v[142:143], s[88:89] op_sel_hi:[1,1,0]
	v_pk_fma_f32 v[140:141], v[136:137], v[140:141], s[82:83] op_sel_hi:[1,1,0]
	v_pk_fma_f32 v[142:143], v[138:139], v[142:143], s[82:83] op_sel_hi:[1,1,0]
	v_pk_fma_f32 v[140:141], v[136:137], v[140:141], s[48:49] op_sel_hi:[1,1,0]
	v_pk_fma_f32 v[142:143], v[138:139], v[142:143], s[48:49] op_sel_hi:[1,1,0]
	v_pk_mul_f32 v[140:141], v[136:137], v[140:141]
	v_pk_mul_f32 v[142:143], v[138:139], v[142:143]
	v_pk_mul_f32 v[140:141], v[140:141], v[144:145]
	v_pk_mul_f32 v[142:143], v[142:143], v[146:147]
	v_max_f32_e32 v84, 0, v84
	v_max_f32_e32 v85, 0, v85
	v_max_f32_e32 v86, 0, v86
	v_max_f32_e32 v87, 0, v87
	v_pk_fma_f32 v[84:85], v[132:133], v[140:141], v[84:85] neg_lo:[1,0,0] neg_hi:[1,0,0]
	v_pk_fma_f32 v[86:87], v[134:135], v[142:143], v[86:87] neg_lo:[1,0,0] neg_hi:[1,0,0]
	v_pk_add_f32 v[2:3], v[2:3], v[84:85]
	v_pk_fma_f32 v[152:153], v[84:85], v[84:85], v[152:153]
	v_pk_add_f32 v[2:3], v[2:3], v[86:87]
	v_pk_fma_f32 v[152:153], v[86:87], v[86:87], v[152:153]
	v_cvt_pk_bf16_f32 v92, v92, v93
	v_cvt_pk_bf16_f32 v93, v94, v95
	v_cvt_pk_bf16_f32 v94, v84, v85
	v_cvt_pk_bf16_f32 v95, v86, v87
	global_store_dwordx4 v148, v[92:95], s[50:51]
	v_and_b32_e32 v132, 0x7fffffff, v76
	v_and_b32_e32 v133, 0x7fffffff, v77
	v_and_b32_e32 v134, 0x7fffffff, v78
	v_and_b32_e32 v135, 0x7fffffff, v79
	v_pk_mul_f32 v[144:145], v[76:77], v[76:77]
	v_pk_mul_f32 v[146:147], v[78:79], v[78:79]
	v_pk_fma_f32 v[136:137], v[132:133], s[84:85], 1.0 op_sel_hi:[1,0,0]
	v_pk_fma_f32 v[138:139], v[134:135], s[84:85], 1.0 op_sel_hi:[1,0,0]
	v_pk_mul_f32 v[144:145], v[144:145], s[80:81] op_sel_hi:[1,0]
	v_pk_mul_f32 v[146:147], v[146:147], s[80:81] op_sel_hi:[1,0]
	v_rcp_f32_e32 v136, v136
	v_rcp_f32_e32 v137, v137
	v_rcp_f32_e32 v138, v138
	v_rcp_f32_e32 v139, v139
	v_exp_f32_e32 v144, v144
	v_exp_f32_e32 v145, v145
	v_exp_f32_e32 v146, v146
	v_exp_f32_e32 v147, v147
	v_pk_fma_f32 v[140:141], v[136:137], s[86:87], v[0:1] op_sel_hi:[1,0,0]
	v_pk_fma_f32 v[142:143], v[138:139], s[86:87], v[0:1] op_sel_hi:[1,0,0]
	v_pk_fma_f32 v[140:141], v[136:137], v[140:141], s[88:89] op_sel_hi:[1,1,0]
	v_pk_fma_f32 v[142:143], v[138:139], v[142:143], s[88:89] op_sel_hi:[1,1,0]
	v_pk_fma_f32 v[140:141], v[136:137], v[140:141], s[82:83] op_sel_hi:[1,1,0]
	v_pk_fma_f32 v[142:143], v[138:139], v[142:143], s[82:83] op_sel_hi:[1,1,0]
	v_pk_fma_f32 v[140:141], v[136:137], v[140:141], s[48:49] op_sel_hi:[1,1,0]
	v_pk_fma_f32 v[142:143], v[138:139], v[142:143], s[48:49] op_sel_hi:[1,1,0]
	v_pk_mul_f32 v[140:141], v[136:137], v[140:141]
	v_pk_mul_f32 v[142:143], v[138:139], v[142:143]
	v_pk_mul_f32 v[140:141], v[140:141], v[144:145]
	v_pk_mul_f32 v[142:143], v[142:143], v[146:147]
	v_max_f32_e32 v76, 0, v76
	v_max_f32_e32 v77, 0, v77
	v_max_f32_e32 v78, 0, v78
	v_max_f32_e32 v79, 0, v79
	v_pk_fma_f32 v[76:77], v[132:133], v[140:141], v[76:77] neg_lo:[1,0,0] neg_hi:[1,0,0]
	v_pk_fma_f32 v[78:79], v[134:135], v[142:143], v[78:79] neg_lo:[1,0,0] neg_hi:[1,0,0]
	v_pk_add_f32 v[2:3], v[2:3], v[76:77]
	v_pk_fma_f32 v[152:153], v[76:77], v[76:77], v[152:153]
	v_pk_add_f32 v[2:3], v[2:3], v[78:79]
	v_pk_fma_f32 v[152:153], v[78:79], v[78:79], v[152:153]
	v_and_b32_e32 v132, 0x7fffffff, v68
	v_and_b32_e32 v133, 0x7fffffff, v69
	v_and_b32_e32 v134, 0x7fffffff, v70
	v_and_b32_e32 v135, 0x7fffffff, v71
	v_pk_mul_f32 v[144:145], v[68:69], v[68:69]
	v_pk_mul_f32 v[146:147], v[70:71], v[70:71]
	v_pk_fma_f32 v[136:137], v[132:133], s[84:85], 1.0 op_sel_hi:[1,0,0]
	v_pk_fma_f32 v[138:139], v[134:135], s[84:85], 1.0 op_sel_hi:[1,0,0]
	v_pk_mul_f32 v[144:145], v[144:145], s[80:81] op_sel_hi:[1,0]
	v_pk_mul_f32 v[146:147], v[146:147], s[80:81] op_sel_hi:[1,0]
	v_rcp_f32_e32 v136, v136
	v_rcp_f32_e32 v137, v137
	v_rcp_f32_e32 v138, v138
	v_rcp_f32_e32 v139, v139
	v_exp_f32_e32 v144, v144
	v_exp_f32_e32 v145, v145
	v_exp_f32_e32 v146, v146
	v_exp_f32_e32 v147, v147
	v_pk_fma_f32 v[140:141], v[136:137], s[86:87], v[0:1] op_sel_hi:[1,0,0]
	v_pk_fma_f32 v[142:143], v[138:139], s[86:87], v[0:1] op_sel_hi:[1,0,0]
	v_pk_fma_f32 v[140:141], v[136:137], v[140:141], s[88:89] op_sel_hi:[1,1,0]
	v_pk_fma_f32 v[142:143], v[138:139], v[142:143], s[88:89] op_sel_hi:[1,1,0]
	v_pk_fma_f32 v[140:141], v[136:137], v[140:141], s[82:83] op_sel_hi:[1,1,0]
	v_pk_fma_f32 v[142:143], v[138:139], v[142:143], s[82:83] op_sel_hi:[1,1,0]
	v_pk_fma_f32 v[140:141], v[136:137], v[140:141], s[48:49] op_sel_hi:[1,1,0]
	v_pk_fma_f32 v[142:143], v[138:139], v[142:143], s[48:49] op_sel_hi:[1,1,0]
	v_pk_mul_f32 v[140:141], v[136:137], v[140:141]
	v_pk_mul_f32 v[142:143], v[138:139], v[142:143]
	v_pk_mul_f32 v[140:141], v[140:141], v[144:145]
	v_pk_mul_f32 v[142:143], v[142:143], v[146:147]
	v_max_f32_e32 v68, 0, v68
	v_max_f32_e32 v69, 0, v69
	v_max_f32_e32 v70, 0, v70
	v_max_f32_e32 v71, 0, v71
	v_pk_fma_f32 v[68:69], v[132:133], v[140:141], v[68:69] neg_lo:[1,0,0] neg_hi:[1,0,0]
	v_pk_fma_f32 v[70:71], v[134:135], v[142:143], v[70:71] neg_lo:[1,0,0] neg_hi:[1,0,0]
	v_pk_add_f32 v[2:3], v[2:3], v[68:69]
	v_pk_fma_f32 v[152:153], v[68:69], v[68:69], v[152:153]
	v_pk_add_f32 v[2:3], v[2:3], v[70:71]
	v_pk_fma_f32 v[152:153], v[70:71], v[70:71], v[152:153]
	v_cvt_pk_bf16_f32 v76, v76, v77
	v_cvt_pk_bf16_f32 v77, v78, v79
	v_cvt_pk_bf16_f32 v78, v68, v69
	v_cvt_pk_bf16_f32 v79, v70, v71
	global_store_dwordx4 v148, v[76:79], s[50:51] offset:256
	v_add_f32_e32 v2, v2, v3
	v_add_f32_e32 v3, v152, v153
	ds_bpermute_b32 v132, v150, v2
	ds_bpermute_b32 v133, v150, v3
	s_waitcnt lgkmcnt(0)
	v_pk_add_f32 v[2:3], v[2:3], v[132:133]
	ds_bpermute_b32 v132, v151, v2
	ds_bpermute_b32 v133, v151, v3
	s_waitcnt lgkmcnt(0)
	v_pk_add_f32 v[2:3], v[2:3], v[132:133]
	s_and_saveexec_b64 s[46:47], s[38:39]
	global_store_dwordx2 v149, v[2:3], s[66:67]
	s_mov_b64 exec, s[46:47]
	s_mul_i32 s30, s81, 5
	v_add_u32_e32 v148, s30, v148
	v_add_u32_e32 v149, 0x1400, v149
	s_cmp_lg_u32 s49, 0
	s_cbranch_scc1 .LBB0_326
	v_and_b32_e32 v132, 0x7fffffff, v64
	v_and_b32_e32 v133, 0x7fffffff, v65
	v_and_b32_e32 v134, 0x7fffffff, v66
	v_and_b32_e32 v135, 0x7fffffff, v67
	v_pk_mul_f32 v[144:145], v[64:65], v[64:65]
	v_pk_mul_f32 v[146:147], v[66:67], v[66:67]
	v_pk_fma_f32 v[136:137], v[132:133], s[84:85], 1.0 op_sel_hi:[1,0,0]
	v_pk_fma_f32 v[138:139], v[134:135], s[84:85], 1.0 op_sel_hi:[1,0,0]
	v_pk_mul_f32 v[144:145], v[144:145], s[80:81] op_sel_hi:[1,0]
	v_pk_mul_f32 v[146:147], v[146:147], s[80:81] op_sel_hi:[1,0]
	v_rcp_f32_e32 v136, v136
	v_rcp_f32_e32 v137, v137
	v_rcp_f32_e32 v138, v138
	v_rcp_f32_e32 v139, v139
	v_exp_f32_e32 v144, v144
	v_exp_f32_e32 v145, v145
	v_exp_f32_e32 v146, v146
	v_exp_f32_e32 v147, v147
	v_pk_fma_f32 v[140:141], v[136:137], s[86:87], v[0:1] op_sel_hi:[1,0,0]
	v_pk_fma_f32 v[142:143], v[138:139], s[86:87], v[0:1] op_sel_hi:[1,0,0]
	v_pk_fma_f32 v[140:141], v[136:137], v[140:141], s[88:89] op_sel_hi:[1,1,0]
	v_pk_fma_f32 v[142:143], v[138:139], v[142:143], s[88:89] op_sel_hi:[1,1,0]
	v_pk_fma_f32 v[140:141], v[136:137], v[140:141], s[82:83] op_sel_hi:[1,1,0]
	v_pk_fma_f32 v[142:143], v[138:139], v[142:143], s[82:83] op_sel_hi:[1,1,0]
	v_pk_fma_f32 v[140:141], v[136:137], v[140:141], s[48:49] op_sel_hi:[1,1,0]
	v_pk_fma_f32 v[142:143], v[138:139], v[142:143], s[48:49] op_sel_hi:[1,1,0]
	v_pk_mul_f32 v[140:141], v[136:137], v[140:141]
	v_pk_mul_f32 v[142:143], v[138:139], v[142:143]
	v_pk_mul_f32 v[140:141], v[140:141], v[144:145]
	v_pk_mul_f32 v[142:143], v[142:143], v[146:147]
	v_max_f32_e32 v64, 0, v64
	v_max_f32_e32 v65, 0, v65
	v_max_f32_e32 v66, 0, v66
	v_max_f32_e32 v67, 0, v67
	v_pk_fma_f32 v[64:65], v[132:133], v[140:141], v[64:65] neg_lo:[1,0,0] neg_hi:[1,0,0]
	v_pk_fma_f32 v[66:67], v[134:135], v[142:143], v[66:67] neg_lo:[1,0,0] neg_hi:[1,0,0]
	v_pk_add_f32 v[2:3], v[64:65], v[66:67]
	v_pk_mul_f32 v[152:153], v[64:65], v[64:65]
	v_pk_fma_f32 v[152:153], v[66:67], v[66:67], v[152:153]
	v_and_b32_e32 v132, 0x7fffffff, v56
	v_and_b32_e32 v133, 0x7fffffff, v57
	v_and_b32_e32 v134, 0x7fffffff, v58
	v_and_b32_e32 v135, 0x7fffffff, v59
	v_pk_mul_f32 v[144:145], v[56:57], v[56:57]
	v_pk_mul_f32 v[146:147], v[58:59], v[58:59]
	v_pk_fma_f32 v[136:137], v[132:133], s[84:85], 1.0 op_sel_hi:[1,0,0]
	v_pk_fma_f32 v[138:139], v[134:135], s[84:85], 1.0 op_sel_hi:[1,0,0]
	v_pk_mul_f32 v[144:145], v[144:145], s[80:81] op_sel_hi:[1,0]
	v_pk_mul_f32 v[146:147], v[146:147], s[80:81] op_sel_hi:[1,0]
	v_rcp_f32_e32 v136, v136
	v_rcp_f32_e32 v137, v137
	v_rcp_f32_e32 v138, v138
	v_rcp_f32_e32 v139, v139
	v_exp_f32_e32 v144, v144
	v_exp_f32_e32 v145, v145
	v_exp_f32_e32 v146, v146
	v_exp_f32_e32 v147, v147
	v_pk_fma_f32 v[140:141], v[136:137], s[86:87], v[0:1] op_sel_hi:[1,0,0]
	v_pk_fma_f32 v[142:143], v[138:139], s[86:87], v[0:1] op_sel_hi:[1,0,0]
	v_pk_fma_f32 v[140:141], v[136:137], v[140:141], s[88:89] op_sel_hi:[1,1,0]
	v_pk_fma_f32 v[142:143], v[138:139], v[142:143], s[88:89] op_sel_hi:[1,1,0]
	v_pk_fma_f32 v[140:141], v[136:137], v[140:141], s[82:83] op_sel_hi:[1,1,0]
	v_pk_fma_f32 v[142:143], v[138:139], v[142:143], s[82:83] op_sel_hi:[1,1,0]
	v_pk_fma_f32 v[140:141], v[136:137], v[140:141], s[48:49] op_sel_hi:[1,1,0]
	v_pk_fma_f32 v[142:143], v[138:139], v[142:143], s[48:49] op_sel_hi:[1,1,0]
	v_pk_mul_f32 v[140:141], v[136:137], v[140:141]
	v_pk_mul_f32 v[142:143], v[138:139], v[142:143]
	v_pk_mul_f32 v[140:141], v[140:141], v[144:145]
	v_pk_mul_f32 v[142:143], v[142:143], v[146:147]
	v_max_f32_e32 v56, 0, v56
	v_max_f32_e32 v57, 0, v57
	v_max_f32_e32 v58, 0, v58
	v_max_f32_e32 v59, 0, v59
	v_pk_fma_f32 v[56:57], v[132:133], v[140:141], v[56:57] neg_lo:[1,0,0] neg_hi:[1,0,0]
	v_pk_fma_f32 v[58:59], v[134:135], v[142:143], v[58:59] neg_lo:[1,0,0] neg_hi:[1,0,0]
	v_pk_add_f32 v[2:3], v[2:3], v[56:57]
	v_pk_fma_f32 v[152:153], v[56:57], v[56:57], v[152:153]
	v_pk_add_f32 v[2:3], v[2:3], v[58:59]
	v_pk_fma_f32 v[152:153], v[58:59], v[58:59], v[152:153]
	v_cvt_pk_bf16_f32 v64, v64, v65
	v_cvt_pk_bf16_f32 v65, v66, v67
	v_cvt_pk_bf16_f32 v66, v56, v57
	v_cvt_pk_bf16_f32 v67, v58, v59
	global_store_dwordx4 v148, v[64:67], s[50:51]
	v_and_b32_e32 v132, 0x7fffffff, v48
	v_and_b32_e32 v133, 0x7fffffff, v49
	v_and_b32_e32 v134, 0x7fffffff, v50
	v_and_b32_e32 v135, 0x7fffffff, v51
	v_pk_mul_f32 v[144:145], v[48:49], v[48:49]
	v_pk_mul_f32 v[146:147], v[50:51], v[50:51]
	v_pk_fma_f32 v[136:137], v[132:133], s[84:85], 1.0 op_sel_hi:[1,0,0]
	v_pk_fma_f32 v[138:139], v[134:135], s[84:85], 1.0 op_sel_hi:[1,0,0]
	v_pk_mul_f32 v[144:145], v[144:145], s[80:81] op_sel_hi:[1,0]
	v_pk_mul_f32 v[146:147], v[146:147], s[80:81] op_sel_hi:[1,0]
	v_rcp_f32_e32 v136, v136
	v_rcp_f32_e32 v137, v137
	v_rcp_f32_e32 v138, v138
	v_rcp_f32_e32 v139, v139
	v_exp_f32_e32 v144, v144
	v_exp_f32_e32 v145, v145
	v_exp_f32_e32 v146, v146
	v_exp_f32_e32 v147, v147
	v_pk_fma_f32 v[140:141], v[136:137], s[86:87], v[0:1] op_sel_hi:[1,0,0]
	v_pk_fma_f32 v[142:143], v[138:139], s[86:87], v[0:1] op_sel_hi:[1,0,0]
	v_pk_fma_f32 v[140:141], v[136:137], v[140:141], s[88:89] op_sel_hi:[1,1,0]
	v_pk_fma_f32 v[142:143], v[138:139], v[142:143], s[88:89] op_sel_hi:[1,1,0]
	v_pk_fma_f32 v[140:141], v[136:137], v[140:141], s[82:83] op_sel_hi:[1,1,0]
	v_pk_fma_f32 v[142:143], v[138:139], v[142:143], s[82:83] op_sel_hi:[1,1,0]
	v_pk_fma_f32 v[140:141], v[136:137], v[140:141], s[48:49] op_sel_hi:[1,1,0]
	v_pk_fma_f32 v[142:143], v[138:139], v[142:143], s[48:49] op_sel_hi:[1,1,0]
	v_pk_mul_f32 v[140:141], v[136:137], v[140:141]
	v_pk_mul_f32 v[142:143], v[138:139], v[142:143]
	v_pk_mul_f32 v[140:141], v[140:141], v[144:145]
	v_pk_mul_f32 v[142:143], v[142:143], v[146:147]
	v_max_f32_e32 v48, 0, v48
	v_max_f32_e32 v49, 0, v49
	v_max_f32_e32 v50, 0, v50
	v_max_f32_e32 v51, 0, v51
	v_pk_fma_f32 v[48:49], v[132:133], v[140:141], v[48:49] neg_lo:[1,0,0] neg_hi:[1,0,0]
	v_pk_fma_f32 v[50:51], v[134:135], v[142:143], v[50:51] neg_lo:[1,0,0] neg_hi:[1,0,0]
	v_pk_add_f32 v[2:3], v[2:3], v[48:49]
	v_pk_fma_f32 v[152:153], v[48:49], v[48:49], v[152:153]
	v_pk_add_f32 v[2:3], v[2:3], v[50:51]
	v_pk_fma_f32 v[152:153], v[50:51], v[50:51], v[152:153]
	v_and_b32_e32 v132, 0x7fffffff, v40
	v_and_b32_e32 v133, 0x7fffffff, v41
	v_and_b32_e32 v134, 0x7fffffff, v42
	v_and_b32_e32 v135, 0x7fffffff, v43
	v_pk_mul_f32 v[144:145], v[40:41], v[40:41]
	v_pk_mul_f32 v[146:147], v[42:43], v[42:43]
	v_pk_fma_f32 v[136:137], v[132:133], s[84:85], 1.0 op_sel_hi:[1,0,0]
	v_pk_fma_f32 v[138:139], v[134:135], s[84:85], 1.0 op_sel_hi:[1,0,0]
	v_pk_mul_f32 v[144:145], v[144:145], s[80:81] op_sel_hi:[1,0]
	v_pk_mul_f32 v[146:147], v[146:147], s[80:81] op_sel_hi:[1,0]
	v_rcp_f32_e32 v136, v136
	v_rcp_f32_e32 v137, v137
	v_rcp_f32_e32 v138, v138
	v_rcp_f32_e32 v139, v139
	v_exp_f32_e32 v144, v144
	v_exp_f32_e32 v145, v145
	v_exp_f32_e32 v146, v146
	v_exp_f32_e32 v147, v147
	v_pk_fma_f32 v[140:141], v[136:137], s[86:87], v[0:1] op_sel_hi:[1,0,0]
	v_pk_fma_f32 v[142:143], v[138:139], s[86:87], v[0:1] op_sel_hi:[1,0,0]
	v_pk_fma_f32 v[140:141], v[136:137], v[140:141], s[88:89] op_sel_hi:[1,1,0]
	v_pk_fma_f32 v[142:143], v[138:139], v[142:143], s[88:89] op_sel_hi:[1,1,0]
	v_pk_fma_f32 v[140:141], v[136:137], v[140:141], s[82:83] op_sel_hi:[1,1,0]
	v_pk_fma_f32 v[142:143], v[138:139], v[142:143], s[82:83] op_sel_hi:[1,1,0]
	v_pk_fma_f32 v[140:141], v[136:137], v[140:141], s[48:49] op_sel_hi:[1,1,0]
	v_pk_fma_f32 v[142:143], v[138:139], v[142:143], s[48:49] op_sel_hi:[1,1,0]
	v_pk_mul_f32 v[140:141], v[136:137], v[140:141]
	v_pk_mul_f32 v[142:143], v[138:139], v[142:143]
	v_pk_mul_f32 v[140:141], v[140:141], v[144:145]
	v_pk_mul_f32 v[142:143], v[142:143], v[146:147]
	v_max_f32_e32 v40, 0, v40
	v_max_f32_e32 v41, 0, v41
	v_max_f32_e32 v42, 0, v42
	v_max_f32_e32 v43, 0, v43
	v_pk_fma_f32 v[40:41], v[132:133], v[140:141], v[40:41] neg_lo:[1,0,0] neg_hi:[1,0,0]
	v_pk_fma_f32 v[42:43], v[134:135], v[142:143], v[42:43] neg_lo:[1,0,0] neg_hi:[1,0,0]
	v_pk_add_f32 v[2:3], v[2:3], v[40:41]
	v_pk_fma_f32 v[152:153], v[40:41], v[40:41], v[152:153]
	v_pk_add_f32 v[2:3], v[2:3], v[42:43]
	v_pk_fma_f32 v[152:153], v[42:43], v[42:43], v[152:153]
	v_cvt_pk_bf16_f32 v48, v48, v49
	v_cvt_pk_bf16_f32 v49, v50, v51
	v_cvt_pk_bf16_f32 v50, v40, v41
	v_cvt_pk_bf16_f32 v51, v42, v43
	global_store_dwordx4 v148, v[48:51], s[50:51] offset:256
	v_add_f32_e32 v2, v2, v3
	v_add_f32_e32 v3, v152, v153
	ds_bpermute_b32 v132, v150, v2
	ds_bpermute_b32 v133, v150, v3
	s_waitcnt lgkmcnt(0)
	v_pk_add_f32 v[2:3], v[2:3], v[132:133]
	ds_bpermute_b32 v132, v151, v2
	ds_bpermute_b32 v133, v151, v3
	s_waitcnt lgkmcnt(0)
	v_pk_add_f32 v[2:3], v[2:3], v[132:133]
	s_and_saveexec_b64 s[46:47], s[38:39]
	global_store_dwordx2 v149, v[2:3], s[66:67]
	s_mov_b64 exec, s[46:47]
	v_add_u32_e32 v148, s81, v148
	v_add_u32_e32 v149, 0x400, v149
	v_and_b32_e32 v132, 0x7fffffff, v60
	v_and_b32_e32 v133, 0x7fffffff, v61
	v_and_b32_e32 v134, 0x7fffffff, v62
	v_and_b32_e32 v135, 0x7fffffff, v63
	v_pk_mul_f32 v[144:145], v[60:61], v[60:61]
	v_pk_mul_f32 v[146:147], v[62:63], v[62:63]
	v_pk_fma_f32 v[136:137], v[132:133], s[84:85], 1.0 op_sel_hi:[1,0,0]
	v_pk_fma_f32 v[138:139], v[134:135], s[84:85], 1.0 op_sel_hi:[1,0,0]
	v_pk_mul_f32 v[144:145], v[144:145], s[80:81] op_sel_hi:[1,0]
	v_pk_mul_f32 v[146:147], v[146:147], s[80:81] op_sel_hi:[1,0]
	v_rcp_f32_e32 v136, v136
	v_rcp_f32_e32 v137, v137
	v_rcp_f32_e32 v138, v138
	v_rcp_f32_e32 v139, v139
	v_exp_f32_e32 v144, v144
	v_exp_f32_e32 v145, v145
	v_exp_f32_e32 v146, v146
	v_exp_f32_e32 v147, v147
	v_pk_fma_f32 v[140:141], v[136:137], s[86:87], v[0:1] op_sel_hi:[1,0,0]
	v_pk_fma_f32 v[142:143], v[138:139], s[86:87], v[0:1] op_sel_hi:[1,0,0]
	v_pk_fma_f32 v[140:141], v[136:137], v[140:141], s[88:89] op_sel_hi:[1,1,0]
	v_pk_fma_f32 v[142:143], v[138:139], v[142:143], s[88:89] op_sel_hi:[1,1,0]
	v_pk_fma_f32 v[140:141], v[136:137], v[140:141], s[82:83] op_sel_hi:[1,1,0]
	v_pk_fma_f32 v[142:143], v[138:139], v[142:143], s[82:83] op_sel_hi:[1,1,0]
	v_pk_fma_f32 v[140:141], v[136:137], v[140:141], s[48:49] op_sel_hi:[1,1,0]
	v_pk_fma_f32 v[142:143], v[138:139], v[142:143], s[48:49] op_sel_hi:[1,1,0]
	v_pk_mul_f32 v[140:141], v[136:137], v[140:141]
	v_pk_mul_f32 v[142:143], v[138:139], v[142:143]
	v_pk_mul_f32 v[140:141], v[140:141], v[144:145]
	v_pk_mul_f32 v[142:143], v[142:143], v[146:147]
	v_max_f32_e32 v60, 0, v60
	v_max_f32_e32 v61, 0, v61
	v_max_f32_e32 v62, 0, v62
	v_max_f32_e32 v63, 0, v63
	v_pk_fma_f32 v[60:61], v[132:133], v[140:141], v[60:61] neg_lo:[1,0,0] neg_hi:[1,0,0]
	v_pk_fma_f32 v[62:63], v[134:135], v[142:143], v[62:63] neg_lo:[1,0,0] neg_hi:[1,0,0]
	v_pk_add_f32 v[2:3], v[60:61], v[62:63]
	v_pk_mul_f32 v[152:153], v[60:61], v[60:61]
	v_pk_fma_f32 v[152:153], v[62:63], v[62:63], v[152:153]
	v_and_b32_e32 v132, 0x7fffffff, v52
	v_and_b32_e32 v133, 0x7fffffff, v53
	v_and_b32_e32 v134, 0x7fffffff, v54
	v_and_b32_e32 v135, 0x7fffffff, v55
	v_pk_mul_f32 v[144:145], v[52:53], v[52:53]
	v_pk_mul_f32 v[146:147], v[54:55], v[54:55]
	v_pk_fma_f32 v[136:137], v[132:133], s[84:85], 1.0 op_sel_hi:[1,0,0]
	v_pk_fma_f32 v[138:139], v[134:135], s[84:85], 1.0 op_sel_hi:[1,0,0]
	v_pk_mul_f32 v[144:145], v[144:145], s[80:81] op_sel_hi:[1,0]
	v_pk_mul_f32 v[146:147], v[146:147], s[80:81] op_sel_hi:[1,0]
	v_rcp_f32_e32 v136, v136
	v_rcp_f32_e32 v137, v137
	v_rcp_f32_e32 v138, v138
	v_rcp_f32_e32 v139, v139
	v_exp_f32_e32 v144, v144
	v_exp_f32_e32 v145, v145
	v_exp_f32_e32 v146, v146
	v_exp_f32_e32 v147, v147
	v_pk_fma_f32 v[140:141], v[136:137], s[86:87], v[0:1] op_sel_hi:[1,0,0]
	v_pk_fma_f32 v[142:143], v[138:139], s[86:87], v[0:1] op_sel_hi:[1,0,0]
	v_pk_fma_f32 v[140:141], v[136:137], v[140:141], s[88:89] op_sel_hi:[1,1,0]
	v_pk_fma_f32 v[142:143], v[138:139], v[142:143], s[88:89] op_sel_hi:[1,1,0]
	v_pk_fma_f32 v[140:141], v[136:137], v[140:141], s[82:83] op_sel_hi:[1,1,0]
	v_pk_fma_f32 v[142:143], v[138:139], v[142:143], s[82:83] op_sel_hi:[1,1,0]
	v_pk_fma_f32 v[140:141], v[136:137], v[140:141], s[48:49] op_sel_hi:[1,1,0]
	v_pk_fma_f32 v[142:143], v[138:139], v[142:143], s[48:49] op_sel_hi:[1,1,0]
	v_pk_mul_f32 v[140:141], v[136:137], v[140:141]
	v_pk_mul_f32 v[142:143], v[138:139], v[142:143]
	v_pk_mul_f32 v[140:141], v[140:141], v[144:145]
	v_pk_mul_f32 v[142:143], v[142:143], v[146:147]
	v_max_f32_e32 v52, 0, v52
	v_max_f32_e32 v53, 0, v53
	v_max_f32_e32 v54, 0, v54
	v_max_f32_e32 v55, 0, v55
	v_pk_fma_f32 v[52:53], v[132:133], v[140:141], v[52:53] neg_lo:[1,0,0] neg_hi:[1,0,0]
	v_pk_fma_f32 v[54:55], v[134:135], v[142:143], v[54:55] neg_lo:[1,0,0] neg_hi:[1,0,0]
	v_pk_add_f32 v[2:3], v[2:3], v[52:53]
	v_pk_fma_f32 v[152:153], v[52:53], v[52:53], v[152:153]
	v_pk_add_f32 v[2:3], v[2:3], v[54:55]
	v_pk_fma_f32 v[152:153], v[54:55], v[54:55], v[152:153]
	v_cvt_pk_bf16_f32 v60, v60, v61
	v_cvt_pk_bf16_f32 v61, v62, v63
	v_cvt_pk_bf16_f32 v62, v52, v53
	v_cvt_pk_bf16_f32 v63, v54, v55
	global_store_dwordx4 v148, v[60:63], s[50:51]
	v_and_b32_e32 v132, 0x7fffffff, v44
	v_and_b32_e32 v133, 0x7fffffff, v45
	v_and_b32_e32 v134, 0x7fffffff, v46
	v_and_b32_e32 v135, 0x7fffffff, v47
	v_pk_mul_f32 v[144:145], v[44:45], v[44:45]
	v_pk_mul_f32 v[146:147], v[46:47], v[46:47]
	v_pk_fma_f32 v[136:137], v[132:133], s[84:85], 1.0 op_sel_hi:[1,0,0]
	v_pk_fma_f32 v[138:139], v[134:135], s[84:85], 1.0 op_sel_hi:[1,0,0]
	v_pk_mul_f32 v[144:145], v[144:145], s[80:81] op_sel_hi:[1,0]
	v_pk_mul_f32 v[146:147], v[146:147], s[80:81] op_sel_hi:[1,0]
	v_rcp_f32_e32 v136, v136
	v_rcp_f32_e32 v137, v137
	v_rcp_f32_e32 v138, v138
	v_rcp_f32_e32 v139, v139
	v_exp_f32_e32 v144, v144
	v_exp_f32_e32 v145, v145
	v_exp_f32_e32 v146, v146
	v_exp_f32_e32 v147, v147
	v_pk_fma_f32 v[140:141], v[136:137], s[86:87], v[0:1] op_sel_hi:[1,0,0]
	v_pk_fma_f32 v[142:143], v[138:139], s[86:87], v[0:1] op_sel_hi:[1,0,0]
	v_pk_fma_f32 v[140:141], v[136:137], v[140:141], s[88:89] op_sel_hi:[1,1,0]
	v_pk_fma_f32 v[142:143], v[138:139], v[142:143], s[88:89] op_sel_hi:[1,1,0]
	v_pk_fma_f32 v[140:141], v[136:137], v[140:141], s[82:83] op_sel_hi:[1,1,0]
	v_pk_fma_f32 v[142:143], v[138:139], v[142:143], s[82:83] op_sel_hi:[1,1,0]
	v_pk_fma_f32 v[140:141], v[136:137], v[140:141], s[48:49] op_sel_hi:[1,1,0]
	v_pk_fma_f32 v[142:143], v[138:139], v[142:143], s[48:49] op_sel_hi:[1,1,0]
	v_pk_mul_f32 v[140:141], v[136:137], v[140:141]
	v_pk_mul_f32 v[142:143], v[138:139], v[142:143]
	v_pk_mul_f32 v[140:141], v[140:141], v[144:145]
	v_pk_mul_f32 v[142:143], v[142:143], v[146:147]
	v_max_f32_e32 v44, 0, v44
	v_max_f32_e32 v45, 0, v45
	v_max_f32_e32 v46, 0, v46
	v_max_f32_e32 v47, 0, v47
	v_pk_fma_f32 v[44:45], v[132:133], v[140:141], v[44:45] neg_lo:[1,0,0] neg_hi:[1,0,0]
	v_pk_fma_f32 v[46:47], v[134:135], v[142:143], v[46:47] neg_lo:[1,0,0] neg_hi:[1,0,0]
	v_pk_add_f32 v[2:3], v[2:3], v[44:45]
	v_pk_fma_f32 v[152:153], v[44:45], v[44:45], v[152:153]
	v_pk_add_f32 v[2:3], v[2:3], v[46:47]
	v_pk_fma_f32 v[152:153], v[46:47], v[46:47], v[152:153]
	v_and_b32_e32 v132, 0x7fffffff, v36
	v_and_b32_e32 v133, 0x7fffffff, v37
	v_and_b32_e32 v134, 0x7fffffff, v38
	v_and_b32_e32 v135, 0x7fffffff, v39
	v_pk_mul_f32 v[144:145], v[36:37], v[36:37]
	v_pk_mul_f32 v[146:147], v[38:39], v[38:39]
	v_pk_fma_f32 v[136:137], v[132:133], s[84:85], 1.0 op_sel_hi:[1,0,0]
	v_pk_fma_f32 v[138:139], v[134:135], s[84:85], 1.0 op_sel_hi:[1,0,0]
	v_pk_mul_f32 v[144:145], v[144:145], s[80:81] op_sel_hi:[1,0]
	v_pk_mul_f32 v[146:147], v[146:147], s[80:81] op_sel_hi:[1,0]
	v_rcp_f32_e32 v136, v136
	v_rcp_f32_e32 v137, v137
	v_rcp_f32_e32 v138, v138
	v_rcp_f32_e32 v139, v139
	v_exp_f32_e32 v144, v144
	v_exp_f32_e32 v145, v145
	v_exp_f32_e32 v146, v146
	v_exp_f32_e32 v147, v147
	v_pk_fma_f32 v[140:141], v[136:137], s[86:87], v[0:1] op_sel_hi:[1,0,0]
	v_pk_fma_f32 v[142:143], v[138:139], s[86:87], v[0:1] op_sel_hi:[1,0,0]
	v_pk_fma_f32 v[140:141], v[136:137], v[140:141], s[88:89] op_sel_hi:[1,1,0]
	v_pk_fma_f32 v[142:143], v[138:139], v[142:143], s[88:89] op_sel_hi:[1,1,0]
	v_pk_fma_f32 v[140:141], v[136:137], v[140:141], s[82:83] op_sel_hi:[1,1,0]
	v_pk_fma_f32 v[142:143], v[138:139], v[142:143], s[82:83] op_sel_hi:[1,1,0]
	v_pk_fma_f32 v[140:141], v[136:137], v[140:141], s[48:49] op_sel_hi:[1,1,0]
	v_pk_fma_f32 v[142:143], v[138:139], v[142:143], s[48:49] op_sel_hi:[1,1,0]
	v_pk_mul_f32 v[140:141], v[136:137], v[140:141]
	v_pk_mul_f32 v[142:143], v[138:139], v[142:143]
	v_pk_mul_f32 v[140:141], v[140:141], v[144:145]
	v_pk_mul_f32 v[142:143], v[142:143], v[146:147]
	v_max_f32_e32 v36, 0, v36
	v_max_f32_e32 v37, 0, v37
	v_max_f32_e32 v38, 0, v38
	v_max_f32_e32 v39, 0, v39
	v_pk_fma_f32 v[36:37], v[132:133], v[140:141], v[36:37] neg_lo:[1,0,0] neg_hi:[1,0,0]
	v_pk_fma_f32 v[38:39], v[134:135], v[142:143], v[38:39] neg_lo:[1,0,0] neg_hi:[1,0,0]
	v_pk_add_f32 v[2:3], v[2:3], v[36:37]
	v_pk_fma_f32 v[152:153], v[36:37], v[36:37], v[152:153]
	v_pk_add_f32 v[2:3], v[2:3], v[38:39]
	v_pk_fma_f32 v[152:153], v[38:39], v[38:39], v[152:153]
	v_cvt_pk_bf16_f32 v44, v44, v45
	v_cvt_pk_bf16_f32 v45, v46, v47
	v_cvt_pk_bf16_f32 v46, v36, v37
	v_cvt_pk_bf16_f32 v47, v38, v39
	global_store_dwordx4 v148, v[44:47], s[50:51] offset:256
	v_add_f32_e32 v2, v2, v3
	v_add_f32_e32 v3, v152, v153
	ds_bpermute_b32 v132, v150, v2
	ds_bpermute_b32 v133, v150, v3
	s_waitcnt lgkmcnt(0)
	v_pk_add_f32 v[2:3], v[2:3], v[132:133]
	ds_bpermute_b32 v132, v151, v2
	ds_bpermute_b32 v133, v151, v3
	s_waitcnt lgkmcnt(0)
	v_pk_add_f32 v[2:3], v[2:3], v[132:133]
	s_and_saveexec_b64 s[46:47], s[38:39]
	global_store_dwordx2 v149, v[2:3], s[66:67]
	s_mov_b64 exec, s[46:47]
	v_add_u32_e32 v148, s81, v148
	v_add_u32_e32 v149, 0x400, v149
	v_and_b32_e32 v132, 0x7fffffff, v32
	v_and_b32_e32 v133, 0x7fffffff, v33
	v_and_b32_e32 v134, 0x7fffffff, v34
	v_and_b32_e32 v135, 0x7fffffff, v35
	v_pk_mul_f32 v[144:145], v[32:33], v[32:33]
	v_pk_mul_f32 v[146:147], v[34:35], v[34:35]
	v_pk_fma_f32 v[136:137], v[132:133], s[84:85], 1.0 op_sel_hi:[1,0,0]
	v_pk_fma_f32 v[138:139], v[134:135], s[84:85], 1.0 op_sel_hi:[1,0,0]
	v_pk_mul_f32 v[144:145], v[144:145], s[80:81] op_sel_hi:[1,0]
	v_pk_mul_f32 v[146:147], v[146:147], s[80:81] op_sel_hi:[1,0]
	v_rcp_f32_e32 v136, v136
	v_rcp_f32_e32 v137, v137
	v_rcp_f32_e32 v138, v138
	v_rcp_f32_e32 v139, v139
	v_exp_f32_e32 v144, v144
	v_exp_f32_e32 v145, v145
	v_exp_f32_e32 v146, v146
	v_exp_f32_e32 v147, v147
	v_pk_fma_f32 v[140:141], v[136:137], s[86:87], v[0:1] op_sel_hi:[1,0,0]
	v_pk_fma_f32 v[142:143], v[138:139], s[86:87], v[0:1] op_sel_hi:[1,0,0]
	v_pk_fma_f32 v[140:141], v[136:137], v[140:141], s[88:89] op_sel_hi:[1,1,0]
	v_pk_fma_f32 v[142:143], v[138:139], v[142:143], s[88:89] op_sel_hi:[1,1,0]
	v_pk_fma_f32 v[140:141], v[136:137], v[140:141], s[82:83] op_sel_hi:[1,1,0]
	v_pk_fma_f32 v[142:143], v[138:139], v[142:143], s[82:83] op_sel_hi:[1,1,0]
	v_pk_fma_f32 v[140:141], v[136:137], v[140:141], s[48:49] op_sel_hi:[1,1,0]
	v_pk_fma_f32 v[142:143], v[138:139], v[142:143], s[48:49] op_sel_hi:[1,1,0]
	v_pk_mul_f32 v[140:141], v[136:137], v[140:141]
	v_pk_mul_f32 v[142:143], v[138:139], v[142:143]
	v_pk_mul_f32 v[140:141], v[140:141], v[144:145]
	v_pk_mul_f32 v[142:143], v[142:143], v[146:147]
	v_max_f32_e32 v32, 0, v32
	v_max_f32_e32 v33, 0, v33
	v_max_f32_e32 v34, 0, v34
	v_max_f32_e32 v35, 0, v35
	v_pk_fma_f32 v[32:33], v[132:133], v[140:141], v[32:33] neg_lo:[1,0,0] neg_hi:[1,0,0]
	v_pk_fma_f32 v[34:35], v[134:135], v[142:143], v[34:35] neg_lo:[1,0,0] neg_hi:[1,0,0]
	v_pk_add_f32 v[2:3], v[32:33], v[34:35]
	v_pk_mul_f32 v[152:153], v[32:33], v[32:33]
	v_pk_fma_f32 v[152:153], v[34:35], v[34:35], v[152:153]
	v_and_b32_e32 v132, 0x7fffffff, v24
	v_and_b32_e32 v133, 0x7fffffff, v25
	v_and_b32_e32 v134, 0x7fffffff, v26
	v_and_b32_e32 v135, 0x7fffffff, v27
	v_pk_mul_f32 v[144:145], v[24:25], v[24:25]
	v_pk_mul_f32 v[146:147], v[26:27], v[26:27]
	v_pk_fma_f32 v[136:137], v[132:133], s[84:85], 1.0 op_sel_hi:[1,0,0]
	v_pk_fma_f32 v[138:139], v[134:135], s[84:85], 1.0 op_sel_hi:[1,0,0]
	v_pk_mul_f32 v[144:145], v[144:145], s[80:81] op_sel_hi:[1,0]
	v_pk_mul_f32 v[146:147], v[146:147], s[80:81] op_sel_hi:[1,0]
	v_rcp_f32_e32 v136, v136
	v_rcp_f32_e32 v137, v137
	v_rcp_f32_e32 v138, v138
	v_rcp_f32_e32 v139, v139
	v_exp_f32_e32 v144, v144
	v_exp_f32_e32 v145, v145
	v_exp_f32_e32 v146, v146
	v_exp_f32_e32 v147, v147
	v_pk_fma_f32 v[140:141], v[136:137], s[86:87], v[0:1] op_sel_hi:[1,0,0]
	v_pk_fma_f32 v[142:143], v[138:139], s[86:87], v[0:1] op_sel_hi:[1,0,0]
	v_pk_fma_f32 v[140:141], v[136:137], v[140:141], s[88:89] op_sel_hi:[1,1,0]
	v_pk_fma_f32 v[142:143], v[138:139], v[142:143], s[88:89] op_sel_hi:[1,1,0]
	v_pk_fma_f32 v[140:141], v[136:137], v[140:141], s[82:83] op_sel_hi:[1,1,0]
	v_pk_fma_f32 v[142:143], v[138:139], v[142:143], s[82:83] op_sel_hi:[1,1,0]
	v_pk_fma_f32 v[140:141], v[136:137], v[140:141], s[48:49] op_sel_hi:[1,1,0]
	v_pk_fma_f32 v[142:143], v[138:139], v[142:143], s[48:49] op_sel_hi:[1,1,0]
	v_pk_mul_f32 v[140:141], v[136:137], v[140:141]
	v_pk_mul_f32 v[142:143], v[138:139], v[142:143]
	v_pk_mul_f32 v[140:141], v[140:141], v[144:145]
	v_pk_mul_f32 v[142:143], v[142:143], v[146:147]
	v_max_f32_e32 v24, 0, v24
	v_max_f32_e32 v25, 0, v25
	v_max_f32_e32 v26, 0, v26
	v_max_f32_e32 v27, 0, v27
	v_pk_fma_f32 v[24:25], v[132:133], v[140:141], v[24:25] neg_lo:[1,0,0] neg_hi:[1,0,0]
	v_pk_fma_f32 v[26:27], v[134:135], v[142:143], v[26:27] neg_lo:[1,0,0] neg_hi:[1,0,0]
	v_pk_add_f32 v[2:3], v[2:3], v[24:25]
	v_pk_fma_f32 v[152:153], v[24:25], v[24:25], v[152:153]
	v_pk_add_f32 v[2:3], v[2:3], v[26:27]
	v_pk_fma_f32 v[152:153], v[26:27], v[26:27], v[152:153]
	v_cvt_pk_bf16_f32 v32, v32, v33
	v_cvt_pk_bf16_f32 v33, v34, v35
	v_cvt_pk_bf16_f32 v34, v24, v25
	v_cvt_pk_bf16_f32 v35, v26, v27
	global_store_dwordx4 v148, v[32:35], s[50:51]
	v_and_b32_e32 v132, 0x7fffffff, v16
	v_and_b32_e32 v133, 0x7fffffff, v17
	v_and_b32_e32 v134, 0x7fffffff, v18
	v_and_b32_e32 v135, 0x7fffffff, v19
	v_pk_mul_f32 v[144:145], v[16:17], v[16:17]
	v_pk_mul_f32 v[146:147], v[18:19], v[18:19]
	v_pk_fma_f32 v[136:137], v[132:133], s[84:85], 1.0 op_sel_hi:[1,0,0]
	v_pk_fma_f32 v[138:139], v[134:135], s[84:85], 1.0 op_sel_hi:[1,0,0]
	v_pk_mul_f32 v[144:145], v[144:145], s[80:81] op_sel_hi:[1,0]
	v_pk_mul_f32 v[146:147], v[146:147], s[80:81] op_sel_hi:[1,0]
	v_rcp_f32_e32 v136, v136
	v_rcp_f32_e32 v137, v137
	v_rcp_f32_e32 v138, v138
	v_rcp_f32_e32 v139, v139
	v_exp_f32_e32 v144, v144
	v_exp_f32_e32 v145, v145
	v_exp_f32_e32 v146, v146
	v_exp_f32_e32 v147, v147
	v_pk_fma_f32 v[140:141], v[136:137], s[86:87], v[0:1] op_sel_hi:[1,0,0]
	v_pk_fma_f32 v[142:143], v[138:139], s[86:87], v[0:1] op_sel_hi:[1,0,0]
	v_pk_fma_f32 v[140:141], v[136:137], v[140:141], s[88:89] op_sel_hi:[1,1,0]
	v_pk_fma_f32 v[142:143], v[138:139], v[142:143], s[88:89] op_sel_hi:[1,1,0]
	v_pk_fma_f32 v[140:141], v[136:137], v[140:141], s[82:83] op_sel_hi:[1,1,0]
	v_pk_fma_f32 v[142:143], v[138:139], v[142:143], s[82:83] op_sel_hi:[1,1,0]
	v_pk_fma_f32 v[140:141], v[136:137], v[140:141], s[48:49] op_sel_hi:[1,1,0]
	v_pk_fma_f32 v[142:143], v[138:139], v[142:143], s[48:49] op_sel_hi:[1,1,0]
	v_pk_mul_f32 v[140:141], v[136:137], v[140:141]
	v_pk_mul_f32 v[142:143], v[138:139], v[142:143]
	v_pk_mul_f32 v[140:141], v[140:141], v[144:145]
	v_pk_mul_f32 v[142:143], v[142:143], v[146:147]
	v_max_f32_e32 v16, 0, v16
	v_max_f32_e32 v17, 0, v17
	v_max_f32_e32 v18, 0, v18
	v_max_f32_e32 v19, 0, v19
	v_pk_fma_f32 v[16:17], v[132:133], v[140:141], v[16:17] neg_lo:[1,0,0] neg_hi:[1,0,0]
	v_pk_fma_f32 v[18:19], v[134:135], v[142:143], v[18:19] neg_lo:[1,0,0] neg_hi:[1,0,0]
	v_pk_add_f32 v[2:3], v[2:3], v[16:17]
	v_pk_fma_f32 v[152:153], v[16:17], v[16:17], v[152:153]
	v_pk_add_f32 v[2:3], v[2:3], v[18:19]
	v_pk_fma_f32 v[152:153], v[18:19], v[18:19], v[152:153]
	v_and_b32_e32 v132, 0x7fffffff, v8
	v_and_b32_e32 v133, 0x7fffffff, v9
	v_and_b32_e32 v134, 0x7fffffff, v10
	v_and_b32_e32 v135, 0x7fffffff, v11
	v_pk_mul_f32 v[144:145], v[8:9], v[8:9]
	v_pk_mul_f32 v[146:147], v[10:11], v[10:11]
	v_pk_fma_f32 v[136:137], v[132:133], s[84:85], 1.0 op_sel_hi:[1,0,0]
	v_pk_fma_f32 v[138:139], v[134:135], s[84:85], 1.0 op_sel_hi:[1,0,0]
	v_pk_mul_f32 v[144:145], v[144:145], s[80:81] op_sel_hi:[1,0]
	v_pk_mul_f32 v[146:147], v[146:147], s[80:81] op_sel_hi:[1,0]
	v_rcp_f32_e32 v136, v136
	v_rcp_f32_e32 v137, v137
	v_rcp_f32_e32 v138, v138
	v_rcp_f32_e32 v139, v139
	v_exp_f32_e32 v144, v144
	v_exp_f32_e32 v145, v145
	v_exp_f32_e32 v146, v146
	v_exp_f32_e32 v147, v147
	v_pk_fma_f32 v[140:141], v[136:137], s[86:87], v[0:1] op_sel_hi:[1,0,0]
	v_pk_fma_f32 v[142:143], v[138:139], s[86:87], v[0:1] op_sel_hi:[1,0,0]
	v_pk_fma_f32 v[140:141], v[136:137], v[140:141], s[88:89] op_sel_hi:[1,1,0]
	v_pk_fma_f32 v[142:143], v[138:139], v[142:143], s[88:89] op_sel_hi:[1,1,0]
	v_pk_fma_f32 v[140:141], v[136:137], v[140:141], s[82:83] op_sel_hi:[1,1,0]
	v_pk_fma_f32 v[142:143], v[138:139], v[142:143], s[82:83] op_sel_hi:[1,1,0]
	v_pk_fma_f32 v[140:141], v[136:137], v[140:141], s[48:49] op_sel_hi:[1,1,0]
	v_pk_fma_f32 v[142:143], v[138:139], v[142:143], s[48:49] op_sel_hi:[1,1,0]
	v_pk_mul_f32 v[140:141], v[136:137], v[140:141]
	v_pk_mul_f32 v[142:143], v[138:139], v[142:143]
	v_pk_mul_f32 v[140:141], v[140:141], v[144:145]
	v_pk_mul_f32 v[142:143], v[142:143], v[146:147]
	v_max_f32_e32 v8, 0, v8
	v_max_f32_e32 v9, 0, v9
	v_max_f32_e32 v10, 0, v10
	v_max_f32_e32 v11, 0, v11
	v_pk_fma_f32 v[8:9], v[132:133], v[140:141], v[8:9] neg_lo:[1,0,0] neg_hi:[1,0,0]
	v_pk_fma_f32 v[10:11], v[134:135], v[142:143], v[10:11] neg_lo:[1,0,0] neg_hi:[1,0,0]
	v_pk_add_f32 v[2:3], v[2:3], v[8:9]
	v_pk_fma_f32 v[152:153], v[8:9], v[8:9], v[152:153]
	v_pk_add_f32 v[2:3], v[2:3], v[10:11]
	v_pk_fma_f32 v[152:153], v[10:11], v[10:11], v[152:153]
	v_cvt_pk_bf16_f32 v16, v16, v17
	v_cvt_pk_bf16_f32 v17, v18, v19
	v_cvt_pk_bf16_f32 v18, v8, v9
	v_cvt_pk_bf16_f32 v19, v10, v11
	global_store_dwordx4 v148, v[16:19], s[50:51] offset:256
	v_add_f32_e32 v2, v2, v3
	v_add_f32_e32 v3, v152, v153
	ds_bpermute_b32 v132, v150, v2
	ds_bpermute_b32 v133, v150, v3
	s_waitcnt lgkmcnt(0)
	v_pk_add_f32 v[2:3], v[2:3], v[132:133]
	ds_bpermute_b32 v132, v151, v2
	ds_bpermute_b32 v133, v151, v3
	s_waitcnt lgkmcnt(0)
	v_pk_add_f32 v[2:3], v[2:3], v[132:133]
	s_and_saveexec_b64 s[46:47], s[38:39]
	global_store_dwordx2 v149, v[2:3], s[66:67]
	s_mov_b64 exec, s[46:47]
	v_add_u32_e32 v148, s81, v148
	v_add_u32_e32 v149, 0x400, v149
	v_and_b32_e32 v132, 0x7fffffff, v28
	v_and_b32_e32 v133, 0x7fffffff, v29
	v_and_b32_e32 v134, 0x7fffffff, v30
	v_and_b32_e32 v135, 0x7fffffff, v31
	v_pk_mul_f32 v[144:145], v[28:29], v[28:29]
	v_pk_mul_f32 v[146:147], v[30:31], v[30:31]
	v_pk_fma_f32 v[136:137], v[132:133], s[84:85], 1.0 op_sel_hi:[1,0,0]
	v_pk_fma_f32 v[138:139], v[134:135], s[84:85], 1.0 op_sel_hi:[1,0,0]
	v_pk_mul_f32 v[144:145], v[144:145], s[80:81] op_sel_hi:[1,0]
	v_pk_mul_f32 v[146:147], v[146:147], s[80:81] op_sel_hi:[1,0]
	v_rcp_f32_e32 v136, v136
	v_rcp_f32_e32 v137, v137
	v_rcp_f32_e32 v138, v138
	v_rcp_f32_e32 v139, v139
	v_exp_f32_e32 v144, v144
	v_exp_f32_e32 v145, v145
	v_exp_f32_e32 v146, v146
	v_exp_f32_e32 v147, v147
	v_pk_fma_f32 v[140:141], v[136:137], s[86:87], v[0:1] op_sel_hi:[1,0,0]
	v_pk_fma_f32 v[142:143], v[138:139], s[86:87], v[0:1] op_sel_hi:[1,0,0]
	v_pk_fma_f32 v[140:141], v[136:137], v[140:141], s[88:89] op_sel_hi:[1,1,0]
	v_pk_fma_f32 v[142:143], v[138:139], v[142:143], s[88:89] op_sel_hi:[1,1,0]
	v_pk_fma_f32 v[140:141], v[136:137], v[140:141], s[82:83] op_sel_hi:[1,1,0]
	v_pk_fma_f32 v[142:143], v[138:139], v[142:143], s[82:83] op_sel_hi:[1,1,0]
	v_pk_fma_f32 v[140:141], v[136:137], v[140:141], s[48:49] op_sel_hi:[1,1,0]
	v_pk_fma_f32 v[142:143], v[138:139], v[142:143], s[48:49] op_sel_hi:[1,1,0]
	v_pk_mul_f32 v[140:141], v[136:137], v[140:141]
	v_pk_mul_f32 v[142:143], v[138:139], v[142:143]
	v_pk_mul_f32 v[140:141], v[140:141], v[144:145]
	v_pk_mul_f32 v[142:143], v[142:143], v[146:147]
	v_max_f32_e32 v28, 0, v28
	v_max_f32_e32 v29, 0, v29
	v_max_f32_e32 v30, 0, v30
	v_max_f32_e32 v31, 0, v31
	v_pk_fma_f32 v[28:29], v[132:133], v[140:141], v[28:29] neg_lo:[1,0,0] neg_hi:[1,0,0]
	v_pk_fma_f32 v[30:31], v[134:135], v[142:143], v[30:31] neg_lo:[1,0,0] neg_hi:[1,0,0]
	v_pk_add_f32 v[2:3], v[28:29], v[30:31]
	v_pk_mul_f32 v[152:153], v[28:29], v[28:29]
	v_pk_fma_f32 v[152:153], v[30:31], v[30:31], v[152:153]
	v_and_b32_e32 v132, 0x7fffffff, v20
	v_and_b32_e32 v133, 0x7fffffff, v21
	v_and_b32_e32 v134, 0x7fffffff, v22
	v_and_b32_e32 v135, 0x7fffffff, v23
	v_pk_mul_f32 v[144:145], v[20:21], v[20:21]
	v_pk_mul_f32 v[146:147], v[22:23], v[22:23]
	v_pk_fma_f32 v[136:137], v[132:133], s[84:85], 1.0 op_sel_hi:[1,0,0]
	v_pk_fma_f32 v[138:139], v[134:135], s[84:85], 1.0 op_sel_hi:[1,0,0]
	v_pk_mul_f32 v[144:145], v[144:145], s[80:81] op_sel_hi:[1,0]
	v_pk_mul_f32 v[146:147], v[146:147], s[80:81] op_sel_hi:[1,0]
	v_rcp_f32_e32 v136, v136
	v_rcp_f32_e32 v137, v137
	v_rcp_f32_e32 v138, v138
	v_rcp_f32_e32 v139, v139
	v_exp_f32_e32 v144, v144
	v_exp_f32_e32 v145, v145
	v_exp_f32_e32 v146, v146
	v_exp_f32_e32 v147, v147
	v_pk_fma_f32 v[140:141], v[136:137], s[86:87], v[0:1] op_sel_hi:[1,0,0]
	v_pk_fma_f32 v[142:143], v[138:139], s[86:87], v[0:1] op_sel_hi:[1,0,0]
	v_pk_fma_f32 v[140:141], v[136:137], v[140:141], s[88:89] op_sel_hi:[1,1,0]
	v_pk_fma_f32 v[142:143], v[138:139], v[142:143], s[88:89] op_sel_hi:[1,1,0]
	v_pk_fma_f32 v[140:141], v[136:137], v[140:141], s[82:83] op_sel_hi:[1,1,0]
	v_pk_fma_f32 v[142:143], v[138:139], v[142:143], s[82:83] op_sel_hi:[1,1,0]
	v_pk_fma_f32 v[140:141], v[136:137], v[140:141], s[48:49] op_sel_hi:[1,1,0]
	v_pk_fma_f32 v[142:143], v[138:139], v[142:143], s[48:49] op_sel_hi:[1,1,0]
	v_pk_mul_f32 v[140:141], v[136:137], v[140:141]
	v_pk_mul_f32 v[142:143], v[138:139], v[142:143]
	v_pk_mul_f32 v[140:141], v[140:141], v[144:145]
	v_pk_mul_f32 v[142:143], v[142:143], v[146:147]
	v_max_f32_e32 v20, 0, v20
	v_max_f32_e32 v21, 0, v21
	v_max_f32_e32 v22, 0, v22
	v_max_f32_e32 v23, 0, v23
	v_pk_fma_f32 v[20:21], v[132:133], v[140:141], v[20:21] neg_lo:[1,0,0] neg_hi:[1,0,0]
	v_pk_fma_f32 v[22:23], v[134:135], v[142:143], v[22:23] neg_lo:[1,0,0] neg_hi:[1,0,0]
	v_pk_add_f32 v[2:3], v[2:3], v[20:21]
	v_pk_fma_f32 v[152:153], v[20:21], v[20:21], v[152:153]
	v_pk_add_f32 v[2:3], v[2:3], v[22:23]
	v_pk_fma_f32 v[152:153], v[22:23], v[22:23], v[152:153]
	v_cvt_pk_bf16_f32 v28, v28, v29
	v_cvt_pk_bf16_f32 v29, v30, v31
	v_cvt_pk_bf16_f32 v30, v20, v21
	v_cvt_pk_bf16_f32 v31, v22, v23
	global_store_dwordx4 v148, v[28:31], s[50:51]
	v_and_b32_e32 v132, 0x7fffffff, v12
	v_and_b32_e32 v133, 0x7fffffff, v13
	v_and_b32_e32 v134, 0x7fffffff, v14
	v_and_b32_e32 v135, 0x7fffffff, v15
	v_pk_mul_f32 v[144:145], v[12:13], v[12:13]
	v_pk_mul_f32 v[146:147], v[14:15], v[14:15]
	v_pk_fma_f32 v[136:137], v[132:133], s[84:85], 1.0 op_sel_hi:[1,0,0]
	v_pk_fma_f32 v[138:139], v[134:135], s[84:85], 1.0 op_sel_hi:[1,0,0]
	v_pk_mul_f32 v[144:145], v[144:145], s[80:81] op_sel_hi:[1,0]
	v_pk_mul_f32 v[146:147], v[146:147], s[80:81] op_sel_hi:[1,0]
	v_rcp_f32_e32 v136, v136
	v_rcp_f32_e32 v137, v137
	v_rcp_f32_e32 v138, v138
	v_rcp_f32_e32 v139, v139
	v_exp_f32_e32 v144, v144
	v_exp_f32_e32 v145, v145
	v_exp_f32_e32 v146, v146
	v_exp_f32_e32 v147, v147
	v_pk_fma_f32 v[140:141], v[136:137], s[86:87], v[0:1] op_sel_hi:[1,0,0]
	v_pk_fma_f32 v[142:143], v[138:139], s[86:87], v[0:1] op_sel_hi:[1,0,0]
	v_pk_fma_f32 v[140:141], v[136:137], v[140:141], s[88:89] op_sel_hi:[1,1,0]
	v_pk_fma_f32 v[142:143], v[138:139], v[142:143], s[88:89] op_sel_hi:[1,1,0]
	v_pk_fma_f32 v[140:141], v[136:137], v[140:141], s[82:83] op_sel_hi:[1,1,0]
	v_pk_fma_f32 v[142:143], v[138:139], v[142:143], s[82:83] op_sel_hi:[1,1,0]
	v_pk_fma_f32 v[140:141], v[136:137], v[140:141], s[48:49] op_sel_hi:[1,1,0]
	v_pk_fma_f32 v[142:143], v[138:139], v[142:143], s[48:49] op_sel_hi:[1,1,0]
	v_pk_mul_f32 v[140:141], v[136:137], v[140:141]
	v_pk_mul_f32 v[142:143], v[138:139], v[142:143]
	v_pk_mul_f32 v[140:141], v[140:141], v[144:145]
	v_pk_mul_f32 v[142:143], v[142:143], v[146:147]
	v_max_f32_e32 v12, 0, v12
	v_max_f32_e32 v13, 0, v13
	v_max_f32_e32 v14, 0, v14
	v_max_f32_e32 v15, 0, v15
	v_pk_fma_f32 v[12:13], v[132:133], v[140:141], v[12:13] neg_lo:[1,0,0] neg_hi:[1,0,0]
	v_pk_fma_f32 v[14:15], v[134:135], v[142:143], v[14:15] neg_lo:[1,0,0] neg_hi:[1,0,0]
	v_pk_add_f32 v[2:3], v[2:3], v[12:13]
	v_pk_fma_f32 v[152:153], v[12:13], v[12:13], v[152:153]
	v_pk_add_f32 v[2:3], v[2:3], v[14:15]
	v_pk_fma_f32 v[152:153], v[14:15], v[14:15], v[152:153]
	v_and_b32_e32 v132, 0x7fffffff, v4
	v_and_b32_e32 v133, 0x7fffffff, v5
	v_and_b32_e32 v134, 0x7fffffff, v6
	v_and_b32_e32 v135, 0x7fffffff, v7
	v_pk_mul_f32 v[144:145], v[4:5], v[4:5]
	v_pk_mul_f32 v[146:147], v[6:7], v[6:7]
	v_pk_fma_f32 v[136:137], v[132:133], s[84:85], 1.0 op_sel_hi:[1,0,0]
	v_pk_fma_f32 v[138:139], v[134:135], s[84:85], 1.0 op_sel_hi:[1,0,0]
	v_pk_mul_f32 v[144:145], v[144:145], s[80:81] op_sel_hi:[1,0]
	v_pk_mul_f32 v[146:147], v[146:147], s[80:81] op_sel_hi:[1,0]
	v_rcp_f32_e32 v136, v136
	v_rcp_f32_e32 v137, v137
	v_rcp_f32_e32 v138, v138
	v_rcp_f32_e32 v139, v139
	v_exp_f32_e32 v144, v144
	v_exp_f32_e32 v145, v145
	v_exp_f32_e32 v146, v146
	v_exp_f32_e32 v147, v147
	v_pk_fma_f32 v[140:141], v[136:137], s[86:87], v[0:1] op_sel_hi:[1,0,0]
	v_pk_fma_f32 v[142:143], v[138:139], s[86:87], v[0:1] op_sel_hi:[1,0,0]
	v_pk_fma_f32 v[140:141], v[136:137], v[140:141], s[88:89] op_sel_hi:[1,1,0]
	v_pk_fma_f32 v[142:143], v[138:139], v[142:143], s[88:89] op_sel_hi:[1,1,0]
	v_pk_fma_f32 v[140:141], v[136:137], v[140:141], s[82:83] op_sel_hi:[1,1,0]
	v_pk_fma_f32 v[142:143], v[138:139], v[142:143], s[82:83] op_sel_hi:[1,1,0]
	v_pk_fma_f32 v[140:141], v[136:137], v[140:141], s[48:49] op_sel_hi:[1,1,0]
	v_pk_fma_f32 v[142:143], v[138:139], v[142:143], s[48:49] op_sel_hi:[1,1,0]
	v_pk_mul_f32 v[140:141], v[136:137], v[140:141]
	v_pk_mul_f32 v[142:143], v[138:139], v[142:143]
	v_pk_mul_f32 v[140:141], v[140:141], v[144:145]
	v_pk_mul_f32 v[142:143], v[142:143], v[146:147]
	v_max_f32_e32 v4, 0, v4
	v_max_f32_e32 v5, 0, v5
	v_max_f32_e32 v6, 0, v6
	v_max_f32_e32 v7, 0, v7
	v_pk_fma_f32 v[4:5], v[132:133], v[140:141], v[4:5] neg_lo:[1,0,0] neg_hi:[1,0,0]
	v_pk_fma_f32 v[6:7], v[134:135], v[142:143], v[6:7] neg_lo:[1,0,0] neg_hi:[1,0,0]
	v_pk_add_f32 v[2:3], v[2:3], v[4:5]
	v_pk_fma_f32 v[152:153], v[4:5], v[4:5], v[152:153]
	v_pk_add_f32 v[2:3], v[2:3], v[6:7]
	v_pk_fma_f32 v[152:153], v[6:7], v[6:7], v[152:153]
	v_cvt_pk_bf16_f32 v12, v12, v13
	v_cvt_pk_bf16_f32 v13, v14, v15
	v_cvt_pk_bf16_f32 v14, v4, v5
	v_cvt_pk_bf16_f32 v15, v6, v7
	global_store_dwordx4 v148, v[12:15], s[50:51] offset:256
	v_add_f32_e32 v2, v2, v3
	v_add_f32_e32 v3, v152, v153
	ds_bpermute_b32 v132, v150, v2
	ds_bpermute_b32 v133, v150, v3
	s_waitcnt lgkmcnt(0)
	v_pk_add_f32 v[2:3], v[2:3], v[132:133]
	ds_bpermute_b32 v132, v151, v2
	ds_bpermute_b32 v133, v151, v3
	s_waitcnt lgkmcnt(0)
	v_pk_add_f32 v[2:3], v[2:3], v[132:133]
	s_and_saveexec_b64 s[46:47], s[38:39]
	global_store_dwordx2 v149, v[2:3], s[66:67]
	s_mov_b64 exec, s[46:47]
	s_branch .LBB0_326
.Lepi_gelu6_e:
	v_and_b32_e32 v132, 0x7fffffff, v128
	v_and_b32_e32 v133, 0x7fffffff, v129
	v_and_b32_e32 v134, 0x7fffffff, v130
	v_and_b32_e32 v135, 0x7fffffff, v131
	v_pk_mul_f32 v[144:145], v[128:129], v[128:129]
	v_pk_mul_f32 v[146:147], v[130:131], v[130:131]
	v_pk_fma_f32 v[136:137], v[132:133], s[84:85], 1.0 op_sel_hi:[1,0,0]
	v_pk_fma_f32 v[138:139], v[134:135], s[84:85], 1.0 op_sel_hi:[1,0,0]
	v_pk_mul_f32 v[144:145], v[144:145], s[80:81] op_sel_hi:[1,0]
	v_pk_mul_f32 v[146:147], v[146:147], s[80:81] op_sel_hi:[1,0]
	v_rcp_f32_e32 v136, v136
	v_rcp_f32_e32 v137, v137
	v_rcp_f32_e32 v138, v138
	v_rcp_f32_e32 v139, v139
	v_exp_f32_e32 v144, v144
	v_exp_f32_e32 v145, v145
	v_exp_f32_e32 v146, v146
	v_exp_f32_e32 v147, v147
	v_pk_fma_f32 v[140:141], v[136:137], s[86:87], v[0:1] op_sel_hi:[1,0,0]
	v_pk_fma_f32 v[142:143], v[138:139], s[86:87], v[0:1] op_sel_hi:[1,0,0]
	v_pk_fma_f32 v[140:141], v[136:137], v[140:141], s[88:89] op_sel_hi:[1,1,0]
	v_pk_fma_f32 v[142:143], v[138:139], v[142:143], s[88:89] op_sel_hi:[1,1,0]
	v_pk_fma_f32 v[140:141], v[136:137], v[140:141], s[82:83] op_sel_hi:[1,1,0]
	v_pk_fma_f32 v[142:143], v[138:139], v[142:143], s[82:83] op_sel_hi:[1,1,0]
	v_pk_fma_f32 v[140:141], v[136:137], v[140:141], s[48:49] op_sel_hi:[1,1,0]
	v_pk_fma_f32 v[142:143], v[138:139], v[142:143], s[48:49] op_sel_hi:[1,1,0]
	v_pk_mul_f32 v[140:141], v[136:137], v[140:141]
	v_pk_mul_f32 v[142:143], v[138:139], v[142:143]
	v_pk_mul_f32 v[140:141], v[140:141], v[144:145]
	v_pk_mul_f32 v[142:143], v[142:143], v[146:147]
	v_max_f32_e32 v128, 0, v128
	v_max_f32_e32 v129, 0, v129
	v_max_f32_e32 v130, 0, v130
	v_max_f32_e32 v131, 0, v131
	v_pk_fma_f32 v[128:129], v[132:133], v[140:141], v[128:129] neg_lo:[1,0,0] neg_hi:[1,0,0]
	v_pk_fma_f32 v[130:131], v[134:135], v[142:143], v[130:131] neg_lo:[1,0,0] neg_hi:[1,0,0]
	v_and_b32_e32 v132, 0x7fffffff, v120
	v_and_b32_e32 v133, 0x7fffffff, v121
	v_and_b32_e32 v134, 0x7fffffff, v122
	v_and_b32_e32 v135, 0x7fffffff, v123
	v_pk_mul_f32 v[144:145], v[120:121], v[120:121]
	v_pk_mul_f32 v[146:147], v[122:123], v[122:123]
	v_pk_fma_f32 v[136:137], v[132:133], s[84:85], 1.0 op_sel_hi:[1,0,0]
	v_pk_fma_f32 v[138:139], v[134:135], s[84:85], 1.0 op_sel_hi:[1,0,0]
	v_pk_mul_f32 v[144:145], v[144:145], s[80:81] op_sel_hi:[1,0]
	v_pk_mul_f32 v[146:147], v[146:147], s[80:81] op_sel_hi:[1,0]
	v_rcp_f32_e32 v136, v136
	v_rcp_f32_e32 v137, v137
	v_rcp_f32_e32 v138, v138
	v_rcp_f32_e32 v139, v139
	v_exp_f32_e32 v144, v144
	v_exp_f32_e32 v145, v145
	v_exp_f32_e32 v146, v146
	v_exp_f32_e32 v147, v147
	v_pk_fma_f32 v[140:141], v[136:137], s[86:87], v[0:1] op_sel_hi:[1,0,0]
	v_pk_fma_f32 v[142:143], v[138:139], s[86:87], v[0:1] op_sel_hi:[1,0,0]
	v_pk_fma_f32 v[140:141], v[136:137], v[140:141], s[88:89] op_sel_hi:[1,1,0]
	v_pk_fma_f32 v[142:143], v[138:139], v[142:143], s[88:89] op_sel_hi:[1,1,0]
	v_pk_fma_f32 v[140:141], v[136:137], v[140:141], s[82:83] op_sel_hi:[1,1,0]
	v_pk_fma_f32 v[142:143], v[138:139], v[142:143], s[82:83] op_sel_hi:[1,1,0]
	v_pk_fma_f32 v[140:141], v[136:137], v[140:141], s[48:49] op_sel_hi:[1,1,0]
	v_pk_fma_f32 v[142:143], v[138:139], v[142:143], s[48:49] op_sel_hi:[1,1,0]
	v_pk_mul_f32 v[140:141], v[136:137], v[140:141]
	v_pk_mul_f32 v[142:143], v[138:139], v[142:143]
	v_pk_mul_f32 v[140:141], v[140:141], v[144:145]
	v_pk_mul_f32 v[142:143], v[142:143], v[146:147]
	v_max_f32_e32 v120, 0, v120
	v_max_f32_e32 v121, 0, v121
	v_max_f32_e32 v122, 0, v122
	v_max_f32_e32 v123, 0, v123
	v_pk_fma_f32 v[120:121], v[132:133], v[140:141], v[120:121] neg_lo:[1,0,0] neg_hi:[1,0,0]
	v_pk_fma_f32 v[122:123], v[134:135], v[142:143], v[122:123] neg_lo:[1,0,0] neg_hi:[1,0,0]
	v_cvt_pk_bf16_f32 v128, v128, v129
	v_cvt_pk_bf16_f32 v129, v130, v131
	v_cvt_pk_bf16_f32 v130, v120, v121
	v_cvt_pk_bf16_f32 v131, v122, v123
	global_store_dwordx4 v148, v[128:131], s[50:51]
	v_and_b32_e32 v132, 0x7fffffff, v112
	v_and_b32_e32 v133, 0x7fffffff, v113
	v_and_b32_e32 v134, 0x7fffffff, v114
	v_and_b32_e32 v135, 0x7fffffff, v115
	v_pk_mul_f32 v[144:145], v[112:113], v[112:113]
	v_pk_mul_f32 v[146:147], v[114:115], v[114:115]
	v_pk_fma_f32 v[136:137], v[132:133], s[84:85], 1.0 op_sel_hi:[1,0,0]
	v_pk_fma_f32 v[138:139], v[134:135], s[84:85], 1.0 op_sel_hi:[1,0,0]
	v_pk_mul_f32 v[144:145], v[144:145], s[80:81] op_sel_hi:[1,0]
	v_pk_mul_f32 v[146:147], v[146:147], s[80:81] op_sel_hi:[1,0]
	v_rcp_f32_e32 v136, v136
	v_rcp_f32_e32 v137, v137
	v_rcp_f32_e32 v138, v138
	v_rcp_f32_e32 v139, v139
	v_exp_f32_e32 v144, v144
	v_exp_f32_e32 v145, v145
	v_exp_f32_e32 v146, v146
	v_exp_f32_e32 v147, v147
	v_pk_fma_f32 v[140:141], v[136:137], s[86:87], v[0:1] op_sel_hi:[1,0,0]
	v_pk_fma_f32 v[142:143], v[138:139], s[86:87], v[0:1] op_sel_hi:[1,0,0]
	v_pk_fma_f32 v[140:141], v[136:137], v[140:141], s[88:89] op_sel_hi:[1,1,0]
	v_pk_fma_f32 v[142:143], v[138:139], v[142:143], s[88:89] op_sel_hi:[1,1,0]
	v_pk_fma_f32 v[140:141], v[136:137], v[140:141], s[82:83] op_sel_hi:[1,1,0]
	v_pk_fma_f32 v[142:143], v[138:139], v[142:143], s[82:83] op_sel_hi:[1,1,0]
	v_pk_fma_f32 v[140:141], v[136:137], v[140:141], s[48:49] op_sel_hi:[1,1,0]
	v_pk_fma_f32 v[142:143], v[138:139], v[142:143], s[48:49] op_sel_hi:[1,1,0]
	v_pk_mul_f32 v[140:141], v[136:137], v[140:141]
	v_pk_mul_f32 v[142:143], v[138:139], v[142:143]
	v_pk_mul_f32 v[140:141], v[140:141], v[144:145]
	v_pk_mul_f32 v[142:143], v[142:143], v[146:147]
	v_max_f32_e32 v112, 0, v112
	v_max_f32_e32 v113, 0, v113
	v_max_f32_e32 v114, 0, v114
	v_max_f32_e32 v115, 0, v115
	v_pk_fma_f32 v[112:113], v[132:133], v[140:141], v[112:113] neg_lo:[1,0,0] neg_hi:[1,0,0]
	v_pk_fma_f32 v[114:115], v[134:135], v[142:143], v[114:115] neg_lo:[1,0,0] neg_hi:[1,0,0]
	v_and_b32_e32 v132, 0x7fffffff, v104
	v_and_b32_e32 v133, 0x7fffffff, v105
	v_and_b32_e32 v134, 0x7fffffff, v106
	v_and_b32_e32 v135, 0x7fffffff, v107
	v_pk_mul_f32 v[144:145], v[104:105], v[104:105]
	v_pk_mul_f32 v[146:147], v[106:107], v[106:107]
	v_pk_fma_f32 v[136:137], v[132:133], s[84:85], 1.0 op_sel_hi:[1,0,0]
	v_pk_fma_f32 v[138:139], v[134:135], s[84:85], 1.0 op_sel_hi:[1,0,0]
	v_pk_mul_f32 v[144:145], v[144:145], s[80:81] op_sel_hi:[1,0]
	v_pk_mul_f32 v[146:147], v[146:147], s[80:81] op_sel_hi:[1,0]
	v_rcp_f32_e32 v136, v136
	v_rcp_f32_e32 v137, v137
	v_rcp_f32_e32 v138, v138
	v_rcp_f32_e32 v139, v139
	v_exp_f32_e32 v144, v144
	v_exp_f32_e32 v145, v145
	v_exp_f32_e32 v146, v146
	v_exp_f32_e32 v147, v147
	v_pk_fma_f32 v[140:141], v[136:137], s[86:87], v[0:1] op_sel_hi:[1,0,0]
	v_pk_fma_f32 v[142:143], v[138:139], s[86:87], v[0:1] op_sel_hi:[1,0,0]
	v_pk_fma_f32 v[140:141], v[136:137], v[140:141], s[88:89] op_sel_hi:[1,1,0]
	v_pk_fma_f32 v[142:143], v[138:139], v[142:143], s[88:89] op_sel_hi:[1,1,0]
	v_pk_fma_f32 v[140:141], v[136:137], v[140:141], s[82:83] op_sel_hi:[1,1,0]
	v_pk_fma_f32 v[142:143], v[138:139], v[142:143], s[82:83] op_sel_hi:[1,1,0]
	v_pk_fma_f32 v[140:141], v[136:137], v[140:141], s[48:49] op_sel_hi:[1,1,0]
	v_pk_fma_f32 v[142:143], v[138:139], v[142:143], s[48:49] op_sel_hi:[1,1,0]
	v_pk_mul_f32 v[140:141], v[136:137], v[140:141]
	v_pk_mul_f32 v[142:143], v[138:139], v[142:143]
	v_pk_mul_f32 v[140:141], v[140:141], v[144:145]
	v_pk_mul_f32 v[142:143], v[142:143], v[146:147]
	v_max_f32_e32 v104, 0, v104
	v_max_f32_e32 v105, 0, v105
	v_max_f32_e32 v106, 0, v106
	v_max_f32_e32 v107, 0, v107
	v_pk_fma_f32 v[104:105], v[132:133], v[140:141], v[104:105] neg_lo:[1,0,0] neg_hi:[1,0,0]
	v_pk_fma_f32 v[106:107], v[134:135], v[142:143], v[106:107] neg_lo:[1,0,0] neg_hi:[1,0,0]
	v_cvt_pk_bf16_f32 v112, v112, v113
	v_cvt_pk_bf16_f32 v113, v114, v115
	v_cvt_pk_bf16_f32 v114, v104, v105
	v_cvt_pk_bf16_f32 v115, v106, v107
	global_store_dwordx4 v148, v[112:115], s[50:51] offset:256
	v_add_u32_e32 v148, s81, v148
	v_and_b32_e32 v132, 0x7fffffff, v124
	v_and_b32_e32 v133, 0x7fffffff, v125
	v_and_b32_e32 v134, 0x7fffffff, v126
	v_and_b32_e32 v135, 0x7fffffff, v127
	v_pk_mul_f32 v[144:145], v[124:125], v[124:125]
	v_pk_mul_f32 v[146:147], v[126:127], v[126:127]
	v_pk_fma_f32 v[136:137], v[132:133], s[84:85], 1.0 op_sel_hi:[1,0,0]
	v_pk_fma_f32 v[138:139], v[134:135], s[84:85], 1.0 op_sel_hi:[1,0,0]
	v_pk_mul_f32 v[144:145], v[144:145], s[80:81] op_sel_hi:[1,0]
	v_pk_mul_f32 v[146:147], v[146:147], s[80:81] op_sel_hi:[1,0]
	v_rcp_f32_e32 v136, v136
	v_rcp_f32_e32 v137, v137
	v_rcp_f32_e32 v138, v138
	v_rcp_f32_e32 v139, v139
	v_exp_f32_e32 v144, v144
	v_exp_f32_e32 v145, v145
	v_exp_f32_e32 v146, v146
	v_exp_f32_e32 v147, v147
	v_pk_fma_f32 v[140:141], v[136:137], s[86:87], v[0:1] op_sel_hi:[1,0,0]
	v_pk_fma_f32 v[142:143], v[138:139], s[86:87], v[0:1] op_sel_hi:[1,0,0]
	v_pk_fma_f32 v[140:141], v[136:137], v[140:141], s[88:89] op_sel_hi:[1,1,0]
	v_pk_fma_f32 v[142:143], v[138:139], v[142:143], s[88:89] op_sel_hi:[1,1,0]
	v_pk_fma_f32 v[140:141], v[136:137], v[140:141], s[82:83] op_sel_hi:[1,1,0]
	v_pk_fma_f32 v[142:143], v[138:139], v[142:143], s[82:83] op_sel_hi:[1,1,0]
	v_pk_fma_f32 v[140:141], v[136:137], v[140:141], s[48:49] op_sel_hi:[1,1,0]
	v_pk_fma_f32 v[142:143], v[138:139], v[142:143], s[48:49] op_sel_hi:[1,1,0]
	v_pk_mul_f32 v[140:141], v[136:137], v[140:141]
	v_pk_mul_f32 v[142:143], v[138:139], v[142:143]
	v_pk_mul_f32 v[140:141], v[140:141], v[144:145]
	v_pk_mul_f32 v[142:143], v[142:143], v[146:147]
	v_max_f32_e32 v124, 0, v124
	v_max_f32_e32 v125, 0, v125
	v_max_f32_e32 v126, 0, v126
	v_max_f32_e32 v127, 0, v127
	v_pk_fma_f32 v[124:125], v[132:133], v[140:141], v[124:125] neg_lo:[1,0,0] neg_hi:[1,0,0]
	v_pk_fma_f32 v[126:127], v[134:135], v[142:143], v[126:127] neg_lo:[1,0,0] neg_hi:[1,0,0]
	v_and_b32_e32 v132, 0x7fffffff, v116
	v_and_b32_e32 v133, 0x7fffffff, v117
	v_and_b32_e32 v134, 0x7fffffff, v118
	v_and_b32_e32 v135, 0x7fffffff, v119
	v_pk_mul_f32 v[144:145], v[116:117], v[116:117]
	v_pk_mul_f32 v[146:147], v[118:119], v[118:119]
	v_pk_fma_f32 v[136:137], v[132:133], s[84:85], 1.0 op_sel_hi:[1,0,0]
	v_pk_fma_f32 v[138:139], v[134:135], s[84:85], 1.0 op_sel_hi:[1,0,0]
	v_pk_mul_f32 v[144:145], v[144:145], s[80:81] op_sel_hi:[1,0]
	v_pk_mul_f32 v[146:147], v[146:147], s[80:81] op_sel_hi:[1,0]
	v_rcp_f32_e32 v136, v136
	v_rcp_f32_e32 v137, v137
	v_rcp_f32_e32 v138, v138
	v_rcp_f32_e32 v139, v139
	v_exp_f32_e32 v144, v144
	v_exp_f32_e32 v145, v145
	v_exp_f32_e32 v146, v146
	v_exp_f32_e32 v147, v147
	v_pk_fma_f32 v[140:141], v[136:137], s[86:87], v[0:1] op_sel_hi:[1,0,0]
	v_pk_fma_f32 v[142:143], v[138:139], s[86:87], v[0:1] op_sel_hi:[1,0,0]
	v_pk_fma_f32 v[140:141], v[136:137], v[140:141], s[88:89] op_sel_hi:[1,1,0]
	v_pk_fma_f32 v[142:143], v[138:139], v[142:143], s[88:89] op_sel_hi:[1,1,0]
	v_pk_fma_f32 v[140:141], v[136:137], v[140:141], s[82:83] op_sel_hi:[1,1,0]
	v_pk_fma_f32 v[142:143], v[138:139], v[142:143], s[82:83] op_sel_hi:[1,1,0]
	v_pk_fma_f32 v[140:141], v[136:137], v[140:141], s[48:49] op_sel_hi:[1,1,0]
	v_pk_fma_f32 v[142:143], v[138:139], v[142:143], s[48:49] op_sel_hi:[1,1,0]
	v_pk_mul_f32 v[140:141], v[136:137], v[140:141]
	v_pk_mul_f32 v[142:143], v[138:139], v[142:143]
	v_pk_mul_f32 v[140:141], v[140:141], v[144:145]
	v_pk_mul_f32 v[142:143], v[142:143], v[146:147]
	v_max_f32_e32 v116, 0, v116
	v_max_f32_e32 v117, 0, v117
	v_max_f32_e32 v118, 0, v118
	v_max_f32_e32 v119, 0, v119
	v_pk_fma_f32 v[116:117], v[132:133], v[140:141], v[116:117] neg_lo:[1,0,0] neg_hi:[1,0,0]
	v_pk_fma_f32 v[118:119], v[134:135], v[142:143], v[118:119] neg_lo:[1,0,0] neg_hi:[1,0,0]
	v_cvt_pk_bf16_f32 v124, v124, v125
	v_cvt_pk_bf16_f32 v125, v126, v127
	v_cvt_pk_bf16_f32 v126, v116, v117
	v_cvt_pk_bf16_f32 v127, v118, v119
	global_store_dwordx4 v148, v[124:127], s[50:51]
	v_and_b32_e32 v132, 0x7fffffff, v108
	v_and_b32_e32 v133, 0x7fffffff, v109
	v_and_b32_e32 v134, 0x7fffffff, v110
	v_and_b32_e32 v135, 0x7fffffff, v111
	v_pk_mul_f32 v[144:145], v[108:109], v[108:109]
	v_pk_mul_f32 v[146:147], v[110:111], v[110:111]
	v_pk_fma_f32 v[136:137], v[132:133], s[84:85], 1.0 op_sel_hi:[1,0,0]
	v_pk_fma_f32 v[138:139], v[134:135], s[84:85], 1.0 op_sel_hi:[1,0,0]
	v_pk_mul_f32 v[144:145], v[144:145], s[80:81] op_sel_hi:[1,0]
	v_pk_mul_f32 v[146:147], v[146:147], s[80:81] op_sel_hi:[1,0]
	v_rcp_f32_e32 v136, v136
	v_rcp_f32_e32 v137, v137
	v_rcp_f32_e32 v138, v138
	v_rcp_f32_e32 v139, v139
	v_exp_f32_e32 v144, v144
	v_exp_f32_e32 v145, v145
	v_exp_f32_e32 v146, v146
	v_exp_f32_e32 v147, v147
	v_pk_fma_f32 v[140:141], v[136:137], s[86:87], v[0:1] op_sel_hi:[1,0,0]
	v_pk_fma_f32 v[142:143], v[138:139], s[86:87], v[0:1] op_sel_hi:[1,0,0]
	v_pk_fma_f32 v[140:141], v[136:137], v[140:141], s[88:89] op_sel_hi:[1,1,0]
	v_pk_fma_f32 v[142:143], v[138:139], v[142:143], s[88:89] op_sel_hi:[1,1,0]
	v_pk_fma_f32 v[140:141], v[136:137], v[140:141], s[82:83] op_sel_hi:[1,1,0]
	v_pk_fma_f32 v[142:143], v[138:139], v[142:143], s[82:83] op_sel_hi:[1,1,0]
	v_pk_fma_f32 v[140:141], v[136:137], v[140:141], s[48:49] op_sel_hi:[1,1,0]
	v_pk_fma_f32 v[142:143], v[138:139], v[142:143], s[48:49] op_sel_hi:[1,1,0]
	v_pk_mul_f32 v[140:141], v[136:137], v[140:141]
	v_pk_mul_f32 v[142:143], v[138:139], v[142:143]
	v_pk_mul_f32 v[140:141], v[140:141], v[144:145]
	v_pk_mul_f32 v[142:143], v[142:143], v[146:147]
	v_max_f32_e32 v108, 0, v108
	v_max_f32_e32 v109, 0, v109
	v_max_f32_e32 v110, 0, v110
	v_max_f32_e32 v111, 0, v111
	v_pk_fma_f32 v[108:109], v[132:133], v[140:141], v[108:109] neg_lo:[1,0,0] neg_hi:[1,0,0]
	v_pk_fma_f32 v[110:111], v[134:135], v[142:143], v[110:111] neg_lo:[1,0,0] neg_hi:[1,0,0]
	v_and_b32_e32 v132, 0x7fffffff, v100
	v_and_b32_e32 v133, 0x7fffffff, v101
	v_and_b32_e32 v134, 0x7fffffff, v102
	v_and_b32_e32 v135, 0x7fffffff, v103
	v_pk_mul_f32 v[144:145], v[100:101], v[100:101]
	v_pk_mul_f32 v[146:147], v[102:103], v[102:103]
	v_pk_fma_f32 v[136:137], v[132:133], s[84:85], 1.0 op_sel_hi:[1,0,0]
	v_pk_fma_f32 v[138:139], v[134:135], s[84:85], 1.0 op_sel_hi:[1,0,0]
	v_pk_mul_f32 v[144:145], v[144:145], s[80:81] op_sel_hi:[1,0]
	v_pk_mul_f32 v[146:147], v[146:147], s[80:81] op_sel_hi:[1,0]
	v_rcp_f32_e32 v136, v136
	v_rcp_f32_e32 v137, v137
	v_rcp_f32_e32 v138, v138
	v_rcp_f32_e32 v139, v139
	v_exp_f32_e32 v144, v144
	v_exp_f32_e32 v145, v145
	v_exp_f32_e32 v146, v146
	v_exp_f32_e32 v147, v147
	v_pk_fma_f32 v[140:141], v[136:137], s[86:87], v[0:1] op_sel_hi:[1,0,0]
	v_pk_fma_f32 v[142:143], v[138:139], s[86:87], v[0:1] op_sel_hi:[1,0,0]
	v_pk_fma_f32 v[140:141], v[136:137], v[140:141], s[88:89] op_sel_hi:[1,1,0]
	v_pk_fma_f32 v[142:143], v[138:139], v[142:143], s[88:89] op_sel_hi:[1,1,0]
	v_pk_fma_f32 v[140:141], v[136:137], v[140:141], s[82:83] op_sel_hi:[1,1,0]
	v_pk_fma_f32 v[142:143], v[138:139], v[142:143], s[82:83] op_sel_hi:[1,1,0]
	v_pk_fma_f32 v[140:141], v[136:137], v[140:141], s[48:49] op_sel_hi:[1,1,0]
	v_pk_fma_f32 v[142:143], v[138:139], v[142:143], s[48:49] op_sel_hi:[1,1,0]
	v_pk_mul_f32 v[140:141], v[136:137], v[140:141]
	v_pk_mul_f32 v[142:143], v[138:139], v[142:143]
	v_pk_mul_f32 v[140:141], v[140:141], v[144:145]
	v_pk_mul_f32 v[142:143], v[142:143], v[146:147]
	v_max_f32_e32 v100, 0, v100
	v_max_f32_e32 v101, 0, v101
	v_max_f32_e32 v102, 0, v102
	v_max_f32_e32 v103, 0, v103
	v_pk_fma_f32 v[100:101], v[132:133], v[140:141], v[100:101] neg_lo:[1,0,0] neg_hi:[1,0,0]
	v_pk_fma_f32 v[102:103], v[134:135], v[142:143], v[102:103] neg_lo:[1,0,0] neg_hi:[1,0,0]
	v_cvt_pk_bf16_f32 v108, v108, v109
	v_cvt_pk_bf16_f32 v109, v110, v111
	v_cvt_pk_bf16_f32 v110, v100, v101
	v_cvt_pk_bf16_f32 v111, v102, v103
	global_store_dwordx4 v148, v[108:111], s[50:51] offset:256
	v_add_u32_e32 v148, s81, v148
	v_and_b32_e32 v132, 0x7fffffff, v96
	v_and_b32_e32 v133, 0x7fffffff, v97
	v_and_b32_e32 v134, 0x7fffffff, v98
	v_and_b32_e32 v135, 0x7fffffff, v99
	v_pk_mul_f32 v[144:145], v[96:97], v[96:97]
	v_pk_mul_f32 v[146:147], v[98:99], v[98:99]
	v_pk_fma_f32 v[136:137], v[132:133], s[84:85], 1.0 op_sel_hi:[1,0,0]
	v_pk_fma_f32 v[138:139], v[134:135], s[84:85], 1.0 op_sel_hi:[1,0,0]
	v_pk_mul_f32 v[144:145], v[144:145], s[80:81] op_sel_hi:[1,0]
	v_pk_mul_f32 v[146:147], v[146:147], s[80:81] op_sel_hi:[1,0]
	v_rcp_f32_e32 v136, v136
	v_rcp_f32_e32 v137, v137
	v_rcp_f32_e32 v138, v138
	v_rcp_f32_e32 v139, v139
	v_exp_f32_e32 v144, v144
	v_exp_f32_e32 v145, v145
	v_exp_f32_e32 v146, v146
	v_exp_f32_e32 v147, v147
	v_pk_fma_f32 v[140:141], v[136:137], s[86:87], v[0:1] op_sel_hi:[1,0,0]
	v_pk_fma_f32 v[142:143], v[138:139], s[86:87], v[0:1] op_sel_hi:[1,0,0]
	v_pk_fma_f32 v[140:141], v[136:137], v[140:141], s[88:89] op_sel_hi:[1,1,0]
	v_pk_fma_f32 v[142:143], v[138:139], v[142:143], s[88:89] op_sel_hi:[1,1,0]
	v_pk_fma_f32 v[140:141], v[136:137], v[140:141], s[82:83] op_sel_hi:[1,1,0]
	v_pk_fma_f32 v[142:143], v[138:139], v[142:143], s[82:83] op_sel_hi:[1,1,0]
	v_pk_fma_f32 v[140:141], v[136:137], v[140:141], s[48:49] op_sel_hi:[1,1,0]
	v_pk_fma_f32 v[142:143], v[138:139], v[142:143], s[48:49] op_sel_hi:[1,1,0]
	v_pk_mul_f32 v[140:141], v[136:137], v[140:141]
	v_pk_mul_f32 v[142:143], v[138:139], v[142:143]
	v_pk_mul_f32 v[140:141], v[140:141], v[144:145]
	v_pk_mul_f32 v[142:143], v[142:143], v[146:147]
	v_max_f32_e32 v96, 0, v96
	v_max_f32_e32 v97, 0, v97
	v_max_f32_e32 v98, 0, v98
	v_max_f32_e32 v99, 0, v99
	v_pk_fma_f32 v[96:97], v[132:133], v[140:141], v[96:97] neg_lo:[1,0,0] neg_hi:[1,0,0]
	v_pk_fma_f32 v[98:99], v[134:135], v[142:143], v[98:99] neg_lo:[1,0,0] neg_hi:[1,0,0]
	v_and_b32_e32 v132, 0x7fffffff, v88
	v_and_b32_e32 v133, 0x7fffffff, v89
	v_and_b32_e32 v134, 0x7fffffff, v90
	v_and_b32_e32 v135, 0x7fffffff, v91
	v_pk_mul_f32 v[144:145], v[88:89], v[88:89]
	v_pk_mul_f32 v[146:147], v[90:91], v[90:91]
	v_pk_fma_f32 v[136:137], v[132:133], s[84:85], 1.0 op_sel_hi:[1,0,0]
	v_pk_fma_f32 v[138:139], v[134:135], s[84:85], 1.0 op_sel_hi:[1,0,0]
	v_pk_mul_f32 v[144:145], v[144:145], s[80:81] op_sel_hi:[1,0]
	v_pk_mul_f32 v[146:147], v[146:147], s[80:81] op_sel_hi:[1,0]
	v_rcp_f32_e32 v136, v136
	v_rcp_f32_e32 v137, v137
	v_rcp_f32_e32 v138, v138
	v_rcp_f32_e32 v139, v139
	v_exp_f32_e32 v144, v144
	v_exp_f32_e32 v145, v145
	v_exp_f32_e32 v146, v146
	v_exp_f32_e32 v147, v147
	v_pk_fma_f32 v[140:141], v[136:137], s[86:87], v[0:1] op_sel_hi:[1,0,0]
	v_pk_fma_f32 v[142:143], v[138:139], s[86:87], v[0:1] op_sel_hi:[1,0,0]
	v_pk_fma_f32 v[140:141], v[136:137], v[140:141], s[88:89] op_sel_hi:[1,1,0]
	v_pk_fma_f32 v[142:143], v[138:139], v[142:143], s[88:89] op_sel_hi:[1,1,0]
	v_pk_fma_f32 v[140:141], v[136:137], v[140:141], s[82:83] op_sel_hi:[1,1,0]
	v_pk_fma_f32 v[142:143], v[138:139], v[142:143], s[82:83] op_sel_hi:[1,1,0]
	v_pk_fma_f32 v[140:141], v[136:137], v[140:141], s[48:49] op_sel_hi:[1,1,0]
	v_pk_fma_f32 v[142:143], v[138:139], v[142:143], s[48:49] op_sel_hi:[1,1,0]
	v_pk_mul_f32 v[140:141], v[136:137], v[140:141]
	v_pk_mul_f32 v[142:143], v[138:139], v[142:143]
	v_pk_mul_f32 v[140:141], v[140:141], v[144:145]
	v_pk_mul_f32 v[142:143], v[142:143], v[146:147]
	v_max_f32_e32 v88, 0, v88
	v_max_f32_e32 v89, 0, v89
	v_max_f32_e32 v90, 0, v90
	v_max_f32_e32 v91, 0, v91
	v_pk_fma_f32 v[88:89], v[132:133], v[140:141], v[88:89] neg_lo:[1,0,0] neg_hi:[1,0,0]
	v_pk_fma_f32 v[90:91], v[134:135], v[142:143], v[90:91] neg_lo:[1,0,0] neg_hi:[1,0,0]
	v_cvt_pk_bf16_f32 v96, v96, v97
	v_cvt_pk_bf16_f32 v97, v98, v99
	v_cvt_pk_bf16_f32 v98, v88, v89
	v_cvt_pk_bf16_f32 v99, v90, v91
	global_store_dwordx4 v148, v[96:99], s[50:51]
	v_and_b32_e32 v132, 0x7fffffff, v80
	v_and_b32_e32 v133, 0x7fffffff, v81
	v_and_b32_e32 v134, 0x7fffffff, v82
	v_and_b32_e32 v135, 0x7fffffff, v83
	v_pk_mul_f32 v[144:145], v[80:81], v[80:81]
	v_pk_mul_f32 v[146:147], v[82:83], v[82:83]
	v_pk_fma_f32 v[136:137], v[132:133], s[84:85], 1.0 op_sel_hi:[1,0,0]
	v_pk_fma_f32 v[138:139], v[134:135], s[84:85], 1.0 op_sel_hi:[1,0,0]
	v_pk_mul_f32 v[144:145], v[144:145], s[80:81] op_sel_hi:[1,0]
	v_pk_mul_f32 v[146:147], v[146:147], s[80:81] op_sel_hi:[1,0]
	v_rcp_f32_e32 v136, v136
	v_rcp_f32_e32 v137, v137
	v_rcp_f32_e32 v138, v138
	v_rcp_f32_e32 v139, v139
	v_exp_f32_e32 v144, v144
	v_exp_f32_e32 v145, v145
	v_exp_f32_e32 v146, v146
	v_exp_f32_e32 v147, v147
	v_pk_fma_f32 v[140:141], v[136:137], s[86:87], v[0:1] op_sel_hi:[1,0,0]
	v_pk_fma_f32 v[142:143], v[138:139], s[86:87], v[0:1] op_sel_hi:[1,0,0]
	v_pk_fma_f32 v[140:141], v[136:137], v[140:141], s[88:89] op_sel_hi:[1,1,0]
	v_pk_fma_f32 v[142:143], v[138:139], v[142:143], s[88:89] op_sel_hi:[1,1,0]
	v_pk_fma_f32 v[140:141], v[136:137], v[140:141], s[82:83] op_sel_hi:[1,1,0]
	v_pk_fma_f32 v[142:143], v[138:139], v[142:143], s[82:83] op_sel_hi:[1,1,0]
	v_pk_fma_f32 v[140:141], v[136:137], v[140:141], s[48:49] op_sel_hi:[1,1,0]
	v_pk_fma_f32 v[142:143], v[138:139], v[142:143], s[48:49] op_sel_hi:[1,1,0]
	v_pk_mul_f32 v[140:141], v[136:137], v[140:141]
	v_pk_mul_f32 v[142:143], v[138:139], v[142:143]
	v_pk_mul_f32 v[140:141], v[140:141], v[144:145]
	v_pk_mul_f32 v[142:143], v[142:143], v[146:147]
	v_max_f32_e32 v80, 0, v80
	v_max_f32_e32 v81, 0, v81
	v_max_f32_e32 v82, 0, v82
	v_max_f32_e32 v83, 0, v83
	v_pk_fma_f32 v[80:81], v[132:133], v[140:141], v[80:81] neg_lo:[1,0,0] neg_hi:[1,0,0]
	v_pk_fma_f32 v[82:83], v[134:135], v[142:143], v[82:83] neg_lo:[1,0,0] neg_hi:[1,0,0]
	v_and_b32_e32 v132, 0x7fffffff, v72
	v_and_b32_e32 v133, 0x7fffffff, v73
	v_and_b32_e32 v134, 0x7fffffff, v74
	v_and_b32_e32 v135, 0x7fffffff, v75
	v_pk_mul_f32 v[144:145], v[72:73], v[72:73]
	v_pk_mul_f32 v[146:147], v[74:75], v[74:75]
	v_pk_fma_f32 v[136:137], v[132:133], s[84:85], 1.0 op_sel_hi:[1,0,0]
	v_pk_fma_f32 v[138:139], v[134:135], s[84:85], 1.0 op_sel_hi:[1,0,0]
	v_pk_mul_f32 v[144:145], v[144:145], s[80:81] op_sel_hi:[1,0]
	v_pk_mul_f32 v[146:147], v[146:147], s[80:81] op_sel_hi:[1,0]
	v_rcp_f32_e32 v136, v136
	v_rcp_f32_e32 v137, v137
	v_rcp_f32_e32 v138, v138
	v_rcp_f32_e32 v139, v139
	v_exp_f32_e32 v144, v144
	v_exp_f32_e32 v145, v145
	v_exp_f32_e32 v146, v146
	v_exp_f32_e32 v147, v147
	v_pk_fma_f32 v[140:141], v[136:137], s[86:87], v[0:1] op_sel_hi:[1,0,0]
	v_pk_fma_f32 v[142:143], v[138:139], s[86:87], v[0:1] op_sel_hi:[1,0,0]
	v_pk_fma_f32 v[140:141], v[136:137], v[140:141], s[88:89] op_sel_hi:[1,1,0]
	v_pk_fma_f32 v[142:143], v[138:139], v[142:143], s[88:89] op_sel_hi:[1,1,0]
	v_pk_fma_f32 v[140:141], v[136:137], v[140:141], s[82:83] op_sel_hi:[1,1,0]
	v_pk_fma_f32 v[142:143], v[138:139], v[142:143], s[82:83] op_sel_hi:[1,1,0]
	v_pk_fma_f32 v[140:141], v[136:137], v[140:141], s[48:49] op_sel_hi:[1,1,0]
	v_pk_fma_f32 v[142:143], v[138:139], v[142:143], s[48:49] op_sel_hi:[1,1,0]
	v_pk_mul_f32 v[140:141], v[136:137], v[140:141]
	v_pk_mul_f32 v[142:143], v[138:139], v[142:143]
	v_pk_mul_f32 v[140:141], v[140:141], v[144:145]
	v_pk_mul_f32 v[142:143], v[142:143], v[146:147]
	v_max_f32_e32 v72, 0, v72
	v_max_f32_e32 v73, 0, v73
	v_max_f32_e32 v74, 0, v74
	v_max_f32_e32 v75, 0, v75
	v_pk_fma_f32 v[72:73], v[132:133], v[140:141], v[72:73] neg_lo:[1,0,0] neg_hi:[1,0,0]
	v_pk_fma_f32 v[74:75], v[134:135], v[142:143], v[74:75] neg_lo:[1,0,0] neg_hi:[1,0,0]
	v_cvt_pk_bf16_f32 v80, v80, v81
	v_cvt_pk_bf16_f32 v81, v82, v83
	v_cvt_pk_bf16_f32 v82, v72, v73
	v_cvt_pk_bf16_f32 v83, v74, v75
	global_store_dwordx4 v148, v[80:83], s[50:51] offset:256
	v_add_u32_e32 v148, s81, v148
	v_and_b32_e32 v132, 0x7fffffff, v92
	v_and_b32_e32 v133, 0x7fffffff, v93
	v_and_b32_e32 v134, 0x7fffffff, v94
	v_and_b32_e32 v135, 0x7fffffff, v95
	v_pk_mul_f32 v[144:145], v[92:93], v[92:93]
	v_pk_mul_f32 v[146:147], v[94:95], v[94:95]
	v_pk_fma_f32 v[136:137], v[132:133], s[84:85], 1.0 op_sel_hi:[1,0,0]
	v_pk_fma_f32 v[138:139], v[134:135], s[84:85], 1.0 op_sel_hi:[1,0,0]
	v_pk_mul_f32 v[144:145], v[144:145], s[80:81] op_sel_hi:[1,0]
	v_pk_mul_f32 v[146:147], v[146:147], s[80:81] op_sel_hi:[1,0]
	v_rcp_f32_e32 v136, v136
	v_rcp_f32_e32 v137, v137
	v_rcp_f32_e32 v138, v138
	v_rcp_f32_e32 v139, v139
	v_exp_f32_e32 v144, v144
	v_exp_f32_e32 v145, v145
	v_exp_f32_e32 v146, v146
	v_exp_f32_e32 v147, v147
	v_pk_fma_f32 v[140:141], v[136:137], s[86:87], v[0:1] op_sel_hi:[1,0,0]
	v_pk_fma_f32 v[142:143], v[138:139], s[86:87], v[0:1] op_sel_hi:[1,0,0]
	v_pk_fma_f32 v[140:141], v[136:137], v[140:141], s[88:89] op_sel_hi:[1,1,0]
	v_pk_fma_f32 v[142:143], v[138:139], v[142:143], s[88:89] op_sel_hi:[1,1,0]
	v_pk_fma_f32 v[140:141], v[136:137], v[140:141], s[82:83] op_sel_hi:[1,1,0]
	v_pk_fma_f32 v[142:143], v[138:139], v[142:143], s[82:83] op_sel_hi:[1,1,0]
	v_pk_fma_f32 v[140:141], v[136:137], v[140:141], s[48:49] op_sel_hi:[1,1,0]
	v_pk_fma_f32 v[142:143], v[138:139], v[142:143], s[48:49] op_sel_hi:[1,1,0]
	v_pk_mul_f32 v[140:141], v[136:137], v[140:141]
	v_pk_mul_f32 v[142:143], v[138:139], v[142:143]
	v_pk_mul_f32 v[140:141], v[140:141], v[144:145]
	v_pk_mul_f32 v[142:143], v[142:143], v[146:147]
	v_max_f32_e32 v92, 0, v92
	v_max_f32_e32 v93, 0, v93
	v_max_f32_e32 v94, 0, v94
	v_max_f32_e32 v95, 0, v95
	v_pk_fma_f32 v[92:93], v[132:133], v[140:141], v[92:93] neg_lo:[1,0,0] neg_hi:[1,0,0]
	v_pk_fma_f32 v[94:95], v[134:135], v[142:143], v[94:95] neg_lo:[1,0,0] neg_hi:[1,0,0]
	v_and_b32_e32 v132, 0x7fffffff, v84
	v_and_b32_e32 v133, 0x7fffffff, v85
	v_and_b32_e32 v134, 0x7fffffff, v86
	v_and_b32_e32 v135, 0x7fffffff, v87
	v_pk_mul_f32 v[144:145], v[84:85], v[84:85]
	v_pk_mul_f32 v[146:147], v[86:87], v[86:87]
	v_pk_fma_f32 v[136:137], v[132:133], s[84:85], 1.0 op_sel_hi:[1,0,0]
	v_pk_fma_f32 v[138:139], v[134:135], s[84:85], 1.0 op_sel_hi:[1,0,0]
	v_pk_mul_f32 v[144:145], v[144:145], s[80:81] op_sel_hi:[1,0]
	v_pk_mul_f32 v[146:147], v[146:147], s[80:81] op_sel_hi:[1,0]
	v_rcp_f32_e32 v136, v136
	v_rcp_f32_e32 v137, v137
	v_rcp_f32_e32 v138, v138
	v_rcp_f32_e32 v139, v139
	v_exp_f32_e32 v144, v144
	v_exp_f32_e32 v145, v145
	v_exp_f32_e32 v146, v146
	v_exp_f32_e32 v147, v147
	v_pk_fma_f32 v[140:141], v[136:137], s[86:87], v[0:1] op_sel_hi:[1,0,0]
	v_pk_fma_f32 v[142:143], v[138:139], s[86:87], v[0:1] op_sel_hi:[1,0,0]
	v_pk_fma_f32 v[140:141], v[136:137], v[140:141], s[88:89] op_sel_hi:[1,1,0]
	v_pk_fma_f32 v[142:143], v[138:139], v[142:143], s[88:89] op_sel_hi:[1,1,0]
	v_pk_fma_f32 v[140:141], v[136:137], v[140:141], s[82:83] op_sel_hi:[1,1,0]
	v_pk_fma_f32 v[142:143], v[138:139], v[142:143], s[82:83] op_sel_hi:[1,1,0]
	v_pk_fma_f32 v[140:141], v[136:137], v[140:141], s[48:49] op_sel_hi:[1,1,0]
	v_pk_fma_f32 v[142:143], v[138:139], v[142:143], s[48:49] op_sel_hi:[1,1,0]
	v_pk_mul_f32 v[140:141], v[136:137], v[140:141]
	v_pk_mul_f32 v[142:143], v[138:139], v[142:143]
	v_pk_mul_f32 v[140:141], v[140:141], v[144:145]
	v_pk_mul_f32 v[142:143], v[142:143], v[146:147]
	v_max_f32_e32 v84, 0, v84
	v_max_f32_e32 v85, 0, v85
	v_max_f32_e32 v86, 0, v86
	v_max_f32_e32 v87, 0, v87
	v_pk_fma_f32 v[84:85], v[132:133], v[140:141], v[84:85] neg_lo:[1,0,0] neg_hi:[1,0,0]
	v_pk_fma_f32 v[86:87], v[134:135], v[142:143], v[86:87] neg_lo:[1,0,0] neg_hi:[1,0,0]
	v_cvt_pk_bf16_f32 v92, v92, v93
	v_cvt_pk_bf16_f32 v93, v94, v95
	v_cvt_pk_bf16_f32 v94, v84, v85
	v_cvt_pk_bf16_f32 v95, v86, v87
	global_store_dwordx4 v148, v[92:95], s[50:51]
	v_and_b32_e32 v132, 0x7fffffff, v76
	v_and_b32_e32 v133, 0x7fffffff, v77
	v_and_b32_e32 v134, 0x7fffffff, v78
	v_and_b32_e32 v135, 0x7fffffff, v79
	v_pk_mul_f32 v[144:145], v[76:77], v[76:77]
	v_pk_mul_f32 v[146:147], v[78:79], v[78:79]
	v_pk_fma_f32 v[136:137], v[132:133], s[84:85], 1.0 op_sel_hi:[1,0,0]
	v_pk_fma_f32 v[138:139], v[134:135], s[84:85], 1.0 op_sel_hi:[1,0,0]
	v_pk_mul_f32 v[144:145], v[144:145], s[80:81] op_sel_hi:[1,0]
	v_pk_mul_f32 v[146:147], v[146:147], s[80:81] op_sel_hi:[1,0]
	v_rcp_f32_e32 v136, v136
	v_rcp_f32_e32 v137, v137
	v_rcp_f32_e32 v138, v138
	v_rcp_f32_e32 v139, v139
	v_exp_f32_e32 v144, v144
	v_exp_f32_e32 v145, v145
	v_exp_f32_e32 v146, v146
	v_exp_f32_e32 v147, v147
	v_pk_fma_f32 v[140:141], v[136:137], s[86:87], v[0:1] op_sel_hi:[1,0,0]
	v_pk_fma_f32 v[142:143], v[138:139], s[86:87], v[0:1] op_sel_hi:[1,0,0]
	v_pk_fma_f32 v[140:141], v[136:137], v[140:141], s[88:89] op_sel_hi:[1,1,0]
	v_pk_fma_f32 v[142:143], v[138:139], v[142:143], s[88:89] op_sel_hi:[1,1,0]
	v_pk_fma_f32 v[140:141], v[136:137], v[140:141], s[82:83] op_sel_hi:[1,1,0]
	v_pk_fma_f32 v[142:143], v[138:139], v[142:143], s[82:83] op_sel_hi:[1,1,0]
	v_pk_fma_f32 v[140:141], v[136:137], v[140:141], s[48:49] op_sel_hi:[1,1,0]
	v_pk_fma_f32 v[142:143], v[138:139], v[142:143], s[48:49] op_sel_hi:[1,1,0]
	v_pk_mul_f32 v[140:141], v[136:137], v[140:141]
	v_pk_mul_f32 v[142:143], v[138:139], v[142:143]
	v_pk_mul_f32 v[140:141], v[140:141], v[144:145]
	v_pk_mul_f32 v[142:143], v[142:143], v[146:147]
	v_max_f32_e32 v76, 0, v76
	v_max_f32_e32 v77, 0, v77
	v_max_f32_e32 v78, 0, v78
	v_max_f32_e32 v79, 0, v79
	v_pk_fma_f32 v[76:77], v[132:133], v[140:141], v[76:77] neg_lo:[1,0,0] neg_hi:[1,0,0]
	v_pk_fma_f32 v[78:79], v[134:135], v[142:143], v[78:79] neg_lo:[1,0,0] neg_hi:[1,0,0]
	v_and_b32_e32 v132, 0x7fffffff, v68
	v_and_b32_e32 v133, 0x7fffffff, v69
	v_and_b32_e32 v134, 0x7fffffff, v70
	v_and_b32_e32 v135, 0x7fffffff, v71
	v_pk_mul_f32 v[144:145], v[68:69], v[68:69]
	v_pk_mul_f32 v[146:147], v[70:71], v[70:71]
	v_pk_fma_f32 v[136:137], v[132:133], s[84:85], 1.0 op_sel_hi:[1,0,0]
	v_pk_fma_f32 v[138:139], v[134:135], s[84:85], 1.0 op_sel_hi:[1,0,0]
	v_pk_mul_f32 v[144:145], v[144:145], s[80:81] op_sel_hi:[1,0]
	v_pk_mul_f32 v[146:147], v[146:147], s[80:81] op_sel_hi:[1,0]
	v_rcp_f32_e32 v136, v136
	v_rcp_f32_e32 v137, v137
	v_rcp_f32_e32 v138, v138
	v_rcp_f32_e32 v139, v139
	v_exp_f32_e32 v144, v144
	v_exp_f32_e32 v145, v145
	v_exp_f32_e32 v146, v146
	v_exp_f32_e32 v147, v147
	v_pk_fma_f32 v[140:141], v[136:137], s[86:87], v[0:1] op_sel_hi:[1,0,0]
	v_pk_fma_f32 v[142:143], v[138:139], s[86:87], v[0:1] op_sel_hi:[1,0,0]
	v_pk_fma_f32 v[140:141], v[136:137], v[140:141], s[88:89] op_sel_hi:[1,1,0]
	v_pk_fma_f32 v[142:143], v[138:139], v[142:143], s[88:89] op_sel_hi:[1,1,0]
	v_pk_fma_f32 v[140:141], v[136:137], v[140:141], s[82:83] op_sel_hi:[1,1,0]
	v_pk_fma_f32 v[142:143], v[138:139], v[142:143], s[82:83] op_sel_hi:[1,1,0]
	v_pk_fma_f32 v[140:141], v[136:137], v[140:141], s[48:49] op_sel_hi:[1,1,0]
	v_pk_fma_f32 v[142:143], v[138:139], v[142:143], s[48:49] op_sel_hi:[1,1,0]
	v_pk_mul_f32 v[140:141], v[136:137], v[140:141]
	v_pk_mul_f32 v[142:143], v[138:139], v[142:143]
	v_pk_mul_f32 v[140:141], v[140:141], v[144:145]
	v_pk_mul_f32 v[142:143], v[142:143], v[146:147]
	v_max_f32_e32 v68, 0, v68
	v_max_f32_e32 v69, 0, v69
	v_max_f32_e32 v70, 0, v70
	v_max_f32_e32 v71, 0, v71
	v_pk_fma_f32 v[68:69], v[132:133], v[140:141], v[68:69] neg_lo:[1,0,0] neg_hi:[1,0,0]
	v_pk_fma_f32 v[70:71], v[134:135], v[142:143], v[70:71] neg_lo:[1,0,0] neg_hi:[1,0,0]
	v_cvt_pk_bf16_f32 v76, v76, v77
	v_cvt_pk_bf16_f32 v77, v78, v79
	v_cvt_pk_bf16_f32 v78, v68, v69
	v_cvt_pk_bf16_f32 v79, v70, v71
	global_store_dwordx4 v148, v[76:79], s[50:51] offset:256
	s_mul_i32 s30, s81, 5
	v_add_u32_e32 v148, s30, v148
	s_cmp_lg_u32 s49, 0
	s_cbranch_scc1 .LBB0_326
	v_and_b32_e32 v132, 0x7fffffff, v64
	v_and_b32_e32 v133, 0x7fffffff, v65
	v_and_b32_e32 v134, 0x7fffffff, v66
	v_and_b32_e32 v135, 0x7fffffff, v67
	v_pk_mul_f32 v[144:145], v[64:65], v[64:65]
	v_pk_mul_f32 v[146:147], v[66:67], v[66:67]
	v_pk_fma_f32 v[136:137], v[132:133], s[84:85], 1.0 op_sel_hi:[1,0,0]
	v_pk_fma_f32 v[138:139], v[134:135], s[84:85], 1.0 op_sel_hi:[1,0,0]
	v_pk_mul_f32 v[144:145], v[144:145], s[80:81] op_sel_hi:[1,0]
	v_pk_mul_f32 v[146:147], v[146:147], s[80:81] op_sel_hi:[1,0]
	v_rcp_f32_e32 v136, v136
	v_rcp_f32_e32 v137, v137
	v_rcp_f32_e32 v138, v138
	v_rcp_f32_e32 v139, v139
	v_exp_f32_e32 v144, v144
	v_exp_f32_e32 v145, v145
	v_exp_f32_e32 v146, v146
	v_exp_f32_e32 v147, v147
	v_pk_fma_f32 v[140:141], v[136:137], s[86:87], v[0:1] op_sel_hi:[1,0,0]
	v_pk_fma_f32 v[142:143], v[138:139], s[86:87], v[0:1] op_sel_hi:[1,0,0]
	v_pk_fma_f32 v[140:141], v[136:137], v[140:141], s[88:89] op_sel_hi:[1,1,0]
	v_pk_fma_f32 v[142:143], v[138:139], v[142:143], s[88:89] op_sel_hi:[1,1,0]
	v_pk_fma_f32 v[140:141], v[136:137], v[140:141], s[82:83] op_sel_hi:[1,1,0]
	v_pk_fma_f32 v[142:143], v[138:139], v[142:143], s[82:83] op_sel_hi:[1,1,0]
	v_pk_fma_f32 v[140:141], v[136:137], v[140:141], s[48:49] op_sel_hi:[1,1,0]
	v_pk_fma_f32 v[142:143], v[138:139], v[142:143], s[48:49] op_sel_hi:[1,1,0]
	v_pk_mul_f32 v[140:141], v[136:137], v[140:141]
	v_pk_mul_f32 v[142:143], v[138:139], v[142:143]
	v_pk_mul_f32 v[140:141], v[140:141], v[144:145]
	v_pk_mul_f32 v[142:143], v[142:143], v[146:147]
	v_max_f32_e32 v64, 0, v64
	v_max_f32_e32 v65, 0, v65
	v_max_f32_e32 v66, 0, v66
	v_max_f32_e32 v67, 0, v67
	v_pk_fma_f32 v[64:65], v[132:133], v[140:141], v[64:65] neg_lo:[1,0,0] neg_hi:[1,0,0]
	v_pk_fma_f32 v[66:67], v[134:135], v[142:143], v[66:67] neg_lo:[1,0,0] neg_hi:[1,0,0]
	v_and_b32_e32 v132, 0x7fffffff, v56
	v_and_b32_e32 v133, 0x7fffffff, v57
	v_and_b32_e32 v134, 0x7fffffff, v58
	v_and_b32_e32 v135, 0x7fffffff, v59
	v_pk_mul_f32 v[144:145], v[56:57], v[56:57]
	v_pk_mul_f32 v[146:147], v[58:59], v[58:59]
	v_pk_fma_f32 v[136:137], v[132:133], s[84:85], 1.0 op_sel_hi:[1,0,0]
	v_pk_fma_f32 v[138:139], v[134:135], s[84:85], 1.0 op_sel_hi:[1,0,0]
	v_pk_mul_f32 v[144:145], v[144:145], s[80:81] op_sel_hi:[1,0]
	v_pk_mul_f32 v[146:147], v[146:147], s[80:81] op_sel_hi:[1,0]
	v_rcp_f32_e32 v136, v136
	v_rcp_f32_e32 v137, v137
	v_rcp_f32_e32 v138, v138
	v_rcp_f32_e32 v139, v139
	v_exp_f32_e32 v144, v144
	v_exp_f32_e32 v145, v145
	v_exp_f32_e32 v146, v146
	v_exp_f32_e32 v147, v147
	v_pk_fma_f32 v[140:141], v[136:137], s[86:87], v[0:1] op_sel_hi:[1,0,0]
	v_pk_fma_f32 v[142:143], v[138:139], s[86:87], v[0:1] op_sel_hi:[1,0,0]
	v_pk_fma_f32 v[140:141], v[136:137], v[140:141], s[88:89] op_sel_hi:[1,1,0]
	v_pk_fma_f32 v[142:143], v[138:139], v[142:143], s[88:89] op_sel_hi:[1,1,0]
	v_pk_fma_f32 v[140:141], v[136:137], v[140:141], s[82:83] op_sel_hi:[1,1,0]
	v_pk_fma_f32 v[142:143], v[138:139], v[142:143], s[82:83] op_sel_hi:[1,1,0]
	v_pk_fma_f32 v[140:141], v[136:137], v[140:141], s[48:49] op_sel_hi:[1,1,0]
	v_pk_fma_f32 v[142:143], v[138:139], v[142:143], s[48:49] op_sel_hi:[1,1,0]
	v_pk_mul_f32 v[140:141], v[136:137], v[140:141]
	v_pk_mul_f32 v[142:143], v[138:139], v[142:143]
	v_pk_mul_f32 v[140:141], v[140:141], v[144:145]
	v_pk_mul_f32 v[142:143], v[142:143], v[146:147]
	v_max_f32_e32 v56, 0, v56
	v_max_f32_e32 v57, 0, v57
	v_max_f32_e32 v58, 0, v58
	v_max_f32_e32 v59, 0, v59
	v_pk_fma_f32 v[56:57], v[132:133], v[140:141], v[56:57] neg_lo:[1,0,0] neg_hi:[1,0,0]
	v_pk_fma_f32 v[58:59], v[134:135], v[142:143], v[58:59] neg_lo:[1,0,0] neg_hi:[1,0,0]
	v_cvt_pk_bf16_f32 v64, v64, v65
	v_cvt_pk_bf16_f32 v65, v66, v67
	v_cvt_pk_bf16_f32 v66, v56, v57
	v_cvt_pk_bf16_f32 v67, v58, v59
	global_store_dwordx4 v148, v[64:67], s[50:51]
	v_and_b32_e32 v132, 0x7fffffff, v48
	v_and_b32_e32 v133, 0x7fffffff, v49
	v_and_b32_e32 v134, 0x7fffffff, v50
	v_and_b32_e32 v135, 0x7fffffff, v51
	v_pk_mul_f32 v[144:145], v[48:49], v[48:49]
	v_pk_mul_f32 v[146:147], v[50:51], v[50:51]
	v_pk_fma_f32 v[136:137], v[132:133], s[84:85], 1.0 op_sel_hi:[1,0,0]
	v_pk_fma_f32 v[138:139], v[134:135], s[84:85], 1.0 op_sel_hi:[1,0,0]
	v_pk_mul_f32 v[144:145], v[144:145], s[80:81] op_sel_hi:[1,0]
	v_pk_mul_f32 v[146:147], v[146:147], s[80:81] op_sel_hi:[1,0]
	v_rcp_f32_e32 v136, v136
	v_rcp_f32_e32 v137, v137
	v_rcp_f32_e32 v138, v138
	v_rcp_f32_e32 v139, v139
	v_exp_f32_e32 v144, v144
	v_exp_f32_e32 v145, v145
	v_exp_f32_e32 v146, v146
	v_exp_f32_e32 v147, v147
	v_pk_fma_f32 v[140:141], v[136:137], s[86:87], v[0:1] op_sel_hi:[1,0,0]
	v_pk_fma_f32 v[142:143], v[138:139], s[86:87], v[0:1] op_sel_hi:[1,0,0]
	v_pk_fma_f32 v[140:141], v[136:137], v[140:141], s[88:89] op_sel_hi:[1,1,0]
	v_pk_fma_f32 v[142:143], v[138:139], v[142:143], s[88:89] op_sel_hi:[1,1,0]
	v_pk_fma_f32 v[140:141], v[136:137], v[140:141], s[82:83] op_sel_hi:[1,1,0]
	v_pk_fma_f32 v[142:143], v[138:139], v[142:143], s[82:83] op_sel_hi:[1,1,0]
	v_pk_fma_f32 v[140:141], v[136:137], v[140:141], s[48:49] op_sel_hi:[1,1,0]
	v_pk_fma_f32 v[142:143], v[138:139], v[142:143], s[48:49] op_sel_hi:[1,1,0]
	v_pk_mul_f32 v[140:141], v[136:137], v[140:141]
	v_pk_mul_f32 v[142:143], v[138:139], v[142:143]
	v_pk_mul_f32 v[140:141], v[140:141], v[144:145]
	v_pk_mul_f32 v[142:143], v[142:143], v[146:147]
	v_max_f32_e32 v48, 0, v48
	v_max_f32_e32 v49, 0, v49
	v_max_f32_e32 v50, 0, v50
	v_max_f32_e32 v51, 0, v51
	v_pk_fma_f32 v[48:49], v[132:133], v[140:141], v[48:49] neg_lo:[1,0,0] neg_hi:[1,0,0]
	v_pk_fma_f32 v[50:51], v[134:135], v[142:143], v[50:51] neg_lo:[1,0,0] neg_hi:[1,0,0]
	v_and_b32_e32 v132, 0x7fffffff, v40
	v_and_b32_e32 v133, 0x7fffffff, v41
	v_and_b32_e32 v134, 0x7fffffff, v42
	v_and_b32_e32 v135, 0x7fffffff, v43
	v_pk_mul_f32 v[144:145], v[40:41], v[40:41]
	v_pk_mul_f32 v[146:147], v[42:43], v[42:43]
	v_pk_fma_f32 v[136:137], v[132:133], s[84:85], 1.0 op_sel_hi:[1,0,0]
	v_pk_fma_f32 v[138:139], v[134:135], s[84:85], 1.0 op_sel_hi:[1,0,0]
	v_pk_mul_f32 v[144:145], v[144:145], s[80:81] op_sel_hi:[1,0]
	v_pk_mul_f32 v[146:147], v[146:147], s[80:81] op_sel_hi:[1,0]
	v_rcp_f32_e32 v136, v136
	v_rcp_f32_e32 v137, v137
	v_rcp_f32_e32 v138, v138
	v_rcp_f32_e32 v139, v139
	v_exp_f32_e32 v144, v144
	v_exp_f32_e32 v145, v145
	v_exp_f32_e32 v146, v146
	v_exp_f32_e32 v147, v147
	v_pk_fma_f32 v[140:141], v[136:137], s[86:87], v[0:1] op_sel_hi:[1,0,0]
	v_pk_fma_f32 v[142:143], v[138:139], s[86:87], v[0:1] op_sel_hi:[1,0,0]
	v_pk_fma_f32 v[140:141], v[136:137], v[140:141], s[88:89] op_sel_hi:[1,1,0]
	v_pk_fma_f32 v[142:143], v[138:139], v[142:143], s[88:89] op_sel_hi:[1,1,0]
	v_pk_fma_f32 v[140:141], v[136:137], v[140:141], s[82:83] op_sel_hi:[1,1,0]
	v_pk_fma_f32 v[142:143], v[138:139], v[142:143], s[82:83] op_sel_hi:[1,1,0]
	v_pk_fma_f32 v[140:141], v[136:137], v[140:141], s[48:49] op_sel_hi:[1,1,0]
	v_pk_fma_f32 v[142:143], v[138:139], v[142:143], s[48:49] op_sel_hi:[1,1,0]
	v_pk_mul_f32 v[140:141], v[136:137], v[140:141]
	v_pk_mul_f32 v[142:143], v[138:139], v[142:143]
	v_pk_mul_f32 v[140:141], v[140:141], v[144:145]
	v_pk_mul_f32 v[142:143], v[142:143], v[146:147]
	v_max_f32_e32 v40, 0, v40
	v_max_f32_e32 v41, 0, v41
	v_max_f32_e32 v42, 0, v42
	v_max_f32_e32 v43, 0, v43
	v_pk_fma_f32 v[40:41], v[132:133], v[140:141], v[40:41] neg_lo:[1,0,0] neg_hi:[1,0,0]
	v_pk_fma_f32 v[42:43], v[134:135], v[142:143], v[42:43] neg_lo:[1,0,0] neg_hi:[1,0,0]
	v_cvt_pk_bf16_f32 v48, v48, v49
	v_cvt_pk_bf16_f32 v49, v50, v51
	v_cvt_pk_bf16_f32 v50, v40, v41
	v_cvt_pk_bf16_f32 v51, v42, v43
	global_store_dwordx4 v148, v[48:51], s[50:51] offset:256
	v_add_u32_e32 v148, s81, v148
	v_and_b32_e32 v132, 0x7fffffff, v60
	v_and_b32_e32 v133, 0x7fffffff, v61
	v_and_b32_e32 v134, 0x7fffffff, v62
	v_and_b32_e32 v135, 0x7fffffff, v63
	v_pk_mul_f32 v[144:145], v[60:61], v[60:61]
	v_pk_mul_f32 v[146:147], v[62:63], v[62:63]
	v_pk_fma_f32 v[136:137], v[132:133], s[84:85], 1.0 op_sel_hi:[1,0,0]
	v_pk_fma_f32 v[138:139], v[134:135], s[84:85], 1.0 op_sel_hi:[1,0,0]
	v_pk_mul_f32 v[144:145], v[144:145], s[80:81] op_sel_hi:[1,0]
	v_pk_mul_f32 v[146:147], v[146:147], s[80:81] op_sel_hi:[1,0]
	v_rcp_f32_e32 v136, v136
	v_rcp_f32_e32 v137, v137
	v_rcp_f32_e32 v138, v138
	v_rcp_f32_e32 v139, v139
	v_exp_f32_e32 v144, v144
	v_exp_f32_e32 v145, v145
	v_exp_f32_e32 v146, v146
	v_exp_f32_e32 v147, v147
	v_pk_fma_f32 v[140:141], v[136:137], s[86:87], v[0:1] op_sel_hi:[1,0,0]
	v_pk_fma_f32 v[142:143], v[138:139], s[86:87], v[0:1] op_sel_hi:[1,0,0]
	v_pk_fma_f32 v[140:141], v[136:137], v[140:141], s[88:89] op_sel_hi:[1,1,0]
	v_pk_fma_f32 v[142:143], v[138:139], v[142:143], s[88:89] op_sel_hi:[1,1,0]
	v_pk_fma_f32 v[140:141], v[136:137], v[140:141], s[82:83] op_sel_hi:[1,1,0]
	v_pk_fma_f32 v[142:143], v[138:139], v[142:143], s[82:83] op_sel_hi:[1,1,0]
	v_pk_fma_f32 v[140:141], v[136:137], v[140:141], s[48:49] op_sel_hi:[1,1,0]
	v_pk_fma_f32 v[142:143], v[138:139], v[142:143], s[48:49] op_sel_hi:[1,1,0]
	v_pk_mul_f32 v[140:141], v[136:137], v[140:141]
	v_pk_mul_f32 v[142:143], v[138:139], v[142:143]
	v_pk_mul_f32 v[140:141], v[140:141], v[144:145]
	v_pk_mul_f32 v[142:143], v[142:143], v[146:147]
	v_max_f32_e32 v60, 0, v60
	v_max_f32_e32 v61, 0, v61
	v_max_f32_e32 v62, 0, v62
	v_max_f32_e32 v63, 0, v63
	v_pk_fma_f32 v[60:61], v[132:133], v[140:141], v[60:61] neg_lo:[1,0,0] neg_hi:[1,0,0]
	v_pk_fma_f32 v[62:63], v[134:135], v[142:143], v[62:63] neg_lo:[1,0,0] neg_hi:[1,0,0]
	v_and_b32_e32 v132, 0x7fffffff, v52
	v_and_b32_e32 v133, 0x7fffffff, v53
	v_and_b32_e32 v134, 0x7fffffff, v54
	v_and_b32_e32 v135, 0x7fffffff, v55
	v_pk_mul_f32 v[144:145], v[52:53], v[52:53]
	v_pk_mul_f32 v[146:147], v[54:55], v[54:55]
	v_pk_fma_f32 v[136:137], v[132:133], s[84:85], 1.0 op_sel_hi:[1,0,0]
	v_pk_fma_f32 v[138:139], v[134:135], s[84:85], 1.0 op_sel_hi:[1,0,0]
	v_pk_mul_f32 v[144:145], v[144:145], s[80:81] op_sel_hi:[1,0]
	v_pk_mul_f32 v[146:147], v[146:147], s[80:81] op_sel_hi:[1,0]
	v_rcp_f32_e32 v136, v136
	v_rcp_f32_e32 v137, v137
	v_rcp_f32_e32 v138, v138
	v_rcp_f32_e32 v139, v139
	v_exp_f32_e32 v144, v144
	v_exp_f32_e32 v145, v145
	v_exp_f32_e32 v146, v146
	v_exp_f32_e32 v147, v147
	v_pk_fma_f32 v[140:141], v[136:137], s[86:87], v[0:1] op_sel_hi:[1,0,0]
	v_pk_fma_f32 v[142:143], v[138:139], s[86:87], v[0:1] op_sel_hi:[1,0,0]
	v_pk_fma_f32 v[140:141], v[136:137], v[140:141], s[88:89] op_sel_hi:[1,1,0]
	v_pk_fma_f32 v[142:143], v[138:139], v[142:143], s[88:89] op_sel_hi:[1,1,0]
	v_pk_fma_f32 v[140:141], v[136:137], v[140:141], s[82:83] op_sel_hi:[1,1,0]
	v_pk_fma_f32 v[142:143], v[138:139], v[142:143], s[82:83] op_sel_hi:[1,1,0]
	v_pk_fma_f32 v[140:141], v[136:137], v[140:141], s[48:49] op_sel_hi:[1,1,0]
	v_pk_fma_f32 v[142:143], v[138:139], v[142:143], s[48:49] op_sel_hi:[1,1,0]
	v_pk_mul_f32 v[140:141], v[136:137], v[140:141]
	v_pk_mul_f32 v[142:143], v[138:139], v[142:143]
	v_pk_mul_f32 v[140:141], v[140:141], v[144:145]
	v_pk_mul_f32 v[142:143], v[142:143], v[146:147]
	v_max_f32_e32 v52, 0, v52
	v_max_f32_e32 v53, 0, v53
	v_max_f32_e32 v54, 0, v54
	v_max_f32_e32 v55, 0, v55
	v_pk_fma_f32 v[52:53], v[132:133], v[140:141], v[52:53] neg_lo:[1,0,0] neg_hi:[1,0,0]
	v_pk_fma_f32 v[54:55], v[134:135], v[142:143], v[54:55] neg_lo:[1,0,0] neg_hi:[1,0,0]
	v_cvt_pk_bf16_f32 v60, v60, v61
	v_cvt_pk_bf16_f32 v61, v62, v63
	v_cvt_pk_bf16_f32 v62, v52, v53
	v_cvt_pk_bf16_f32 v63, v54, v55
	global_store_dwordx4 v148, v[60:63], s[50:51]
	v_and_b32_e32 v132, 0x7fffffff, v44
	v_and_b32_e32 v133, 0x7fffffff, v45
	v_and_b32_e32 v134, 0x7fffffff, v46
	v_and_b32_e32 v135, 0x7fffffff, v47
	v_pk_mul_f32 v[144:145], v[44:45], v[44:45]
	v_pk_mul_f32 v[146:147], v[46:47], v[46:47]
	v_pk_fma_f32 v[136:137], v[132:133], s[84:85], 1.0 op_sel_hi:[1,0,0]
	v_pk_fma_f32 v[138:139], v[134:135], s[84:85], 1.0 op_sel_hi:[1,0,0]
	v_pk_mul_f32 v[144:145], v[144:145], s[80:81] op_sel_hi:[1,0]
	v_pk_mul_f32 v[146:147], v[146:147], s[80:81] op_sel_hi:[1,0]
	v_rcp_f32_e32 v136, v136
	v_rcp_f32_e32 v137, v137
	v_rcp_f32_e32 v138, v138
	v_rcp_f32_e32 v139, v139
	v_exp_f32_e32 v144, v144
	v_exp_f32_e32 v145, v145
	v_exp_f32_e32 v146, v146
	v_exp_f32_e32 v147, v147
	v_pk_fma_f32 v[140:141], v[136:137], s[86:87], v[0:1] op_sel_hi:[1,0,0]
	v_pk_fma_f32 v[142:143], v[138:139], s[86:87], v[0:1] op_sel_hi:[1,0,0]
	v_pk_fma_f32 v[140:141], v[136:137], v[140:141], s[88:89] op_sel_hi:[1,1,0]
	v_pk_fma_f32 v[142:143], v[138:139], v[142:143], s[88:89] op_sel_hi:[1,1,0]
	v_pk_fma_f32 v[140:141], v[136:137], v[140:141], s[82:83] op_sel_hi:[1,1,0]
	v_pk_fma_f32 v[142:143], v[138:139], v[142:143], s[82:83] op_sel_hi:[1,1,0]
	v_pk_fma_f32 v[140:141], v[136:137], v[140:141], s[48:49] op_sel_hi:[1,1,0]
	v_pk_fma_f32 v[142:143], v[138:139], v[142:143], s[48:49] op_sel_hi:[1,1,0]
	v_pk_mul_f32 v[140:141], v[136:137], v[140:141]
	v_pk_mul_f32 v[142:143], v[138:139], v[142:143]
	v_pk_mul_f32 v[140:141], v[140:141], v[144:145]
	v_pk_mul_f32 v[142:143], v[142:143], v[146:147]
	v_max_f32_e32 v44, 0, v44
	v_max_f32_e32 v45, 0, v45
	v_max_f32_e32 v46, 0, v46
	v_max_f32_e32 v47, 0, v47
	v_pk_fma_f32 v[44:45], v[132:133], v[140:141], v[44:45] neg_lo:[1,0,0] neg_hi:[1,0,0]
	v_pk_fma_f32 v[46:47], v[134:135], v[142:143], v[46:47] neg_lo:[1,0,0] neg_hi:[1,0,0]
	v_and_b32_e32 v132, 0x7fffffff, v36
	v_and_b32_e32 v133, 0x7fffffff, v37
	v_and_b32_e32 v134, 0x7fffffff, v38
	v_and_b32_e32 v135, 0x7fffffff, v39
	v_pk_mul_f32 v[144:145], v[36:37], v[36:37]
	v_pk_mul_f32 v[146:147], v[38:39], v[38:39]
	v_pk_fma_f32 v[136:137], v[132:133], s[84:85], 1.0 op_sel_hi:[1,0,0]
	v_pk_fma_f32 v[138:139], v[134:135], s[84:85], 1.0 op_sel_hi:[1,0,0]
	v_pk_mul_f32 v[144:145], v[144:145], s[80:81] op_sel_hi:[1,0]
	v_pk_mul_f32 v[146:147], v[146:147], s[80:81] op_sel_hi:[1,0]
	v_rcp_f32_e32 v136, v136
	v_rcp_f32_e32 v137, v137
	v_rcp_f32_e32 v138, v138
	v_rcp_f32_e32 v139, v139
	v_exp_f32_e32 v144, v144
	v_exp_f32_e32 v145, v145
	v_exp_f32_e32 v146, v146
	v_exp_f32_e32 v147, v147
	v_pk_fma_f32 v[140:141], v[136:137], s[86:87], v[0:1] op_sel_hi:[1,0,0]
	v_pk_fma_f32 v[142:143], v[138:139], s[86:87], v[0:1] op_sel_hi:[1,0,0]
	v_pk_fma_f32 v[140:141], v[136:137], v[140:141], s[88:89] op_sel_hi:[1,1,0]
	v_pk_fma_f32 v[142:143], v[138:139], v[142:143], s[88:89] op_sel_hi:[1,1,0]
	v_pk_fma_f32 v[140:141], v[136:137], v[140:141], s[82:83] op_sel_hi:[1,1,0]
	v_pk_fma_f32 v[142:143], v[138:139], v[142:143], s[82:83] op_sel_hi:[1,1,0]
	v_pk_fma_f32 v[140:141], v[136:137], v[140:141], s[48:49] op_sel_hi:[1,1,0]
	v_pk_fma_f32 v[142:143], v[138:139], v[142:143], s[48:49] op_sel_hi:[1,1,0]
	v_pk_mul_f32 v[140:141], v[136:137], v[140:141]
	v_pk_mul_f32 v[142:143], v[138:139], v[142:143]
	v_pk_mul_f32 v[140:141], v[140:141], v[144:145]
	v_pk_mul_f32 v[142:143], v[142:143], v[146:147]
	v_max_f32_e32 v36, 0, v36
	v_max_f32_e32 v37, 0, v37
	v_max_f32_e32 v38, 0, v38
	v_max_f32_e32 v39, 0, v39
	v_pk_fma_f32 v[36:37], v[132:133], v[140:141], v[36:37] neg_lo:[1,0,0] neg_hi:[1,0,0]
	v_pk_fma_f32 v[38:39], v[134:135], v[142:143], v[38:39] neg_lo:[1,0,0] neg_hi:[1,0,0]
	v_cvt_pk_bf16_f32 v44, v44, v45
	v_cvt_pk_bf16_f32 v45, v46, v47
	v_cvt_pk_bf16_f32 v46, v36, v37
	v_cvt_pk_bf16_f32 v47, v38, v39
	global_store_dwordx4 v148, v[44:47], s[50:51] offset:256
	v_add_u32_e32 v148, s81, v148
	v_and_b32_e32 v132, 0x7fffffff, v32
	v_and_b32_e32 v133, 0x7fffffff, v33
	v_and_b32_e32 v134, 0x7fffffff, v34
	v_and_b32_e32 v135, 0x7fffffff, v35
	v_pk_mul_f32 v[144:145], v[32:33], v[32:33]
	v_pk_mul_f32 v[146:147], v[34:35], v[34:35]
	v_pk_fma_f32 v[136:137], v[132:133], s[84:85], 1.0 op_sel_hi:[1,0,0]
	v_pk_fma_f32 v[138:139], v[134:135], s[84:85], 1.0 op_sel_hi:[1,0,0]
	v_pk_mul_f32 v[144:145], v[144:145], s[80:81] op_sel_hi:[1,0]
	v_pk_mul_f32 v[146:147], v[146:147], s[80:81] op_sel_hi:[1,0]
	v_rcp_f32_e32 v136, v136
	v_rcp_f32_e32 v137, v137
	v_rcp_f32_e32 v138, v138
	v_rcp_f32_e32 v139, v139
	v_exp_f32_e32 v144, v144
	v_exp_f32_e32 v145, v145
	v_exp_f32_e32 v146, v146
	v_exp_f32_e32 v147, v147
	v_pk_fma_f32 v[140:141], v[136:137], s[86:87], v[0:1] op_sel_hi:[1,0,0]
	v_pk_fma_f32 v[142:143], v[138:139], s[86:87], v[0:1] op_sel_hi:[1,0,0]
	v_pk_fma_f32 v[140:141], v[136:137], v[140:141], s[88:89] op_sel_hi:[1,1,0]
	v_pk_fma_f32 v[142:143], v[138:139], v[142:143], s[88:89] op_sel_hi:[1,1,0]
	v_pk_fma_f32 v[140:141], v[136:137], v[140:141], s[82:83] op_sel_hi:[1,1,0]
	v_pk_fma_f32 v[142:143], v[138:139], v[142:143], s[82:83] op_sel_hi:[1,1,0]
	v_pk_fma_f32 v[140:141], v[136:137], v[140:141], s[48:49] op_sel_hi:[1,1,0]
	v_pk_fma_f32 v[142:143], v[138:139], v[142:143], s[48:49] op_sel_hi:[1,1,0]
	v_pk_mul_f32 v[140:141], v[136:137], v[140:141]
	v_pk_mul_f32 v[142:143], v[138:139], v[142:143]
	v_pk_mul_f32 v[140:141], v[140:141], v[144:145]
	v_pk_mul_f32 v[142:143], v[142:143], v[146:147]
	v_max_f32_e32 v32, 0, v32
	v_max_f32_e32 v33, 0, v33
	v_max_f32_e32 v34, 0, v34
	v_max_f32_e32 v35, 0, v35
	v_pk_fma_f32 v[32:33], v[132:133], v[140:141], v[32:33] neg_lo:[1,0,0] neg_hi:[1,0,0]
	v_pk_fma_f32 v[34:35], v[134:135], v[142:143], v[34:35] neg_lo:[1,0,0] neg_hi:[1,0,0]
	v_and_b32_e32 v132, 0x7fffffff, v24
	v_and_b32_e32 v133, 0x7fffffff, v25
	v_and_b32_e32 v134, 0x7fffffff, v26
	v_and_b32_e32 v135, 0x7fffffff, v27
	v_pk_mul_f32 v[144:145], v[24:25], v[24:25]
	v_pk_mul_f32 v[146:147], v[26:27], v[26:27]
	v_pk_fma_f32 v[136:137], v[132:133], s[84:85], 1.0 op_sel_hi:[1,0,0]
	v_pk_fma_f32 v[138:139], v[134:135], s[84:85], 1.0 op_sel_hi:[1,0,0]
	v_pk_mul_f32 v[144:145], v[144:145], s[80:81] op_sel_hi:[1,0]
	v_pk_mul_f32 v[146:147], v[146:147], s[80:81] op_sel_hi:[1,0]
	v_rcp_f32_e32 v136, v136
	v_rcp_f32_e32 v137, v137
	v_rcp_f32_e32 v138, v138
	v_rcp_f32_e32 v139, v139
	v_exp_f32_e32 v144, v144
	v_exp_f32_e32 v145, v145
	v_exp_f32_e32 v146, v146
	v_exp_f32_e32 v147, v147
	v_pk_fma_f32 v[140:141], v[136:137], s[86:87], v[0:1] op_sel_hi:[1,0,0]
	v_pk_fma_f32 v[142:143], v[138:139], s[86:87], v[0:1] op_sel_hi:[1,0,0]
	v_pk_fma_f32 v[140:141], v[136:137], v[140:141], s[88:89] op_sel_hi:[1,1,0]
	v_pk_fma_f32 v[142:143], v[138:139], v[142:143], s[88:89] op_sel_hi:[1,1,0]
	v_pk_fma_f32 v[140:141], v[136:137], v[140:141], s[82:83] op_sel_hi:[1,1,0]
	v_pk_fma_f32 v[142:143], v[138:139], v[142:143], s[82:83] op_sel_hi:[1,1,0]
	v_pk_fma_f32 v[140:141], v[136:137], v[140:141], s[48:49] op_sel_hi:[1,1,0]
	v_pk_fma_f32 v[142:143], v[138:139], v[142:143], s[48:49] op_sel_hi:[1,1,0]
	v_pk_mul_f32 v[140:141], v[136:137], v[140:141]
	v_pk_mul_f32 v[142:143], v[138:139], v[142:143]
	v_pk_mul_f32 v[140:141], v[140:141], v[144:145]
	v_pk_mul_f32 v[142:143], v[142:143], v[146:147]
	v_max_f32_e32 v24, 0, v24
	v_max_f32_e32 v25, 0, v25
	v_max_f32_e32 v26, 0, v26
	v_max_f32_e32 v27, 0, v27
	v_pk_fma_f32 v[24:25], v[132:133], v[140:141], v[24:25] neg_lo:[1,0,0] neg_hi:[1,0,0]
	v_pk_fma_f32 v[26:27], v[134:135], v[142:143], v[26:27] neg_lo:[1,0,0] neg_hi:[1,0,0]
	v_cvt_pk_bf16_f32 v32, v32, v33
	v_cvt_pk_bf16_f32 v33, v34, v35
	v_cvt_pk_bf16_f32 v34, v24, v25
	v_cvt_pk_bf16_f32 v35, v26, v27
	global_store_dwordx4 v148, v[32:35], s[50:51]
	v_and_b32_e32 v132, 0x7fffffff, v16
	v_and_b32_e32 v133, 0x7fffffff, v17
	v_and_b32_e32 v134, 0x7fffffff, v18
	v_and_b32_e32 v135, 0x7fffffff, v19
	v_pk_mul_f32 v[144:145], v[16:17], v[16:17]
	v_pk_mul_f32 v[146:147], v[18:19], v[18:19]
	v_pk_fma_f32 v[136:137], v[132:133], s[84:85], 1.0 op_sel_hi:[1,0,0]
	v_pk_fma_f32 v[138:139], v[134:135], s[84:85], 1.0 op_sel_hi:[1,0,0]
	v_pk_mul_f32 v[144:145], v[144:145], s[80:81] op_sel_hi:[1,0]
	v_pk_mul_f32 v[146:147], v[146:147], s[80:81] op_sel_hi:[1,0]
	v_rcp_f32_e32 v136, v136
	v_rcp_f32_e32 v137, v137
	v_rcp_f32_e32 v138, v138
	v_rcp_f32_e32 v139, v139
	v_exp_f32_e32 v144, v144
	v_exp_f32_e32 v145, v145
	v_exp_f32_e32 v146, v146
	v_exp_f32_e32 v147, v147
	v_pk_fma_f32 v[140:141], v[136:137], s[86:87], v[0:1] op_sel_hi:[1,0,0]
	v_pk_fma_f32 v[142:143], v[138:139], s[86:87], v[0:1] op_sel_hi:[1,0,0]
	v_pk_fma_f32 v[140:141], v[136:137], v[140:141], s[88:89] op_sel_hi:[1,1,0]
	v_pk_fma_f32 v[142:143], v[138:139], v[142:143], s[88:89] op_sel_hi:[1,1,0]
	v_pk_fma_f32 v[140:141], v[136:137], v[140:141], s[82:83] op_sel_hi:[1,1,0]
	v_pk_fma_f32 v[142:143], v[138:139], v[142:143], s[82:83] op_sel_hi:[1,1,0]
	v_pk_fma_f32 v[140:141], v[136:137], v[140:141], s[48:49] op_sel_hi:[1,1,0]
	v_pk_fma_f32 v[142:143], v[138:139], v[142:143], s[48:49] op_sel_hi:[1,1,0]
	v_pk_mul_f32 v[140:141], v[136:137], v[140:141]
	v_pk_mul_f32 v[142:143], v[138:139], v[142:143]
	v_pk_mul_f32 v[140:141], v[140:141], v[144:145]
	v_pk_mul_f32 v[142:143], v[142:143], v[146:147]
	v_max_f32_e32 v16, 0, v16
	v_max_f32_e32 v17, 0, v17
	v_max_f32_e32 v18, 0, v18
	v_max_f32_e32 v19, 0, v19
	v_pk_fma_f32 v[16:17], v[132:133], v[140:141], v[16:17] neg_lo:[1,0,0] neg_hi:[1,0,0]
	v_pk_fma_f32 v[18:19], v[134:135], v[142:143], v[18:19] neg_lo:[1,0,0] neg_hi:[1,0,0]
	v_and_b32_e32 v132, 0x7fffffff, v8
	v_and_b32_e32 v133, 0x7fffffff, v9
	v_and_b32_e32 v134, 0x7fffffff, v10
	v_and_b32_e32 v135, 0x7fffffff, v11
	v_pk_mul_f32 v[144:145], v[8:9], v[8:9]
	v_pk_mul_f32 v[146:147], v[10:11], v[10:11]
	v_pk_fma_f32 v[136:137], v[132:133], s[84:85], 1.0 op_sel_hi:[1,0,0]
	v_pk_fma_f32 v[138:139], v[134:135], s[84:85], 1.0 op_sel_hi:[1,0,0]
	v_pk_mul_f32 v[144:145], v[144:145], s[80:81] op_sel_hi:[1,0]
	v_pk_mul_f32 v[146:147], v[146:147], s[80:81] op_sel_hi:[1,0]
	v_rcp_f32_e32 v136, v136
	v_rcp_f32_e32 v137, v137
	v_rcp_f32_e32 v138, v138
	v_rcp_f32_e32 v139, v139
	v_exp_f32_e32 v144, v144
	v_exp_f32_e32 v145, v145
	v_exp_f32_e32 v146, v146
	v_exp_f32_e32 v147, v147
	v_pk_fma_f32 v[140:141], v[136:137], s[86:87], v[0:1] op_sel_hi:[1,0,0]
	v_pk_fma_f32 v[142:143], v[138:139], s[86:87], v[0:1] op_sel_hi:[1,0,0]
	v_pk_fma_f32 v[140:141], v[136:137], v[140:141], s[88:89] op_sel_hi:[1,1,0]
	v_pk_fma_f32 v[142:143], v[138:139], v[142:143], s[88:89] op_sel_hi:[1,1,0]
	v_pk_fma_f32 v[140:141], v[136:137], v[140:141], s[82:83] op_sel_hi:[1,1,0]
	v_pk_fma_f32 v[142:143], v[138:139], v[142:143], s[82:83] op_sel_hi:[1,1,0]
	v_pk_fma_f32 v[140:141], v[136:137], v[140:141], s[48:49] op_sel_hi:[1,1,0]
	v_pk_fma_f32 v[142:143], v[138:139], v[142:143], s[48:49] op_sel_hi:[1,1,0]
	v_pk_mul_f32 v[140:141], v[136:137], v[140:141]
	v_pk_mul_f32 v[142:143], v[138:139], v[142:143]
	v_pk_mul_f32 v[140:141], v[140:141], v[144:145]
	v_pk_mul_f32 v[142:143], v[142:143], v[146:147]
	v_max_f32_e32 v8, 0, v8
	v_max_f32_e32 v9, 0, v9
	v_max_f32_e32 v10, 0, v10
	v_max_f32_e32 v11, 0, v11
	v_pk_fma_f32 v[8:9], v[132:133], v[140:141], v[8:9] neg_lo:[1,0,0] neg_hi:[1,0,0]
	v_pk_fma_f32 v[10:11], v[134:135], v[142:143], v[10:11] neg_lo:[1,0,0] neg_hi:[1,0,0]
	v_cvt_pk_bf16_f32 v16, v16, v17
	v_cvt_pk_bf16_f32 v17, v18, v19
	v_cvt_pk_bf16_f32 v18, v8, v9
	v_cvt_pk_bf16_f32 v19, v10, v11
	global_store_dwordx4 v148, v[16:19], s[50:51] offset:256
	v_add_u32_e32 v148, s81, v148
	v_and_b32_e32 v132, 0x7fffffff, v28
	v_and_b32_e32 v133, 0x7fffffff, v29
	v_and_b32_e32 v134, 0x7fffffff, v30
	v_and_b32_e32 v135, 0x7fffffff, v31
	v_pk_mul_f32 v[144:145], v[28:29], v[28:29]
	v_pk_mul_f32 v[146:147], v[30:31], v[30:31]
	v_pk_fma_f32 v[136:137], v[132:133], s[84:85], 1.0 op_sel_hi:[1,0,0]
	v_pk_fma_f32 v[138:139], v[134:135], s[84:85], 1.0 op_sel_hi:[1,0,0]
	v_pk_mul_f32 v[144:145], v[144:145], s[80:81] op_sel_hi:[1,0]
	v_pk_mul_f32 v[146:147], v[146:147], s[80:81] op_sel_hi:[1,0]
	v_rcp_f32_e32 v136, v136
	v_rcp_f32_e32 v137, v137
	v_rcp_f32_e32 v138, v138
	v_rcp_f32_e32 v139, v139
	v_exp_f32_e32 v144, v144
	v_exp_f32_e32 v145, v145
	v_exp_f32_e32 v146, v146
	v_exp_f32_e32 v147, v147
	v_pk_fma_f32 v[140:141], v[136:137], s[86:87], v[0:1] op_sel_hi:[1,0,0]
	v_pk_fma_f32 v[142:143], v[138:139], s[86:87], v[0:1] op_sel_hi:[1,0,0]
	v_pk_fma_f32 v[140:141], v[136:137], v[140:141], s[88:89] op_sel_hi:[1,1,0]
	v_pk_fma_f32 v[142:143], v[138:139], v[142:143], s[88:89] op_sel_hi:[1,1,0]
	v_pk_fma_f32 v[140:141], v[136:137], v[140:141], s[82:83] op_sel_hi:[1,1,0]
	v_pk_fma_f32 v[142:143], v[138:139], v[142:143], s[82:83] op_sel_hi:[1,1,0]
	v_pk_fma_f32 v[140:141], v[136:137], v[140:141], s[48:49] op_sel_hi:[1,1,0]
	v_pk_fma_f32 v[142:143], v[138:139], v[142:143], s[48:49] op_sel_hi:[1,1,0]
	v_pk_mul_f32 v[140:141], v[136:137], v[140:141]
	v_pk_mul_f32 v[142:143], v[138:139], v[142:143]
	v_pk_mul_f32 v[140:141], v[140:141], v[144:145]
	v_pk_mul_f32 v[142:143], v[142:143], v[146:147]
	v_max_f32_e32 v28, 0, v28
	v_max_f32_e32 v29, 0, v29
	v_max_f32_e32 v30, 0, v30
	v_max_f32_e32 v31, 0, v31
	v_pk_fma_f32 v[28:29], v[132:133], v[140:141], v[28:29] neg_lo:[1,0,0] neg_hi:[1,0,0]
	v_pk_fma_f32 v[30:31], v[134:135], v[142:143], v[30:31] neg_lo:[1,0,0] neg_hi:[1,0,0]
	v_and_b32_e32 v132, 0x7fffffff, v20
	v_and_b32_e32 v133, 0x7fffffff, v21
	v_and_b32_e32 v134, 0x7fffffff, v22
	v_and_b32_e32 v135, 0x7fffffff, v23
	v_pk_mul_f32 v[144:145], v[20:21], v[20:21]
	v_pk_mul_f32 v[146:147], v[22:23], v[22:23]
	v_pk_fma_f32 v[136:137], v[132:133], s[84:85], 1.0 op_sel_hi:[1,0,0]
	v_pk_fma_f32 v[138:139], v[134:135], s[84:85], 1.0 op_sel_hi:[1,0,0]
	v_pk_mul_f32 v[144:145], v[144:145], s[80:81] op_sel_hi:[1,0]
	v_pk_mul_f32 v[146:147], v[146:147], s[80:81] op_sel_hi:[1,0]
	v_rcp_f32_e32 v136, v136
	v_rcp_f32_e32 v137, v137
	v_rcp_f32_e32 v138, v138
	v_rcp_f32_e32 v139, v139
	v_exp_f32_e32 v144, v144
	v_exp_f32_e32 v145, v145
	v_exp_f32_e32 v146, v146
	v_exp_f32_e32 v147, v147
	v_pk_fma_f32 v[140:141], v[136:137], s[86:87], v[0:1] op_sel_hi:[1,0,0]
	v_pk_fma_f32 v[142:143], v[138:139], s[86:87], v[0:1] op_sel_hi:[1,0,0]
	v_pk_fma_f32 v[140:141], v[136:137], v[140:141], s[88:89] op_sel_hi:[1,1,0]
	v_pk_fma_f32 v[142:143], v[138:139], v[142:143], s[88:89] op_sel_hi:[1,1,0]
	v_pk_fma_f32 v[140:141], v[136:137], v[140:141], s[82:83] op_sel_hi:[1,1,0]
	v_pk_fma_f32 v[142:143], v[138:139], v[142:143], s[82:83] op_sel_hi:[1,1,0]
	v_pk_fma_f32 v[140:141], v[136:137], v[140:141], s[48:49] op_sel_hi:[1,1,0]
	v_pk_fma_f32 v[142:143], v[138:139], v[142:143], s[48:49] op_sel_hi:[1,1,0]
	v_pk_mul_f32 v[140:141], v[136:137], v[140:141]
	v_pk_mul_f32 v[142:143], v[138:139], v[142:143]
	v_pk_mul_f32 v[140:141], v[140:141], v[144:145]
	v_pk_mul_f32 v[142:143], v[142:143], v[146:147]
	v_max_f32_e32 v20, 0, v20
	v_max_f32_e32 v21, 0, v21
	v_max_f32_e32 v22, 0, v22
	v_max_f32_e32 v23, 0, v23
	v_pk_fma_f32 v[20:21], v[132:133], v[140:141], v[20:21] neg_lo:[1,0,0] neg_hi:[1,0,0]
	v_pk_fma_f32 v[22:23], v[134:135], v[142:143], v[22:23] neg_lo:[1,0,0] neg_hi:[1,0,0]
	v_cvt_pk_bf16_f32 v28, v28, v29
	v_cvt_pk_bf16_f32 v29, v30, v31
	v_cvt_pk_bf16_f32 v30, v20, v21
	v_cvt_pk_bf16_f32 v31, v22, v23
	global_store_dwordx4 v148, v[28:31], s[50:51]
	v_and_b32_e32 v132, 0x7fffffff, v12
	v_and_b32_e32 v133, 0x7fffffff, v13
	v_and_b32_e32 v134, 0x7fffffff, v14
	v_and_b32_e32 v135, 0x7fffffff, v15
	v_pk_mul_f32 v[144:145], v[12:13], v[12:13]
	v_pk_mul_f32 v[146:147], v[14:15], v[14:15]
	v_pk_fma_f32 v[136:137], v[132:133], s[84:85], 1.0 op_sel_hi:[1,0,0]
	v_pk_fma_f32 v[138:139], v[134:135], s[84:85], 1.0 op_sel_hi:[1,0,0]
	v_pk_mul_f32 v[144:145], v[144:145], s[80:81] op_sel_hi:[1,0]
	v_pk_mul_f32 v[146:147], v[146:147], s[80:81] op_sel_hi:[1,0]
	v_rcp_f32_e32 v136, v136
	v_rcp_f32_e32 v137, v137
	v_rcp_f32_e32 v138, v138
	v_rcp_f32_e32 v139, v139
	v_exp_f32_e32 v144, v144
	v_exp_f32_e32 v145, v145
	v_exp_f32_e32 v146, v146
	v_exp_f32_e32 v147, v147
	v_pk_fma_f32 v[140:141], v[136:137], s[86:87], v[0:1] op_sel_hi:[1,0,0]
	v_pk_fma_f32 v[142:143], v[138:139], s[86:87], v[0:1] op_sel_hi:[1,0,0]
	v_pk_fma_f32 v[140:141], v[136:137], v[140:141], s[88:89] op_sel_hi:[1,1,0]
	v_pk_fma_f32 v[142:143], v[138:139], v[142:143], s[88:89] op_sel_hi:[1,1,0]
	v_pk_fma_f32 v[140:141], v[136:137], v[140:141], s[82:83] op_sel_hi:[1,1,0]
	v_pk_fma_f32 v[142:143], v[138:139], v[142:143], s[82:83] op_sel_hi:[1,1,0]
	v_pk_fma_f32 v[140:141], v[136:137], v[140:141], s[48:49] op_sel_hi:[1,1,0]
	v_pk_fma_f32 v[142:143], v[138:139], v[142:143], s[48:49] op_sel_hi:[1,1,0]
	v_pk_mul_f32 v[140:141], v[136:137], v[140:141]
	v_pk_mul_f32 v[142:143], v[138:139], v[142:143]
	v_pk_mul_f32 v[140:141], v[140:141], v[144:145]
	v_pk_mul_f32 v[142:143], v[142:143], v[146:147]
	v_max_f32_e32 v12, 0, v12
	v_max_f32_e32 v13, 0, v13
	v_max_f32_e32 v14, 0, v14
	v_max_f32_e32 v15, 0, v15
	v_pk_fma_f32 v[12:13], v[132:133], v[140:141], v[12:13] neg_lo:[1,0,0] neg_hi:[1,0,0]
	v_pk_fma_f32 v[14:15], v[134:135], v[142:143], v[14:15] neg_lo:[1,0,0] neg_hi:[1,0,0]
	v_and_b32_e32 v132, 0x7fffffff, v4
	v_and_b32_e32 v133, 0x7fffffff, v5
	v_and_b32_e32 v134, 0x7fffffff, v6
	v_and_b32_e32 v135, 0x7fffffff, v7
	v_pk_mul_f32 v[144:145], v[4:5], v[4:5]
	v_pk_mul_f32 v[146:147], v[6:7], v[6:7]
	v_pk_fma_f32 v[136:137], v[132:133], s[84:85], 1.0 op_sel_hi:[1,0,0]
	v_pk_fma_f32 v[138:139], v[134:135], s[84:85], 1.0 op_sel_hi:[1,0,0]
	v_pk_mul_f32 v[144:145], v[144:145], s[80:81] op_sel_hi:[1,0]
	v_pk_mul_f32 v[146:147], v[146:147], s[80:81] op_sel_hi:[1,0]
	v_rcp_f32_e32 v136, v136
	v_rcp_f32_e32 v137, v137
	v_rcp_f32_e32 v138, v138
	v_rcp_f32_e32 v139, v139
	v_exp_f32_e32 v144, v144
	v_exp_f32_e32 v145, v145
	v_exp_f32_e32 v146, v146
	v_exp_f32_e32 v147, v147
	v_pk_fma_f32 v[140:141], v[136:137], s[86:87], v[0:1] op_sel_hi:[1,0,0]
	v_pk_fma_f32 v[142:143], v[138:139], s[86:87], v[0:1] op_sel_hi:[1,0,0]
	v_pk_fma_f32 v[140:141], v[136:137], v[140:141], s[88:89] op_sel_hi:[1,1,0]
	v_pk_fma_f32 v[142:143], v[138:139], v[142:143], s[88:89] op_sel_hi:[1,1,0]
	v_pk_fma_f32 v[140:141], v[136:137], v[140:141], s[82:83] op_sel_hi:[1,1,0]
	v_pk_fma_f32 v[142:143], v[138:139], v[142:143], s[82:83] op_sel_hi:[1,1,0]
	v_pk_fma_f32 v[140:141], v[136:137], v[140:141], s[48:49] op_sel_hi:[1,1,0]
	v_pk_fma_f32 v[142:143], v[138:139], v[142:143], s[48:49] op_sel_hi:[1,1,0]
	v_pk_mul_f32 v[140:141], v[136:137], v[140:141]
	v_pk_mul_f32 v[142:143], v[138:139], v[142:143]
	v_pk_mul_f32 v[140:141], v[140:141], v[144:145]
	v_pk_mul_f32 v[142:143], v[142:143], v[146:147]
	v_max_f32_e32 v4, 0, v4
	v_max_f32_e32 v5, 0, v5
	v_max_f32_e32 v6, 0, v6
	v_max_f32_e32 v7, 0, v7
	v_pk_fma_f32 v[4:5], v[132:133], v[140:141], v[4:5] neg_lo:[1,0,0] neg_hi:[1,0,0]
	v_pk_fma_f32 v[6:7], v[134:135], v[142:143], v[6:7] neg_lo:[1,0,0] neg_hi:[1,0,0]
	v_cvt_pk_bf16_f32 v12, v12, v13
	v_cvt_pk_bf16_f32 v13, v14, v15
	v_cvt_pk_bf16_f32 v14, v4, v5
	v_cvt_pk_bf16_f32 v15, v6, v7
	global_store_dwordx4 v148, v[12:15], s[50:51] offset:256
	s_branch .LBB0_326

.Ltramp_104:
	s_branch .LBB0_104
.LBB0_330:
	s_load_dwordx2 s[38:39], s[28:29], 0xa8
	s_andn2_b64 vcc, exec, s[40:41]
	s_cbranch_vccnz .LBB0_114

.LBB0_540:
	s_cmp_lt_u32 s68, 3
	s_cbranch_scc0 .Lp25_last
	v_lshl_or_b32 v90, s69, 8, v161
	v_ashrrev_i32_e32 v91, 31, v90
	v_lshl_add_u64 v[90:91], v[90:91], 2, s[28:29]
	global_load_dwordx4 v[102:105], v[90:91], off
	global_load_dwordx4 v[98:101], v[90:91], off offset:16
	global_load_dwordx4 v[94:97], v[90:91], off offset:512
	s_nop 0
	global_load_dwordx4 v[90:93], v[90:91], off offset:528
	s_mul_i32 s43, s70, 12
	s_add_i32 s60, s43, s69
	s_ashr_i32 s61, s60, 31
	s_lshl_b64 s[60:61], s[60:61], 17
	s_add_u32 s60, s60, 0x1000
	s_addc_u32 s61, s61, 0
	v_lshl_add_u64 v[158:159], v[152:153], 0, s[60:61]
	s_mov_b32 s60, 0xbfb8aa3b
	s_mov_b32 s61, 0xbfb8aa3b
	s_waitcnt vmcnt(0)
	v_pk_mul_f32 v[102:103], v[102:103], s[60:61]
	v_pk_mul_f32 v[104:105], v[104:105], s[60:61]
	v_pk_mul_f32 v[98:99], v[98:99], s[60:61]
	v_pk_mul_f32 v[100:101], v[100:101], s[60:61]
	v_pk_mul_f32 v[94:95], v[94:95], s[60:61]
	v_pk_mul_f32 v[96:97], v[96:97], s[60:61]
	v_pk_mul_f32 v[90:91], v[90:91], s[60:61]
	v_pk_mul_f32 v[92:93], v[92:93], s[60:61]
	v_pk_fma_f32 v[142:143], v[142:143], s[60:61], v[102:103]
	v_pk_fma_f32 v[144:145], v[144:145], s[60:61], v[104:105]
	v_pk_fma_f32 v[138:139], v[138:139], s[60:61], v[98:99]
	v_pk_fma_f32 v[140:141], v[140:141], s[60:61], v[100:101]
	v_exp_f32_e32 v142, v142
	v_exp_f32_e32 v143, v143
	v_exp_f32_e32 v144, v144
	v_exp_f32_e32 v145, v145
	v_exp_f32_e32 v138, v138
	v_exp_f32_e32 v139, v139
	v_exp_f32_e32 v140, v140
	v_exp_f32_e32 v141, v141
	v_pk_add_f32 v[142:143], v[142:143], 1.0 op_sel_hi:[1,0]
	v_pk_add_f32 v[144:145], v[144:145], 1.0 op_sel_hi:[1,0]
	v_pk_add_f32 v[138:139], v[138:139], 1.0 op_sel_hi:[1,0]
	v_pk_add_f32 v[140:141], v[140:141], 1.0 op_sel_hi:[1,0]
	v_min_f32_e32 v142, 0x5d5e0b6b, v142
	v_min_f32_e32 v143, 0x5d5e0b6b, v143
	v_min_f32_e32 v144, 0x5d5e0b6b, v144
	v_min_f32_e32 v145, 0x5d5e0b6b, v145
	v_min_f32_e32 v138, 0x5d5e0b6b, v138
	v_min_f32_e32 v139, 0x5d5e0b6b, v139
	v_min_f32_e32 v140, 0x5d5e0b6b, v140
	v_min_f32_e32 v141, 0x5d5e0b6b, v141
	v_cvt_pk_bf16_f32 v142, v142, v143
	v_cvt_pk_bf16_f32 v143, v144, v145
	v_cvt_pk_bf16_f32 v144, v138, v139
	v_cvt_pk_bf16_f32 v145, v140, v141
	global_store_dwordx4 v[158:159], v[142:145], off offset:-4096
	v_pk_fma_f32 v[134:135], v[134:135], s[60:61], v[94:95]
	v_pk_fma_f32 v[136:137], v[136:137], s[60:61], v[96:97]
	v_pk_fma_f32 v[130:131], v[130:131], s[60:61], v[90:91]
	v_pk_fma_f32 v[132:133], v[132:133], s[60:61], v[92:93]
	v_exp_f32_e32 v134, v134
	v_exp_f32_e32 v135, v135
	v_exp_f32_e32 v136, v136
	v_exp_f32_e32 v137, v137
	v_exp_f32_e32 v130, v130
	v_exp_f32_e32 v131, v131
	v_exp_f32_e32 v132, v132
	v_exp_f32_e32 v133, v133
	v_pk_add_f32 v[134:135], v[134:135], 1.0 op_sel_hi:[1,0]
	v_pk_add_f32 v[136:137], v[136:137], 1.0 op_sel_hi:[1,0]
	v_pk_add_f32 v[130:131], v[130:131], 1.0 op_sel_hi:[1,0]
	v_pk_add_f32 v[132:133], v[132:133], 1.0 op_sel_hi:[1,0]
	v_min_f32_e32 v134, 0x5d5e0b6b, v134
	v_min_f32_e32 v135, 0x5d5e0b6b, v135
	v_min_f32_e32 v136, 0x5d5e0b6b, v136
	v_min_f32_e32 v137, 0x5d5e0b6b, v137
	v_min_f32_e32 v130, 0x5d5e0b6b, v130
	v_min_f32_e32 v131, 0x5d5e0b6b, v131
	v_min_f32_e32 v132, 0x5d5e0b6b, v132
	v_min_f32_e32 v133, 0x5d5e0b6b, v133
	v_cvt_pk_bf16_f32 v134, v134, v135
	v_cvt_pk_bf16_f32 v135, v136, v137
	v_cvt_pk_bf16_f32 v136, v130, v131
	v_cvt_pk_bf16_f32 v137, v132, v133
	global_store_dwordx4 v[158:159], v[134:137], off offset:-3072
	v_pk_fma_f32 v[126:127], v[126:127], s[60:61], v[102:103]
	v_pk_fma_f32 v[128:129], v[128:129], s[60:61], v[104:105]
	v_pk_fma_f32 v[122:123], v[122:123], s[60:61], v[98:99]
	v_pk_fma_f32 v[124:125], v[124:125], s[60:61], v[100:101]
	v_exp_f32_e32 v126, v126
	v_exp_f32_e32 v127, v127
	v_exp_f32_e32 v128, v128
	v_exp_f32_e32 v129, v129
	v_exp_f32_e32 v122, v122
	v_exp_f32_e32 v123, v123
	v_exp_f32_e32 v124, v124
	v_exp_f32_e32 v125, v125
	v_pk_add_f32 v[126:127], v[126:127], 1.0 op_sel_hi:[1,0]
	v_pk_add_f32 v[128:129], v[128:129], 1.0 op_sel_hi:[1,0]
	v_pk_add_f32 v[122:123], v[122:123], 1.0 op_sel_hi:[1,0]
	v_pk_add_f32 v[124:125], v[124:125], 1.0 op_sel_hi:[1,0]
	v_min_f32_e32 v126, 0x5d5e0b6b, v126
	v_min_f32_e32 v127, 0x5d5e0b6b, v127
	v_min_f32_e32 v128, 0x5d5e0b6b, v128
	v_min_f32_e32 v129, 0x5d5e0b6b, v129
	v_min_f32_e32 v122, 0x5d5e0b6b, v122
	v_min_f32_e32 v123, 0x5d5e0b6b, v123
	v_min_f32_e32 v124, 0x5d5e0b6b, v124
	v_min_f32_e32 v125, 0x5d5e0b6b, v125
	v_cvt_pk_bf16_f32 v126, v126, v127
	v_cvt_pk_bf16_f32 v127, v128, v129
	v_cvt_pk_bf16_f32 v128, v122, v123
	v_cvt_pk_bf16_f32 v129, v124, v125
	global_store_dwordx4 v[158:159], v[126:129], off offset:-2048
	v_pk_fma_f32 v[118:119], v[118:119], s[60:61], v[94:95]
	v_pk_fma_f32 v[120:121], v[120:121], s[60:61], v[96:97]
	v_pk_fma_f32 v[114:115], v[114:115], s[60:61], v[90:91]
	v_pk_fma_f32 v[116:117], v[116:117], s[60:61], v[92:93]
	v_exp_f32_e32 v118, v118
	v_exp_f32_e32 v119, v119
	v_exp_f32_e32 v120, v120
	v_exp_f32_e32 v121, v121
	v_exp_f32_e32 v114, v114
	v_exp_f32_e32 v115, v115
	v_exp_f32_e32 v116, v116
	v_exp_f32_e32 v117, v117
	v_pk_add_f32 v[118:119], v[118:119], 1.0 op_sel_hi:[1,0]
	v_pk_add_f32 v[120:121], v[120:121], 1.0 op_sel_hi:[1,0]
	v_pk_add_f32 v[114:115], v[114:115], 1.0 op_sel_hi:[1,0]
	v_pk_add_f32 v[116:117], v[116:117], 1.0 op_sel_hi:[1,0]
	v_min_f32_e32 v118, 0x5d5e0b6b, v118
	v_min_f32_e32 v119, 0x5d5e0b6b, v119
	v_min_f32_e32 v120, 0x5d5e0b6b, v120
	v_min_f32_e32 v121, 0x5d5e0b6b, v121
	v_min_f32_e32 v114, 0x5d5e0b6b, v114
	v_min_f32_e32 v115, 0x5d5e0b6b, v115
	v_min_f32_e32 v116, 0x5d5e0b6b, v116
	v_min_f32_e32 v117, 0x5d5e0b6b, v117
	v_cvt_pk_bf16_f32 v118, v118, v119
	v_cvt_pk_bf16_f32 v119, v120, v121
	v_cvt_pk_bf16_f32 v120, v114, v115
	v_cvt_pk_bf16_f32 v121, v116, v117
	global_store_dwordx4 v[158:159], v[118:121], off offset:-1024
	v_pk_fma_f32 v[110:111], v[110:111], s[60:61], v[102:103]
	v_pk_fma_f32 v[112:113], v[112:113], s[60:61], v[104:105]
	v_pk_fma_f32 v[106:107], v[106:107], s[60:61], v[98:99]
	v_pk_fma_f32 v[108:109], v[108:109], s[60:61], v[100:101]
	v_exp_f32_e32 v110, v110
	v_exp_f32_e32 v111, v111
	v_exp_f32_e32 v112, v112
	v_exp_f32_e32 v113, v113
	v_exp_f32_e32 v106, v106
	v_exp_f32_e32 v107, v107
	v_exp_f32_e32 v108, v108
	v_exp_f32_e32 v109, v109
	v_pk_add_f32 v[110:111], v[110:111], 1.0 op_sel_hi:[1,0]
	v_pk_add_f32 v[112:113], v[112:113], 1.0 op_sel_hi:[1,0]
	v_pk_add_f32 v[106:107], v[106:107], 1.0 op_sel_hi:[1,0]
	v_pk_add_f32 v[108:109], v[108:109], 1.0 op_sel_hi:[1,0]
	v_min_f32_e32 v110, 0x5d5e0b6b, v110
	v_min_f32_e32 v111, 0x5d5e0b6b, v111
	v_min_f32_e32 v112, 0x5d5e0b6b, v112
	v_min_f32_e32 v113, 0x5d5e0b6b, v113
	v_min_f32_e32 v106, 0x5d5e0b6b, v106
	v_min_f32_e32 v107, 0x5d5e0b6b, v107
	v_min_f32_e32 v108, 0x5d5e0b6b, v108
	v_min_f32_e32 v109, 0x5d5e0b6b, v109
	v_cvt_pk_bf16_f32 v110, v110, v111
	v_cvt_pk_bf16_f32 v111, v112, v113
	v_cvt_pk_bf16_f32 v112, v106, v107
	v_cvt_pk_bf16_f32 v113, v108, v109
	global_store_dwordx4 v[158:159], v[110:113], off
	v_pk_fma_f32 v[86:87], v[86:87], s[60:61], v[94:95]
	v_pk_fma_f32 v[88:89], v[88:89], s[60:61], v[96:97]
	v_pk_fma_f32 v[82:83], v[82:83], s[60:61], v[90:91]
	v_pk_fma_f32 v[84:85], v[84:85], s[60:61], v[92:93]
	v_exp_f32_e32 v86, v86
	v_exp_f32_e32 v87, v87
	v_exp_f32_e32 v88, v88
	v_exp_f32_e32 v89, v89
	v_exp_f32_e32 v82, v82
	v_exp_f32_e32 v83, v83
	v_exp_f32_e32 v84, v84
	v_exp_f32_e32 v85, v85
	v_pk_add_f32 v[86:87], v[86:87], 1.0 op_sel_hi:[1,0]
	v_pk_add_f32 v[88:89], v[88:89], 1.0 op_sel_hi:[1,0]
	v_pk_add_f32 v[82:83], v[82:83], 1.0 op_sel_hi:[1,0]
	v_pk_add_f32 v[84:85], v[84:85], 1.0 op_sel_hi:[1,0]
	v_min_f32_e32 v86, 0x5d5e0b6b, v86
	v_min_f32_e32 v87, 0x5d5e0b6b, v87
	v_min_f32_e32 v88, 0x5d5e0b6b, v88
	v_min_f32_e32 v89, 0x5d5e0b6b, v89
	v_min_f32_e32 v82, 0x5d5e0b6b, v82
	v_min_f32_e32 v83, 0x5d5e0b6b, v83
	v_min_f32_e32 v84, 0x5d5e0b6b, v84
	v_min_f32_e32 v85, 0x5d5e0b6b, v85
	v_cvt_pk_bf16_f32 v86, v86, v87
	v_cvt_pk_bf16_f32 v87, v88, v89
	v_cvt_pk_bf16_f32 v88, v82, v83
	v_cvt_pk_bf16_f32 v89, v84, v85
	global_store_dwordx4 v[158:159], v[86:89], off offset:1024
	v_pk_fma_f32 v[78:79], v[78:79], s[60:61], v[102:103]
	v_pk_fma_f32 v[80:81], v[80:81], s[60:61], v[104:105]
	v_pk_fma_f32 v[74:75], v[74:75], s[60:61], v[98:99]
	v_pk_fma_f32 v[76:77], v[76:77], s[60:61], v[100:101]
	v_exp_f32_e32 v78, v78
	v_exp_f32_e32 v79, v79
	v_exp_f32_e32 v80, v80
	v_exp_f32_e32 v81, v81
	v_exp_f32_e32 v74, v74
	v_exp_f32_e32 v75, v75
	v_exp_f32_e32 v76, v76
	v_exp_f32_e32 v77, v77
	v_pk_add_f32 v[78:79], v[78:79], 1.0 op_sel_hi:[1,0]
	v_pk_add_f32 v[80:81], v[80:81], 1.0 op_sel_hi:[1,0]
	v_pk_add_f32 v[74:75], v[74:75], 1.0 op_sel_hi:[1,0]
	v_pk_add_f32 v[76:77], v[76:77], 1.0 op_sel_hi:[1,0]
	v_min_f32_e32 v78, 0x5d5e0b6b, v78
	v_min_f32_e32 v79, 0x5d5e0b6b, v79
	v_min_f32_e32 v80, 0x5d5e0b6b, v80
	v_min_f32_e32 v81, 0x5d5e0b6b, v81
	v_min_f32_e32 v74, 0x5d5e0b6b, v74
	v_min_f32_e32 v75, 0x5d5e0b6b, v75
	v_min_f32_e32 v76, 0x5d5e0b6b, v76
	v_min_f32_e32 v77, 0x5d5e0b6b, v77
	v_cvt_pk_bf16_f32 v78, v78, v79
	v_cvt_pk_bf16_f32 v79, v80, v81
	v_cvt_pk_bf16_f32 v80, v74, v75
	v_cvt_pk_bf16_f32 v81, v76, v77
	global_store_dwordx4 v[158:159], v[78:81], off offset:2048
	v_pk_fma_f32 v[70:71], v[70:71], s[60:61], v[94:95]
	v_pk_fma_f32 v[72:73], v[72:73], s[60:61], v[96:97]
	v_pk_fma_f32 v[66:67], v[66:67], s[60:61], v[90:91]
	v_pk_fma_f32 v[68:69], v[68:69], s[60:61], v[92:93]
	v_exp_f32_e32 v70, v70
	v_exp_f32_e32 v71, v71
	v_exp_f32_e32 v72, v72
	v_exp_f32_e32 v73, v73
	v_exp_f32_e32 v66, v66
	v_exp_f32_e32 v67, v67
	v_exp_f32_e32 v68, v68
	v_exp_f32_e32 v69, v69
	v_pk_add_f32 v[70:71], v[70:71], 1.0 op_sel_hi:[1,0]
	v_pk_add_f32 v[72:73], v[72:73], 1.0 op_sel_hi:[1,0]
	v_pk_add_f32 v[66:67], v[66:67], 1.0 op_sel_hi:[1,0]
	v_pk_add_f32 v[68:69], v[68:69], 1.0 op_sel_hi:[1,0]
	v_min_f32_e32 v70, 0x5d5e0b6b, v70
	v_min_f32_e32 v71, 0x5d5e0b6b, v71
	v_min_f32_e32 v72, 0x5d5e0b6b, v72
	v_min_f32_e32 v73, 0x5d5e0b6b, v73
	v_min_f32_e32 v66, 0x5d5e0b6b, v66
	v_min_f32_e32 v67, 0x5d5e0b6b, v67
	v_min_f32_e32 v68, 0x5d5e0b6b, v68
	v_min_f32_e32 v69, 0x5d5e0b6b, v69
	v_cvt_pk_bf16_f32 v70, v70, v71
	v_cvt_pk_bf16_f32 v71, v72, v73
	v_cvt_pk_bf16_f32 v72, v66, v67
	v_cvt_pk_bf16_f32 v73, v68, v69
	global_store_dwordx4 v[158:159], v[70:73], off offset:3072
	v_add_co_u32_e32 v158, vcc, 0x2000, v158
	s_nop 1
	v_addc_co_u32_e32 v159, vcc, 0, v159, vcc
	v_pk_fma_f32 v[62:63], v[62:63], s[60:61], v[102:103]
	v_pk_fma_f32 v[64:65], v[64:65], s[60:61], v[104:105]
	v_pk_fma_f32 v[58:59], v[58:59], s[60:61], v[98:99]
	v_pk_fma_f32 v[60:61], v[60:61], s[60:61], v[100:101]
	v_exp_f32_e32 v62, v62
	v_exp_f32_e32 v63, v63
	v_exp_f32_e32 v64, v64
	v_exp_f32_e32 v65, v65
	v_exp_f32_e32 v58, v58
	v_exp_f32_e32 v59, v59
	v_exp_f32_e32 v60, v60
	v_exp_f32_e32 v61, v61
	v_pk_add_f32 v[62:63], v[62:63], 1.0 op_sel_hi:[1,0]
	v_pk_add_f32 v[64:65], v[64:65], 1.0 op_sel_hi:[1,0]
	v_pk_add_f32 v[58:59], v[58:59], 1.0 op_sel_hi:[1,0]
	v_pk_add_f32 v[60:61], v[60:61], 1.0 op_sel_hi:[1,0]
	v_min_f32_e32 v62, 0x5d5e0b6b, v62
	v_min_f32_e32 v63, 0x5d5e0b6b, v63
	v_min_f32_e32 v64, 0x5d5e0b6b, v64
	v_min_f32_e32 v65, 0x5d5e0b6b, v65
	v_min_f32_e32 v58, 0x5d5e0b6b, v58
	v_min_f32_e32 v59, 0x5d5e0b6b, v59
	v_min_f32_e32 v60, 0x5d5e0b6b, v60
	v_min_f32_e32 v61, 0x5d5e0b6b, v61
	v_cvt_pk_bf16_f32 v62, v62, v63
	v_cvt_pk_bf16_f32 v63, v64, v65
	v_cvt_pk_bf16_f32 v64, v58, v59
	v_cvt_pk_bf16_f32 v65, v60, v61
	global_store_dwordx4 v[158:159], v[62:65], off offset:-4096
	v_pk_fma_f32 v[54:55], v[54:55], s[60:61], v[94:95]
	v_pk_fma_f32 v[56:57], v[56:57], s[60:61], v[96:97]
	v_pk_fma_f32 v[50:51], v[50:51], s[60:61], v[90:91]
	v_pk_fma_f32 v[52:53], v[52:53], s[60:61], v[92:93]
	v_exp_f32_e32 v54, v54
	v_exp_f32_e32 v55, v55
	v_exp_f32_e32 v56, v56
	v_exp_f32_e32 v57, v57
	v_exp_f32_e32 v50, v50
	v_exp_f32_e32 v51, v51
	v_exp_f32_e32 v52, v52
	v_exp_f32_e32 v53, v53
	v_pk_add_f32 v[54:55], v[54:55], 1.0 op_sel_hi:[1,0]
	v_pk_add_f32 v[56:57], v[56:57], 1.0 op_sel_hi:[1,0]
	v_pk_add_f32 v[50:51], v[50:51], 1.0 op_sel_hi:[1,0]
	v_pk_add_f32 v[52:53], v[52:53], 1.0 op_sel_hi:[1,0]
	v_min_f32_e32 v54, 0x5d5e0b6b, v54
	v_min_f32_e32 v55, 0x5d5e0b6b, v55
	v_min_f32_e32 v56, 0x5d5e0b6b, v56
	v_min_f32_e32 v57, 0x5d5e0b6b, v57
	v_min_f32_e32 v50, 0x5d5e0b6b, v50
	v_min_f32_e32 v51, 0x5d5e0b6b, v51
	v_min_f32_e32 v52, 0x5d5e0b6b, v52
	v_min_f32_e32 v53, 0x5d5e0b6b, v53
	v_cvt_pk_bf16_f32 v54, v54, v55
	v_cvt_pk_bf16_f32 v55, v56, v57
	v_cvt_pk_bf16_f32 v56, v50, v51
	v_cvt_pk_bf16_f32 v57, v52, v53
	global_store_dwordx4 v[158:159], v[54:57], off offset:-3072
	v_pk_fma_f32 v[46:47], v[46:47], s[60:61], v[102:103]
	v_pk_fma_f32 v[48:49], v[48:49], s[60:61], v[104:105]
	v_pk_fma_f32 v[42:43], v[42:43], s[60:61], v[98:99]
	v_pk_fma_f32 v[44:45], v[44:45], s[60:61], v[100:101]
	v_exp_f32_e32 v46, v46
	v_exp_f32_e32 v47, v47
	v_exp_f32_e32 v48, v48
	v_exp_f32_e32 v49, v49
	v_exp_f32_e32 v42, v42
	v_exp_f32_e32 v43, v43
	v_exp_f32_e32 v44, v44
	v_exp_f32_e32 v45, v45
	v_pk_add_f32 v[46:47], v[46:47], 1.0 op_sel_hi:[1,0]
	v_pk_add_f32 v[48:49], v[48:49], 1.0 op_sel_hi:[1,0]
	v_pk_add_f32 v[42:43], v[42:43], 1.0 op_sel_hi:[1,0]
	v_pk_add_f32 v[44:45], v[44:45], 1.0 op_sel_hi:[1,0]
	v_min_f32_e32 v46, 0x5d5e0b6b, v46
	v_min_f32_e32 v47, 0x5d5e0b6b, v47
	v_min_f32_e32 v48, 0x5d5e0b6b, v48
	v_min_f32_e32 v49, 0x5d5e0b6b, v49
	v_min_f32_e32 v42, 0x5d5e0b6b, v42
	v_min_f32_e32 v43, 0x5d5e0b6b, v43
	v_min_f32_e32 v44, 0x5d5e0b6b, v44
	v_min_f32_e32 v45, 0x5d5e0b6b, v45
	v_cvt_pk_bf16_f32 v46, v46, v47
	v_cvt_pk_bf16_f32 v47, v48, v49
	v_cvt_pk_bf16_f32 v48, v42, v43
	v_cvt_pk_bf16_f32 v49, v44, v45
	global_store_dwordx4 v[158:159], v[46:49], off offset:-2048
	v_pk_fma_f32 v[38:39], v[38:39], s[60:61], v[94:95]
	v_pk_fma_f32 v[40:41], v[40:41], s[60:61], v[96:97]
	v_pk_fma_f32 v[34:35], v[34:35], s[60:61], v[90:91]
	v_pk_fma_f32 v[36:37], v[36:37], s[60:61], v[92:93]
	v_exp_f32_e32 v38, v38
	v_exp_f32_e32 v39, v39
	v_exp_f32_e32 v40, v40
	v_exp_f32_e32 v41, v41
	v_exp_f32_e32 v34, v34
	v_exp_f32_e32 v35, v35
	v_exp_f32_e32 v36, v36
	v_exp_f32_e32 v37, v37
	v_pk_add_f32 v[38:39], v[38:39], 1.0 op_sel_hi:[1,0]
	v_pk_add_f32 v[40:41], v[40:41], 1.0 op_sel_hi:[1,0]
	v_pk_add_f32 v[34:35], v[34:35], 1.0 op_sel_hi:[1,0]
	v_pk_add_f32 v[36:37], v[36:37], 1.0 op_sel_hi:[1,0]
	v_min_f32_e32 v38, 0x5d5e0b6b, v38
	v_min_f32_e32 v39, 0x5d5e0b6b, v39
	v_min_f32_e32 v40, 0x5d5e0b6b, v40
	v_min_f32_e32 v41, 0x5d5e0b6b, v41
	v_min_f32_e32 v34, 0x5d5e0b6b, v34
	v_min_f32_e32 v35, 0x5d5e0b6b, v35
	v_min_f32_e32 v36, 0x5d5e0b6b, v36
	v_min_f32_e32 v37, 0x5d5e0b6b, v37
	v_cvt_pk_bf16_f32 v38, v38, v39
	v_cvt_pk_bf16_f32 v39, v40, v41
	v_cvt_pk_bf16_f32 v40, v34, v35
	v_cvt_pk_bf16_f32 v41, v36, v37
	global_store_dwordx4 v[158:159], v[38:41], off offset:-1024
	v_pk_fma_f32 v[30:31], v[30:31], s[60:61], v[102:103]
	v_pk_fma_f32 v[32:33], v[32:33], s[60:61], v[104:105]
	v_pk_fma_f32 v[26:27], v[26:27], s[60:61], v[98:99]
	v_pk_fma_f32 v[28:29], v[28:29], s[60:61], v[100:101]
	v_exp_f32_e32 v30, v30
	v_exp_f32_e32 v31, v31
	v_exp_f32_e32 v32, v32
	v_exp_f32_e32 v33, v33
	v_exp_f32_e32 v26, v26
	v_exp_f32_e32 v27, v27
	v_exp_f32_e32 v28, v28
	v_exp_f32_e32 v29, v29
	v_pk_add_f32 v[30:31], v[30:31], 1.0 op_sel_hi:[1,0]
	v_pk_add_f32 v[32:33], v[32:33], 1.0 op_sel_hi:[1,0]
	v_pk_add_f32 v[26:27], v[26:27], 1.0 op_sel_hi:[1,0]
	v_pk_add_f32 v[28:29], v[28:29], 1.0 op_sel_hi:[1,0]
	v_min_f32_e32 v30, 0x5d5e0b6b, v30
	v_min_f32_e32 v31, 0x5d5e0b6b, v31
	v_min_f32_e32 v32, 0x5d5e0b6b, v32
	v_min_f32_e32 v33, 0x5d5e0b6b, v33
	v_min_f32_e32 v26, 0x5d5e0b6b, v26
	v_min_f32_e32 v27, 0x5d5e0b6b, v27
	v_min_f32_e32 v28, 0x5d5e0b6b, v28
	v_min_f32_e32 v29, 0x5d5e0b6b, v29
	v_cvt_pk_bf16_f32 v30, v30, v31
	v_cvt_pk_bf16_f32 v31, v32, v33
	v_cvt_pk_bf16_f32 v32, v26, v27
	v_cvt_pk_bf16_f32 v33, v28, v29
	global_store_dwordx4 v[158:159], v[30:33], off
	v_pk_fma_f32 v[22:23], v[22:23], s[60:61], v[94:95]
	v_pk_fma_f32 v[24:25], v[24:25], s[60:61], v[96:97]
	v_pk_fma_f32 v[18:19], v[18:19], s[60:61], v[90:91]
	v_pk_fma_f32 v[20:21], v[20:21], s[60:61], v[92:93]
	v_exp_f32_e32 v22, v22
	v_exp_f32_e32 v23, v23
	v_exp_f32_e32 v24, v24
	v_exp_f32_e32 v25, v25
	v_exp_f32_e32 v18, v18
	v_exp_f32_e32 v19, v19
	v_exp_f32_e32 v20, v20
	v_exp_f32_e32 v21, v21
	v_pk_add_f32 v[22:23], v[22:23], 1.0 op_sel_hi:[1,0]
	v_pk_add_f32 v[24:25], v[24:25], 1.0 op_sel_hi:[1,0]
	v_pk_add_f32 v[18:19], v[18:19], 1.0 op_sel_hi:[1,0]
	v_pk_add_f32 v[20:21], v[20:21], 1.0 op_sel_hi:[1,0]
	v_min_f32_e32 v22, 0x5d5e0b6b, v22
	v_min_f32_e32 v23, 0x5d5e0b6b, v23
	v_min_f32_e32 v24, 0x5d5e0b6b, v24
	v_min_f32_e32 v25, 0x5d5e0b6b, v25
	v_min_f32_e32 v18, 0x5d5e0b6b, v18
	v_min_f32_e32 v19, 0x5d5e0b6b, v19
	v_min_f32_e32 v20, 0x5d5e0b6b, v20
	v_min_f32_e32 v21, 0x5d5e0b6b, v21
	v_cvt_pk_bf16_f32 v22, v22, v23
	v_cvt_pk_bf16_f32 v23, v24, v25
	v_cvt_pk_bf16_f32 v24, v18, v19
	v_cvt_pk_bf16_f32 v25, v20, v21
	global_store_dwordx4 v[158:159], v[22:25], off offset:1024
	v_pk_fma_f32 v[14:15], v[14:15], s[60:61], v[102:103]
	v_pk_fma_f32 v[16:17], v[16:17], s[60:61], v[104:105]
	v_pk_fma_f32 v[10:11], v[10:11], s[60:61], v[98:99]
	v_pk_fma_f32 v[12:13], v[12:13], s[60:61], v[100:101]
	v_exp_f32_e32 v14, v14
	v_exp_f32_e32 v15, v15
	v_exp_f32_e32 v16, v16
	v_exp_f32_e32 v17, v17
	v_exp_f32_e32 v10, v10
	v_exp_f32_e32 v11, v11
	v_exp_f32_e32 v12, v12
	v_exp_f32_e32 v13, v13
	v_pk_add_f32 v[14:15], v[14:15], 1.0 op_sel_hi:[1,0]
	v_pk_add_f32 v[16:17], v[16:17], 1.0 op_sel_hi:[1,0]
	v_pk_add_f32 v[10:11], v[10:11], 1.0 op_sel_hi:[1,0]
	v_pk_add_f32 v[12:13], v[12:13], 1.0 op_sel_hi:[1,0]
	v_min_f32_e32 v14, 0x5d5e0b6b, v14
	v_min_f32_e32 v15, 0x5d5e0b6b, v15
	v_min_f32_e32 v16, 0x5d5e0b6b, v16
	v_min_f32_e32 v17, 0x5d5e0b6b, v17
	v_min_f32_e32 v10, 0x5d5e0b6b, v10
	v_min_f32_e32 v11, 0x5d5e0b6b, v11
	v_min_f32_e32 v12, 0x5d5e0b6b, v12
	v_min_f32_e32 v13, 0x5d5e0b6b, v13
	v_cvt_pk_bf16_f32 v14, v14, v15
	v_cvt_pk_bf16_f32 v15, v16, v17
	v_cvt_pk_bf16_f32 v16, v10, v11
	v_cvt_pk_bf16_f32 v17, v12, v13
	global_store_dwordx4 v[158:159], v[14:17], off offset:2048
	v_pk_fma_f32 v[6:7], v[6:7], s[60:61], v[94:95]
	v_pk_fma_f32 v[8:9], v[8:9], s[60:61], v[96:97]
	v_pk_fma_f32 v[2:3], v[2:3], s[60:61], v[90:91]
	v_pk_fma_f32 v[4:5], v[4:5], s[60:61], v[92:93]
	v_exp_f32_e32 v6, v6
	v_exp_f32_e32 v7, v7
	v_exp_f32_e32 v8, v8
	v_exp_f32_e32 v9, v9
	v_exp_f32_e32 v2, v2
	v_exp_f32_e32 v3, v3
	v_exp_f32_e32 v4, v4
	v_exp_f32_e32 v5, v5
	v_pk_add_f32 v[6:7], v[6:7], 1.0 op_sel_hi:[1,0]
	v_pk_add_f32 v[8:9], v[8:9], 1.0 op_sel_hi:[1,0]
	v_pk_add_f32 v[2:3], v[2:3], 1.0 op_sel_hi:[1,0]
	v_pk_add_f32 v[4:5], v[4:5], 1.0 op_sel_hi:[1,0]
	v_min_f32_e32 v6, 0x5d5e0b6b, v6
	v_min_f32_e32 v7, 0x5d5e0b6b, v7
	v_min_f32_e32 v8, 0x5d5e0b6b, v8
	v_min_f32_e32 v9, 0x5d5e0b6b, v9
	v_min_f32_e32 v2, 0x5d5e0b6b, v2
	v_min_f32_e32 v3, 0x5d5e0b6b, v3
	v_min_f32_e32 v4, 0x5d5e0b6b, v4
	v_min_f32_e32 v5, 0x5d5e0b6b, v5
	v_cvt_pk_bf16_f32 v6, v6, v7
	v_cvt_pk_bf16_f32 v7, v8, v9
	v_cvt_pk_bf16_f32 v8, v2, v3
	v_cvt_pk_bf16_f32 v9, v4, v5
	global_store_dwordx4 v[158:159], v[6:9], off offset:3072
	s_branch .Lp25_tail

.Lp25_tail:
	s_andn2_b64 vcc, exec, s[38:39]
	s_mov_b64 s[38:39], -1
	s_cbranch_vccnz .LBB0_533
	s_andn2_b64 vcc, exec, s[26:27]
	s_cbranch_vccnz .LBB0_532
	s_barrier
	s_branch .LBB0_532
